# FFN epilogues read row statistics and conv weights from a double-buffered per-wave LDS slot that the previous tile's epilogue fills by LDS-DMA (static LDS block behind the dynamic one)
# baseline (speedup 1.0000x reference)
.LBB0_363:
	ds_read_b128 v[76:79], v231
	ds_read_b128 v[80:83], v216
	ds_read_b128 v[84:87], v231 offset:2048
	ds_read_b128 v[88:91], v216 offset:2048
	s_add_u32 s8, s6, 0x100
	s_addc_u32 s9, s7, 0
	s_cmp_eq_u32 s65, 28
	s_cselect_b32 s39, s31, s9
	s_cselect_b32 s38, s33, s8
	s_cselect_b32 s11, s29, s64
	s_cselect_b32 s10, s62, s63
	s_add_i32 m0, s44, 0xc000
	ds_read_b128 v[92:95], v241
	ds_read_b128 v[96:99], v217
	ds_read_b128 v[100:103], v241 offset:2048
	ds_read_b128 v[104:107], v217 offset:2048
	ds_read_b128 v[180:183], v241 offset:4096
	ds_read_b128 v[184:187], v217 offset:4096
	ds_read_b128 v[188:191], v241 offset:6144
	ds_read_b128 v[192:195], v217 offset:6144
	global_load_lds_dwordx4 v172, s[6:7]
	s_add_i32 m0, s44, 0xe000
	s_nop 0
	global_load_lds_dwordx4 v174, s[6:7]
	s_waitcnt lgkmcnt(8)
	s_barrier
	s_waitcnt lgkmcnt(0)
	s_setprio 1
	s_waitcnt lgkmcnt(0)
	v_mfma_f32_16x16x32_bf16 v[158:161], v[76:79], v[92:95], v[158:161]
	v_mfma_f32_16x16x32_bf16 v[158:161], v[80:83], v[96:99], v[158:161]
	v_mfma_f32_16x16x32_bf16 v[60:63], v[88:91], v[96:99], v[60:63]
	v_mfma_f32_16x16x32_bf16 v[60:63], v[84:87], v[92:95], v[60:63]
	v_mfma_f32_16x16x32_bf16 v[52:55], v[84:87], v[100:103], v[52:55]
	v_mfma_f32_16x16x32_bf16 v[52:55], v[88:91], v[104:107], v[52:55]
	v_mfma_f32_16x16x32_bf16 v[150:153], v[80:83], v[104:107], v[150:153]
	v_mfma_f32_16x16x32_bf16 v[150:153], v[76:79], v[100:103], v[150:153]
	v_mfma_f32_16x16x32_bf16 v[146:149], v[76:79], v[180:183], v[146:149]
	v_mfma_f32_16x16x32_bf16 v[146:149], v[80:83], v[184:187], v[146:149]
	v_mfma_f32_16x16x32_bf16 v[48:51], v[88:91], v[184:187], v[48:51]
	v_mfma_f32_16x16x32_bf16 v[48:51], v[84:87], v[180:183], v[48:51]
	v_mfma_f32_16x16x32_bf16 v[40:43], v[84:87], v[188:191], v[40:43]
	v_mfma_f32_16x16x32_bf16 v[40:43], v[88:91], v[192:195], v[40:43]
	v_mfma_f32_16x16x32_bf16 v[138:141], v[80:83], v[192:195], v[138:141]
	v_mfma_f32_16x16x32_bf16 v[138:141], v[76:79], v[188:191], v[138:141]
	s_setprio 0
	s_barrier
	s_add_i32 s6, s58, s42
	s_add_u32 s98, s10, s14
	s_addc_u32 s99, s11, s15
	s_mov_b32 m0, s6
	ds_read_b128 v[196:199], v242
	ds_read_b128 v[200:203], v244
	ds_read_b128 v[204:207], v242 offset:2048
	ds_read_b128 v[208:211], v244 offset:2048
	global_load_lds_dwordx4 v164, s[10:11]
	s_add_i32 m0, s6, 0x2000
	s_nop 0
	global_load_lds_dwordx4 v166, s[10:11]
	s_barrier
	s_waitcnt lgkmcnt(0)
	s_setprio 1
	s_waitcnt lgkmcnt(0)
	v_mfma_f32_16x16x32_bf16 v[154:157], v[196:199], v[92:95], v[154:157]
	v_mfma_f32_16x16x32_bf16 v[154:157], v[200:203], v[96:99], v[154:157]
	v_mfma_f32_16x16x32_bf16 v[56:59], v[208:211], v[96:99], v[56:59]
	v_mfma_f32_16x16x32_bf16 v[56:59], v[204:207], v[92:95], v[56:59]
	v_mfma_f32_16x16x32_bf16 v[44:47], v[204:207], v[100:103], v[44:47]
	v_mfma_f32_16x16x32_bf16 v[44:47], v[208:211], v[104:107], v[44:47]
	v_mfma_f32_16x16x32_bf16 v[36:39], v[208:211], v[184:187], v[36:39]
	v_mfma_f32_16x16x32_bf16 v[36:39], v[204:207], v[180:183], v[36:39]
	v_mfma_f32_16x16x32_bf16 v[32:35], v[204:207], v[188:191], v[32:35]
	v_mfma_f32_16x16x32_bf16 v[32:35], v[208:211], v[192:195], v[32:35]
	v_mfma_f32_16x16x32_bf16 v[92:95], v[196:199], v[100:103], v[142:145]
	v_mfma_f32_16x16x32_bf16 v[92:95], v[200:203], v[104:107], v[92:95]
	v_mfma_f32_16x16x32_bf16 v[96:99], v[200:203], v[184:187], v[134:137]
	v_mfma_f32_16x16x32_bf16 v[96:99], v[196:199], v[180:183], v[96:99]
	v_mfma_f32_16x16x32_bf16 v[100:103], v[196:199], v[188:191], v[130:133]
	v_mfma_f32_16x16x32_bf16 v[100:103], v[200:203], v[192:195], v[100:103]
	s_setprio 0
	s_mov_b32 m0, s44
	s_add_u32 s100, s38, s14
	s_addc_u32 s101, s39, s15
	s_barrier
	ds_read_b128 v[104:107], v241 offset:16384
	ds_read_b128 v[130:133], v217 offset:16384
	ds_read_b128 v[134:137], v241 offset:18432
	ds_read_b128 v[142:145], v217 offset:18432
	ds_read_b128 v[180:183], v241 offset:20480
	ds_read_b128 v[184:187], v217 offset:20480
	ds_read_b128 v[188:191], v241 offset:22528
	ds_read_b128 v[192:195], v217 offset:22528
	global_load_lds_dwordx4 v170, s[38:39]
	s_mov_b32 m0, s45
	s_nop 0
	global_load_lds_dwordx4 v168, s[38:39]
	s_barrier
	s_waitcnt lgkmcnt(0)
	s_setprio 1
	s_waitcnt lgkmcnt(0)
	v_mfma_f32_16x16x32_bf16 v[126:129], v[76:79], v[104:107], v[126:129]
	v_mfma_f32_16x16x32_bf16 v[126:129], v[80:83], v[130:133], v[126:129]
	v_mfma_f32_16x16x32_bf16 v[28:31], v[88:91], v[130:133], v[28:31]
	v_mfma_f32_16x16x32_bf16 v[28:31], v[84:87], v[104:107], v[28:31]
	v_mfma_f32_16x16x32_bf16 v[24:27], v[84:87], v[134:137], v[24:27]
	v_mfma_f32_16x16x32_bf16 v[24:27], v[88:91], v[142:145], v[24:27]
	v_mfma_f32_16x16x32_bf16 v[122:125], v[80:83], v[142:145], v[122:125]
	v_mfma_f32_16x16x32_bf16 v[122:125], v[76:79], v[134:137], v[122:125]
	v_mfma_f32_16x16x32_bf16 v[114:117], v[76:79], v[180:183], v[114:117]
	v_mfma_f32_16x16x32_bf16 v[114:117], v[80:83], v[184:187], v[114:117]
	v_mfma_f32_16x16x32_bf16 v[20:23], v[88:91], v[184:187], v[20:23]
	v_mfma_f32_16x16x32_bf16 v[20:23], v[84:87], v[180:183], v[20:23]
	v_mfma_f32_16x16x32_bf16 v[4:7], v[84:87], v[188:191], v[4:7]
	v_mfma_f32_16x16x32_bf16 v[4:7], v[88:91], v[192:195], v[4:7]
	v_mfma_f32_16x16x32_bf16 v[72:75], v[80:83], v[192:195], v[72:75]
	v_mfma_f32_16x16x32_bf16 v[72:75], v[76:79], v[188:191], v[72:75]
	s_setprio 0
	s_barrier
	s_add_u32 s6, s10, 0x1600000
	s_addc_u32 s7, s11, 0
	s_add_i32 s66, s59, s42
	s_mov_b32 m0, s66
	s_nop 0
	global_load_lds_dwordx4 v164, s[6:7]
	s_add_i32 m0, s66, 0x2000
	s_nop 0
	global_load_lds_dwordx4 v166, s[6:7]
	s_waitcnt vmcnt(6)
	s_barrier
	s_setprio 1
	v_mfma_f32_16x16x32_bf16 v[16:19], v[204:207], v[104:107], v[16:19]
	v_mfma_f32_16x16x32_bf16 v[16:19], v[208:211], v[130:133], v[16:19]
	v_mfma_f32_16x16x32_bf16 v[12:15], v[208:211], v[142:145], v[12:15]
	v_mfma_f32_16x16x32_bf16 v[12:15], v[204:207], v[134:137], v[12:15]
	v_mfma_f32_16x16x32_bf16 v[8:11], v[204:207], v[180:183], v[8:11]
	v_mfma_f32_16x16x32_bf16 v[8:11], v[208:211], v[184:187], v[8:11]
	v_mfma_f32_16x16x32_bf16 v[68:71], v[200:203], v[184:187], v[68:71]
	v_mfma_f32_16x16x32_bf16 v[68:71], v[196:199], v[180:183], v[68:71]
	v_mfma_f32_16x16x32_bf16 v[64:67], v[196:199], v[188:191], v[64:67]
	v_mfma_f32_16x16x32_bf16 v[64:67], v[200:203], v[192:195], v[64:67]
	v_mfma_f32_16x16x32_bf16 v[0:3], v[208:211], v[192:195], v[0:3]
	v_mfma_f32_16x16x32_bf16 v[0:3], v[204:207], v[188:191], v[0:3]
	v_mfma_f32_16x16x32_bf16 v[76:79], v[196:199], v[104:107], v[118:121]
	v_mfma_f32_16x16x32_bf16 v[76:79], v[200:203], v[130:133], v[76:79]
	v_mfma_f32_16x16x32_bf16 v[80:83], v[200:203], v[142:145], v[110:113]
	v_mfma_f32_16x16x32_bf16 v[80:83], v[196:199], v[134:137], v[80:83]
	s_setprio 0
	s_add_i32 s66, 0, 0x18000
	s_barrier
	ds_read_b128 v[84:87], v245
	ds_read_b128 v[88:91], v246
	ds_read_b128 v[104:107], v245 offset:2048
	ds_read_b128 v[108:111], v246 offset:2048
	s_add_u32 s6, s38, 0x40000
	s_addc_u32 s7, s39, 0
	s_mov_b32 m0, s46
	ds_read_b128 v[118:121], v241 offset:32768
	ds_read_b128 v[130:133], v217 offset:32768
	ds_read_b128 v[134:137], v241 offset:34816
	ds_read_b128 v[180:183], v217 offset:34816
	ds_read_b128 v[184:187], v241 offset:36864
	ds_read_b128 v[188:191], v217 offset:36864
	ds_read_b128 v[192:195], v241 offset:38912
	ds_read_b128 v[196:199], v217 offset:38912
	global_load_lds_dwordx4 v170, s[6:7]
	s_mov_b32 m0, s47
	s_nop 0
	global_load_lds_dwordx4 v168, s[6:7]
	s_waitcnt lgkmcnt(8)
	s_barrier
	s_waitcnt lgkmcnt(0)
	s_setprio 1
	s_waitcnt lgkmcnt(0)
	v_mfma_f32_16x16x32_bf16 v[142:145], v[84:87], v[118:121], v[158:161]
	v_mfma_f32_16x16x32_bf16 v[158:161], v[88:91], v[130:133], v[142:145]
	v_mfma_f32_16x16x32_bf16 v[60:63], v[108:111], v[130:133], v[60:63]
	v_mfma_f32_16x16x32_bf16 v[60:63], v[104:107], v[118:121], v[60:63]
	v_mfma_f32_16x16x32_bf16 v[52:55], v[104:107], v[134:137], v[52:55]
	v_mfma_f32_16x16x32_bf16 v[52:55], v[108:111], v[180:183], v[52:55]
	v_mfma_f32_16x16x32_bf16 v[48:51], v[108:111], v[188:191], v[48:51]
	v_mfma_f32_16x16x32_bf16 v[48:51], v[104:107], v[184:187], v[48:51]
	v_mfma_f32_16x16x32_bf16 v[40:43], v[104:107], v[192:195], v[40:43]
	v_mfma_f32_16x16x32_bf16 v[40:43], v[108:111], v[196:199], v[40:43]
	v_mfma_f32_16x16x32_bf16 v[138:141], v[88:91], v[196:199], v[138:141]
	v_mfma_f32_16x16x32_bf16 v[138:141], v[84:87], v[192:195], v[138:141]
	v_mfma_f32_16x16x32_bf16 v[142:145], v[84:87], v[134:137], v[150:153]
	v_mfma_f32_16x16x32_bf16 v[150:153], v[88:91], v[180:183], v[142:145]
	v_mfma_f32_16x16x32_bf16 v[142:145], v[84:87], v[184:187], v[146:149]
	v_mfma_f32_16x16x32_bf16 v[146:149], v[88:91], v[188:191], v[142:145]
	s_setprio 0
	s_barrier
	s_add_i32 s38, 0, 0x1c000
	s_add_i32 s6, s66, s42
	ds_read_b128 v[200:203], v247
	ds_read_b128 v[204:207], v248
	ds_read_b128 v[208:211], v247 offset:2048
	ds_read_b128 v[212:215], v248 offset:2048
	s_mov_b32 m0, s6
	s_nop 0
	global_load_lds_dwordx4 v164, s[98:99]
	s_add_i32 m0, s6, 0x2000
	s_nop 0
	global_load_lds_dwordx4 v166, s[98:99]
	s_barrier
	s_waitcnt lgkmcnt(0)
	s_setprio 1
	s_waitcnt lgkmcnt(0)
	v_mfma_f32_16x16x32_bf16 v[142:145], v[200:203], v[118:121], v[154:157]
	v_mfma_f32_16x16x32_bf16 v[154:157], v[204:207], v[130:133], v[142:145]
	v_mfma_f32_16x16x32_bf16 v[56:59], v[212:215], v[130:133], v[56:59]
	v_mfma_f32_16x16x32_bf16 v[56:59], v[208:211], v[118:121], v[56:59]
	v_mfma_f32_16x16x32_bf16 v[44:47], v[208:211], v[134:137], v[44:47]
	v_mfma_f32_16x16x32_bf16 v[44:47], v[212:215], v[180:183], v[44:47]
	v_mfma_f32_16x16x32_bf16 v[36:39], v[212:215], v[188:191], v[36:39]
	v_mfma_f32_16x16x32_bf16 v[36:39], v[208:211], v[184:187], v[36:39]
	v_mfma_f32_16x16x32_bf16 v[32:35], v[208:211], v[192:195], v[32:35]
	v_mfma_f32_16x16x32_bf16 v[32:35], v[212:215], v[196:199], v[32:35]
	v_mfma_f32_16x16x32_bf16 v[92:95], v[200:203], v[134:137], v[92:95]
	v_mfma_f32_16x16x32_bf16 v[142:145], v[204:207], v[180:183], v[92:95]
	v_mfma_f32_16x16x32_bf16 v[92:95], v[200:203], v[184:187], v[96:99]
	v_mfma_f32_16x16x32_bf16 v[134:137], v[204:207], v[188:191], v[92:95]
	v_mfma_f32_16x16x32_bf16 v[92:95], v[200:203], v[192:195], v[100:103]
	v_mfma_f32_16x16x32_bf16 v[130:133], v[204:207], v[196:199], v[92:95]
	s_setprio 0
	s_mov_b32 m0, s52
	s_barrier
	ds_read_b128 v[92:95], v241 offset:49152
	ds_read_b128 v[96:99], v217 offset:49152
	ds_read_b128 v[100:103], v241 offset:51200
	ds_read_b128 v[180:183], v217 offset:51200
	ds_read_b128 v[184:187], v241 offset:53248
	ds_read_b128 v[188:191], v217 offset:53248
	ds_read_b128 v[192:195], v241 offset:55296
	ds_read_b128 v[196:199], v217 offset:55296
	global_load_lds_dwordx4 v170, s[100:101]
	s_mov_b32 m0, s53
	s_nop 0
	global_load_lds_dwordx4 v168, s[100:101]
	s_barrier
	s_waitcnt lgkmcnt(0)
	s_setprio 1
	s_waitcnt lgkmcnt(0)
	v_mfma_f32_16x16x32_bf16 v[118:121], v[84:87], v[92:95], v[126:129]
	v_mfma_f32_16x16x32_bf16 v[126:129], v[88:91], v[96:99], v[118:121]
	v_mfma_f32_16x16x32_bf16 v[28:31], v[108:111], v[96:99], v[28:31]
	v_mfma_f32_16x16x32_bf16 v[28:31], v[104:107], v[92:95], v[28:31]
	v_mfma_f32_16x16x32_bf16 v[24:27], v[104:107], v[100:103], v[24:27]
	v_mfma_f32_16x16x32_bf16 v[24:27], v[108:111], v[180:183], v[24:27]
	v_mfma_f32_16x16x32_bf16 v[20:23], v[108:111], v[188:191], v[20:23]
	v_mfma_f32_16x16x32_bf16 v[20:23], v[104:107], v[184:187], v[20:23]
	v_mfma_f32_16x16x32_bf16 v[112:115], v[84:87], v[184:187], v[114:117]
	v_mfma_f32_16x16x32_bf16 v[114:117], v[88:91], v[188:191], v[112:115]
	v_mfma_f32_16x16x32_bf16 v[72:75], v[88:91], v[196:199], v[72:75]
	v_mfma_f32_16x16x32_bf16 v[72:75], v[84:87], v[192:195], v[72:75]
	v_mfma_f32_16x16x32_bf16 v[118:121], v[84:87], v[100:103], v[122:125]
	v_mfma_f32_16x16x32_bf16 v[122:125], v[88:91], v[180:183], v[118:121]
	v_mfma_f32_16x16x32_bf16 v[4:7], v[104:107], v[192:195], v[4:7]
	v_mfma_f32_16x16x32_bf16 v[4:7], v[108:111], v[196:199], v[4:7]
	s_setprio 0
	s_barrier
	s_add_u32 s6, s10, 0x1600080
	s_addc_u32 s7, s11, 0
	s_add_i32 s10, s38, s42
	s_mov_b32 m0, s10
	s_nop 0
	global_load_lds_dwordx4 v164, s[6:7]
	s_add_i32 m0, s10, 0x2000
	s_nop 0
	global_load_lds_dwordx4 v166, s[6:7]
	s_waitcnt vmcnt(6)
	s_barrier
	s_setprio 1
	v_mfma_f32_16x16x32_bf16 v[76:79], v[200:203], v[92:95], v[76:79]
	v_mfma_f32_16x16x32_bf16 v[118:121], v[204:207], v[96:99], v[76:79]
	v_mfma_f32_16x16x32_bf16 v[16:19], v[212:215], v[96:99], v[16:19]
	v_mfma_f32_16x16x32_bf16 v[16:19], v[208:211], v[92:95], v[16:19]
	v_mfma_f32_16x16x32_bf16 v[12:15], v[208:211], v[100:103], v[12:15]
	v_mfma_f32_16x16x32_bf16 v[12:15], v[212:215], v[180:183], v[12:15]
	v_mfma_f32_16x16x32_bf16 v[8:11], v[212:215], v[188:191], v[8:11]
	v_mfma_f32_16x16x32_bf16 v[8:11], v[208:211], v[184:187], v[8:11]
	v_mfma_f32_16x16x32_bf16 v[68:71], v[200:203], v[184:187], v[68:71]
	v_mfma_f32_16x16x32_bf16 v[68:71], v[204:207], v[188:191], v[68:71]
	v_mfma_f32_16x16x32_bf16 v[64:67], v[204:207], v[196:199], v[64:67]
	v_mfma_f32_16x16x32_bf16 v[64:67], v[200:203], v[192:195], v[64:67]
	v_mfma_f32_16x16x32_bf16 v[76:79], v[200:203], v[100:103], v[80:83]
	v_mfma_f32_16x16x32_bf16 v[110:113], v[204:207], v[180:183], v[76:79]
	v_mfma_f32_16x16x32_bf16 v[0:3], v[208:211], v[192:195], v[0:3]
	v_mfma_f32_16x16x32_bf16 v[0:3], v[212:215], v[196:199], v[0:3]
	s_setprio 0
	s_add_i32 s65, s65, 2
	s_add_u32 s63, s63, 0x100
	s_addc_u32 s64, s64, 0
	s_cmp_gt_u32 s65, 29
	s_mov_b64 s[6:7], s[8:9]
	s_barrier
	s_cbranch_scc0 .LBB0_363
	s_cmp_eq_u32 s48, 1
	s_cbranch_scc1 .Lfs3_first
	s_lshl_b32 s8, s0, 8
	s_add_i32 s8, s8, s56
	s_lshl_b32 s9, s1, 7
	s_add_i32 s9, s9, s49
	s_lshl_b32 s10, s0, 3
	s_lshr_b32 s11, s56, 5
	s_add_i32 s10, s10, s11
	v_add_u32_e32 v200, s8, v163
	v_lshlrev_b32_e32 v213, 2, v200
	v_lshl_add_u32 v201, v225, 3, s9
	v_lshlrev_b32_e32 v212, 2, v201
	v_lshrrev_b32_e32 v109, 6, v222
	s_and_b32 s9, s48, 1
	v_readfirstlane_b32 s11, v109
	s_mul_i32 s9, s9, 0x3000
	s_mul_i32 s11, s11, 0x600
	s_add_i32 s9, s9, s11
	s_add_i32 s9, s9, 0x21040
	s_xor_b32 s11, s48, 1
	s_and_b32 s11, s11, 1
	s_mul_i32 s11, s11, 0x3000
	v_mul_u32_u24_e32 v109, 0x600, v109
	v_add_u32_e32 v109, s11, v109
	v_add_u32_e32 v109, 0x21040, v109
	v_lshl_add_u32 v213, v163, 2, v109
	ds_read_b32 v188, v213
	ds_read_b32 v189, v213 offset:64
	ds_read_b32 v190, v213 offset:128
	ds_read_b32 v191, v213 offset:192
	ds_read_b32 v192, v213 offset:256
	ds_read_b32 v193, v213 offset:320
	ds_read_b32 v194, v213 offset:384
	ds_read_b32 v195, v213 offset:448
	v_lshl_add_u32 v109, v225, 5, v109
	v_add_u32_e32 v109, 512, v109
	ds_read_b128 v[76:79], v109 offset:0
	ds_read_b128 v[80:83], v109 offset:128
	ds_read_b128 v[84:87], v109 offset:256
	ds_read_b128 v[88:91], v109 offset:384
	ds_read_b128 v[92:95], v109 offset:512
	ds_read_b128 v[96:99], v109 offset:640
	ds_read_b128 v[100:103], v109 offset:768
	ds_read_b128 v[104:107], v109 offset:896
	v_mul_u32_u24_e32 v215, 0x2c00, v200
	v_lshl_add_u32 v215, v201, 1, v215
	v_add_u32_e32 v213, s10, v163
	v_mul_u32_u24_e32 v217, 0xb000, v213
	v_add_u32_e32 v217, v217, v212
	v_cmp_lt_u32_e64 s[10:11], 13, v163
	v_cmp_lt_u32_e32 vcc, 1, v163
	v_mov_b32_e32 v214, 1.0
	v_mov_b32_e32 v216, 0xbfb8aa3b
	v_mov_b32_e32 v108, 0x3727c5ac
	s_waitcnt lgkmcnt(0)
	v_fmamk_f32 v188, v188, 0x3a000000, v108
	v_fmamk_f32 v189, v189, 0x3a000000, v108
	v_fmamk_f32 v190, v190, 0x3a000000, v108
	v_fmamk_f32 v191, v191, 0x3a000000, v108
	v_fmamk_f32 v192, v192, 0x3a000000, v108
	v_fmamk_f32 v193, v193, 0x3a000000, v108
	v_fmamk_f32 v194, v194, 0x3a000000, v108
	v_fmamk_f32 v195, v195, 0x3a000000, v108
	v_rsq_f32_e32 v188, v188
	v_rsq_f32_e32 v189, v189
	v_rsq_f32_e32 v190, v190
	v_rsq_f32_e32 v191, v191
	v_rsq_f32_e32 v192, v192
	v_rsq_f32_e32 v193, v193
	v_rsq_f32_e32 v194, v194
	v_rsq_f32_e32 v195, v195
	v_pk_mul_f32 v[158:159], v[158:159], v[188:189] op_sel_hi:[1,0]
	v_pk_mul_f32 v[160:161], v[160:161], v[188:189] op_sel_hi:[1,0]
	v_pk_mul_f32 v[60:61], v[60:61], v[188:189] op_sel_hi:[1,0]
	v_pk_mul_f32 v[62:63], v[62:63], v[188:189] op_sel_hi:[1,0]
	v_pk_mul_f32 v[154:155], v[154:155], v[188:189] op_sel_hi:[1,0]
	v_pk_mul_f32 v[156:157], v[156:157], v[188:189] op_sel_hi:[1,0]
	v_pk_mul_f32 v[56:57], v[56:57], v[188:189] op_sel_hi:[1,0]
	v_pk_mul_f32 v[58:59], v[58:59], v[188:189] op_sel_hi:[1,0]
	v_pk_mul_f32 v[150:151], v[150:151], v[188:189] op_sel:[0,1] op_sel_hi:[1,1]
	v_pk_mul_f32 v[152:153], v[152:153], v[188:189] op_sel:[0,1] op_sel_hi:[1,1]
	v_pk_mul_f32 v[52:53], v[52:53], v[188:189] op_sel:[0,1] op_sel_hi:[1,1]
	v_pk_mul_f32 v[54:55], v[54:55], v[188:189] op_sel:[0,1] op_sel_hi:[1,1]
	v_pk_mul_f32 v[142:143], v[142:143], v[188:189] op_sel:[0,1] op_sel_hi:[1,1]
	v_pk_mul_f32 v[144:145], v[144:145], v[188:189] op_sel:[0,1] op_sel_hi:[1,1]
	v_pk_mul_f32 v[44:45], v[44:45], v[188:189] op_sel:[0,1] op_sel_hi:[1,1]
	v_pk_mul_f32 v[46:47], v[46:47], v[188:189] op_sel:[0,1] op_sel_hi:[1,1]
	v_pk_mul_f32 v[146:147], v[146:147], v[190:191] op_sel_hi:[1,0]
	v_pk_mul_f32 v[148:149], v[148:149], v[190:191] op_sel_hi:[1,0]
	v_pk_mul_f32 v[48:49], v[48:49], v[190:191] op_sel_hi:[1,0]
	v_pk_mul_f32 v[50:51], v[50:51], v[190:191] op_sel_hi:[1,0]
	v_pk_mul_f32 v[134:135], v[134:135], v[190:191] op_sel_hi:[1,0]
	v_pk_mul_f32 v[136:137], v[136:137], v[190:191] op_sel_hi:[1,0]
	v_pk_mul_f32 v[36:37], v[36:37], v[190:191] op_sel_hi:[1,0]
	v_pk_mul_f32 v[38:39], v[38:39], v[190:191] op_sel_hi:[1,0]
	v_pk_mul_f32 v[138:139], v[138:139], v[190:191] op_sel:[0,1] op_sel_hi:[1,1]
	v_pk_mul_f32 v[140:141], v[140:141], v[190:191] op_sel:[0,1] op_sel_hi:[1,1]
	v_pk_mul_f32 v[40:41], v[40:41], v[190:191] op_sel:[0,1] op_sel_hi:[1,1]
	v_pk_mul_f32 v[42:43], v[42:43], v[190:191] op_sel:[0,1] op_sel_hi:[1,1]
	v_pk_mul_f32 v[130:131], v[130:131], v[190:191] op_sel:[0,1] op_sel_hi:[1,1]
	v_pk_mul_f32 v[132:133], v[132:133], v[190:191] op_sel:[0,1] op_sel_hi:[1,1]
	v_pk_mul_f32 v[32:33], v[32:33], v[190:191] op_sel:[0,1] op_sel_hi:[1,1]
	v_pk_mul_f32 v[34:35], v[34:35], v[190:191] op_sel:[0,1] op_sel_hi:[1,1]
	v_pk_mul_f32 v[126:127], v[126:127], v[192:193] op_sel_hi:[1,0]
	v_pk_mul_f32 v[128:129], v[128:129], v[192:193] op_sel_hi:[1,0]
	v_pk_mul_f32 v[28:29], v[28:29], v[192:193] op_sel_hi:[1,0]
	v_pk_mul_f32 v[30:31], v[30:31], v[192:193] op_sel_hi:[1,0]
	v_pk_mul_f32 v[118:119], v[118:119], v[192:193] op_sel_hi:[1,0]
	v_pk_mul_f32 v[120:121], v[120:121], v[192:193] op_sel_hi:[1,0]
	v_pk_mul_f32 v[16:17], v[16:17], v[192:193] op_sel_hi:[1,0]
	v_pk_mul_f32 v[18:19], v[18:19], v[192:193] op_sel_hi:[1,0]
	v_pk_mul_f32 v[122:123], v[122:123], v[192:193] op_sel:[0,1] op_sel_hi:[1,1]
	v_pk_mul_f32 v[124:125], v[124:125], v[192:193] op_sel:[0,1] op_sel_hi:[1,1]
	v_pk_mul_f32 v[24:25], v[24:25], v[192:193] op_sel:[0,1] op_sel_hi:[1,1]
	v_pk_mul_f32 v[26:27], v[26:27], v[192:193] op_sel:[0,1] op_sel_hi:[1,1]
	v_pk_mul_f32 v[110:111], v[110:111], v[192:193] op_sel:[0,1] op_sel_hi:[1,1]
	v_pk_mul_f32 v[112:113], v[112:113], v[192:193] op_sel:[0,1] op_sel_hi:[1,1]
	v_pk_mul_f32 v[12:13], v[12:13], v[192:193] op_sel:[0,1] op_sel_hi:[1,1]
	v_pk_mul_f32 v[14:15], v[14:15], v[192:193] op_sel:[0,1] op_sel_hi:[1,1]
	v_pk_mul_f32 v[114:115], v[114:115], v[194:195] op_sel_hi:[1,0]
	v_pk_mul_f32 v[116:117], v[116:117], v[194:195] op_sel_hi:[1,0]
	v_pk_mul_f32 v[20:21], v[20:21], v[194:195] op_sel_hi:[1,0]
	v_pk_mul_f32 v[22:23], v[22:23], v[194:195] op_sel_hi:[1,0]
	v_pk_mul_f32 v[68:69], v[68:69], v[194:195] op_sel_hi:[1,0]
	v_pk_mul_f32 v[70:71], v[70:71], v[194:195] op_sel_hi:[1,0]
	v_pk_mul_f32 v[8:9], v[8:9], v[194:195] op_sel_hi:[1,0]
	v_pk_mul_f32 v[10:11], v[10:11], v[194:195] op_sel_hi:[1,0]
	v_pk_mul_f32 v[72:73], v[72:73], v[194:195] op_sel:[0,1] op_sel_hi:[1,1]
	v_pk_mul_f32 v[74:75], v[74:75], v[194:195] op_sel:[0,1] op_sel_hi:[1,1]
	v_pk_mul_f32 v[4:5], v[4:5], v[194:195] op_sel:[0,1] op_sel_hi:[1,1]
	v_pk_mul_f32 v[6:7], v[6:7], v[194:195] op_sel:[0,1] op_sel_hi:[1,1]
	v_pk_mul_f32 v[64:65], v[64:65], v[194:195] op_sel:[0,1] op_sel_hi:[1,1]
	v_pk_mul_f32 v[66:67], v[66:67], v[194:195] op_sel:[0,1] op_sel_hi:[1,1]
	v_pk_mul_f32 v[0:1], v[0:1], v[194:195] op_sel:[0,1] op_sel_hi:[1,1]
	v_pk_mul_f32 v[2:3], v[2:3], v[194:195] op_sel:[0,1] op_sel_hi:[1,1]
	v_cmp_gt_u32_e32 vcc, 2, v163
	s_nop 1
	s_mov_b64 exec, vcc
	v_add_u32_e32 v213, 0x5800, v217
	global_store_dwordx4 v217, v[158:161], s[70:71]
	global_store_dwordx4 v213, v[154:157], s[70:71]
	global_store_dwordx4 v217, v[60:63], s[70:71] offset:16
	global_store_dwordx4 v213, v[56:59], s[70:71] offset:16
	s_mov_b64 exec, s[10:11]
	v_add_u32_e32 v213, 0xfff7c000, v217
	global_store_dwordx4 v213, v[72:75], s[70:71]
	global_store_dwordx4 v213, v[4:7], s[70:71] offset:16
	v_add_u32_e32 v213, 0xfff81800, v217
	global_store_dwordx4 v213, v[64:67], s[70:71]
	global_store_dwordx4 v213, v[0:3], s[70:71] offset:16
	s_mov_b64 exec, -1
	v_cmp_lt_u32_e32 vcc, 1, v163
	s_cmp_lg_u64 s[4:5], 0
	s_cselect_b32 s8, s0, s30
	s_cselect_b32 s10, s1, s28
	s_lshl_b32 s8, s8, 8
	s_add_i32 s8, s8, s56
	s_lshl_b32 s10, s10, 7
	s_add_i32 s10, s10, s49
	v_and_b32_e32 v213, 63, v222
	v_add_u32_e32 v188, s8, v213
	v_lshlrev_b32_e32 v188, 2, v188
	s_mov_b32 m0, s9
	v_add_u32_e32 v189, 0x100, v188
	global_load_lds_dword v188, s[12:13]
	s_add_i32 m0, s9, 0x100
	v_and_b32_e32 v190, 7, v213
	global_load_lds_dword v189, s[12:13]
	v_lshrrev_b32_e32 v191, 3, v213
	v_lshlrev_b32_e32 v190, 4, v190
	s_lshl_b32 s10, s10, 2
	v_add_u32_e32 v190, s10, v190
	v_lshrrev_b32_e32 v192, 2, v191
	v_and_b32_e32 v191, 3, v191
	v_mul_u32_u24_e32 v192, 0x5800, v192
	v_add_u32_e32 v190, v190, v192
	v_mul_u32_u24_e32 v192, 0xb000, v191
	v_add_u32_e32 v192, v192, v190
	s_add_i32 m0, s9, 0x200
	s_mov_b32 s10, 0xff000000
	s_mov_b32 s11, 0xff000000
	s_andn2_b64 exec, exec, s[10:11]
	global_load_lds_dwordx4 v192, s[82:83]
	s_mov_b64 exec, s[10:11]
	global_load_lds_dwordx4 v190, s[84:85]
	s_mov_b64 exec, -1
	ds_read_b128 v[204:207], v109 offset:784
	ds_read_b128 v[208:211], v109 offset:912
	s_waitcnt lgkmcnt(0)
	v_pk_fma_f32 v[188:189], v[158:159], v[84:85], v[88:89]
	v_pk_fma_f32 v[190:191], v[160:161], v[86:87], v[90:91]
	v_pk_fma_f32 v[192:193], v[154:155], v[100:101], v[104:105]
	v_pk_fma_f32 v[194:195], v[156:157], v[102:103], v[106:107]
	v_fmac_f32_dpp v188, v158, v80 row_shr:1 row_mask:0xf bank_mask:0xf
	v_fmac_f32_dpp v189, v159, v81 row_shr:1 row_mask:0xf bank_mask:0xf
	v_fmac_f32_dpp v190, v160, v82 row_shr:1 row_mask:0xf bank_mask:0xf
	v_fmac_f32_dpp v191, v161, v83 row_shr:1 row_mask:0xf bank_mask:0xf
	v_fmac_f32_dpp v192, v154, v96 row_shr:1 row_mask:0xf bank_mask:0xf
	v_fmac_f32_dpp v193, v155, v97 row_shr:1 row_mask:0xf bank_mask:0xf
	v_fmac_f32_dpp v194, v156, v98 row_shr:1 row_mask:0xf bank_mask:0xf
	v_fmac_f32_dpp v195, v157, v99 row_shr:1 row_mask:0xf bank_mask:0xf
	v_fmac_f32_dpp v188, v158, v76 row_shr:2 row_mask:0xf bank_mask:0xf
	v_fmac_f32_dpp v189, v159, v77 row_shr:2 row_mask:0xf bank_mask:0xf
	v_fmac_f32_dpp v190, v160, v78 row_shr:2 row_mask:0xf bank_mask:0xf
	v_fmac_f32_dpp v191, v161, v79 row_shr:2 row_mask:0xf bank_mask:0xf
	v_fmac_f32_dpp v192, v154, v92 row_shr:2 row_mask:0xf bank_mask:0xf
	v_fmac_f32_dpp v193, v155, v93 row_shr:2 row_mask:0xf bank_mask:0xf
	v_fmac_f32_dpp v194, v156, v94 row_shr:2 row_mask:0xf bank_mask:0xf
	v_fmac_f32_dpp v195, v157, v95 row_shr:2 row_mask:0xf bank_mask:0xf
	v_pk_mul_f32 v[196:197], v[188:189], v[216:217] op_sel_hi:[1,0]
	v_pk_mul_f32 v[198:199], v[190:191], v[216:217] op_sel_hi:[1,0]
	v_exp_f32_e32 v196, v196
	v_exp_f32_e32 v197, v197
	v_exp_f32_e32 v198, v198
	v_exp_f32_e32 v199, v199
	v_pk_add_f32 v[196:197], v[196:197], v[214:215] op_sel_hi:[1,0]
	v_pk_add_f32 v[198:199], v[198:199], v[214:215] op_sel_hi:[1,0]
	v_rcp_f32_e32 v196, v196
	v_rcp_f32_e32 v197, v197
	v_rcp_f32_e32 v198, v198
	v_rcp_f32_e32 v199, v199
	v_pk_mul_f32 v[188:189], v[188:189], v[196:197]
	v_pk_mul_f32 v[190:191], v[190:191], v[198:199]
	v_pk_mul_f32 v[188:189], v[188:189], v[192:193]
	v_pk_mul_f32 v[190:191], v[190:191], v[194:195]
	v_cvt_pk_bf16_f32 v200, v188, v189
	v_cvt_pk_bf16_f32 v201, v190, v191
	v_pk_fma_f32 v[188:189], v[150:151], v[84:85], v[88:89]
	v_pk_fma_f32 v[190:191], v[152:153], v[86:87], v[90:91]
	v_pk_fma_f32 v[192:193], v[142:143], v[100:101], v[104:105]
	v_pk_fma_f32 v[194:195], v[144:145], v[102:103], v[106:107]
	v_fmac_f32_dpp v188, v150, v80 row_shr:1 row_mask:0xf bank_mask:0xf
	v_fmac_f32_dpp v189, v151, v81 row_shr:1 row_mask:0xf bank_mask:0xf
	v_fmac_f32_dpp v190, v152, v82 row_shr:1 row_mask:0xf bank_mask:0xf
	v_fmac_f32_dpp v191, v153, v83 row_shr:1 row_mask:0xf bank_mask:0xf
	v_fmac_f32_dpp v192, v142, v96 row_shr:1 row_mask:0xf bank_mask:0xf
	v_fmac_f32_dpp v193, v143, v97 row_shr:1 row_mask:0xf bank_mask:0xf
	v_fmac_f32_dpp v194, v144, v98 row_shr:1 row_mask:0xf bank_mask:0xf
	v_fmac_f32_dpp v195, v145, v99 row_shr:1 row_mask:0xf bank_mask:0xf
	v_fmac_f32_dpp v188, v150, v76 row_shr:2 row_mask:0xf bank_mask:0xf
	v_fmac_f32_dpp v189, v151, v77 row_shr:2 row_mask:0xf bank_mask:0xf
	v_fmac_f32_dpp v190, v152, v78 row_shr:2 row_mask:0xf bank_mask:0xf
	v_fmac_f32_dpp v191, v153, v79 row_shr:2 row_mask:0xf bank_mask:0xf
	v_fmac_f32_dpp v192, v142, v92 row_shr:2 row_mask:0xf bank_mask:0xf
	v_fmac_f32_dpp v193, v143, v93 row_shr:2 row_mask:0xf bank_mask:0xf
	v_fmac_f32_dpp v194, v144, v94 row_shr:2 row_mask:0xf bank_mask:0xf
	v_fmac_f32_dpp v195, v145, v95 row_shr:2 row_mask:0xf bank_mask:0xf
	v_fmac_f32_dpp v188, v158, v80 row_shl:15 row_mask:0xf bank_mask:0xf
	v_fmac_f32_dpp v189, v159, v81 row_shl:15 row_mask:0xf bank_mask:0xf
	v_fmac_f32_dpp v190, v160, v82 row_shl:15 row_mask:0xf bank_mask:0xf
	v_fmac_f32_dpp v191, v161, v83 row_shl:15 row_mask:0xf bank_mask:0xf
	v_fmac_f32_dpp v192, v154, v96 row_shl:15 row_mask:0xf bank_mask:0xf
	v_fmac_f32_dpp v193, v155, v97 row_shl:15 row_mask:0xf bank_mask:0xf
	v_fmac_f32_dpp v194, v156, v98 row_shl:15 row_mask:0xf bank_mask:0xf
	v_fmac_f32_dpp v195, v157, v99 row_shl:15 row_mask:0xf bank_mask:0xf
	v_fmac_f32_dpp v188, v158, v76 row_shl:14 row_mask:0xf bank_mask:0xf
	v_fmac_f32_dpp v189, v159, v77 row_shl:14 row_mask:0xf bank_mask:0xf
	v_fmac_f32_dpp v190, v160, v78 row_shl:14 row_mask:0xf bank_mask:0xf
	v_fmac_f32_dpp v191, v161, v79 row_shl:14 row_mask:0xf bank_mask:0xf
	v_fmac_f32_dpp v192, v154, v92 row_shl:14 row_mask:0xf bank_mask:0xf
	v_fmac_f32_dpp v193, v155, v93 row_shl:14 row_mask:0xf bank_mask:0xf
	v_fmac_f32_dpp v194, v156, v94 row_shl:14 row_mask:0xf bank_mask:0xf
	v_fmac_f32_dpp v195, v157, v95 row_shl:14 row_mask:0xf bank_mask:0xf
	v_pk_mul_f32 v[196:197], v[188:189], v[216:217] op_sel_hi:[1,0]
	v_pk_mul_f32 v[198:199], v[190:191], v[216:217] op_sel_hi:[1,0]
	v_exp_f32_e32 v196, v196
	v_exp_f32_e32 v197, v197
	v_exp_f32_e32 v198, v198
	v_exp_f32_e32 v199, v199
	v_pk_add_f32 v[196:197], v[196:197], v[214:215] op_sel_hi:[1,0]
	v_pk_add_f32 v[198:199], v[198:199], v[214:215] op_sel_hi:[1,0]
	v_rcp_f32_e32 v196, v196
	v_rcp_f32_e32 v197, v197
	v_rcp_f32_e32 v198, v198
	v_rcp_f32_e32 v199, v199
	v_pk_mul_f32 v[188:189], v[188:189], v[196:197]
	v_pk_mul_f32 v[190:191], v[190:191], v[198:199]
	v_pk_mul_f32 v[188:189], v[188:189], v[192:193]
	v_pk_mul_f32 v[190:191], v[190:191], v[194:195]
	v_cvt_pk_bf16_f32 v158, v188, v189
	v_cvt_pk_bf16_f32 v159, v190, v191
	ds_read_b128 v[154:157], v109 offset:16
	v_pk_fma_f32 v[188:189], v[146:147], v[84:85], v[88:89]
	v_pk_fma_f32 v[190:191], v[148:149], v[86:87], v[90:91]
	v_pk_fma_f32 v[192:193], v[134:135], v[100:101], v[104:105]
	v_pk_fma_f32 v[194:195], v[136:137], v[102:103], v[106:107]
	v_fmac_f32_dpp v188, v146, v80 row_shr:1 row_mask:0xf bank_mask:0xf
	v_fmac_f32_dpp v189, v147, v81 row_shr:1 row_mask:0xf bank_mask:0xf
	v_fmac_f32_dpp v190, v148, v82 row_shr:1 row_mask:0xf bank_mask:0xf
	v_fmac_f32_dpp v191, v149, v83 row_shr:1 row_mask:0xf bank_mask:0xf
	v_fmac_f32_dpp v192, v134, v96 row_shr:1 row_mask:0xf bank_mask:0xf
	v_fmac_f32_dpp v193, v135, v97 row_shr:1 row_mask:0xf bank_mask:0xf
	v_fmac_f32_dpp v194, v136, v98 row_shr:1 row_mask:0xf bank_mask:0xf
	v_fmac_f32_dpp v195, v137, v99 row_shr:1 row_mask:0xf bank_mask:0xf
	v_fmac_f32_dpp v188, v146, v76 row_shr:2 row_mask:0xf bank_mask:0xf
	v_fmac_f32_dpp v189, v147, v77 row_shr:2 row_mask:0xf bank_mask:0xf
	v_fmac_f32_dpp v190, v148, v78 row_shr:2 row_mask:0xf bank_mask:0xf
	v_fmac_f32_dpp v191, v149, v79 row_shr:2 row_mask:0xf bank_mask:0xf
	v_fmac_f32_dpp v192, v134, v92 row_shr:2 row_mask:0xf bank_mask:0xf
	v_fmac_f32_dpp v193, v135, v93 row_shr:2 row_mask:0xf bank_mask:0xf
	v_fmac_f32_dpp v194, v136, v94 row_shr:2 row_mask:0xf bank_mask:0xf
	v_fmac_f32_dpp v195, v137, v95 row_shr:2 row_mask:0xf bank_mask:0xf
	v_fmac_f32_dpp v188, v150, v80 row_shl:15 row_mask:0xf bank_mask:0xf
	v_fmac_f32_dpp v189, v151, v81 row_shl:15 row_mask:0xf bank_mask:0xf
	v_fmac_f32_dpp v190, v152, v82 row_shl:15 row_mask:0xf bank_mask:0xf
	v_fmac_f32_dpp v191, v153, v83 row_shl:15 row_mask:0xf bank_mask:0xf
	v_fmac_f32_dpp v192, v142, v96 row_shl:15 row_mask:0xf bank_mask:0xf
	v_fmac_f32_dpp v193, v143, v97 row_shl:15 row_mask:0xf bank_mask:0xf
	v_fmac_f32_dpp v194, v144, v98 row_shl:15 row_mask:0xf bank_mask:0xf
	v_fmac_f32_dpp v195, v145, v99 row_shl:15 row_mask:0xf bank_mask:0xf
	v_fmac_f32_dpp v188, v150, v76 row_shl:14 row_mask:0xf bank_mask:0xf
	v_fmac_f32_dpp v189, v151, v77 row_shl:14 row_mask:0xf bank_mask:0xf
	v_fmac_f32_dpp v190, v152, v78 row_shl:14 row_mask:0xf bank_mask:0xf
	v_fmac_f32_dpp v191, v153, v79 row_shl:14 row_mask:0xf bank_mask:0xf
	v_fmac_f32_dpp v192, v142, v92 row_shl:14 row_mask:0xf bank_mask:0xf
	v_fmac_f32_dpp v193, v143, v93 row_shl:14 row_mask:0xf bank_mask:0xf
	v_fmac_f32_dpp v194, v144, v94 row_shl:14 row_mask:0xf bank_mask:0xf
	v_fmac_f32_dpp v195, v145, v95 row_shl:14 row_mask:0xf bank_mask:0xf
	v_pk_mul_f32 v[196:197], v[188:189], v[216:217] op_sel_hi:[1,0]
	v_pk_mul_f32 v[198:199], v[190:191], v[216:217] op_sel_hi:[1,0]
	v_exp_f32_e32 v196, v196
	v_exp_f32_e32 v197, v197
	v_exp_f32_e32 v198, v198
	v_exp_f32_e32 v199, v199
	v_pk_add_f32 v[196:197], v[196:197], v[214:215] op_sel_hi:[1,0]
	v_pk_add_f32 v[198:199], v[198:199], v[214:215] op_sel_hi:[1,0]
	v_rcp_f32_e32 v196, v196
	v_rcp_f32_e32 v197, v197
	v_rcp_f32_e32 v198, v198
	v_rcp_f32_e32 v199, v199
	v_pk_mul_f32 v[188:189], v[188:189], v[196:197]
	v_pk_mul_f32 v[190:191], v[190:191], v[198:199]
	v_pk_mul_f32 v[188:189], v[188:189], v[192:193]
	v_pk_mul_f32 v[190:191], v[190:191], v[194:195]
	v_cvt_pk_bf16_f32 v150, v188, v189
	v_cvt_pk_bf16_f32 v151, v190, v191
	ds_read_b128 v[142:145], v109 offset:144
	v_pk_fma_f32 v[188:189], v[138:139], v[84:85], v[88:89]
	v_pk_fma_f32 v[190:191], v[140:141], v[86:87], v[90:91]
	v_pk_fma_f32 v[192:193], v[130:131], v[100:101], v[104:105]
	v_pk_fma_f32 v[194:195], v[132:133], v[102:103], v[106:107]
	v_fmac_f32_dpp v188, v138, v80 row_shr:1 row_mask:0xf bank_mask:0xf
	v_fmac_f32_dpp v189, v139, v81 row_shr:1 row_mask:0xf bank_mask:0xf
	v_fmac_f32_dpp v190, v140, v82 row_shr:1 row_mask:0xf bank_mask:0xf
	v_fmac_f32_dpp v191, v141, v83 row_shr:1 row_mask:0xf bank_mask:0xf
	v_fmac_f32_dpp v192, v130, v96 row_shr:1 row_mask:0xf bank_mask:0xf
	v_fmac_f32_dpp v193, v131, v97 row_shr:1 row_mask:0xf bank_mask:0xf
	v_fmac_f32_dpp v194, v132, v98 row_shr:1 row_mask:0xf bank_mask:0xf
	v_fmac_f32_dpp v195, v133, v99 row_shr:1 row_mask:0xf bank_mask:0xf
	v_fmac_f32_dpp v188, v138, v76 row_shr:2 row_mask:0xf bank_mask:0xf
	v_fmac_f32_dpp v189, v139, v77 row_shr:2 row_mask:0xf bank_mask:0xf
	v_fmac_f32_dpp v190, v140, v78 row_shr:2 row_mask:0xf bank_mask:0xf
	v_fmac_f32_dpp v191, v141, v79 row_shr:2 row_mask:0xf bank_mask:0xf
	v_fmac_f32_dpp v192, v130, v92 row_shr:2 row_mask:0xf bank_mask:0xf
	v_fmac_f32_dpp v193, v131, v93 row_shr:2 row_mask:0xf bank_mask:0xf
	v_fmac_f32_dpp v194, v132, v94 row_shr:2 row_mask:0xf bank_mask:0xf
	v_fmac_f32_dpp v195, v133, v95 row_shr:2 row_mask:0xf bank_mask:0xf
	v_fmac_f32_dpp v188, v146, v80 row_shl:15 row_mask:0xf bank_mask:0xf
	v_fmac_f32_dpp v189, v147, v81 row_shl:15 row_mask:0xf bank_mask:0xf
	v_fmac_f32_dpp v190, v148, v82 row_shl:15 row_mask:0xf bank_mask:0xf
	v_fmac_f32_dpp v191, v149, v83 row_shl:15 row_mask:0xf bank_mask:0xf
	v_fmac_f32_dpp v192, v134, v96 row_shl:15 row_mask:0xf bank_mask:0xf
	v_fmac_f32_dpp v193, v135, v97 row_shl:15 row_mask:0xf bank_mask:0xf
	v_fmac_f32_dpp v194, v136, v98 row_shl:15 row_mask:0xf bank_mask:0xf
	v_fmac_f32_dpp v195, v137, v99 row_shl:15 row_mask:0xf bank_mask:0xf
	v_fmac_f32_dpp v188, v146, v76 row_shl:14 row_mask:0xf bank_mask:0xf
	v_fmac_f32_dpp v189, v147, v77 row_shl:14 row_mask:0xf bank_mask:0xf
	v_fmac_f32_dpp v190, v148, v78 row_shl:14 row_mask:0xf bank_mask:0xf
	v_fmac_f32_dpp v191, v149, v79 row_shl:14 row_mask:0xf bank_mask:0xf
	v_fmac_f32_dpp v192, v134, v92 row_shl:14 row_mask:0xf bank_mask:0xf
	v_fmac_f32_dpp v193, v135, v93 row_shl:14 row_mask:0xf bank_mask:0xf
	v_fmac_f32_dpp v194, v136, v94 row_shl:14 row_mask:0xf bank_mask:0xf
	v_fmac_f32_dpp v195, v137, v95 row_shl:14 row_mask:0xf bank_mask:0xf
	v_pk_mul_f32 v[196:197], v[188:189], v[216:217] op_sel_hi:[1,0]
	v_pk_mul_f32 v[198:199], v[190:191], v[216:217] op_sel_hi:[1,0]
	v_exp_f32_e32 v196, v196
	v_exp_f32_e32 v197, v197
	v_exp_f32_e32 v198, v198
	v_exp_f32_e32 v199, v199
	v_pk_add_f32 v[196:197], v[196:197], v[214:215] op_sel_hi:[1,0]
	v_pk_add_f32 v[198:199], v[198:199], v[214:215] op_sel_hi:[1,0]
	v_rcp_f32_e32 v196, v196
	v_rcp_f32_e32 v197, v197
	v_rcp_f32_e32 v198, v198
	v_rcp_f32_e32 v199, v199
	v_pk_mul_f32 v[188:189], v[188:189], v[196:197]
	v_pk_mul_f32 v[190:191], v[190:191], v[198:199]
	v_pk_mul_f32 v[188:189], v[188:189], v[192:193]
	v_pk_mul_f32 v[190:191], v[190:191], v[194:195]
	v_cvt_pk_bf16_f32 v146, v188, v189
	v_cvt_pk_bf16_f32 v147, v190, v191
	ds_read_b128 v[134:137], v109 offset:272
	v_pk_fma_f32 v[188:189], v[126:127], v[84:85], v[88:89]
	v_pk_fma_f32 v[190:191], v[128:129], v[86:87], v[90:91]
	v_pk_fma_f32 v[192:193], v[118:119], v[100:101], v[104:105]
	v_pk_fma_f32 v[194:195], v[120:121], v[102:103], v[106:107]
	v_fmac_f32_dpp v188, v126, v80 row_shr:1 row_mask:0xf bank_mask:0xf
	v_fmac_f32_dpp v189, v127, v81 row_shr:1 row_mask:0xf bank_mask:0xf
	v_fmac_f32_dpp v190, v128, v82 row_shr:1 row_mask:0xf bank_mask:0xf
	v_fmac_f32_dpp v191, v129, v83 row_shr:1 row_mask:0xf bank_mask:0xf
	v_fmac_f32_dpp v192, v118, v96 row_shr:1 row_mask:0xf bank_mask:0xf
	v_fmac_f32_dpp v193, v119, v97 row_shr:1 row_mask:0xf bank_mask:0xf
	v_fmac_f32_dpp v194, v120, v98 row_shr:1 row_mask:0xf bank_mask:0xf
	v_fmac_f32_dpp v195, v121, v99 row_shr:1 row_mask:0xf bank_mask:0xf
	v_fmac_f32_dpp v188, v126, v76 row_shr:2 row_mask:0xf bank_mask:0xf
	v_fmac_f32_dpp v189, v127, v77 row_shr:2 row_mask:0xf bank_mask:0xf
	v_fmac_f32_dpp v190, v128, v78 row_shr:2 row_mask:0xf bank_mask:0xf
	v_fmac_f32_dpp v191, v129, v79 row_shr:2 row_mask:0xf bank_mask:0xf
	v_fmac_f32_dpp v192, v118, v92 row_shr:2 row_mask:0xf bank_mask:0xf
	v_fmac_f32_dpp v193, v119, v93 row_shr:2 row_mask:0xf bank_mask:0xf
	v_fmac_f32_dpp v194, v120, v94 row_shr:2 row_mask:0xf bank_mask:0xf
	v_fmac_f32_dpp v195, v121, v95 row_shr:2 row_mask:0xf bank_mask:0xf
	v_fmac_f32_dpp v188, v138, v80 row_shl:15 row_mask:0xf bank_mask:0xf
	v_fmac_f32_dpp v189, v139, v81 row_shl:15 row_mask:0xf bank_mask:0xf
	v_fmac_f32_dpp v190, v140, v82 row_shl:15 row_mask:0xf bank_mask:0xf
	v_fmac_f32_dpp v191, v141, v83 row_shl:15 row_mask:0xf bank_mask:0xf
	v_fmac_f32_dpp v192, v130, v96 row_shl:15 row_mask:0xf bank_mask:0xf
	v_fmac_f32_dpp v193, v131, v97 row_shl:15 row_mask:0xf bank_mask:0xf
	v_fmac_f32_dpp v194, v132, v98 row_shl:15 row_mask:0xf bank_mask:0xf
	v_fmac_f32_dpp v195, v133, v99 row_shl:15 row_mask:0xf bank_mask:0xf
	v_fmac_f32_dpp v188, v138, v76 row_shl:14 row_mask:0xf bank_mask:0xf
	v_fmac_f32_dpp v189, v139, v77 row_shl:14 row_mask:0xf bank_mask:0xf
	v_fmac_f32_dpp v190, v140, v78 row_shl:14 row_mask:0xf bank_mask:0xf
	v_fmac_f32_dpp v191, v141, v79 row_shl:14 row_mask:0xf bank_mask:0xf
	v_fmac_f32_dpp v192, v130, v92 row_shl:14 row_mask:0xf bank_mask:0xf
	v_fmac_f32_dpp v193, v131, v93 row_shl:14 row_mask:0xf bank_mask:0xf
	v_fmac_f32_dpp v194, v132, v94 row_shl:14 row_mask:0xf bank_mask:0xf
	v_fmac_f32_dpp v195, v133, v95 row_shl:14 row_mask:0xf bank_mask:0xf
	v_pk_mul_f32 v[196:197], v[188:189], v[216:217] op_sel_hi:[1,0]
	v_pk_mul_f32 v[198:199], v[190:191], v[216:217] op_sel_hi:[1,0]
	v_exp_f32_e32 v196, v196
	v_exp_f32_e32 v197, v197
	v_exp_f32_e32 v198, v198
	v_exp_f32_e32 v199, v199
	v_pk_add_f32 v[196:197], v[196:197], v[214:215] op_sel_hi:[1,0]
	v_pk_add_f32 v[198:199], v[198:199], v[214:215] op_sel_hi:[1,0]
	v_rcp_f32_e32 v196, v196
	v_rcp_f32_e32 v197, v197
	v_rcp_f32_e32 v198, v198
	v_rcp_f32_e32 v199, v199
	v_pk_mul_f32 v[188:189], v[188:189], v[196:197]
	v_pk_mul_f32 v[190:191], v[190:191], v[198:199]
	v_pk_mul_f32 v[188:189], v[188:189], v[192:193]
	v_pk_mul_f32 v[190:191], v[190:191], v[194:195]
	v_cvt_pk_bf16_f32 v138, v188, v189
	v_cvt_pk_bf16_f32 v139, v190, v191
	ds_read_b128 v[130:133], v109 offset:400
	v_pk_fma_f32 v[188:189], v[122:123], v[84:85], v[88:89]
	v_pk_fma_f32 v[190:191], v[124:125], v[86:87], v[90:91]
	v_pk_fma_f32 v[192:193], v[110:111], v[100:101], v[104:105]
	v_pk_fma_f32 v[194:195], v[112:113], v[102:103], v[106:107]
	v_fmac_f32_dpp v188, v122, v80 row_shr:1 row_mask:0xf bank_mask:0xf
	v_fmac_f32_dpp v189, v123, v81 row_shr:1 row_mask:0xf bank_mask:0xf
	v_fmac_f32_dpp v190, v124, v82 row_shr:1 row_mask:0xf bank_mask:0xf
	v_fmac_f32_dpp v191, v125, v83 row_shr:1 row_mask:0xf bank_mask:0xf
	v_fmac_f32_dpp v192, v110, v96 row_shr:1 row_mask:0xf bank_mask:0xf
	v_fmac_f32_dpp v193, v111, v97 row_shr:1 row_mask:0xf bank_mask:0xf
	v_fmac_f32_dpp v194, v112, v98 row_shr:1 row_mask:0xf bank_mask:0xf
	v_fmac_f32_dpp v195, v113, v99 row_shr:1 row_mask:0xf bank_mask:0xf
	v_fmac_f32_dpp v188, v122, v76 row_shr:2 row_mask:0xf bank_mask:0xf
	v_fmac_f32_dpp v189, v123, v77 row_shr:2 row_mask:0xf bank_mask:0xf
	v_fmac_f32_dpp v190, v124, v78 row_shr:2 row_mask:0xf bank_mask:0xf
	v_fmac_f32_dpp v191, v125, v79 row_shr:2 row_mask:0xf bank_mask:0xf
	v_fmac_f32_dpp v192, v110, v92 row_shr:2 row_mask:0xf bank_mask:0xf
	v_fmac_f32_dpp v193, v111, v93 row_shr:2 row_mask:0xf bank_mask:0xf
	v_fmac_f32_dpp v194, v112, v94 row_shr:2 row_mask:0xf bank_mask:0xf
	v_fmac_f32_dpp v195, v113, v95 row_shr:2 row_mask:0xf bank_mask:0xf
	v_fmac_f32_dpp v188, v126, v80 row_shl:15 row_mask:0xf bank_mask:0xf
	v_fmac_f32_dpp v189, v127, v81 row_shl:15 row_mask:0xf bank_mask:0xf
	v_fmac_f32_dpp v190, v128, v82 row_shl:15 row_mask:0xf bank_mask:0xf
	v_fmac_f32_dpp v191, v129, v83 row_shl:15 row_mask:0xf bank_mask:0xf
	v_fmac_f32_dpp v192, v118, v96 row_shl:15 row_mask:0xf bank_mask:0xf
	v_fmac_f32_dpp v193, v119, v97 row_shl:15 row_mask:0xf bank_mask:0xf
	v_fmac_f32_dpp v194, v120, v98 row_shl:15 row_mask:0xf bank_mask:0xf
	v_fmac_f32_dpp v195, v121, v99 row_shl:15 row_mask:0xf bank_mask:0xf
	v_fmac_f32_dpp v188, v126, v76 row_shl:14 row_mask:0xf bank_mask:0xf
	v_fmac_f32_dpp v189, v127, v77 row_shl:14 row_mask:0xf bank_mask:0xf
	v_fmac_f32_dpp v190, v128, v78 row_shl:14 row_mask:0xf bank_mask:0xf
	v_fmac_f32_dpp v191, v129, v79 row_shl:14 row_mask:0xf bank_mask:0xf
	v_fmac_f32_dpp v192, v118, v92 row_shl:14 row_mask:0xf bank_mask:0xf
	v_fmac_f32_dpp v193, v119, v93 row_shl:14 row_mask:0xf bank_mask:0xf
	v_fmac_f32_dpp v194, v120, v94 row_shl:14 row_mask:0xf bank_mask:0xf
	v_fmac_f32_dpp v195, v121, v95 row_shl:14 row_mask:0xf bank_mask:0xf
	v_pk_mul_f32 v[196:197], v[188:189], v[216:217] op_sel_hi:[1,0]
	v_pk_mul_f32 v[198:199], v[190:191], v[216:217] op_sel_hi:[1,0]
	v_exp_f32_e32 v196, v196
	v_exp_f32_e32 v197, v197
	v_exp_f32_e32 v198, v198
	v_exp_f32_e32 v199, v199
	v_pk_add_f32 v[196:197], v[196:197], v[214:215] op_sel_hi:[1,0]
	v_pk_add_f32 v[198:199], v[198:199], v[214:215] op_sel_hi:[1,0]
	v_rcp_f32_e32 v196, v196
	v_rcp_f32_e32 v197, v197
	v_rcp_f32_e32 v198, v198
	v_rcp_f32_e32 v199, v199
	v_pk_mul_f32 v[188:189], v[188:189], v[196:197]
	v_pk_mul_f32 v[190:191], v[190:191], v[198:199]
	v_pk_mul_f32 v[188:189], v[188:189], v[192:193]
	v_pk_mul_f32 v[190:191], v[190:191], v[194:195]
	v_cvt_pk_bf16_f32 v126, v188, v189
	v_cvt_pk_bf16_f32 v127, v190, v191
	ds_read_b128 v[118:121], v109 offset:528
	v_pk_fma_f32 v[188:189], v[114:115], v[84:85], v[88:89]
	v_pk_fma_f32 v[190:191], v[116:117], v[86:87], v[90:91]
	v_pk_fma_f32 v[192:193], v[68:69], v[100:101], v[104:105]
	v_pk_fma_f32 v[194:195], v[70:71], v[102:103], v[106:107]
	v_fmac_f32_dpp v188, v114, v80 row_shr:1 row_mask:0xf bank_mask:0xf
	v_fmac_f32_dpp v189, v115, v81 row_shr:1 row_mask:0xf bank_mask:0xf
	v_fmac_f32_dpp v190, v116, v82 row_shr:1 row_mask:0xf bank_mask:0xf
	v_fmac_f32_dpp v191, v117, v83 row_shr:1 row_mask:0xf bank_mask:0xf
	v_fmac_f32_dpp v192, v68, v96 row_shr:1 row_mask:0xf bank_mask:0xf
	v_fmac_f32_dpp v193, v69, v97 row_shr:1 row_mask:0xf bank_mask:0xf
	v_fmac_f32_dpp v194, v70, v98 row_shr:1 row_mask:0xf bank_mask:0xf
	v_fmac_f32_dpp v195, v71, v99 row_shr:1 row_mask:0xf bank_mask:0xf
	v_fmac_f32_dpp v188, v114, v76 row_shr:2 row_mask:0xf bank_mask:0xf
	v_fmac_f32_dpp v189, v115, v77 row_shr:2 row_mask:0xf bank_mask:0xf
	v_fmac_f32_dpp v190, v116, v78 row_shr:2 row_mask:0xf bank_mask:0xf
	v_fmac_f32_dpp v191, v117, v79 row_shr:2 row_mask:0xf bank_mask:0xf
	v_fmac_f32_dpp v192, v68, v92 row_shr:2 row_mask:0xf bank_mask:0xf
	v_fmac_f32_dpp v193, v69, v93 row_shr:2 row_mask:0xf bank_mask:0xf
	v_fmac_f32_dpp v194, v70, v94 row_shr:2 row_mask:0xf bank_mask:0xf
	v_fmac_f32_dpp v195, v71, v95 row_shr:2 row_mask:0xf bank_mask:0xf
	v_fmac_f32_dpp v188, v122, v80 row_shl:15 row_mask:0xf bank_mask:0xf
	v_fmac_f32_dpp v189, v123, v81 row_shl:15 row_mask:0xf bank_mask:0xf
	v_fmac_f32_dpp v190, v124, v82 row_shl:15 row_mask:0xf bank_mask:0xf
	v_fmac_f32_dpp v191, v125, v83 row_shl:15 row_mask:0xf bank_mask:0xf
	v_fmac_f32_dpp v192, v110, v96 row_shl:15 row_mask:0xf bank_mask:0xf
	v_fmac_f32_dpp v193, v111, v97 row_shl:15 row_mask:0xf bank_mask:0xf
	v_fmac_f32_dpp v194, v112, v98 row_shl:15 row_mask:0xf bank_mask:0xf
	v_fmac_f32_dpp v195, v113, v99 row_shl:15 row_mask:0xf bank_mask:0xf
	v_fmac_f32_dpp v188, v122, v76 row_shl:14 row_mask:0xf bank_mask:0xf
	v_fmac_f32_dpp v189, v123, v77 row_shl:14 row_mask:0xf bank_mask:0xf
	v_fmac_f32_dpp v190, v124, v78 row_shl:14 row_mask:0xf bank_mask:0xf
	v_fmac_f32_dpp v191, v125, v79 row_shl:14 row_mask:0xf bank_mask:0xf
	v_fmac_f32_dpp v192, v110, v92 row_shl:14 row_mask:0xf bank_mask:0xf
	v_fmac_f32_dpp v193, v111, v93 row_shl:14 row_mask:0xf bank_mask:0xf
	v_fmac_f32_dpp v194, v112, v94 row_shl:14 row_mask:0xf bank_mask:0xf
	v_fmac_f32_dpp v195, v113, v95 row_shl:14 row_mask:0xf bank_mask:0xf
	v_pk_mul_f32 v[196:197], v[188:189], v[216:217] op_sel_hi:[1,0]
	v_pk_mul_f32 v[198:199], v[190:191], v[216:217] op_sel_hi:[1,0]
	v_exp_f32_e32 v196, v196
	v_exp_f32_e32 v197, v197
	v_exp_f32_e32 v198, v198
	v_exp_f32_e32 v199, v199
	v_pk_add_f32 v[196:197], v[196:197], v[214:215] op_sel_hi:[1,0]
	v_pk_add_f32 v[198:199], v[198:199], v[214:215] op_sel_hi:[1,0]
	v_rcp_f32_e32 v196, v196
	v_rcp_f32_e32 v197, v197
	v_rcp_f32_e32 v198, v198
	v_rcp_f32_e32 v199, v199
	v_pk_mul_f32 v[188:189], v[188:189], v[196:197]
	v_pk_mul_f32 v[190:191], v[190:191], v[198:199]
	v_pk_mul_f32 v[188:189], v[188:189], v[192:193]
	v_pk_mul_f32 v[190:191], v[190:191], v[194:195]
	v_cvt_pk_bf16_f32 v122, v188, v189
	v_cvt_pk_bf16_f32 v123, v190, v191
	ds_read_b128 v[110:113], v109 offset:656
	v_pk_fma_f32 v[188:189], v[72:73], v[84:85], v[88:89]
	v_pk_fma_f32 v[190:191], v[74:75], v[86:87], v[90:91]
	v_pk_fma_f32 v[192:193], v[64:65], v[100:101], v[104:105]
	v_pk_fma_f32 v[194:195], v[66:67], v[102:103], v[106:107]
	v_fmac_f32_dpp v188, v72, v80 row_shr:1 row_mask:0xf bank_mask:0xf
	v_fmac_f32_dpp v189, v73, v81 row_shr:1 row_mask:0xf bank_mask:0xf
	v_fmac_f32_dpp v190, v74, v82 row_shr:1 row_mask:0xf bank_mask:0xf
	v_fmac_f32_dpp v191, v75, v83 row_shr:1 row_mask:0xf bank_mask:0xf
	v_fmac_f32_dpp v192, v64, v96 row_shr:1 row_mask:0xf bank_mask:0xf
	v_fmac_f32_dpp v193, v65, v97 row_shr:1 row_mask:0xf bank_mask:0xf
	v_fmac_f32_dpp v194, v66, v98 row_shr:1 row_mask:0xf bank_mask:0xf
	v_fmac_f32_dpp v195, v67, v99 row_shr:1 row_mask:0xf bank_mask:0xf
	v_fmac_f32_dpp v188, v72, v76 row_shr:2 row_mask:0xf bank_mask:0xf
	v_fmac_f32_dpp v189, v73, v77 row_shr:2 row_mask:0xf bank_mask:0xf
	v_fmac_f32_dpp v190, v74, v78 row_shr:2 row_mask:0xf bank_mask:0xf
	v_fmac_f32_dpp v191, v75, v79 row_shr:2 row_mask:0xf bank_mask:0xf
	v_fmac_f32_dpp v192, v64, v92 row_shr:2 row_mask:0xf bank_mask:0xf
	v_fmac_f32_dpp v193, v65, v93 row_shr:2 row_mask:0xf bank_mask:0xf
	v_fmac_f32_dpp v194, v66, v94 row_shr:2 row_mask:0xf bank_mask:0xf
	v_fmac_f32_dpp v195, v67, v95 row_shr:2 row_mask:0xf bank_mask:0xf
	v_fmac_f32_dpp v188, v114, v80 row_shl:15 row_mask:0xf bank_mask:0xf
	v_fmac_f32_dpp v189, v115, v81 row_shl:15 row_mask:0xf bank_mask:0xf
	v_fmac_f32_dpp v190, v116, v82 row_shl:15 row_mask:0xf bank_mask:0xf
	v_fmac_f32_dpp v191, v117, v83 row_shl:15 row_mask:0xf bank_mask:0xf
	v_fmac_f32_dpp v192, v68, v96 row_shl:15 row_mask:0xf bank_mask:0xf
	v_fmac_f32_dpp v193, v69, v97 row_shl:15 row_mask:0xf bank_mask:0xf
	v_fmac_f32_dpp v194, v70, v98 row_shl:15 row_mask:0xf bank_mask:0xf
	v_fmac_f32_dpp v195, v71, v99 row_shl:15 row_mask:0xf bank_mask:0xf
	v_fmac_f32_dpp v188, v114, v76 row_shl:14 row_mask:0xf bank_mask:0xf
	v_fmac_f32_dpp v189, v115, v77 row_shl:14 row_mask:0xf bank_mask:0xf
	v_fmac_f32_dpp v190, v116, v78 row_shl:14 row_mask:0xf bank_mask:0xf
	v_fmac_f32_dpp v191, v117, v79 row_shl:14 row_mask:0xf bank_mask:0xf
	v_fmac_f32_dpp v192, v68, v92 row_shl:14 row_mask:0xf bank_mask:0xf
	v_fmac_f32_dpp v193, v69, v93 row_shl:14 row_mask:0xf bank_mask:0xf
	v_fmac_f32_dpp v194, v70, v94 row_shl:14 row_mask:0xf bank_mask:0xf
	v_fmac_f32_dpp v195, v71, v95 row_shl:14 row_mask:0xf bank_mask:0xf
	v_pk_mul_f32 v[196:197], v[188:189], v[216:217] op_sel_hi:[1,0]
	v_pk_mul_f32 v[198:199], v[190:191], v[216:217] op_sel_hi:[1,0]
	v_exp_f32_e32 v196, v196
	v_exp_f32_e32 v197, v197
	v_exp_f32_e32 v198, v198
	v_exp_f32_e32 v199, v199
	v_pk_add_f32 v[196:197], v[196:197], v[214:215] op_sel_hi:[1,0]
	v_pk_add_f32 v[198:199], v[198:199], v[214:215] op_sel_hi:[1,0]
	v_rcp_f32_e32 v196, v196
	v_rcp_f32_e32 v197, v197
	v_rcp_f32_e32 v198, v198
	v_rcp_f32_e32 v199, v199
	v_pk_mul_f32 v[188:189], v[188:189], v[196:197]
	v_pk_mul_f32 v[190:191], v[190:191], v[198:199]
	v_pk_mul_f32 v[188:189], v[188:189], v[192:193]
	v_pk_mul_f32 v[190:191], v[190:191], v[194:195]
	v_cvt_pk_bf16_f32 v114, v188, v189
	v_cvt_pk_bf16_f32 v115, v190, v191
	s_waitcnt lgkmcnt(0)
	v_pk_fma_f32 v[188:189], v[60:61], v[134:135], v[130:131]
	v_pk_fma_f32 v[190:191], v[62:63], v[136:137], v[132:133]
	v_pk_fma_f32 v[192:193], v[56:57], v[204:205], v[208:209]
	v_pk_fma_f32 v[194:195], v[58:59], v[206:207], v[210:211]
	v_fmac_f32_dpp v188, v60, v142 row_shr:1 row_mask:0xf bank_mask:0xf
	v_fmac_f32_dpp v189, v61, v143 row_shr:1 row_mask:0xf bank_mask:0xf
	v_fmac_f32_dpp v190, v62, v144 row_shr:1 row_mask:0xf bank_mask:0xf
	v_fmac_f32_dpp v191, v63, v145 row_shr:1 row_mask:0xf bank_mask:0xf
	v_fmac_f32_dpp v192, v56, v110 row_shr:1 row_mask:0xf bank_mask:0xf
	v_fmac_f32_dpp v193, v57, v111 row_shr:1 row_mask:0xf bank_mask:0xf
	v_fmac_f32_dpp v194, v58, v112 row_shr:1 row_mask:0xf bank_mask:0xf
	v_fmac_f32_dpp v195, v59, v113 row_shr:1 row_mask:0xf bank_mask:0xf
	v_fmac_f32_dpp v188, v60, v154 row_shr:2 row_mask:0xf bank_mask:0xf
	v_fmac_f32_dpp v189, v61, v155 row_shr:2 row_mask:0xf bank_mask:0xf
	v_fmac_f32_dpp v190, v62, v156 row_shr:2 row_mask:0xf bank_mask:0xf
	v_fmac_f32_dpp v191, v63, v157 row_shr:2 row_mask:0xf bank_mask:0xf
	v_fmac_f32_dpp v192, v56, v118 row_shr:2 row_mask:0xf bank_mask:0xf
	v_fmac_f32_dpp v193, v57, v119 row_shr:2 row_mask:0xf bank_mask:0xf
	v_fmac_f32_dpp v194, v58, v120 row_shr:2 row_mask:0xf bank_mask:0xf
	v_fmac_f32_dpp v195, v59, v121 row_shr:2 row_mask:0xf bank_mask:0xf
	v_pk_mul_f32 v[196:197], v[188:189], v[216:217] op_sel_hi:[1,0]
	v_pk_mul_f32 v[198:199], v[190:191], v[216:217] op_sel_hi:[1,0]
	v_exp_f32_e32 v196, v196
	v_exp_f32_e32 v197, v197
	v_exp_f32_e32 v198, v198
	v_exp_f32_e32 v199, v199
	v_pk_add_f32 v[196:197], v[196:197], v[214:215] op_sel_hi:[1,0]
	v_pk_add_f32 v[198:199], v[198:199], v[214:215] op_sel_hi:[1,0]
	v_rcp_f32_e32 v196, v196
	v_rcp_f32_e32 v197, v197
	v_rcp_f32_e32 v198, v198
	v_rcp_f32_e32 v199, v199
	v_pk_mul_f32 v[188:189], v[188:189], v[196:197]
	v_pk_mul_f32 v[190:191], v[190:191], v[198:199]
	v_pk_mul_f32 v[188:189], v[188:189], v[192:193]
	v_pk_mul_f32 v[190:191], v[190:191], v[194:195]
	v_cvt_pk_bf16_f32 v202, v188, v189
	v_cvt_pk_bf16_f32 v203, v190, v191
	s_mov_b64 exec, vcc
	global_store_dwordx4 v215, v[200:203], s[96:97]
	s_mov_b64 exec, -1
	v_pk_fma_f32 v[188:189], v[52:53], v[134:135], v[130:131]
	v_pk_fma_f32 v[190:191], v[54:55], v[136:137], v[132:133]
	v_pk_fma_f32 v[192:193], v[44:45], v[204:205], v[208:209]
	v_pk_fma_f32 v[194:195], v[46:47], v[206:207], v[210:211]
	v_fmac_f32_dpp v188, v52, v142 row_shr:1 row_mask:0xf bank_mask:0xf
	v_fmac_f32_dpp v189, v53, v143 row_shr:1 row_mask:0xf bank_mask:0xf
	v_fmac_f32_dpp v190, v54, v144 row_shr:1 row_mask:0xf bank_mask:0xf
	v_fmac_f32_dpp v191, v55, v145 row_shr:1 row_mask:0xf bank_mask:0xf
	v_fmac_f32_dpp v192, v44, v110 row_shr:1 row_mask:0xf bank_mask:0xf
	v_fmac_f32_dpp v193, v45, v111 row_shr:1 row_mask:0xf bank_mask:0xf
	v_fmac_f32_dpp v194, v46, v112 row_shr:1 row_mask:0xf bank_mask:0xf
	v_fmac_f32_dpp v195, v47, v113 row_shr:1 row_mask:0xf bank_mask:0xf
	v_fmac_f32_dpp v188, v52, v154 row_shr:2 row_mask:0xf bank_mask:0xf
	v_fmac_f32_dpp v189, v53, v155 row_shr:2 row_mask:0xf bank_mask:0xf
	v_fmac_f32_dpp v190, v54, v156 row_shr:2 row_mask:0xf bank_mask:0xf
	v_fmac_f32_dpp v191, v55, v157 row_shr:2 row_mask:0xf bank_mask:0xf
	v_fmac_f32_dpp v192, v44, v118 row_shr:2 row_mask:0xf bank_mask:0xf
	v_fmac_f32_dpp v193, v45, v119 row_shr:2 row_mask:0xf bank_mask:0xf
	v_fmac_f32_dpp v194, v46, v120 row_shr:2 row_mask:0xf bank_mask:0xf
	v_fmac_f32_dpp v195, v47, v121 row_shr:2 row_mask:0xf bank_mask:0xf
	v_fmac_f32_dpp v188, v60, v142 row_shl:15 row_mask:0xf bank_mask:0xf
	v_fmac_f32_dpp v189, v61, v143 row_shl:15 row_mask:0xf bank_mask:0xf
	v_fmac_f32_dpp v190, v62, v144 row_shl:15 row_mask:0xf bank_mask:0xf
	v_fmac_f32_dpp v191, v63, v145 row_shl:15 row_mask:0xf bank_mask:0xf
	v_fmac_f32_dpp v192, v56, v110 row_shl:15 row_mask:0xf bank_mask:0xf
	v_fmac_f32_dpp v193, v57, v111 row_shl:15 row_mask:0xf bank_mask:0xf
	v_fmac_f32_dpp v194, v58, v112 row_shl:15 row_mask:0xf bank_mask:0xf
	v_fmac_f32_dpp v195, v59, v113 row_shl:15 row_mask:0xf bank_mask:0xf
	v_fmac_f32_dpp v188, v60, v154 row_shl:14 row_mask:0xf bank_mask:0xf
	v_fmac_f32_dpp v189, v61, v155 row_shl:14 row_mask:0xf bank_mask:0xf
	v_fmac_f32_dpp v190, v62, v156 row_shl:14 row_mask:0xf bank_mask:0xf
	v_fmac_f32_dpp v191, v63, v157 row_shl:14 row_mask:0xf bank_mask:0xf
	v_fmac_f32_dpp v192, v56, v118 row_shl:14 row_mask:0xf bank_mask:0xf
	v_fmac_f32_dpp v193, v57, v119 row_shl:14 row_mask:0xf bank_mask:0xf
	v_fmac_f32_dpp v194, v58, v120 row_shl:14 row_mask:0xf bank_mask:0xf
	v_fmac_f32_dpp v195, v59, v121 row_shl:14 row_mask:0xf bank_mask:0xf
	v_pk_mul_f32 v[196:197], v[188:189], v[216:217] op_sel_hi:[1,0]
	v_pk_mul_f32 v[198:199], v[190:191], v[216:217] op_sel_hi:[1,0]
	v_exp_f32_e32 v196, v196
	v_exp_f32_e32 v197, v197
	v_exp_f32_e32 v198, v198
	v_exp_f32_e32 v199, v199
	v_pk_add_f32 v[196:197], v[196:197], v[214:215] op_sel_hi:[1,0]
	v_pk_add_f32 v[198:199], v[198:199], v[214:215] op_sel_hi:[1,0]
	v_rcp_f32_e32 v196, v196
	v_rcp_f32_e32 v197, v197
	v_rcp_f32_e32 v198, v198
	v_rcp_f32_e32 v199, v199
	v_pk_mul_f32 v[188:189], v[188:189], v[196:197]
	v_pk_mul_f32 v[190:191], v[190:191], v[198:199]
	v_pk_mul_f32 v[188:189], v[188:189], v[192:193]
	v_pk_mul_f32 v[190:191], v[190:191], v[194:195]
	v_cvt_pk_bf16_f32 v160, v188, v189
	v_cvt_pk_bf16_f32 v161, v190, v191
	v_add_u32_e32 v213, 0x2c000, v215
	global_store_dwordx4 v213, v[158:161], s[96:97]
	v_pk_fma_f32 v[188:189], v[48:49], v[134:135], v[130:131]
	v_pk_fma_f32 v[190:191], v[50:51], v[136:137], v[132:133]
	v_pk_fma_f32 v[192:193], v[36:37], v[204:205], v[208:209]
	v_pk_fma_f32 v[194:195], v[38:39], v[206:207], v[210:211]
	v_fmac_f32_dpp v188, v48, v142 row_shr:1 row_mask:0xf bank_mask:0xf
	v_fmac_f32_dpp v189, v49, v143 row_shr:1 row_mask:0xf bank_mask:0xf
	v_fmac_f32_dpp v190, v50, v144 row_shr:1 row_mask:0xf bank_mask:0xf
	v_fmac_f32_dpp v191, v51, v145 row_shr:1 row_mask:0xf bank_mask:0xf
	v_fmac_f32_dpp v192, v36, v110 row_shr:1 row_mask:0xf bank_mask:0xf
	v_fmac_f32_dpp v193, v37, v111 row_shr:1 row_mask:0xf bank_mask:0xf
	v_fmac_f32_dpp v194, v38, v112 row_shr:1 row_mask:0xf bank_mask:0xf
	v_fmac_f32_dpp v195, v39, v113 row_shr:1 row_mask:0xf bank_mask:0xf
	v_fmac_f32_dpp v188, v48, v154 row_shr:2 row_mask:0xf bank_mask:0xf
	v_fmac_f32_dpp v189, v49, v155 row_shr:2 row_mask:0xf bank_mask:0xf
	v_fmac_f32_dpp v190, v50, v156 row_shr:2 row_mask:0xf bank_mask:0xf
	v_fmac_f32_dpp v191, v51, v157 row_shr:2 row_mask:0xf bank_mask:0xf
	v_fmac_f32_dpp v192, v36, v118 row_shr:2 row_mask:0xf bank_mask:0xf
	v_fmac_f32_dpp v193, v37, v119 row_shr:2 row_mask:0xf bank_mask:0xf
	v_fmac_f32_dpp v194, v38, v120 row_shr:2 row_mask:0xf bank_mask:0xf
	v_fmac_f32_dpp v195, v39, v121 row_shr:2 row_mask:0xf bank_mask:0xf
	v_fmac_f32_dpp v188, v52, v142 row_shl:15 row_mask:0xf bank_mask:0xf
	v_fmac_f32_dpp v189, v53, v143 row_shl:15 row_mask:0xf bank_mask:0xf
	v_fmac_f32_dpp v190, v54, v144 row_shl:15 row_mask:0xf bank_mask:0xf
	v_fmac_f32_dpp v191, v55, v145 row_shl:15 row_mask:0xf bank_mask:0xf
	v_fmac_f32_dpp v192, v44, v110 row_shl:15 row_mask:0xf bank_mask:0xf
	v_fmac_f32_dpp v193, v45, v111 row_shl:15 row_mask:0xf bank_mask:0xf
	v_fmac_f32_dpp v194, v46, v112 row_shl:15 row_mask:0xf bank_mask:0xf
	v_fmac_f32_dpp v195, v47, v113 row_shl:15 row_mask:0xf bank_mask:0xf
	v_fmac_f32_dpp v188, v52, v154 row_shl:14 row_mask:0xf bank_mask:0xf
	v_fmac_f32_dpp v189, v53, v155 row_shl:14 row_mask:0xf bank_mask:0xf
	v_fmac_f32_dpp v190, v54, v156 row_shl:14 row_mask:0xf bank_mask:0xf
	v_fmac_f32_dpp v191, v55, v157 row_shl:14 row_mask:0xf bank_mask:0xf
	v_fmac_f32_dpp v192, v44, v118 row_shl:14 row_mask:0xf bank_mask:0xf
	v_fmac_f32_dpp v193, v45, v119 row_shl:14 row_mask:0xf bank_mask:0xf
	v_fmac_f32_dpp v194, v46, v120 row_shl:14 row_mask:0xf bank_mask:0xf
	v_fmac_f32_dpp v195, v47, v121 row_shl:14 row_mask:0xf bank_mask:0xf
	v_pk_mul_f32 v[196:197], v[188:189], v[216:217] op_sel_hi:[1,0]
	v_pk_mul_f32 v[198:199], v[190:191], v[216:217] op_sel_hi:[1,0]
	v_exp_f32_e32 v196, v196
	v_exp_f32_e32 v197, v197
	v_exp_f32_e32 v198, v198
	v_exp_f32_e32 v199, v199
	v_pk_add_f32 v[196:197], v[196:197], v[214:215] op_sel_hi:[1,0]
	v_pk_add_f32 v[198:199], v[198:199], v[214:215] op_sel_hi:[1,0]
	v_rcp_f32_e32 v196, v196
	v_rcp_f32_e32 v197, v197
	v_rcp_f32_e32 v198, v198
	v_rcp_f32_e32 v199, v199
	v_pk_mul_f32 v[188:189], v[188:189], v[196:197]
	v_pk_mul_f32 v[190:191], v[190:191], v[198:199]
	v_pk_mul_f32 v[188:189], v[188:189], v[192:193]
	v_pk_mul_f32 v[190:191], v[190:191], v[194:195]
	v_cvt_pk_bf16_f32 v152, v188, v189
	v_cvt_pk_bf16_f32 v153, v190, v191
	v_add_u32_e32 v213, 0x58000, v215
	global_store_dwordx4 v213, v[150:153], s[96:97]
	v_pk_fma_f32 v[188:189], v[40:41], v[134:135], v[130:131]
	v_pk_fma_f32 v[190:191], v[42:43], v[136:137], v[132:133]
	v_pk_fma_f32 v[192:193], v[32:33], v[204:205], v[208:209]
	v_pk_fma_f32 v[194:195], v[34:35], v[206:207], v[210:211]
	v_fmac_f32_dpp v188, v40, v142 row_shr:1 row_mask:0xf bank_mask:0xf
	v_fmac_f32_dpp v189, v41, v143 row_shr:1 row_mask:0xf bank_mask:0xf
	v_fmac_f32_dpp v190, v42, v144 row_shr:1 row_mask:0xf bank_mask:0xf
	v_fmac_f32_dpp v191, v43, v145 row_shr:1 row_mask:0xf bank_mask:0xf
	v_fmac_f32_dpp v192, v32, v110 row_shr:1 row_mask:0xf bank_mask:0xf
	v_fmac_f32_dpp v193, v33, v111 row_shr:1 row_mask:0xf bank_mask:0xf
	v_fmac_f32_dpp v194, v34, v112 row_shr:1 row_mask:0xf bank_mask:0xf
	v_fmac_f32_dpp v195, v35, v113 row_shr:1 row_mask:0xf bank_mask:0xf
	v_fmac_f32_dpp v188, v40, v154 row_shr:2 row_mask:0xf bank_mask:0xf
	v_fmac_f32_dpp v189, v41, v155 row_shr:2 row_mask:0xf bank_mask:0xf
	v_fmac_f32_dpp v190, v42, v156 row_shr:2 row_mask:0xf bank_mask:0xf
	v_fmac_f32_dpp v191, v43, v157 row_shr:2 row_mask:0xf bank_mask:0xf
	v_fmac_f32_dpp v192, v32, v118 row_shr:2 row_mask:0xf bank_mask:0xf
	v_fmac_f32_dpp v193, v33, v119 row_shr:2 row_mask:0xf bank_mask:0xf
	v_fmac_f32_dpp v194, v34, v120 row_shr:2 row_mask:0xf bank_mask:0xf
	v_fmac_f32_dpp v195, v35, v121 row_shr:2 row_mask:0xf bank_mask:0xf
	v_fmac_f32_dpp v188, v48, v142 row_shl:15 row_mask:0xf bank_mask:0xf
	v_fmac_f32_dpp v189, v49, v143 row_shl:15 row_mask:0xf bank_mask:0xf
	v_fmac_f32_dpp v190, v50, v144 row_shl:15 row_mask:0xf bank_mask:0xf
	v_fmac_f32_dpp v191, v51, v145 row_shl:15 row_mask:0xf bank_mask:0xf
	v_fmac_f32_dpp v192, v36, v110 row_shl:15 row_mask:0xf bank_mask:0xf
	v_fmac_f32_dpp v193, v37, v111 row_shl:15 row_mask:0xf bank_mask:0xf
	v_fmac_f32_dpp v194, v38, v112 row_shl:15 row_mask:0xf bank_mask:0xf
	v_fmac_f32_dpp v195, v39, v113 row_shl:15 row_mask:0xf bank_mask:0xf
	v_fmac_f32_dpp v188, v48, v154 row_shl:14 row_mask:0xf bank_mask:0xf
	v_fmac_f32_dpp v189, v49, v155 row_shl:14 row_mask:0xf bank_mask:0xf
	v_fmac_f32_dpp v190, v50, v156 row_shl:14 row_mask:0xf bank_mask:0xf
	v_fmac_f32_dpp v191, v51, v157 row_shl:14 row_mask:0xf bank_mask:0xf
	v_fmac_f32_dpp v192, v36, v118 row_shl:14 row_mask:0xf bank_mask:0xf
	v_fmac_f32_dpp v193, v37, v119 row_shl:14 row_mask:0xf bank_mask:0xf
	v_fmac_f32_dpp v194, v38, v120 row_shl:14 row_mask:0xf bank_mask:0xf
	v_fmac_f32_dpp v195, v39, v121 row_shl:14 row_mask:0xf bank_mask:0xf
	v_pk_mul_f32 v[196:197], v[188:189], v[216:217] op_sel_hi:[1,0]
	v_pk_mul_f32 v[198:199], v[190:191], v[216:217] op_sel_hi:[1,0]
	v_exp_f32_e32 v196, v196
	v_exp_f32_e32 v197, v197
	v_exp_f32_e32 v198, v198
	v_exp_f32_e32 v199, v199
	v_pk_add_f32 v[196:197], v[196:197], v[214:215] op_sel_hi:[1,0]
	v_pk_add_f32 v[198:199], v[198:199], v[214:215] op_sel_hi:[1,0]
	v_rcp_f32_e32 v196, v196
	v_rcp_f32_e32 v197, v197
	v_rcp_f32_e32 v198, v198
	v_rcp_f32_e32 v199, v199
	v_pk_mul_f32 v[188:189], v[188:189], v[196:197]
	v_pk_mul_f32 v[190:191], v[190:191], v[198:199]
	v_pk_mul_f32 v[188:189], v[188:189], v[192:193]
	v_pk_mul_f32 v[190:191], v[190:191], v[194:195]
	v_cvt_pk_bf16_f32 v148, v188, v189
	v_cvt_pk_bf16_f32 v149, v190, v191
	v_add_u32_e32 v213, 0x84000, v215
	global_store_dwordx4 v213, v[146:149], s[96:97]
	v_pk_fma_f32 v[188:189], v[28:29], v[134:135], v[130:131]
	v_pk_fma_f32 v[190:191], v[30:31], v[136:137], v[132:133]
	v_pk_fma_f32 v[192:193], v[16:17], v[204:205], v[208:209]
	v_pk_fma_f32 v[194:195], v[18:19], v[206:207], v[210:211]
	v_fmac_f32_dpp v188, v28, v142 row_shr:1 row_mask:0xf bank_mask:0xf
	v_fmac_f32_dpp v189, v29, v143 row_shr:1 row_mask:0xf bank_mask:0xf
	v_fmac_f32_dpp v190, v30, v144 row_shr:1 row_mask:0xf bank_mask:0xf
	v_fmac_f32_dpp v191, v31, v145 row_shr:1 row_mask:0xf bank_mask:0xf
	v_fmac_f32_dpp v192, v16, v110 row_shr:1 row_mask:0xf bank_mask:0xf
	v_fmac_f32_dpp v193, v17, v111 row_shr:1 row_mask:0xf bank_mask:0xf
	v_fmac_f32_dpp v194, v18, v112 row_shr:1 row_mask:0xf bank_mask:0xf
	v_fmac_f32_dpp v195, v19, v113 row_shr:1 row_mask:0xf bank_mask:0xf
	v_fmac_f32_dpp v188, v28, v154 row_shr:2 row_mask:0xf bank_mask:0xf
	v_fmac_f32_dpp v189, v29, v155 row_shr:2 row_mask:0xf bank_mask:0xf
	v_fmac_f32_dpp v190, v30, v156 row_shr:2 row_mask:0xf bank_mask:0xf
	v_fmac_f32_dpp v191, v31, v157 row_shr:2 row_mask:0xf bank_mask:0xf
	v_fmac_f32_dpp v192, v16, v118 row_shr:2 row_mask:0xf bank_mask:0xf
	v_fmac_f32_dpp v193, v17, v119 row_shr:2 row_mask:0xf bank_mask:0xf
	v_fmac_f32_dpp v194, v18, v120 row_shr:2 row_mask:0xf bank_mask:0xf
	v_fmac_f32_dpp v195, v19, v121 row_shr:2 row_mask:0xf bank_mask:0xf
	v_fmac_f32_dpp v188, v40, v142 row_shl:15 row_mask:0xf bank_mask:0xf
	v_fmac_f32_dpp v189, v41, v143 row_shl:15 row_mask:0xf bank_mask:0xf
	v_fmac_f32_dpp v190, v42, v144 row_shl:15 row_mask:0xf bank_mask:0xf
	v_fmac_f32_dpp v191, v43, v145 row_shl:15 row_mask:0xf bank_mask:0xf
	v_fmac_f32_dpp v192, v32, v110 row_shl:15 row_mask:0xf bank_mask:0xf
	v_fmac_f32_dpp v193, v33, v111 row_shl:15 row_mask:0xf bank_mask:0xf
	v_fmac_f32_dpp v194, v34, v112 row_shl:15 row_mask:0xf bank_mask:0xf
	v_fmac_f32_dpp v195, v35, v113 row_shl:15 row_mask:0xf bank_mask:0xf
	v_fmac_f32_dpp v188, v40, v154 row_shl:14 row_mask:0xf bank_mask:0xf
	v_fmac_f32_dpp v189, v41, v155 row_shl:14 row_mask:0xf bank_mask:0xf
	v_fmac_f32_dpp v190, v42, v156 row_shl:14 row_mask:0xf bank_mask:0xf
	v_fmac_f32_dpp v191, v43, v157 row_shl:14 row_mask:0xf bank_mask:0xf
	v_fmac_f32_dpp v192, v32, v118 row_shl:14 row_mask:0xf bank_mask:0xf
	v_fmac_f32_dpp v193, v33, v119 row_shl:14 row_mask:0xf bank_mask:0xf
	v_fmac_f32_dpp v194, v34, v120 row_shl:14 row_mask:0xf bank_mask:0xf
	v_fmac_f32_dpp v195, v35, v121 row_shl:14 row_mask:0xf bank_mask:0xf
	v_pk_mul_f32 v[196:197], v[188:189], v[216:217] op_sel_hi:[1,0]
	v_pk_mul_f32 v[198:199], v[190:191], v[216:217] op_sel_hi:[1,0]
	v_exp_f32_e32 v196, v196
	v_exp_f32_e32 v197, v197
	v_exp_f32_e32 v198, v198
	v_exp_f32_e32 v199, v199
	v_pk_add_f32 v[196:197], v[196:197], v[214:215] op_sel_hi:[1,0]
	v_pk_add_f32 v[198:199], v[198:199], v[214:215] op_sel_hi:[1,0]
	v_rcp_f32_e32 v196, v196
	v_rcp_f32_e32 v197, v197
	v_rcp_f32_e32 v198, v198
	v_rcp_f32_e32 v199, v199
	v_pk_mul_f32 v[188:189], v[188:189], v[196:197]
	v_pk_mul_f32 v[190:191], v[190:191], v[198:199]
	v_pk_mul_f32 v[188:189], v[188:189], v[192:193]
	v_pk_mul_f32 v[190:191], v[190:191], v[194:195]
	v_cvt_pk_bf16_f32 v140, v188, v189
	v_cvt_pk_bf16_f32 v141, v190, v191
	v_add_u32_e32 v213, 0xb0000, v215
	global_store_dwordx4 v213, v[138:141], s[96:97]
	v_pk_fma_f32 v[188:189], v[24:25], v[134:135], v[130:131]
	v_pk_fma_f32 v[190:191], v[26:27], v[136:137], v[132:133]
	v_pk_fma_f32 v[192:193], v[12:13], v[204:205], v[208:209]
	v_pk_fma_f32 v[194:195], v[14:15], v[206:207], v[210:211]
	v_fmac_f32_dpp v188, v24, v142 row_shr:1 row_mask:0xf bank_mask:0xf
	v_fmac_f32_dpp v189, v25, v143 row_shr:1 row_mask:0xf bank_mask:0xf
	v_fmac_f32_dpp v190, v26, v144 row_shr:1 row_mask:0xf bank_mask:0xf
	v_fmac_f32_dpp v191, v27, v145 row_shr:1 row_mask:0xf bank_mask:0xf
	v_fmac_f32_dpp v192, v12, v110 row_shr:1 row_mask:0xf bank_mask:0xf
	v_fmac_f32_dpp v193, v13, v111 row_shr:1 row_mask:0xf bank_mask:0xf
	v_fmac_f32_dpp v194, v14, v112 row_shr:1 row_mask:0xf bank_mask:0xf
	v_fmac_f32_dpp v195, v15, v113 row_shr:1 row_mask:0xf bank_mask:0xf
	v_fmac_f32_dpp v188, v24, v154 row_shr:2 row_mask:0xf bank_mask:0xf
	v_fmac_f32_dpp v189, v25, v155 row_shr:2 row_mask:0xf bank_mask:0xf
	v_fmac_f32_dpp v190, v26, v156 row_shr:2 row_mask:0xf bank_mask:0xf
	v_fmac_f32_dpp v191, v27, v157 row_shr:2 row_mask:0xf bank_mask:0xf
	v_fmac_f32_dpp v192, v12, v118 row_shr:2 row_mask:0xf bank_mask:0xf
	v_fmac_f32_dpp v193, v13, v119 row_shr:2 row_mask:0xf bank_mask:0xf
	v_fmac_f32_dpp v194, v14, v120 row_shr:2 row_mask:0xf bank_mask:0xf
	v_fmac_f32_dpp v195, v15, v121 row_shr:2 row_mask:0xf bank_mask:0xf
	v_fmac_f32_dpp v188, v28, v142 row_shl:15 row_mask:0xf bank_mask:0xf
	v_fmac_f32_dpp v189, v29, v143 row_shl:15 row_mask:0xf bank_mask:0xf
	v_fmac_f32_dpp v190, v30, v144 row_shl:15 row_mask:0xf bank_mask:0xf
	v_fmac_f32_dpp v191, v31, v145 row_shl:15 row_mask:0xf bank_mask:0xf
	v_fmac_f32_dpp v192, v16, v110 row_shl:15 row_mask:0xf bank_mask:0xf
	v_fmac_f32_dpp v193, v17, v111 row_shl:15 row_mask:0xf bank_mask:0xf
	v_fmac_f32_dpp v194, v18, v112 row_shl:15 row_mask:0xf bank_mask:0xf
	v_fmac_f32_dpp v195, v19, v113 row_shl:15 row_mask:0xf bank_mask:0xf
	v_fmac_f32_dpp v188, v28, v154 row_shl:14 row_mask:0xf bank_mask:0xf
	v_fmac_f32_dpp v189, v29, v155 row_shl:14 row_mask:0xf bank_mask:0xf
	v_fmac_f32_dpp v190, v30, v156 row_shl:14 row_mask:0xf bank_mask:0xf
	v_fmac_f32_dpp v191, v31, v157 row_shl:14 row_mask:0xf bank_mask:0xf
	v_fmac_f32_dpp v192, v16, v118 row_shl:14 row_mask:0xf bank_mask:0xf
	v_fmac_f32_dpp v193, v17, v119 row_shl:14 row_mask:0xf bank_mask:0xf
	v_fmac_f32_dpp v194, v18, v120 row_shl:14 row_mask:0xf bank_mask:0xf
	v_fmac_f32_dpp v195, v19, v121 row_shl:14 row_mask:0xf bank_mask:0xf
	v_pk_mul_f32 v[196:197], v[188:189], v[216:217] op_sel_hi:[1,0]
	v_pk_mul_f32 v[198:199], v[190:191], v[216:217] op_sel_hi:[1,0]
	v_exp_f32_e32 v196, v196
	v_exp_f32_e32 v197, v197
	v_exp_f32_e32 v198, v198
	v_exp_f32_e32 v199, v199
	v_pk_add_f32 v[196:197], v[196:197], v[214:215] op_sel_hi:[1,0]
	v_pk_add_f32 v[198:199], v[198:199], v[214:215] op_sel_hi:[1,0]
	v_rcp_f32_e32 v196, v196
	v_rcp_f32_e32 v197, v197
	v_rcp_f32_e32 v198, v198
	v_rcp_f32_e32 v199, v199
	v_pk_mul_f32 v[188:189], v[188:189], v[196:197]
	v_pk_mul_f32 v[190:191], v[190:191], v[198:199]
	v_pk_mul_f32 v[188:189], v[188:189], v[192:193]
	v_pk_mul_f32 v[190:191], v[190:191], v[194:195]
	v_cvt_pk_bf16_f32 v128, v188, v189
	v_cvt_pk_bf16_f32 v129, v190, v191
	v_add_u32_e32 v213, 0xdc000, v215
	global_store_dwordx4 v213, v[126:129], s[96:97]
	v_pk_fma_f32 v[188:189], v[20:21], v[134:135], v[130:131]
	v_pk_fma_f32 v[190:191], v[22:23], v[136:137], v[132:133]
	v_pk_fma_f32 v[192:193], v[8:9], v[204:205], v[208:209]
	v_pk_fma_f32 v[194:195], v[10:11], v[206:207], v[210:211]
	v_fmac_f32_dpp v188, v20, v142 row_shr:1 row_mask:0xf bank_mask:0xf
	v_fmac_f32_dpp v189, v21, v143 row_shr:1 row_mask:0xf bank_mask:0xf
	v_fmac_f32_dpp v190, v22, v144 row_shr:1 row_mask:0xf bank_mask:0xf
	v_fmac_f32_dpp v191, v23, v145 row_shr:1 row_mask:0xf bank_mask:0xf
	v_fmac_f32_dpp v192, v8, v110 row_shr:1 row_mask:0xf bank_mask:0xf
	v_fmac_f32_dpp v193, v9, v111 row_shr:1 row_mask:0xf bank_mask:0xf
	v_fmac_f32_dpp v194, v10, v112 row_shr:1 row_mask:0xf bank_mask:0xf
	v_fmac_f32_dpp v195, v11, v113 row_shr:1 row_mask:0xf bank_mask:0xf
	v_fmac_f32_dpp v188, v20, v154 row_shr:2 row_mask:0xf bank_mask:0xf
	v_fmac_f32_dpp v189, v21, v155 row_shr:2 row_mask:0xf bank_mask:0xf
	v_fmac_f32_dpp v190, v22, v156 row_shr:2 row_mask:0xf bank_mask:0xf
	v_fmac_f32_dpp v191, v23, v157 row_shr:2 row_mask:0xf bank_mask:0xf
	v_fmac_f32_dpp v192, v8, v118 row_shr:2 row_mask:0xf bank_mask:0xf
	v_fmac_f32_dpp v193, v9, v119 row_shr:2 row_mask:0xf bank_mask:0xf
	v_fmac_f32_dpp v194, v10, v120 row_shr:2 row_mask:0xf bank_mask:0xf
	v_fmac_f32_dpp v195, v11, v121 row_shr:2 row_mask:0xf bank_mask:0xf
	v_fmac_f32_dpp v188, v24, v142 row_shl:15 row_mask:0xf bank_mask:0xf
	v_fmac_f32_dpp v189, v25, v143 row_shl:15 row_mask:0xf bank_mask:0xf
	v_fmac_f32_dpp v190, v26, v144 row_shl:15 row_mask:0xf bank_mask:0xf
	v_fmac_f32_dpp v191, v27, v145 row_shl:15 row_mask:0xf bank_mask:0xf
	v_fmac_f32_dpp v192, v12, v110 row_shl:15 row_mask:0xf bank_mask:0xf
	v_fmac_f32_dpp v193, v13, v111 row_shl:15 row_mask:0xf bank_mask:0xf
	v_fmac_f32_dpp v194, v14, v112 row_shl:15 row_mask:0xf bank_mask:0xf
	v_fmac_f32_dpp v195, v15, v113 row_shl:15 row_mask:0xf bank_mask:0xf
	v_fmac_f32_dpp v188, v24, v154 row_shl:14 row_mask:0xf bank_mask:0xf
	v_fmac_f32_dpp v189, v25, v155 row_shl:14 row_mask:0xf bank_mask:0xf
	v_fmac_f32_dpp v190, v26, v156 row_shl:14 row_mask:0xf bank_mask:0xf
	v_fmac_f32_dpp v191, v27, v157 row_shl:14 row_mask:0xf bank_mask:0xf
	v_fmac_f32_dpp v192, v12, v118 row_shl:14 row_mask:0xf bank_mask:0xf
	v_fmac_f32_dpp v193, v13, v119 row_shl:14 row_mask:0xf bank_mask:0xf
	v_fmac_f32_dpp v194, v14, v120 row_shl:14 row_mask:0xf bank_mask:0xf
	v_fmac_f32_dpp v195, v15, v121 row_shl:14 row_mask:0xf bank_mask:0xf
	v_pk_mul_f32 v[196:197], v[188:189], v[216:217] op_sel_hi:[1,0]
	v_pk_mul_f32 v[198:199], v[190:191], v[216:217] op_sel_hi:[1,0]
	v_exp_f32_e32 v196, v196
	v_exp_f32_e32 v197, v197
	v_exp_f32_e32 v198, v198
	v_exp_f32_e32 v199, v199
	v_pk_add_f32 v[196:197], v[196:197], v[214:215] op_sel_hi:[1,0]
	v_pk_add_f32 v[198:199], v[198:199], v[214:215] op_sel_hi:[1,0]
	v_rcp_f32_e32 v196, v196
	v_rcp_f32_e32 v197, v197
	v_rcp_f32_e32 v198, v198
	v_rcp_f32_e32 v199, v199
	v_pk_mul_f32 v[188:189], v[188:189], v[196:197]
	v_pk_mul_f32 v[190:191], v[190:191], v[198:199]
	v_pk_mul_f32 v[188:189], v[188:189], v[192:193]
	v_pk_mul_f32 v[190:191], v[190:191], v[194:195]
	v_cvt_pk_bf16_f32 v124, v188, v189
	v_cvt_pk_bf16_f32 v125, v190, v191
	v_add_u32_e32 v213, 0x108000, v215
	global_store_dwordx4 v213, v[122:125], s[96:97]
	v_pk_fma_f32 v[188:189], v[4:5], v[134:135], v[130:131]
	v_pk_fma_f32 v[190:191], v[6:7], v[136:137], v[132:133]
	v_pk_fma_f32 v[192:193], v[0:1], v[204:205], v[208:209]
	v_pk_fma_f32 v[194:195], v[2:3], v[206:207], v[210:211]
	v_fmac_f32_dpp v188, v4, v142 row_shr:1 row_mask:0xf bank_mask:0xf
	v_fmac_f32_dpp v189, v5, v143 row_shr:1 row_mask:0xf bank_mask:0xf
	v_fmac_f32_dpp v190, v6, v144 row_shr:1 row_mask:0xf bank_mask:0xf
	v_fmac_f32_dpp v191, v7, v145 row_shr:1 row_mask:0xf bank_mask:0xf
	v_fmac_f32_dpp v192, v0, v110 row_shr:1 row_mask:0xf bank_mask:0xf
	v_fmac_f32_dpp v193, v1, v111 row_shr:1 row_mask:0xf bank_mask:0xf
	v_fmac_f32_dpp v194, v2, v112 row_shr:1 row_mask:0xf bank_mask:0xf
	v_fmac_f32_dpp v195, v3, v113 row_shr:1 row_mask:0xf bank_mask:0xf
	v_fmac_f32_dpp v188, v4, v154 row_shr:2 row_mask:0xf bank_mask:0xf
	v_fmac_f32_dpp v189, v5, v155 row_shr:2 row_mask:0xf bank_mask:0xf
	v_fmac_f32_dpp v190, v6, v156 row_shr:2 row_mask:0xf bank_mask:0xf
	v_fmac_f32_dpp v191, v7, v157 row_shr:2 row_mask:0xf bank_mask:0xf
	v_fmac_f32_dpp v192, v0, v118 row_shr:2 row_mask:0xf bank_mask:0xf
	v_fmac_f32_dpp v193, v1, v119 row_shr:2 row_mask:0xf bank_mask:0xf
	v_fmac_f32_dpp v194, v2, v120 row_shr:2 row_mask:0xf bank_mask:0xf
	v_fmac_f32_dpp v195, v3, v121 row_shr:2 row_mask:0xf bank_mask:0xf
	v_fmac_f32_dpp v188, v20, v142 row_shl:15 row_mask:0xf bank_mask:0xf
	v_fmac_f32_dpp v189, v21, v143 row_shl:15 row_mask:0xf bank_mask:0xf
	v_fmac_f32_dpp v190, v22, v144 row_shl:15 row_mask:0xf bank_mask:0xf
	v_fmac_f32_dpp v191, v23, v145 row_shl:15 row_mask:0xf bank_mask:0xf
	v_fmac_f32_dpp v192, v8, v110 row_shl:15 row_mask:0xf bank_mask:0xf
	v_fmac_f32_dpp v193, v9, v111 row_shl:15 row_mask:0xf bank_mask:0xf
	v_fmac_f32_dpp v194, v10, v112 row_shl:15 row_mask:0xf bank_mask:0xf
	v_fmac_f32_dpp v195, v11, v113 row_shl:15 row_mask:0xf bank_mask:0xf
	v_fmac_f32_dpp v188, v20, v154 row_shl:14 row_mask:0xf bank_mask:0xf
	v_fmac_f32_dpp v189, v21, v155 row_shl:14 row_mask:0xf bank_mask:0xf
	v_fmac_f32_dpp v190, v22, v156 row_shl:14 row_mask:0xf bank_mask:0xf
	v_fmac_f32_dpp v191, v23, v157 row_shl:14 row_mask:0xf bank_mask:0xf
	v_fmac_f32_dpp v192, v8, v118 row_shl:14 row_mask:0xf bank_mask:0xf
	v_fmac_f32_dpp v193, v9, v119 row_shl:14 row_mask:0xf bank_mask:0xf
	v_fmac_f32_dpp v194, v10, v120 row_shl:14 row_mask:0xf bank_mask:0xf
	v_fmac_f32_dpp v195, v11, v121 row_shl:14 row_mask:0xf bank_mask:0xf
	v_pk_mul_f32 v[196:197], v[188:189], v[216:217] op_sel_hi:[1,0]
	v_pk_mul_f32 v[198:199], v[190:191], v[216:217] op_sel_hi:[1,0]
	v_exp_f32_e32 v196, v196
	v_exp_f32_e32 v197, v197
	v_exp_f32_e32 v198, v198
	v_exp_f32_e32 v199, v199
	v_pk_add_f32 v[196:197], v[196:197], v[214:215] op_sel_hi:[1,0]
	v_pk_add_f32 v[198:199], v[198:199], v[214:215] op_sel_hi:[1,0]
	v_rcp_f32_e32 v196, v196
	v_rcp_f32_e32 v197, v197
	v_rcp_f32_e32 v198, v198
	v_rcp_f32_e32 v199, v199
	v_pk_mul_f32 v[188:189], v[188:189], v[196:197]
	v_pk_mul_f32 v[190:191], v[190:191], v[198:199]
	v_pk_mul_f32 v[188:189], v[188:189], v[192:193]
	v_pk_mul_f32 v[190:191], v[190:191], v[194:195]
	v_cvt_pk_bf16_f32 v116, v188, v189
	v_cvt_pk_bf16_f32 v117, v190, v191
	v_add_u32_e32 v213, 0x134000, v215
	global_store_dwordx4 v213, v[114:117], s[96:97]
	s_branch .LBB0_359
.Lfs3_first:
	s_lshl_b32 s8, s0, 8
	s_add_i32 s8, s8, s56
	s_lshl_b32 s9, s1, 7
	s_add_i32 s9, s9, s49
	s_lshl_b32 s10, s0, 3
	s_lshr_b32 s11, s56, 5
	s_add_i32 s10, s10, s11
	v_add_u32_e32 v200, s8, v163
	v_lshlrev_b32_e32 v213, 2, v200
	v_lshl_add_u32 v201, v225, 3, s9
	v_lshlrev_b32_e32 v212, 2, v201
	v_lshrrev_b32_e32 v109, 6, v222
	s_and_b32 s9, s48, 1
	v_readfirstlane_b32 s11, v109
	s_mul_i32 s9, s9, 0x3000
	s_mul_i32 s11, s11, 0x600
	s_add_i32 s9, s9, s11
	s_add_i32 s9, s9, 0x21040
	global_load_dword v188, v213, s[12:13]
	global_load_dword v189, v213, s[12:13] offset:64
	global_load_dword v190, v213, s[12:13] offset:128
	global_load_dword v191, v213, s[12:13] offset:192
	global_load_dword v192, v213, s[12:13] offset:256
	global_load_dword v193, v213, s[12:13] offset:320
	global_load_dword v194, v213, s[12:13] offset:384
	global_load_dword v195, v213, s[12:13] offset:448
	global_load_dwordx4 v[76:79], v212, s[82:83]
	v_add_u32_e32 v213, 0xb000, v212
	global_load_dwordx4 v[80:83], v213, s[82:83]
	v_add_u32_e32 v213, 0x16000, v212
	global_load_dwordx4 v[84:87], v213, s[82:83]
	global_load_dwordx4 v[88:91], v212, s[84:85]
	v_add_u32_e32 v213, 0x5800, v212
	global_load_dwordx4 v[92:95], v213, s[82:83]
	v_add_u32_e32 v213, 0x10800, v212
	global_load_dwordx4 v[96:99], v213, s[82:83]
	v_add_u32_e32 v213, 0x1b800, v212
	global_load_dwordx4 v[100:103], v213, s[82:83]
	v_add_u32_e32 v213, 0x5800, v212
	global_load_dwordx4 v[104:107], v213, s[84:85]
	v_mul_u32_u24_e32 v215, 0x2c00, v200
	v_lshl_add_u32 v215, v201, 1, v215
	v_add_u32_e32 v213, s10, v163
	v_mul_u32_u24_e32 v217, 0xb000, v213
	v_add_u32_e32 v217, v217, v212
	v_cmp_lt_u32_e64 s[10:11], 13, v163
	v_cmp_lt_u32_e32 vcc, 1, v163
	v_mov_b32_e32 v214, 1.0
	v_mov_b32_e32 v216, 0xbfb8aa3b
	v_mov_b32_e32 v108, 0x3727c5ac
	s_waitcnt vmcnt(8)
	v_fmamk_f32 v188, v188, 0x3a000000, v108
	v_fmamk_f32 v189, v189, 0x3a000000, v108
	v_fmamk_f32 v190, v190, 0x3a000000, v108
	v_fmamk_f32 v191, v191, 0x3a000000, v108
	v_fmamk_f32 v192, v192, 0x3a000000, v108
	v_fmamk_f32 v193, v193, 0x3a000000, v108
	v_fmamk_f32 v194, v194, 0x3a000000, v108
	v_fmamk_f32 v195, v195, 0x3a000000, v108
	v_rsq_f32_e32 v188, v188
	v_rsq_f32_e32 v189, v189
	v_rsq_f32_e32 v190, v190
	v_rsq_f32_e32 v191, v191
	v_rsq_f32_e32 v192, v192
	v_rsq_f32_e32 v193, v193
	v_rsq_f32_e32 v194, v194
	v_rsq_f32_e32 v195, v195
	v_pk_mul_f32 v[158:159], v[158:159], v[188:189] op_sel_hi:[1,0]
	v_pk_mul_f32 v[160:161], v[160:161], v[188:189] op_sel_hi:[1,0]
	v_pk_mul_f32 v[60:61], v[60:61], v[188:189] op_sel_hi:[1,0]
	v_pk_mul_f32 v[62:63], v[62:63], v[188:189] op_sel_hi:[1,0]
	v_pk_mul_f32 v[154:155], v[154:155], v[188:189] op_sel_hi:[1,0]
	v_pk_mul_f32 v[156:157], v[156:157], v[188:189] op_sel_hi:[1,0]
	v_pk_mul_f32 v[56:57], v[56:57], v[188:189] op_sel_hi:[1,0]
	v_pk_mul_f32 v[58:59], v[58:59], v[188:189] op_sel_hi:[1,0]
	v_pk_mul_f32 v[150:151], v[150:151], v[188:189] op_sel:[0,1] op_sel_hi:[1,1]
	v_pk_mul_f32 v[152:153], v[152:153], v[188:189] op_sel:[0,1] op_sel_hi:[1,1]
	v_pk_mul_f32 v[52:53], v[52:53], v[188:189] op_sel:[0,1] op_sel_hi:[1,1]
	v_pk_mul_f32 v[54:55], v[54:55], v[188:189] op_sel:[0,1] op_sel_hi:[1,1]
	v_pk_mul_f32 v[142:143], v[142:143], v[188:189] op_sel:[0,1] op_sel_hi:[1,1]
	v_pk_mul_f32 v[144:145], v[144:145], v[188:189] op_sel:[0,1] op_sel_hi:[1,1]
	v_pk_mul_f32 v[44:45], v[44:45], v[188:189] op_sel:[0,1] op_sel_hi:[1,1]
	v_pk_mul_f32 v[46:47], v[46:47], v[188:189] op_sel:[0,1] op_sel_hi:[1,1]
	v_pk_mul_f32 v[146:147], v[146:147], v[190:191] op_sel_hi:[1,0]
	v_pk_mul_f32 v[148:149], v[148:149], v[190:191] op_sel_hi:[1,0]
	v_pk_mul_f32 v[48:49], v[48:49], v[190:191] op_sel_hi:[1,0]
	v_pk_mul_f32 v[50:51], v[50:51], v[190:191] op_sel_hi:[1,0]
	v_pk_mul_f32 v[134:135], v[134:135], v[190:191] op_sel_hi:[1,0]
	v_pk_mul_f32 v[136:137], v[136:137], v[190:191] op_sel_hi:[1,0]
	v_pk_mul_f32 v[36:37], v[36:37], v[190:191] op_sel_hi:[1,0]
	v_pk_mul_f32 v[38:39], v[38:39], v[190:191] op_sel_hi:[1,0]
	v_pk_mul_f32 v[138:139], v[138:139], v[190:191] op_sel:[0,1] op_sel_hi:[1,1]
	v_pk_mul_f32 v[140:141], v[140:141], v[190:191] op_sel:[0,1] op_sel_hi:[1,1]
	v_pk_mul_f32 v[40:41], v[40:41], v[190:191] op_sel:[0,1] op_sel_hi:[1,1]
	v_pk_mul_f32 v[42:43], v[42:43], v[190:191] op_sel:[0,1] op_sel_hi:[1,1]
	v_pk_mul_f32 v[130:131], v[130:131], v[190:191] op_sel:[0,1] op_sel_hi:[1,1]
	v_pk_mul_f32 v[132:133], v[132:133], v[190:191] op_sel:[0,1] op_sel_hi:[1,1]
	v_pk_mul_f32 v[32:33], v[32:33], v[190:191] op_sel:[0,1] op_sel_hi:[1,1]
	v_pk_mul_f32 v[34:35], v[34:35], v[190:191] op_sel:[0,1] op_sel_hi:[1,1]
	v_pk_mul_f32 v[126:127], v[126:127], v[192:193] op_sel_hi:[1,0]
	v_pk_mul_f32 v[128:129], v[128:129], v[192:193] op_sel_hi:[1,0]
	v_pk_mul_f32 v[28:29], v[28:29], v[192:193] op_sel_hi:[1,0]
	v_pk_mul_f32 v[30:31], v[30:31], v[192:193] op_sel_hi:[1,0]
	v_pk_mul_f32 v[118:119], v[118:119], v[192:193] op_sel_hi:[1,0]
	v_pk_mul_f32 v[120:121], v[120:121], v[192:193] op_sel_hi:[1,0]
	v_pk_mul_f32 v[16:17], v[16:17], v[192:193] op_sel_hi:[1,0]
	v_pk_mul_f32 v[18:19], v[18:19], v[192:193] op_sel_hi:[1,0]
	v_pk_mul_f32 v[122:123], v[122:123], v[192:193] op_sel:[0,1] op_sel_hi:[1,1]
	v_pk_mul_f32 v[124:125], v[124:125], v[192:193] op_sel:[0,1] op_sel_hi:[1,1]
	v_pk_mul_f32 v[24:25], v[24:25], v[192:193] op_sel:[0,1] op_sel_hi:[1,1]
	v_pk_mul_f32 v[26:27], v[26:27], v[192:193] op_sel:[0,1] op_sel_hi:[1,1]
	v_pk_mul_f32 v[110:111], v[110:111], v[192:193] op_sel:[0,1] op_sel_hi:[1,1]
	v_pk_mul_f32 v[112:113], v[112:113], v[192:193] op_sel:[0,1] op_sel_hi:[1,1]
	v_pk_mul_f32 v[12:13], v[12:13], v[192:193] op_sel:[0,1] op_sel_hi:[1,1]
	v_pk_mul_f32 v[14:15], v[14:15], v[192:193] op_sel:[0,1] op_sel_hi:[1,1]
	v_pk_mul_f32 v[114:115], v[114:115], v[194:195] op_sel_hi:[1,0]
	v_pk_mul_f32 v[116:117], v[116:117], v[194:195] op_sel_hi:[1,0]
	v_pk_mul_f32 v[20:21], v[20:21], v[194:195] op_sel_hi:[1,0]
	v_pk_mul_f32 v[22:23], v[22:23], v[194:195] op_sel_hi:[1,0]
	v_pk_mul_f32 v[68:69], v[68:69], v[194:195] op_sel_hi:[1,0]
	v_pk_mul_f32 v[70:71], v[70:71], v[194:195] op_sel_hi:[1,0]
	v_pk_mul_f32 v[8:9], v[8:9], v[194:195] op_sel_hi:[1,0]
	v_pk_mul_f32 v[10:11], v[10:11], v[194:195] op_sel_hi:[1,0]
	v_pk_mul_f32 v[72:73], v[72:73], v[194:195] op_sel:[0,1] op_sel_hi:[1,1]
	v_pk_mul_f32 v[74:75], v[74:75], v[194:195] op_sel:[0,1] op_sel_hi:[1,1]
	v_pk_mul_f32 v[4:5], v[4:5], v[194:195] op_sel:[0,1] op_sel_hi:[1,1]
	v_pk_mul_f32 v[6:7], v[6:7], v[194:195] op_sel:[0,1] op_sel_hi:[1,1]
	v_pk_mul_f32 v[64:65], v[64:65], v[194:195] op_sel:[0,1] op_sel_hi:[1,1]
	v_pk_mul_f32 v[66:67], v[66:67], v[194:195] op_sel:[0,1] op_sel_hi:[1,1]
	v_pk_mul_f32 v[0:1], v[0:1], v[194:195] op_sel:[0,1] op_sel_hi:[1,1]
	v_pk_mul_f32 v[2:3], v[2:3], v[194:195] op_sel:[0,1] op_sel_hi:[1,1]
	v_cmp_gt_u32_e32 vcc, 2, v163
	s_nop 1
	s_mov_b64 exec, vcc
	v_add_u32_e32 v213, 0x5800, v217
	global_store_dwordx4 v217, v[158:161], s[70:71]
	global_store_dwordx4 v213, v[154:157], s[70:71]
	global_store_dwordx4 v217, v[60:63], s[70:71] offset:16
	global_store_dwordx4 v213, v[56:59], s[70:71] offset:16
	s_mov_b64 exec, s[10:11]
	v_add_u32_e32 v213, 0xfff7c000, v217
	global_store_dwordx4 v213, v[72:75], s[70:71]
	global_store_dwordx4 v213, v[4:7], s[70:71] offset:16
	v_add_u32_e32 v213, 0xfff81800, v217
	global_store_dwordx4 v213, v[64:67], s[70:71]
	global_store_dwordx4 v213, v[0:3], s[70:71] offset:16
	s_mov_b64 exec, -1
	v_cmp_lt_u32_e32 vcc, 1, v163
	s_cmp_lg_u64 s[4:5], 0
	s_cselect_b32 s8, s0, s30
	s_cselect_b32 s10, s1, s28
	s_lshl_b32 s8, s8, 8
	s_add_i32 s8, s8, s56
	s_lshl_b32 s10, s10, 7
	s_add_i32 s10, s10, s49
	v_and_b32_e32 v213, 63, v222
	v_add_u32_e32 v188, s8, v213
	v_lshlrev_b32_e32 v188, 2, v188
	s_mov_b32 m0, s9
	v_add_u32_e32 v189, 0x100, v188
	global_load_lds_dword v188, s[12:13]
	s_add_i32 m0, s9, 0x100
	v_and_b32_e32 v190, 7, v213
	global_load_lds_dword v189, s[12:13]
	v_lshrrev_b32_e32 v191, 3, v213
	v_lshlrev_b32_e32 v190, 4, v190
	s_lshl_b32 s10, s10, 2
	v_add_u32_e32 v190, s10, v190
	v_lshrrev_b32_e32 v192, 2, v191
	v_and_b32_e32 v191, 3, v191
	v_mul_u32_u24_e32 v192, 0x5800, v192
	v_add_u32_e32 v190, v190, v192
	v_mul_u32_u24_e32 v192, 0xb000, v191
	v_add_u32_e32 v192, v192, v190
	s_add_i32 m0, s9, 0x200
	s_mov_b32 s10, 0xff000000
	s_mov_b32 s11, 0xff000000
	s_andn2_b64 exec, exec, s[10:11]
	global_load_lds_dwordx4 v192, s[82:83]
	s_mov_b64 exec, s[10:11]
	global_load_lds_dwordx4 v190, s[84:85]
	s_mov_b64 exec, -1
	v_add_u32_e32 v213, 0x1b800, v212
	global_load_dwordx4 v[204:207], v213, s[82:83] offset:16
	v_add_u32_e32 v213, 0x5800, v212
	global_load_dwordx4 v[208:211], v213, s[84:85] offset:16
	s_waitcnt vmcnt(14)
	v_pk_fma_f32 v[188:189], v[158:159], v[84:85], v[88:89]
	v_pk_fma_f32 v[190:191], v[160:161], v[86:87], v[90:91]
	v_pk_fma_f32 v[192:193], v[154:155], v[100:101], v[104:105]
	v_pk_fma_f32 v[194:195], v[156:157], v[102:103], v[106:107]
	v_fmac_f32_dpp v188, v158, v80 row_shr:1 row_mask:0xf bank_mask:0xf
	v_fmac_f32_dpp v189, v159, v81 row_shr:1 row_mask:0xf bank_mask:0xf
	v_fmac_f32_dpp v190, v160, v82 row_shr:1 row_mask:0xf bank_mask:0xf
	v_fmac_f32_dpp v191, v161, v83 row_shr:1 row_mask:0xf bank_mask:0xf
	v_fmac_f32_dpp v192, v154, v96 row_shr:1 row_mask:0xf bank_mask:0xf
	v_fmac_f32_dpp v193, v155, v97 row_shr:1 row_mask:0xf bank_mask:0xf
	v_fmac_f32_dpp v194, v156, v98 row_shr:1 row_mask:0xf bank_mask:0xf
	v_fmac_f32_dpp v195, v157, v99 row_shr:1 row_mask:0xf bank_mask:0xf
	v_fmac_f32_dpp v188, v158, v76 row_shr:2 row_mask:0xf bank_mask:0xf
	v_fmac_f32_dpp v189, v159, v77 row_shr:2 row_mask:0xf bank_mask:0xf
	v_fmac_f32_dpp v190, v160, v78 row_shr:2 row_mask:0xf bank_mask:0xf
	v_fmac_f32_dpp v191, v161, v79 row_shr:2 row_mask:0xf bank_mask:0xf
	v_fmac_f32_dpp v192, v154, v92 row_shr:2 row_mask:0xf bank_mask:0xf
	v_fmac_f32_dpp v193, v155, v93 row_shr:2 row_mask:0xf bank_mask:0xf
	v_fmac_f32_dpp v194, v156, v94 row_shr:2 row_mask:0xf bank_mask:0xf
	v_fmac_f32_dpp v195, v157, v95 row_shr:2 row_mask:0xf bank_mask:0xf
	v_pk_mul_f32 v[196:197], v[188:189], v[216:217] op_sel_hi:[1,0]
	v_pk_mul_f32 v[198:199], v[190:191], v[216:217] op_sel_hi:[1,0]
	v_exp_f32_e32 v196, v196
	v_exp_f32_e32 v197, v197
	v_exp_f32_e32 v198, v198
	v_exp_f32_e32 v199, v199
	v_pk_add_f32 v[196:197], v[196:197], v[214:215] op_sel_hi:[1,0]
	v_pk_add_f32 v[198:199], v[198:199], v[214:215] op_sel_hi:[1,0]
	v_rcp_f32_e32 v196, v196
	v_rcp_f32_e32 v197, v197
	v_rcp_f32_e32 v198, v198
	v_rcp_f32_e32 v199, v199
	v_pk_mul_f32 v[188:189], v[188:189], v[196:197]
	v_pk_mul_f32 v[190:191], v[190:191], v[198:199]
	v_pk_mul_f32 v[188:189], v[188:189], v[192:193]
	v_pk_mul_f32 v[190:191], v[190:191], v[194:195]
	v_cvt_pk_bf16_f32 v200, v188, v189
	v_cvt_pk_bf16_f32 v201, v190, v191
	v_pk_fma_f32 v[188:189], v[150:151], v[84:85], v[88:89]
	v_pk_fma_f32 v[190:191], v[152:153], v[86:87], v[90:91]
	v_pk_fma_f32 v[192:193], v[142:143], v[100:101], v[104:105]
	v_pk_fma_f32 v[194:195], v[144:145], v[102:103], v[106:107]
	v_fmac_f32_dpp v188, v150, v80 row_shr:1 row_mask:0xf bank_mask:0xf
	v_fmac_f32_dpp v189, v151, v81 row_shr:1 row_mask:0xf bank_mask:0xf
	v_fmac_f32_dpp v190, v152, v82 row_shr:1 row_mask:0xf bank_mask:0xf
	v_fmac_f32_dpp v191, v153, v83 row_shr:1 row_mask:0xf bank_mask:0xf
	v_fmac_f32_dpp v192, v142, v96 row_shr:1 row_mask:0xf bank_mask:0xf
	v_fmac_f32_dpp v193, v143, v97 row_shr:1 row_mask:0xf bank_mask:0xf
	v_fmac_f32_dpp v194, v144, v98 row_shr:1 row_mask:0xf bank_mask:0xf
	v_fmac_f32_dpp v195, v145, v99 row_shr:1 row_mask:0xf bank_mask:0xf
	v_fmac_f32_dpp v188, v150, v76 row_shr:2 row_mask:0xf bank_mask:0xf
	v_fmac_f32_dpp v189, v151, v77 row_shr:2 row_mask:0xf bank_mask:0xf
	v_fmac_f32_dpp v190, v152, v78 row_shr:2 row_mask:0xf bank_mask:0xf
	v_fmac_f32_dpp v191, v153, v79 row_shr:2 row_mask:0xf bank_mask:0xf
	v_fmac_f32_dpp v192, v142, v92 row_shr:2 row_mask:0xf bank_mask:0xf
	v_fmac_f32_dpp v193, v143, v93 row_shr:2 row_mask:0xf bank_mask:0xf
	v_fmac_f32_dpp v194, v144, v94 row_shr:2 row_mask:0xf bank_mask:0xf
	v_fmac_f32_dpp v195, v145, v95 row_shr:2 row_mask:0xf bank_mask:0xf
	v_fmac_f32_dpp v188, v158, v80 row_shl:15 row_mask:0xf bank_mask:0xf
	v_fmac_f32_dpp v189, v159, v81 row_shl:15 row_mask:0xf bank_mask:0xf
	v_fmac_f32_dpp v190, v160, v82 row_shl:15 row_mask:0xf bank_mask:0xf
	v_fmac_f32_dpp v191, v161, v83 row_shl:15 row_mask:0xf bank_mask:0xf
	v_fmac_f32_dpp v192, v154, v96 row_shl:15 row_mask:0xf bank_mask:0xf
	v_fmac_f32_dpp v193, v155, v97 row_shl:15 row_mask:0xf bank_mask:0xf
	v_fmac_f32_dpp v194, v156, v98 row_shl:15 row_mask:0xf bank_mask:0xf
	v_fmac_f32_dpp v195, v157, v99 row_shl:15 row_mask:0xf bank_mask:0xf
	v_fmac_f32_dpp v188, v158, v76 row_shl:14 row_mask:0xf bank_mask:0xf
	v_fmac_f32_dpp v189, v159, v77 row_shl:14 row_mask:0xf bank_mask:0xf
	v_fmac_f32_dpp v190, v160, v78 row_shl:14 row_mask:0xf bank_mask:0xf
	v_fmac_f32_dpp v191, v161, v79 row_shl:14 row_mask:0xf bank_mask:0xf
	v_fmac_f32_dpp v192, v154, v92 row_shl:14 row_mask:0xf bank_mask:0xf
	v_fmac_f32_dpp v193, v155, v93 row_shl:14 row_mask:0xf bank_mask:0xf
	v_fmac_f32_dpp v194, v156, v94 row_shl:14 row_mask:0xf bank_mask:0xf
	v_fmac_f32_dpp v195, v157, v95 row_shl:14 row_mask:0xf bank_mask:0xf
	v_pk_mul_f32 v[196:197], v[188:189], v[216:217] op_sel_hi:[1,0]
	v_pk_mul_f32 v[198:199], v[190:191], v[216:217] op_sel_hi:[1,0]
	v_exp_f32_e32 v196, v196
	v_exp_f32_e32 v197, v197
	v_exp_f32_e32 v198, v198
	v_exp_f32_e32 v199, v199
	v_pk_add_f32 v[196:197], v[196:197], v[214:215] op_sel_hi:[1,0]
	v_pk_add_f32 v[198:199], v[198:199], v[214:215] op_sel_hi:[1,0]
	v_rcp_f32_e32 v196, v196
	v_rcp_f32_e32 v197, v197
	v_rcp_f32_e32 v198, v198
	v_rcp_f32_e32 v199, v199
	v_pk_mul_f32 v[188:189], v[188:189], v[196:197]
	v_pk_mul_f32 v[190:191], v[190:191], v[198:199]
	v_pk_mul_f32 v[188:189], v[188:189], v[192:193]
	v_pk_mul_f32 v[190:191], v[190:191], v[194:195]
	v_cvt_pk_bf16_f32 v158, v188, v189
	v_cvt_pk_bf16_f32 v159, v190, v191
	global_load_dwordx4 v[154:157], v212, s[82:83] offset:16
	v_pk_fma_f32 v[188:189], v[146:147], v[84:85], v[88:89]
	v_pk_fma_f32 v[190:191], v[148:149], v[86:87], v[90:91]
	v_pk_fma_f32 v[192:193], v[134:135], v[100:101], v[104:105]
	v_pk_fma_f32 v[194:195], v[136:137], v[102:103], v[106:107]
	v_fmac_f32_dpp v188, v146, v80 row_shr:1 row_mask:0xf bank_mask:0xf
	v_fmac_f32_dpp v189, v147, v81 row_shr:1 row_mask:0xf bank_mask:0xf
	v_fmac_f32_dpp v190, v148, v82 row_shr:1 row_mask:0xf bank_mask:0xf
	v_fmac_f32_dpp v191, v149, v83 row_shr:1 row_mask:0xf bank_mask:0xf
	v_fmac_f32_dpp v192, v134, v96 row_shr:1 row_mask:0xf bank_mask:0xf
	v_fmac_f32_dpp v193, v135, v97 row_shr:1 row_mask:0xf bank_mask:0xf
	v_fmac_f32_dpp v194, v136, v98 row_shr:1 row_mask:0xf bank_mask:0xf
	v_fmac_f32_dpp v195, v137, v99 row_shr:1 row_mask:0xf bank_mask:0xf
	v_fmac_f32_dpp v188, v146, v76 row_shr:2 row_mask:0xf bank_mask:0xf
	v_fmac_f32_dpp v189, v147, v77 row_shr:2 row_mask:0xf bank_mask:0xf
	v_fmac_f32_dpp v190, v148, v78 row_shr:2 row_mask:0xf bank_mask:0xf
	v_fmac_f32_dpp v191, v149, v79 row_shr:2 row_mask:0xf bank_mask:0xf
	v_fmac_f32_dpp v192, v134, v92 row_shr:2 row_mask:0xf bank_mask:0xf
	v_fmac_f32_dpp v193, v135, v93 row_shr:2 row_mask:0xf bank_mask:0xf
	v_fmac_f32_dpp v194, v136, v94 row_shr:2 row_mask:0xf bank_mask:0xf
	v_fmac_f32_dpp v195, v137, v95 row_shr:2 row_mask:0xf bank_mask:0xf
	v_fmac_f32_dpp v188, v150, v80 row_shl:15 row_mask:0xf bank_mask:0xf
	v_fmac_f32_dpp v189, v151, v81 row_shl:15 row_mask:0xf bank_mask:0xf
	v_fmac_f32_dpp v190, v152, v82 row_shl:15 row_mask:0xf bank_mask:0xf
	v_fmac_f32_dpp v191, v153, v83 row_shl:15 row_mask:0xf bank_mask:0xf
	v_fmac_f32_dpp v192, v142, v96 row_shl:15 row_mask:0xf bank_mask:0xf
	v_fmac_f32_dpp v193, v143, v97 row_shl:15 row_mask:0xf bank_mask:0xf
	v_fmac_f32_dpp v194, v144, v98 row_shl:15 row_mask:0xf bank_mask:0xf
	v_fmac_f32_dpp v195, v145, v99 row_shl:15 row_mask:0xf bank_mask:0xf
	v_fmac_f32_dpp v188, v150, v76 row_shl:14 row_mask:0xf bank_mask:0xf
	v_fmac_f32_dpp v189, v151, v77 row_shl:14 row_mask:0xf bank_mask:0xf
	v_fmac_f32_dpp v190, v152, v78 row_shl:14 row_mask:0xf bank_mask:0xf
	v_fmac_f32_dpp v191, v153, v79 row_shl:14 row_mask:0xf bank_mask:0xf
	v_fmac_f32_dpp v192, v142, v92 row_shl:14 row_mask:0xf bank_mask:0xf
	v_fmac_f32_dpp v193, v143, v93 row_shl:14 row_mask:0xf bank_mask:0xf
	v_fmac_f32_dpp v194, v144, v94 row_shl:14 row_mask:0xf bank_mask:0xf
	v_fmac_f32_dpp v195, v145, v95 row_shl:14 row_mask:0xf bank_mask:0xf
	v_pk_mul_f32 v[196:197], v[188:189], v[216:217] op_sel_hi:[1,0]
	v_pk_mul_f32 v[198:199], v[190:191], v[216:217] op_sel_hi:[1,0]
	v_exp_f32_e32 v196, v196
	v_exp_f32_e32 v197, v197
	v_exp_f32_e32 v198, v198
	v_exp_f32_e32 v199, v199
	v_pk_add_f32 v[196:197], v[196:197], v[214:215] op_sel_hi:[1,0]
	v_pk_add_f32 v[198:199], v[198:199], v[214:215] op_sel_hi:[1,0]
	v_rcp_f32_e32 v196, v196
	v_rcp_f32_e32 v197, v197
	v_rcp_f32_e32 v198, v198
	v_rcp_f32_e32 v199, v199
	v_pk_mul_f32 v[188:189], v[188:189], v[196:197]
	v_pk_mul_f32 v[190:191], v[190:191], v[198:199]
	v_pk_mul_f32 v[188:189], v[188:189], v[192:193]
	v_pk_mul_f32 v[190:191], v[190:191], v[194:195]
	v_cvt_pk_bf16_f32 v150, v188, v189
	v_cvt_pk_bf16_f32 v151, v190, v191
	v_add_u32_e32 v213, 0xb000, v212
	global_load_dwordx4 v[142:145], v213, s[82:83] offset:16
	v_pk_fma_f32 v[188:189], v[138:139], v[84:85], v[88:89]
	v_pk_fma_f32 v[190:191], v[140:141], v[86:87], v[90:91]
	v_pk_fma_f32 v[192:193], v[130:131], v[100:101], v[104:105]
	v_pk_fma_f32 v[194:195], v[132:133], v[102:103], v[106:107]
	v_fmac_f32_dpp v188, v138, v80 row_shr:1 row_mask:0xf bank_mask:0xf
	v_fmac_f32_dpp v189, v139, v81 row_shr:1 row_mask:0xf bank_mask:0xf
	v_fmac_f32_dpp v190, v140, v82 row_shr:1 row_mask:0xf bank_mask:0xf
	v_fmac_f32_dpp v191, v141, v83 row_shr:1 row_mask:0xf bank_mask:0xf
	v_fmac_f32_dpp v192, v130, v96 row_shr:1 row_mask:0xf bank_mask:0xf
	v_fmac_f32_dpp v193, v131, v97 row_shr:1 row_mask:0xf bank_mask:0xf
	v_fmac_f32_dpp v194, v132, v98 row_shr:1 row_mask:0xf bank_mask:0xf
	v_fmac_f32_dpp v195, v133, v99 row_shr:1 row_mask:0xf bank_mask:0xf
	v_fmac_f32_dpp v188, v138, v76 row_shr:2 row_mask:0xf bank_mask:0xf
	v_fmac_f32_dpp v189, v139, v77 row_shr:2 row_mask:0xf bank_mask:0xf
	v_fmac_f32_dpp v190, v140, v78 row_shr:2 row_mask:0xf bank_mask:0xf
	v_fmac_f32_dpp v191, v141, v79 row_shr:2 row_mask:0xf bank_mask:0xf
	v_fmac_f32_dpp v192, v130, v92 row_shr:2 row_mask:0xf bank_mask:0xf
	v_fmac_f32_dpp v193, v131, v93 row_shr:2 row_mask:0xf bank_mask:0xf
	v_fmac_f32_dpp v194, v132, v94 row_shr:2 row_mask:0xf bank_mask:0xf
	v_fmac_f32_dpp v195, v133, v95 row_shr:2 row_mask:0xf bank_mask:0xf
	v_fmac_f32_dpp v188, v146, v80 row_shl:15 row_mask:0xf bank_mask:0xf
	v_fmac_f32_dpp v189, v147, v81 row_shl:15 row_mask:0xf bank_mask:0xf
	v_fmac_f32_dpp v190, v148, v82 row_shl:15 row_mask:0xf bank_mask:0xf
	v_fmac_f32_dpp v191, v149, v83 row_shl:15 row_mask:0xf bank_mask:0xf
	v_fmac_f32_dpp v192, v134, v96 row_shl:15 row_mask:0xf bank_mask:0xf
	v_fmac_f32_dpp v193, v135, v97 row_shl:15 row_mask:0xf bank_mask:0xf
	v_fmac_f32_dpp v194, v136, v98 row_shl:15 row_mask:0xf bank_mask:0xf
	v_fmac_f32_dpp v195, v137, v99 row_shl:15 row_mask:0xf bank_mask:0xf
	v_fmac_f32_dpp v188, v146, v76 row_shl:14 row_mask:0xf bank_mask:0xf
	v_fmac_f32_dpp v189, v147, v77 row_shl:14 row_mask:0xf bank_mask:0xf
	v_fmac_f32_dpp v190, v148, v78 row_shl:14 row_mask:0xf bank_mask:0xf
	v_fmac_f32_dpp v191, v149, v79 row_shl:14 row_mask:0xf bank_mask:0xf
	v_fmac_f32_dpp v192, v134, v92 row_shl:14 row_mask:0xf bank_mask:0xf
	v_fmac_f32_dpp v193, v135, v93 row_shl:14 row_mask:0xf bank_mask:0xf
	v_fmac_f32_dpp v194, v136, v94 row_shl:14 row_mask:0xf bank_mask:0xf
	v_fmac_f32_dpp v195, v137, v95 row_shl:14 row_mask:0xf bank_mask:0xf
	v_pk_mul_f32 v[196:197], v[188:189], v[216:217] op_sel_hi:[1,0]
	v_pk_mul_f32 v[198:199], v[190:191], v[216:217] op_sel_hi:[1,0]
	v_exp_f32_e32 v196, v196
	v_exp_f32_e32 v197, v197
	v_exp_f32_e32 v198, v198
	v_exp_f32_e32 v199, v199
	v_pk_add_f32 v[196:197], v[196:197], v[214:215] op_sel_hi:[1,0]
	v_pk_add_f32 v[198:199], v[198:199], v[214:215] op_sel_hi:[1,0]
	v_rcp_f32_e32 v196, v196
	v_rcp_f32_e32 v197, v197
	v_rcp_f32_e32 v198, v198
	v_rcp_f32_e32 v199, v199
	v_pk_mul_f32 v[188:189], v[188:189], v[196:197]
	v_pk_mul_f32 v[190:191], v[190:191], v[198:199]
	v_pk_mul_f32 v[188:189], v[188:189], v[192:193]
	v_pk_mul_f32 v[190:191], v[190:191], v[194:195]
	v_cvt_pk_bf16_f32 v146, v188, v189
	v_cvt_pk_bf16_f32 v147, v190, v191
	v_add_u32_e32 v213, 0x16000, v212
	global_load_dwordx4 v[134:137], v213, s[82:83] offset:16
	v_pk_fma_f32 v[188:189], v[126:127], v[84:85], v[88:89]
	v_pk_fma_f32 v[190:191], v[128:129], v[86:87], v[90:91]
	v_pk_fma_f32 v[192:193], v[118:119], v[100:101], v[104:105]
	v_pk_fma_f32 v[194:195], v[120:121], v[102:103], v[106:107]
	v_fmac_f32_dpp v188, v126, v80 row_shr:1 row_mask:0xf bank_mask:0xf
	v_fmac_f32_dpp v189, v127, v81 row_shr:1 row_mask:0xf bank_mask:0xf
	v_fmac_f32_dpp v190, v128, v82 row_shr:1 row_mask:0xf bank_mask:0xf
	v_fmac_f32_dpp v191, v129, v83 row_shr:1 row_mask:0xf bank_mask:0xf
	v_fmac_f32_dpp v192, v118, v96 row_shr:1 row_mask:0xf bank_mask:0xf
	v_fmac_f32_dpp v193, v119, v97 row_shr:1 row_mask:0xf bank_mask:0xf
	v_fmac_f32_dpp v194, v120, v98 row_shr:1 row_mask:0xf bank_mask:0xf
	v_fmac_f32_dpp v195, v121, v99 row_shr:1 row_mask:0xf bank_mask:0xf
	v_fmac_f32_dpp v188, v126, v76 row_shr:2 row_mask:0xf bank_mask:0xf
	v_fmac_f32_dpp v189, v127, v77 row_shr:2 row_mask:0xf bank_mask:0xf
	v_fmac_f32_dpp v190, v128, v78 row_shr:2 row_mask:0xf bank_mask:0xf
	v_fmac_f32_dpp v191, v129, v79 row_shr:2 row_mask:0xf bank_mask:0xf
	v_fmac_f32_dpp v192, v118, v92 row_shr:2 row_mask:0xf bank_mask:0xf
	v_fmac_f32_dpp v193, v119, v93 row_shr:2 row_mask:0xf bank_mask:0xf
	v_fmac_f32_dpp v194, v120, v94 row_shr:2 row_mask:0xf bank_mask:0xf
	v_fmac_f32_dpp v195, v121, v95 row_shr:2 row_mask:0xf bank_mask:0xf
	v_fmac_f32_dpp v188, v138, v80 row_shl:15 row_mask:0xf bank_mask:0xf
	v_fmac_f32_dpp v189, v139, v81 row_shl:15 row_mask:0xf bank_mask:0xf
	v_fmac_f32_dpp v190, v140, v82 row_shl:15 row_mask:0xf bank_mask:0xf
	v_fmac_f32_dpp v191, v141, v83 row_shl:15 row_mask:0xf bank_mask:0xf
	v_fmac_f32_dpp v192, v130, v96 row_shl:15 row_mask:0xf bank_mask:0xf
	v_fmac_f32_dpp v193, v131, v97 row_shl:15 row_mask:0xf bank_mask:0xf
	v_fmac_f32_dpp v194, v132, v98 row_shl:15 row_mask:0xf bank_mask:0xf
	v_fmac_f32_dpp v195, v133, v99 row_shl:15 row_mask:0xf bank_mask:0xf
	v_fmac_f32_dpp v188, v138, v76 row_shl:14 row_mask:0xf bank_mask:0xf
	v_fmac_f32_dpp v189, v139, v77 row_shl:14 row_mask:0xf bank_mask:0xf
	v_fmac_f32_dpp v190, v140, v78 row_shl:14 row_mask:0xf bank_mask:0xf
	v_fmac_f32_dpp v191, v141, v79 row_shl:14 row_mask:0xf bank_mask:0xf
	v_fmac_f32_dpp v192, v130, v92 row_shl:14 row_mask:0xf bank_mask:0xf
	v_fmac_f32_dpp v193, v131, v93 row_shl:14 row_mask:0xf bank_mask:0xf
	v_fmac_f32_dpp v194, v132, v94 row_shl:14 row_mask:0xf bank_mask:0xf
	v_fmac_f32_dpp v195, v133, v95 row_shl:14 row_mask:0xf bank_mask:0xf
	v_pk_mul_f32 v[196:197], v[188:189], v[216:217] op_sel_hi:[1,0]
	v_pk_mul_f32 v[198:199], v[190:191], v[216:217] op_sel_hi:[1,0]
	v_exp_f32_e32 v196, v196
	v_exp_f32_e32 v197, v197
	v_exp_f32_e32 v198, v198
	v_exp_f32_e32 v199, v199
	v_pk_add_f32 v[196:197], v[196:197], v[214:215] op_sel_hi:[1,0]
	v_pk_add_f32 v[198:199], v[198:199], v[214:215] op_sel_hi:[1,0]
	v_rcp_f32_e32 v196, v196
	v_rcp_f32_e32 v197, v197
	v_rcp_f32_e32 v198, v198
	v_rcp_f32_e32 v199, v199
	v_pk_mul_f32 v[188:189], v[188:189], v[196:197]
	v_pk_mul_f32 v[190:191], v[190:191], v[198:199]
	v_pk_mul_f32 v[188:189], v[188:189], v[192:193]
	v_pk_mul_f32 v[190:191], v[190:191], v[194:195]
	v_cvt_pk_bf16_f32 v138, v188, v189
	v_cvt_pk_bf16_f32 v139, v190, v191
	global_load_dwordx4 v[130:133], v212, s[84:85] offset:16
	v_pk_fma_f32 v[188:189], v[122:123], v[84:85], v[88:89]
	v_pk_fma_f32 v[190:191], v[124:125], v[86:87], v[90:91]
	v_pk_fma_f32 v[192:193], v[110:111], v[100:101], v[104:105]
	v_pk_fma_f32 v[194:195], v[112:113], v[102:103], v[106:107]
	v_fmac_f32_dpp v188, v122, v80 row_shr:1 row_mask:0xf bank_mask:0xf
	v_fmac_f32_dpp v189, v123, v81 row_shr:1 row_mask:0xf bank_mask:0xf
	v_fmac_f32_dpp v190, v124, v82 row_shr:1 row_mask:0xf bank_mask:0xf
	v_fmac_f32_dpp v191, v125, v83 row_shr:1 row_mask:0xf bank_mask:0xf
	v_fmac_f32_dpp v192, v110, v96 row_shr:1 row_mask:0xf bank_mask:0xf
	v_fmac_f32_dpp v193, v111, v97 row_shr:1 row_mask:0xf bank_mask:0xf
	v_fmac_f32_dpp v194, v112, v98 row_shr:1 row_mask:0xf bank_mask:0xf
	v_fmac_f32_dpp v195, v113, v99 row_shr:1 row_mask:0xf bank_mask:0xf
	v_fmac_f32_dpp v188, v122, v76 row_shr:2 row_mask:0xf bank_mask:0xf
	v_fmac_f32_dpp v189, v123, v77 row_shr:2 row_mask:0xf bank_mask:0xf
	v_fmac_f32_dpp v190, v124, v78 row_shr:2 row_mask:0xf bank_mask:0xf
	v_fmac_f32_dpp v191, v125, v79 row_shr:2 row_mask:0xf bank_mask:0xf
	v_fmac_f32_dpp v192, v110, v92 row_shr:2 row_mask:0xf bank_mask:0xf
	v_fmac_f32_dpp v193, v111, v93 row_shr:2 row_mask:0xf bank_mask:0xf
	v_fmac_f32_dpp v194, v112, v94 row_shr:2 row_mask:0xf bank_mask:0xf
	v_fmac_f32_dpp v195, v113, v95 row_shr:2 row_mask:0xf bank_mask:0xf
	v_fmac_f32_dpp v188, v126, v80 row_shl:15 row_mask:0xf bank_mask:0xf
	v_fmac_f32_dpp v189, v127, v81 row_shl:15 row_mask:0xf bank_mask:0xf
	v_fmac_f32_dpp v190, v128, v82 row_shl:15 row_mask:0xf bank_mask:0xf
	v_fmac_f32_dpp v191, v129, v83 row_shl:15 row_mask:0xf bank_mask:0xf
	v_fmac_f32_dpp v192, v118, v96 row_shl:15 row_mask:0xf bank_mask:0xf
	v_fmac_f32_dpp v193, v119, v97 row_shl:15 row_mask:0xf bank_mask:0xf
	v_fmac_f32_dpp v194, v120, v98 row_shl:15 row_mask:0xf bank_mask:0xf
	v_fmac_f32_dpp v195, v121, v99 row_shl:15 row_mask:0xf bank_mask:0xf
	v_fmac_f32_dpp v188, v126, v76 row_shl:14 row_mask:0xf bank_mask:0xf
	v_fmac_f32_dpp v189, v127, v77 row_shl:14 row_mask:0xf bank_mask:0xf
	v_fmac_f32_dpp v190, v128, v78 row_shl:14 row_mask:0xf bank_mask:0xf
	v_fmac_f32_dpp v191, v129, v79 row_shl:14 row_mask:0xf bank_mask:0xf
	v_fmac_f32_dpp v192, v118, v92 row_shl:14 row_mask:0xf bank_mask:0xf
	v_fmac_f32_dpp v193, v119, v93 row_shl:14 row_mask:0xf bank_mask:0xf
	v_fmac_f32_dpp v194, v120, v94 row_shl:14 row_mask:0xf bank_mask:0xf
	v_fmac_f32_dpp v195, v121, v95 row_shl:14 row_mask:0xf bank_mask:0xf
	v_pk_mul_f32 v[196:197], v[188:189], v[216:217] op_sel_hi:[1,0]
	v_pk_mul_f32 v[198:199], v[190:191], v[216:217] op_sel_hi:[1,0]
	v_exp_f32_e32 v196, v196
	v_exp_f32_e32 v197, v197
	v_exp_f32_e32 v198, v198
	v_exp_f32_e32 v199, v199
	v_pk_add_f32 v[196:197], v[196:197], v[214:215] op_sel_hi:[1,0]
	v_pk_add_f32 v[198:199], v[198:199], v[214:215] op_sel_hi:[1,0]
	v_rcp_f32_e32 v196, v196
	v_rcp_f32_e32 v197, v197
	v_rcp_f32_e32 v198, v198
	v_rcp_f32_e32 v199, v199
	v_pk_mul_f32 v[188:189], v[188:189], v[196:197]
	v_pk_mul_f32 v[190:191], v[190:191], v[198:199]
	v_pk_mul_f32 v[188:189], v[188:189], v[192:193]
	v_pk_mul_f32 v[190:191], v[190:191], v[194:195]
	v_cvt_pk_bf16_f32 v126, v188, v189
	v_cvt_pk_bf16_f32 v127, v190, v191
	v_add_u32_e32 v213, 0x5800, v212
	global_load_dwordx4 v[118:121], v213, s[82:83] offset:16
	v_pk_fma_f32 v[188:189], v[114:115], v[84:85], v[88:89]
	v_pk_fma_f32 v[190:191], v[116:117], v[86:87], v[90:91]
	v_pk_fma_f32 v[192:193], v[68:69], v[100:101], v[104:105]
	v_pk_fma_f32 v[194:195], v[70:71], v[102:103], v[106:107]
	v_fmac_f32_dpp v188, v114, v80 row_shr:1 row_mask:0xf bank_mask:0xf
	v_fmac_f32_dpp v189, v115, v81 row_shr:1 row_mask:0xf bank_mask:0xf
	v_fmac_f32_dpp v190, v116, v82 row_shr:1 row_mask:0xf bank_mask:0xf
	v_fmac_f32_dpp v191, v117, v83 row_shr:1 row_mask:0xf bank_mask:0xf
	v_fmac_f32_dpp v192, v68, v96 row_shr:1 row_mask:0xf bank_mask:0xf
	v_fmac_f32_dpp v193, v69, v97 row_shr:1 row_mask:0xf bank_mask:0xf
	v_fmac_f32_dpp v194, v70, v98 row_shr:1 row_mask:0xf bank_mask:0xf
	v_fmac_f32_dpp v195, v71, v99 row_shr:1 row_mask:0xf bank_mask:0xf
	v_fmac_f32_dpp v188, v114, v76 row_shr:2 row_mask:0xf bank_mask:0xf
	v_fmac_f32_dpp v189, v115, v77 row_shr:2 row_mask:0xf bank_mask:0xf
	v_fmac_f32_dpp v190, v116, v78 row_shr:2 row_mask:0xf bank_mask:0xf
	v_fmac_f32_dpp v191, v117, v79 row_shr:2 row_mask:0xf bank_mask:0xf
	v_fmac_f32_dpp v192, v68, v92 row_shr:2 row_mask:0xf bank_mask:0xf
	v_fmac_f32_dpp v193, v69, v93 row_shr:2 row_mask:0xf bank_mask:0xf
	v_fmac_f32_dpp v194, v70, v94 row_shr:2 row_mask:0xf bank_mask:0xf
	v_fmac_f32_dpp v195, v71, v95 row_shr:2 row_mask:0xf bank_mask:0xf
	v_fmac_f32_dpp v188, v122, v80 row_shl:15 row_mask:0xf bank_mask:0xf
	v_fmac_f32_dpp v189, v123, v81 row_shl:15 row_mask:0xf bank_mask:0xf
	v_fmac_f32_dpp v190, v124, v82 row_shl:15 row_mask:0xf bank_mask:0xf
	v_fmac_f32_dpp v191, v125, v83 row_shl:15 row_mask:0xf bank_mask:0xf
	v_fmac_f32_dpp v192, v110, v96 row_shl:15 row_mask:0xf bank_mask:0xf
	v_fmac_f32_dpp v193, v111, v97 row_shl:15 row_mask:0xf bank_mask:0xf
	v_fmac_f32_dpp v194, v112, v98 row_shl:15 row_mask:0xf bank_mask:0xf
	v_fmac_f32_dpp v195, v113, v99 row_shl:15 row_mask:0xf bank_mask:0xf
	v_fmac_f32_dpp v188, v122, v76 row_shl:14 row_mask:0xf bank_mask:0xf
	v_fmac_f32_dpp v189, v123, v77 row_shl:14 row_mask:0xf bank_mask:0xf
	v_fmac_f32_dpp v190, v124, v78 row_shl:14 row_mask:0xf bank_mask:0xf
	v_fmac_f32_dpp v191, v125, v79 row_shl:14 row_mask:0xf bank_mask:0xf
	v_fmac_f32_dpp v192, v110, v92 row_shl:14 row_mask:0xf bank_mask:0xf
	v_fmac_f32_dpp v193, v111, v93 row_shl:14 row_mask:0xf bank_mask:0xf
	v_fmac_f32_dpp v194, v112, v94 row_shl:14 row_mask:0xf bank_mask:0xf
	v_fmac_f32_dpp v195, v113, v95 row_shl:14 row_mask:0xf bank_mask:0xf
	v_pk_mul_f32 v[196:197], v[188:189], v[216:217] op_sel_hi:[1,0]
	v_pk_mul_f32 v[198:199], v[190:191], v[216:217] op_sel_hi:[1,0]
	v_exp_f32_e32 v196, v196
	v_exp_f32_e32 v197, v197
	v_exp_f32_e32 v198, v198
	v_exp_f32_e32 v199, v199
	v_pk_add_f32 v[196:197], v[196:197], v[214:215] op_sel_hi:[1,0]
	v_pk_add_f32 v[198:199], v[198:199], v[214:215] op_sel_hi:[1,0]
	v_rcp_f32_e32 v196, v196
	v_rcp_f32_e32 v197, v197
	v_rcp_f32_e32 v198, v198
	v_rcp_f32_e32 v199, v199
	v_pk_mul_f32 v[188:189], v[188:189], v[196:197]
	v_pk_mul_f32 v[190:191], v[190:191], v[198:199]
	v_pk_mul_f32 v[188:189], v[188:189], v[192:193]
	v_pk_mul_f32 v[190:191], v[190:191], v[194:195]
	v_cvt_pk_bf16_f32 v122, v188, v189
	v_cvt_pk_bf16_f32 v123, v190, v191
	v_add_u32_e32 v213, 0x10800, v212
	global_load_dwordx4 v[110:113], v213, s[82:83] offset:16
	v_pk_fma_f32 v[188:189], v[72:73], v[84:85], v[88:89]
	v_pk_fma_f32 v[190:191], v[74:75], v[86:87], v[90:91]
	v_pk_fma_f32 v[192:193], v[64:65], v[100:101], v[104:105]
	v_pk_fma_f32 v[194:195], v[66:67], v[102:103], v[106:107]
	v_fmac_f32_dpp v188, v72, v80 row_shr:1 row_mask:0xf bank_mask:0xf
	v_fmac_f32_dpp v189, v73, v81 row_shr:1 row_mask:0xf bank_mask:0xf
	v_fmac_f32_dpp v190, v74, v82 row_shr:1 row_mask:0xf bank_mask:0xf
	v_fmac_f32_dpp v191, v75, v83 row_shr:1 row_mask:0xf bank_mask:0xf
	v_fmac_f32_dpp v192, v64, v96 row_shr:1 row_mask:0xf bank_mask:0xf
	v_fmac_f32_dpp v193, v65, v97 row_shr:1 row_mask:0xf bank_mask:0xf
	v_fmac_f32_dpp v194, v66, v98 row_shr:1 row_mask:0xf bank_mask:0xf
	v_fmac_f32_dpp v195, v67, v99 row_shr:1 row_mask:0xf bank_mask:0xf
	v_fmac_f32_dpp v188, v72, v76 row_shr:2 row_mask:0xf bank_mask:0xf
	v_fmac_f32_dpp v189, v73, v77 row_shr:2 row_mask:0xf bank_mask:0xf
	v_fmac_f32_dpp v190, v74, v78 row_shr:2 row_mask:0xf bank_mask:0xf
	v_fmac_f32_dpp v191, v75, v79 row_shr:2 row_mask:0xf bank_mask:0xf
	v_fmac_f32_dpp v192, v64, v92 row_shr:2 row_mask:0xf bank_mask:0xf
	v_fmac_f32_dpp v193, v65, v93 row_shr:2 row_mask:0xf bank_mask:0xf
	v_fmac_f32_dpp v194, v66, v94 row_shr:2 row_mask:0xf bank_mask:0xf
	v_fmac_f32_dpp v195, v67, v95 row_shr:2 row_mask:0xf bank_mask:0xf
	v_fmac_f32_dpp v188, v114, v80 row_shl:15 row_mask:0xf bank_mask:0xf
	v_fmac_f32_dpp v189, v115, v81 row_shl:15 row_mask:0xf bank_mask:0xf
	v_fmac_f32_dpp v190, v116, v82 row_shl:15 row_mask:0xf bank_mask:0xf
	v_fmac_f32_dpp v191, v117, v83 row_shl:15 row_mask:0xf bank_mask:0xf
	v_fmac_f32_dpp v192, v68, v96 row_shl:15 row_mask:0xf bank_mask:0xf
	v_fmac_f32_dpp v193, v69, v97 row_shl:15 row_mask:0xf bank_mask:0xf
	v_fmac_f32_dpp v194, v70, v98 row_shl:15 row_mask:0xf bank_mask:0xf
	v_fmac_f32_dpp v195, v71, v99 row_shl:15 row_mask:0xf bank_mask:0xf
	v_fmac_f32_dpp v188, v114, v76 row_shl:14 row_mask:0xf bank_mask:0xf
	v_fmac_f32_dpp v189, v115, v77 row_shl:14 row_mask:0xf bank_mask:0xf
	v_fmac_f32_dpp v190, v116, v78 row_shl:14 row_mask:0xf bank_mask:0xf
	v_fmac_f32_dpp v191, v117, v79 row_shl:14 row_mask:0xf bank_mask:0xf
	v_fmac_f32_dpp v192, v68, v92 row_shl:14 row_mask:0xf bank_mask:0xf
	v_fmac_f32_dpp v193, v69, v93 row_shl:14 row_mask:0xf bank_mask:0xf
	v_fmac_f32_dpp v194, v70, v94 row_shl:14 row_mask:0xf bank_mask:0xf
	v_fmac_f32_dpp v195, v71, v95 row_shl:14 row_mask:0xf bank_mask:0xf
	v_pk_mul_f32 v[196:197], v[188:189], v[216:217] op_sel_hi:[1,0]
	v_pk_mul_f32 v[198:199], v[190:191], v[216:217] op_sel_hi:[1,0]
	v_exp_f32_e32 v196, v196
	v_exp_f32_e32 v197, v197
	v_exp_f32_e32 v198, v198
	v_exp_f32_e32 v199, v199
	v_pk_add_f32 v[196:197], v[196:197], v[214:215] op_sel_hi:[1,0]
	v_pk_add_f32 v[198:199], v[198:199], v[214:215] op_sel_hi:[1,0]
	v_rcp_f32_e32 v196, v196
	v_rcp_f32_e32 v197, v197
	v_rcp_f32_e32 v198, v198
	v_rcp_f32_e32 v199, v199
	v_pk_mul_f32 v[188:189], v[188:189], v[196:197]
	v_pk_mul_f32 v[190:191], v[190:191], v[198:199]
	v_pk_mul_f32 v[188:189], v[188:189], v[192:193]
	v_pk_mul_f32 v[190:191], v[190:191], v[194:195]
	v_cvt_pk_bf16_f32 v114, v188, v189
	v_cvt_pk_bf16_f32 v115, v190, v191
	s_waitcnt vmcnt(0)
	v_pk_fma_f32 v[188:189], v[60:61], v[134:135], v[130:131]
	v_pk_fma_f32 v[190:191], v[62:63], v[136:137], v[132:133]
	v_pk_fma_f32 v[192:193], v[56:57], v[204:205], v[208:209]
	v_pk_fma_f32 v[194:195], v[58:59], v[206:207], v[210:211]
	v_fmac_f32_dpp v188, v60, v142 row_shr:1 row_mask:0xf bank_mask:0xf
	v_fmac_f32_dpp v189, v61, v143 row_shr:1 row_mask:0xf bank_mask:0xf
	v_fmac_f32_dpp v190, v62, v144 row_shr:1 row_mask:0xf bank_mask:0xf
	v_fmac_f32_dpp v191, v63, v145 row_shr:1 row_mask:0xf bank_mask:0xf
	v_fmac_f32_dpp v192, v56, v110 row_shr:1 row_mask:0xf bank_mask:0xf
	v_fmac_f32_dpp v193, v57, v111 row_shr:1 row_mask:0xf bank_mask:0xf
	v_fmac_f32_dpp v194, v58, v112 row_shr:1 row_mask:0xf bank_mask:0xf
	v_fmac_f32_dpp v195, v59, v113 row_shr:1 row_mask:0xf bank_mask:0xf
	v_fmac_f32_dpp v188, v60, v154 row_shr:2 row_mask:0xf bank_mask:0xf
	v_fmac_f32_dpp v189, v61, v155 row_shr:2 row_mask:0xf bank_mask:0xf
	v_fmac_f32_dpp v190, v62, v156 row_shr:2 row_mask:0xf bank_mask:0xf
	v_fmac_f32_dpp v191, v63, v157 row_shr:2 row_mask:0xf bank_mask:0xf
	v_fmac_f32_dpp v192, v56, v118 row_shr:2 row_mask:0xf bank_mask:0xf
	v_fmac_f32_dpp v193, v57, v119 row_shr:2 row_mask:0xf bank_mask:0xf
	v_fmac_f32_dpp v194, v58, v120 row_shr:2 row_mask:0xf bank_mask:0xf
	v_fmac_f32_dpp v195, v59, v121 row_shr:2 row_mask:0xf bank_mask:0xf
	v_pk_mul_f32 v[196:197], v[188:189], v[216:217] op_sel_hi:[1,0]
	v_pk_mul_f32 v[198:199], v[190:191], v[216:217] op_sel_hi:[1,0]
	v_exp_f32_e32 v196, v196
	v_exp_f32_e32 v197, v197
	v_exp_f32_e32 v198, v198
	v_exp_f32_e32 v199, v199
	v_pk_add_f32 v[196:197], v[196:197], v[214:215] op_sel_hi:[1,0]
	v_pk_add_f32 v[198:199], v[198:199], v[214:215] op_sel_hi:[1,0]
	v_rcp_f32_e32 v196, v196
	v_rcp_f32_e32 v197, v197
	v_rcp_f32_e32 v198, v198
	v_rcp_f32_e32 v199, v199
	v_pk_mul_f32 v[188:189], v[188:189], v[196:197]
	v_pk_mul_f32 v[190:191], v[190:191], v[198:199]
	v_pk_mul_f32 v[188:189], v[188:189], v[192:193]
	v_pk_mul_f32 v[190:191], v[190:191], v[194:195]
	v_cvt_pk_bf16_f32 v202, v188, v189
	v_cvt_pk_bf16_f32 v203, v190, v191
	s_mov_b64 exec, vcc
	global_store_dwordx4 v215, v[200:203], s[96:97]
	s_mov_b64 exec, -1
	v_pk_fma_f32 v[188:189], v[52:53], v[134:135], v[130:131]
	v_pk_fma_f32 v[190:191], v[54:55], v[136:137], v[132:133]
	v_pk_fma_f32 v[192:193], v[44:45], v[204:205], v[208:209]
	v_pk_fma_f32 v[194:195], v[46:47], v[206:207], v[210:211]
	v_fmac_f32_dpp v188, v52, v142 row_shr:1 row_mask:0xf bank_mask:0xf
	v_fmac_f32_dpp v189, v53, v143 row_shr:1 row_mask:0xf bank_mask:0xf
	v_fmac_f32_dpp v190, v54, v144 row_shr:1 row_mask:0xf bank_mask:0xf
	v_fmac_f32_dpp v191, v55, v145 row_shr:1 row_mask:0xf bank_mask:0xf
	v_fmac_f32_dpp v192, v44, v110 row_shr:1 row_mask:0xf bank_mask:0xf
	v_fmac_f32_dpp v193, v45, v111 row_shr:1 row_mask:0xf bank_mask:0xf
	v_fmac_f32_dpp v194, v46, v112 row_shr:1 row_mask:0xf bank_mask:0xf
	v_fmac_f32_dpp v195, v47, v113 row_shr:1 row_mask:0xf bank_mask:0xf
	v_fmac_f32_dpp v188, v52, v154 row_shr:2 row_mask:0xf bank_mask:0xf
	v_fmac_f32_dpp v189, v53, v155 row_shr:2 row_mask:0xf bank_mask:0xf
	v_fmac_f32_dpp v190, v54, v156 row_shr:2 row_mask:0xf bank_mask:0xf
	v_fmac_f32_dpp v191, v55, v157 row_shr:2 row_mask:0xf bank_mask:0xf
	v_fmac_f32_dpp v192, v44, v118 row_shr:2 row_mask:0xf bank_mask:0xf
	v_fmac_f32_dpp v193, v45, v119 row_shr:2 row_mask:0xf bank_mask:0xf
	v_fmac_f32_dpp v194, v46, v120 row_shr:2 row_mask:0xf bank_mask:0xf
	v_fmac_f32_dpp v195, v47, v121 row_shr:2 row_mask:0xf bank_mask:0xf
	v_fmac_f32_dpp v188, v60, v142 row_shl:15 row_mask:0xf bank_mask:0xf
	v_fmac_f32_dpp v189, v61, v143 row_shl:15 row_mask:0xf bank_mask:0xf
	v_fmac_f32_dpp v190, v62, v144 row_shl:15 row_mask:0xf bank_mask:0xf
	v_fmac_f32_dpp v191, v63, v145 row_shl:15 row_mask:0xf bank_mask:0xf
	v_fmac_f32_dpp v192, v56, v110 row_shl:15 row_mask:0xf bank_mask:0xf
	v_fmac_f32_dpp v193, v57, v111 row_shl:15 row_mask:0xf bank_mask:0xf
	v_fmac_f32_dpp v194, v58, v112 row_shl:15 row_mask:0xf bank_mask:0xf
	v_fmac_f32_dpp v195, v59, v113 row_shl:15 row_mask:0xf bank_mask:0xf
	v_fmac_f32_dpp v188, v60, v154 row_shl:14 row_mask:0xf bank_mask:0xf
	v_fmac_f32_dpp v189, v61, v155 row_shl:14 row_mask:0xf bank_mask:0xf
	v_fmac_f32_dpp v190, v62, v156 row_shl:14 row_mask:0xf bank_mask:0xf
	v_fmac_f32_dpp v191, v63, v157 row_shl:14 row_mask:0xf bank_mask:0xf
	v_fmac_f32_dpp v192, v56, v118 row_shl:14 row_mask:0xf bank_mask:0xf
	v_fmac_f32_dpp v193, v57, v119 row_shl:14 row_mask:0xf bank_mask:0xf
	v_fmac_f32_dpp v194, v58, v120 row_shl:14 row_mask:0xf bank_mask:0xf
	v_fmac_f32_dpp v195, v59, v121 row_shl:14 row_mask:0xf bank_mask:0xf
	v_pk_mul_f32 v[196:197], v[188:189], v[216:217] op_sel_hi:[1,0]
	v_pk_mul_f32 v[198:199], v[190:191], v[216:217] op_sel_hi:[1,0]
	v_exp_f32_e32 v196, v196
	v_exp_f32_e32 v197, v197
	v_exp_f32_e32 v198, v198
	v_exp_f32_e32 v199, v199
	v_pk_add_f32 v[196:197], v[196:197], v[214:215] op_sel_hi:[1,0]
	v_pk_add_f32 v[198:199], v[198:199], v[214:215] op_sel_hi:[1,0]
	v_rcp_f32_e32 v196, v196
	v_rcp_f32_e32 v197, v197
	v_rcp_f32_e32 v198, v198
	v_rcp_f32_e32 v199, v199
	v_pk_mul_f32 v[188:189], v[188:189], v[196:197]
	v_pk_mul_f32 v[190:191], v[190:191], v[198:199]
	v_pk_mul_f32 v[188:189], v[188:189], v[192:193]
	v_pk_mul_f32 v[190:191], v[190:191], v[194:195]
	v_cvt_pk_bf16_f32 v160, v188, v189
	v_cvt_pk_bf16_f32 v161, v190, v191
	v_add_u32_e32 v213, 0x2c000, v215
	global_store_dwordx4 v213, v[158:161], s[96:97]
	v_pk_fma_f32 v[188:189], v[48:49], v[134:135], v[130:131]
	v_pk_fma_f32 v[190:191], v[50:51], v[136:137], v[132:133]
	v_pk_fma_f32 v[192:193], v[36:37], v[204:205], v[208:209]
	v_pk_fma_f32 v[194:195], v[38:39], v[206:207], v[210:211]
	v_fmac_f32_dpp v188, v48, v142 row_shr:1 row_mask:0xf bank_mask:0xf
	v_fmac_f32_dpp v189, v49, v143 row_shr:1 row_mask:0xf bank_mask:0xf
	v_fmac_f32_dpp v190, v50, v144 row_shr:1 row_mask:0xf bank_mask:0xf
	v_fmac_f32_dpp v191, v51, v145 row_shr:1 row_mask:0xf bank_mask:0xf
	v_fmac_f32_dpp v192, v36, v110 row_shr:1 row_mask:0xf bank_mask:0xf
	v_fmac_f32_dpp v193, v37, v111 row_shr:1 row_mask:0xf bank_mask:0xf
	v_fmac_f32_dpp v194, v38, v112 row_shr:1 row_mask:0xf bank_mask:0xf
	v_fmac_f32_dpp v195, v39, v113 row_shr:1 row_mask:0xf bank_mask:0xf
	v_fmac_f32_dpp v188, v48, v154 row_shr:2 row_mask:0xf bank_mask:0xf
	v_fmac_f32_dpp v189, v49, v155 row_shr:2 row_mask:0xf bank_mask:0xf
	v_fmac_f32_dpp v190, v50, v156 row_shr:2 row_mask:0xf bank_mask:0xf
	v_fmac_f32_dpp v191, v51, v157 row_shr:2 row_mask:0xf bank_mask:0xf
	v_fmac_f32_dpp v192, v36, v118 row_shr:2 row_mask:0xf bank_mask:0xf
	v_fmac_f32_dpp v193, v37, v119 row_shr:2 row_mask:0xf bank_mask:0xf
	v_fmac_f32_dpp v194, v38, v120 row_shr:2 row_mask:0xf bank_mask:0xf
	v_fmac_f32_dpp v195, v39, v121 row_shr:2 row_mask:0xf bank_mask:0xf
	v_fmac_f32_dpp v188, v52, v142 row_shl:15 row_mask:0xf bank_mask:0xf
	v_fmac_f32_dpp v189, v53, v143 row_shl:15 row_mask:0xf bank_mask:0xf
	v_fmac_f32_dpp v190, v54, v144 row_shl:15 row_mask:0xf bank_mask:0xf
	v_fmac_f32_dpp v191, v55, v145 row_shl:15 row_mask:0xf bank_mask:0xf
	v_fmac_f32_dpp v192, v44, v110 row_shl:15 row_mask:0xf bank_mask:0xf
	v_fmac_f32_dpp v193, v45, v111 row_shl:15 row_mask:0xf bank_mask:0xf
	v_fmac_f32_dpp v194, v46, v112 row_shl:15 row_mask:0xf bank_mask:0xf
	v_fmac_f32_dpp v195, v47, v113 row_shl:15 row_mask:0xf bank_mask:0xf
	v_fmac_f32_dpp v188, v52, v154 row_shl:14 row_mask:0xf bank_mask:0xf
	v_fmac_f32_dpp v189, v53, v155 row_shl:14 row_mask:0xf bank_mask:0xf
	v_fmac_f32_dpp v190, v54, v156 row_shl:14 row_mask:0xf bank_mask:0xf
	v_fmac_f32_dpp v191, v55, v157 row_shl:14 row_mask:0xf bank_mask:0xf
	v_fmac_f32_dpp v192, v44, v118 row_shl:14 row_mask:0xf bank_mask:0xf
	v_fmac_f32_dpp v193, v45, v119 row_shl:14 row_mask:0xf bank_mask:0xf
	v_fmac_f32_dpp v194, v46, v120 row_shl:14 row_mask:0xf bank_mask:0xf
	v_fmac_f32_dpp v195, v47, v121 row_shl:14 row_mask:0xf bank_mask:0xf
	v_pk_mul_f32 v[196:197], v[188:189], v[216:217] op_sel_hi:[1,0]
	v_pk_mul_f32 v[198:199], v[190:191], v[216:217] op_sel_hi:[1,0]
	v_exp_f32_e32 v196, v196
	v_exp_f32_e32 v197, v197
	v_exp_f32_e32 v198, v198
	v_exp_f32_e32 v199, v199
	v_pk_add_f32 v[196:197], v[196:197], v[214:215] op_sel_hi:[1,0]
	v_pk_add_f32 v[198:199], v[198:199], v[214:215] op_sel_hi:[1,0]
	v_rcp_f32_e32 v196, v196
	v_rcp_f32_e32 v197, v197
	v_rcp_f32_e32 v198, v198
	v_rcp_f32_e32 v199, v199
	v_pk_mul_f32 v[188:189], v[188:189], v[196:197]
	v_pk_mul_f32 v[190:191], v[190:191], v[198:199]
	v_pk_mul_f32 v[188:189], v[188:189], v[192:193]
	v_pk_mul_f32 v[190:191], v[190:191], v[194:195]
	v_cvt_pk_bf16_f32 v152, v188, v189
	v_cvt_pk_bf16_f32 v153, v190, v191
	v_add_u32_e32 v213, 0x58000, v215
	global_store_dwordx4 v213, v[150:153], s[96:97]
	v_pk_fma_f32 v[188:189], v[40:41], v[134:135], v[130:131]
	v_pk_fma_f32 v[190:191], v[42:43], v[136:137], v[132:133]
	v_pk_fma_f32 v[192:193], v[32:33], v[204:205], v[208:209]
	v_pk_fma_f32 v[194:195], v[34:35], v[206:207], v[210:211]
	v_fmac_f32_dpp v188, v40, v142 row_shr:1 row_mask:0xf bank_mask:0xf
	v_fmac_f32_dpp v189, v41, v143 row_shr:1 row_mask:0xf bank_mask:0xf
	v_fmac_f32_dpp v190, v42, v144 row_shr:1 row_mask:0xf bank_mask:0xf
	v_fmac_f32_dpp v191, v43, v145 row_shr:1 row_mask:0xf bank_mask:0xf
	v_fmac_f32_dpp v192, v32, v110 row_shr:1 row_mask:0xf bank_mask:0xf
	v_fmac_f32_dpp v193, v33, v111 row_shr:1 row_mask:0xf bank_mask:0xf
	v_fmac_f32_dpp v194, v34, v112 row_shr:1 row_mask:0xf bank_mask:0xf
	v_fmac_f32_dpp v195, v35, v113 row_shr:1 row_mask:0xf bank_mask:0xf
	v_fmac_f32_dpp v188, v40, v154 row_shr:2 row_mask:0xf bank_mask:0xf
	v_fmac_f32_dpp v189, v41, v155 row_shr:2 row_mask:0xf bank_mask:0xf
	v_fmac_f32_dpp v190, v42, v156 row_shr:2 row_mask:0xf bank_mask:0xf
	v_fmac_f32_dpp v191, v43, v157 row_shr:2 row_mask:0xf bank_mask:0xf
	v_fmac_f32_dpp v192, v32, v118 row_shr:2 row_mask:0xf bank_mask:0xf
	v_fmac_f32_dpp v193, v33, v119 row_shr:2 row_mask:0xf bank_mask:0xf
	v_fmac_f32_dpp v194, v34, v120 row_shr:2 row_mask:0xf bank_mask:0xf
	v_fmac_f32_dpp v195, v35, v121 row_shr:2 row_mask:0xf bank_mask:0xf
	v_fmac_f32_dpp v188, v48, v142 row_shl:15 row_mask:0xf bank_mask:0xf
	v_fmac_f32_dpp v189, v49, v143 row_shl:15 row_mask:0xf bank_mask:0xf
	v_fmac_f32_dpp v190, v50, v144 row_shl:15 row_mask:0xf bank_mask:0xf
	v_fmac_f32_dpp v191, v51, v145 row_shl:15 row_mask:0xf bank_mask:0xf
	v_fmac_f32_dpp v192, v36, v110 row_shl:15 row_mask:0xf bank_mask:0xf
	v_fmac_f32_dpp v193, v37, v111 row_shl:15 row_mask:0xf bank_mask:0xf
	v_fmac_f32_dpp v194, v38, v112 row_shl:15 row_mask:0xf bank_mask:0xf
	v_fmac_f32_dpp v195, v39, v113 row_shl:15 row_mask:0xf bank_mask:0xf
	v_fmac_f32_dpp v188, v48, v154 row_shl:14 row_mask:0xf bank_mask:0xf
	v_fmac_f32_dpp v189, v49, v155 row_shl:14 row_mask:0xf bank_mask:0xf
	v_fmac_f32_dpp v190, v50, v156 row_shl:14 row_mask:0xf bank_mask:0xf
	v_fmac_f32_dpp v191, v51, v157 row_shl:14 row_mask:0xf bank_mask:0xf
	v_fmac_f32_dpp v192, v36, v118 row_shl:14 row_mask:0xf bank_mask:0xf
	v_fmac_f32_dpp v193, v37, v119 row_shl:14 row_mask:0xf bank_mask:0xf
	v_fmac_f32_dpp v194, v38, v120 row_shl:14 row_mask:0xf bank_mask:0xf
	v_fmac_f32_dpp v195, v39, v121 row_shl:14 row_mask:0xf bank_mask:0xf
	v_pk_mul_f32 v[196:197], v[188:189], v[216:217] op_sel_hi:[1,0]
	v_pk_mul_f32 v[198:199], v[190:191], v[216:217] op_sel_hi:[1,0]
	v_exp_f32_e32 v196, v196
	v_exp_f32_e32 v197, v197
	v_exp_f32_e32 v198, v198
	v_exp_f32_e32 v199, v199
	v_pk_add_f32 v[196:197], v[196:197], v[214:215] op_sel_hi:[1,0]
	v_pk_add_f32 v[198:199], v[198:199], v[214:215] op_sel_hi:[1,0]
	v_rcp_f32_e32 v196, v196
	v_rcp_f32_e32 v197, v197
	v_rcp_f32_e32 v198, v198
	v_rcp_f32_e32 v199, v199
	v_pk_mul_f32 v[188:189], v[188:189], v[196:197]
	v_pk_mul_f32 v[190:191], v[190:191], v[198:199]
	v_pk_mul_f32 v[188:189], v[188:189], v[192:193]
	v_pk_mul_f32 v[190:191], v[190:191], v[194:195]
	v_cvt_pk_bf16_f32 v148, v188, v189
	v_cvt_pk_bf16_f32 v149, v190, v191
	v_add_u32_e32 v213, 0x84000, v215
	global_store_dwordx4 v213, v[146:149], s[96:97]
	v_pk_fma_f32 v[188:189], v[28:29], v[134:135], v[130:131]
	v_pk_fma_f32 v[190:191], v[30:31], v[136:137], v[132:133]
	v_pk_fma_f32 v[192:193], v[16:17], v[204:205], v[208:209]
	v_pk_fma_f32 v[194:195], v[18:19], v[206:207], v[210:211]
	v_fmac_f32_dpp v188, v28, v142 row_shr:1 row_mask:0xf bank_mask:0xf
	v_fmac_f32_dpp v189, v29, v143 row_shr:1 row_mask:0xf bank_mask:0xf
	v_fmac_f32_dpp v190, v30, v144 row_shr:1 row_mask:0xf bank_mask:0xf
	v_fmac_f32_dpp v191, v31, v145 row_shr:1 row_mask:0xf bank_mask:0xf
	v_fmac_f32_dpp v192, v16, v110 row_shr:1 row_mask:0xf bank_mask:0xf
	v_fmac_f32_dpp v193, v17, v111 row_shr:1 row_mask:0xf bank_mask:0xf
	v_fmac_f32_dpp v194, v18, v112 row_shr:1 row_mask:0xf bank_mask:0xf
	v_fmac_f32_dpp v195, v19, v113 row_shr:1 row_mask:0xf bank_mask:0xf
	v_fmac_f32_dpp v188, v28, v154 row_shr:2 row_mask:0xf bank_mask:0xf
	v_fmac_f32_dpp v189, v29, v155 row_shr:2 row_mask:0xf bank_mask:0xf
	v_fmac_f32_dpp v190, v30, v156 row_shr:2 row_mask:0xf bank_mask:0xf
	v_fmac_f32_dpp v191, v31, v157 row_shr:2 row_mask:0xf bank_mask:0xf
	v_fmac_f32_dpp v192, v16, v118 row_shr:2 row_mask:0xf bank_mask:0xf
	v_fmac_f32_dpp v193, v17, v119 row_shr:2 row_mask:0xf bank_mask:0xf
	v_fmac_f32_dpp v194, v18, v120 row_shr:2 row_mask:0xf bank_mask:0xf
	v_fmac_f32_dpp v195, v19, v121 row_shr:2 row_mask:0xf bank_mask:0xf
	v_fmac_f32_dpp v188, v40, v142 row_shl:15 row_mask:0xf bank_mask:0xf
	v_fmac_f32_dpp v189, v41, v143 row_shl:15 row_mask:0xf bank_mask:0xf
	v_fmac_f32_dpp v190, v42, v144 row_shl:15 row_mask:0xf bank_mask:0xf
	v_fmac_f32_dpp v191, v43, v145 row_shl:15 row_mask:0xf bank_mask:0xf
	v_fmac_f32_dpp v192, v32, v110 row_shl:15 row_mask:0xf bank_mask:0xf
	v_fmac_f32_dpp v193, v33, v111 row_shl:15 row_mask:0xf bank_mask:0xf
	v_fmac_f32_dpp v194, v34, v112 row_shl:15 row_mask:0xf bank_mask:0xf
	v_fmac_f32_dpp v195, v35, v113 row_shl:15 row_mask:0xf bank_mask:0xf
	v_fmac_f32_dpp v188, v40, v154 row_shl:14 row_mask:0xf bank_mask:0xf
	v_fmac_f32_dpp v189, v41, v155 row_shl:14 row_mask:0xf bank_mask:0xf
	v_fmac_f32_dpp v190, v42, v156 row_shl:14 row_mask:0xf bank_mask:0xf
	v_fmac_f32_dpp v191, v43, v157 row_shl:14 row_mask:0xf bank_mask:0xf
	v_fmac_f32_dpp v192, v32, v118 row_shl:14 row_mask:0xf bank_mask:0xf
	v_fmac_f32_dpp v193, v33, v119 row_shl:14 row_mask:0xf bank_mask:0xf
	v_fmac_f32_dpp v194, v34, v120 row_shl:14 row_mask:0xf bank_mask:0xf
	v_fmac_f32_dpp v195, v35, v121 row_shl:14 row_mask:0xf bank_mask:0xf
	v_pk_mul_f32 v[196:197], v[188:189], v[216:217] op_sel_hi:[1,0]
	v_pk_mul_f32 v[198:199], v[190:191], v[216:217] op_sel_hi:[1,0]
	v_exp_f32_e32 v196, v196
	v_exp_f32_e32 v197, v197
	v_exp_f32_e32 v198, v198
	v_exp_f32_e32 v199, v199
	v_pk_add_f32 v[196:197], v[196:197], v[214:215] op_sel_hi:[1,0]
	v_pk_add_f32 v[198:199], v[198:199], v[214:215] op_sel_hi:[1,0]
	v_rcp_f32_e32 v196, v196
	v_rcp_f32_e32 v197, v197
	v_rcp_f32_e32 v198, v198
	v_rcp_f32_e32 v199, v199
	v_pk_mul_f32 v[188:189], v[188:189], v[196:197]
	v_pk_mul_f32 v[190:191], v[190:191], v[198:199]
	v_pk_mul_f32 v[188:189], v[188:189], v[192:193]
	v_pk_mul_f32 v[190:191], v[190:191], v[194:195]
	v_cvt_pk_bf16_f32 v140, v188, v189
	v_cvt_pk_bf16_f32 v141, v190, v191
	v_add_u32_e32 v213, 0xb0000, v215
	global_store_dwordx4 v213, v[138:141], s[96:97]
	v_pk_fma_f32 v[188:189], v[24:25], v[134:135], v[130:131]
	v_pk_fma_f32 v[190:191], v[26:27], v[136:137], v[132:133]
	v_pk_fma_f32 v[192:193], v[12:13], v[204:205], v[208:209]
	v_pk_fma_f32 v[194:195], v[14:15], v[206:207], v[210:211]
	v_fmac_f32_dpp v188, v24, v142 row_shr:1 row_mask:0xf bank_mask:0xf
	v_fmac_f32_dpp v189, v25, v143 row_shr:1 row_mask:0xf bank_mask:0xf
	v_fmac_f32_dpp v190, v26, v144 row_shr:1 row_mask:0xf bank_mask:0xf
	v_fmac_f32_dpp v191, v27, v145 row_shr:1 row_mask:0xf bank_mask:0xf
	v_fmac_f32_dpp v192, v12, v110 row_shr:1 row_mask:0xf bank_mask:0xf
	v_fmac_f32_dpp v193, v13, v111 row_shr:1 row_mask:0xf bank_mask:0xf
	v_fmac_f32_dpp v194, v14, v112 row_shr:1 row_mask:0xf bank_mask:0xf
	v_fmac_f32_dpp v195, v15, v113 row_shr:1 row_mask:0xf bank_mask:0xf
	v_fmac_f32_dpp v188, v24, v154 row_shr:2 row_mask:0xf bank_mask:0xf
	v_fmac_f32_dpp v189, v25, v155 row_shr:2 row_mask:0xf bank_mask:0xf
	v_fmac_f32_dpp v190, v26, v156 row_shr:2 row_mask:0xf bank_mask:0xf
	v_fmac_f32_dpp v191, v27, v157 row_shr:2 row_mask:0xf bank_mask:0xf
	v_fmac_f32_dpp v192, v12, v118 row_shr:2 row_mask:0xf bank_mask:0xf
	v_fmac_f32_dpp v193, v13, v119 row_shr:2 row_mask:0xf bank_mask:0xf
	v_fmac_f32_dpp v194, v14, v120 row_shr:2 row_mask:0xf bank_mask:0xf
	v_fmac_f32_dpp v195, v15, v121 row_shr:2 row_mask:0xf bank_mask:0xf
	v_fmac_f32_dpp v188, v28, v142 row_shl:15 row_mask:0xf bank_mask:0xf
	v_fmac_f32_dpp v189, v29, v143 row_shl:15 row_mask:0xf bank_mask:0xf
	v_fmac_f32_dpp v190, v30, v144 row_shl:15 row_mask:0xf bank_mask:0xf
	v_fmac_f32_dpp v191, v31, v145 row_shl:15 row_mask:0xf bank_mask:0xf
	v_fmac_f32_dpp v192, v16, v110 row_shl:15 row_mask:0xf bank_mask:0xf
	v_fmac_f32_dpp v193, v17, v111 row_shl:15 row_mask:0xf bank_mask:0xf
	v_fmac_f32_dpp v194, v18, v112 row_shl:15 row_mask:0xf bank_mask:0xf
	v_fmac_f32_dpp v195, v19, v113 row_shl:15 row_mask:0xf bank_mask:0xf
	v_fmac_f32_dpp v188, v28, v154 row_shl:14 row_mask:0xf bank_mask:0xf
	v_fmac_f32_dpp v189, v29, v155 row_shl:14 row_mask:0xf bank_mask:0xf
	v_fmac_f32_dpp v190, v30, v156 row_shl:14 row_mask:0xf bank_mask:0xf
	v_fmac_f32_dpp v191, v31, v157 row_shl:14 row_mask:0xf bank_mask:0xf
	v_fmac_f32_dpp v192, v16, v118 row_shl:14 row_mask:0xf bank_mask:0xf
	v_fmac_f32_dpp v193, v17, v119 row_shl:14 row_mask:0xf bank_mask:0xf
	v_fmac_f32_dpp v194, v18, v120 row_shl:14 row_mask:0xf bank_mask:0xf
	v_fmac_f32_dpp v195, v19, v121 row_shl:14 row_mask:0xf bank_mask:0xf
	v_pk_mul_f32 v[196:197], v[188:189], v[216:217] op_sel_hi:[1,0]
	v_pk_mul_f32 v[198:199], v[190:191], v[216:217] op_sel_hi:[1,0]
	v_exp_f32_e32 v196, v196
	v_exp_f32_e32 v197, v197
	v_exp_f32_e32 v198, v198
	v_exp_f32_e32 v199, v199
	v_pk_add_f32 v[196:197], v[196:197], v[214:215] op_sel_hi:[1,0]
	v_pk_add_f32 v[198:199], v[198:199], v[214:215] op_sel_hi:[1,0]
	v_rcp_f32_e32 v196, v196
	v_rcp_f32_e32 v197, v197
	v_rcp_f32_e32 v198, v198
	v_rcp_f32_e32 v199, v199
	v_pk_mul_f32 v[188:189], v[188:189], v[196:197]
	v_pk_mul_f32 v[190:191], v[190:191], v[198:199]
	v_pk_mul_f32 v[188:189], v[188:189], v[192:193]
	v_pk_mul_f32 v[190:191], v[190:191], v[194:195]
	v_cvt_pk_bf16_f32 v128, v188, v189
	v_cvt_pk_bf16_f32 v129, v190, v191
	v_add_u32_e32 v213, 0xdc000, v215
	global_store_dwordx4 v213, v[126:129], s[96:97]
	v_pk_fma_f32 v[188:189], v[20:21], v[134:135], v[130:131]
	v_pk_fma_f32 v[190:191], v[22:23], v[136:137], v[132:133]
	v_pk_fma_f32 v[192:193], v[8:9], v[204:205], v[208:209]
	v_pk_fma_f32 v[194:195], v[10:11], v[206:207], v[210:211]
	v_fmac_f32_dpp v188, v20, v142 row_shr:1 row_mask:0xf bank_mask:0xf
	v_fmac_f32_dpp v189, v21, v143 row_shr:1 row_mask:0xf bank_mask:0xf
	v_fmac_f32_dpp v190, v22, v144 row_shr:1 row_mask:0xf bank_mask:0xf
	v_fmac_f32_dpp v191, v23, v145 row_shr:1 row_mask:0xf bank_mask:0xf
	v_fmac_f32_dpp v192, v8, v110 row_shr:1 row_mask:0xf bank_mask:0xf
	v_fmac_f32_dpp v193, v9, v111 row_shr:1 row_mask:0xf bank_mask:0xf
	v_fmac_f32_dpp v194, v10, v112 row_shr:1 row_mask:0xf bank_mask:0xf
	v_fmac_f32_dpp v195, v11, v113 row_shr:1 row_mask:0xf bank_mask:0xf
	v_fmac_f32_dpp v188, v20, v154 row_shr:2 row_mask:0xf bank_mask:0xf
	v_fmac_f32_dpp v189, v21, v155 row_shr:2 row_mask:0xf bank_mask:0xf
	v_fmac_f32_dpp v190, v22, v156 row_shr:2 row_mask:0xf bank_mask:0xf
	v_fmac_f32_dpp v191, v23, v157 row_shr:2 row_mask:0xf bank_mask:0xf
	v_fmac_f32_dpp v192, v8, v118 row_shr:2 row_mask:0xf bank_mask:0xf
	v_fmac_f32_dpp v193, v9, v119 row_shr:2 row_mask:0xf bank_mask:0xf
	v_fmac_f32_dpp v194, v10, v120 row_shr:2 row_mask:0xf bank_mask:0xf
	v_fmac_f32_dpp v195, v11, v121 row_shr:2 row_mask:0xf bank_mask:0xf
	v_fmac_f32_dpp v188, v24, v142 row_shl:15 row_mask:0xf bank_mask:0xf
	v_fmac_f32_dpp v189, v25, v143 row_shl:15 row_mask:0xf bank_mask:0xf
	v_fmac_f32_dpp v190, v26, v144 row_shl:15 row_mask:0xf bank_mask:0xf
	v_fmac_f32_dpp v191, v27, v145 row_shl:15 row_mask:0xf bank_mask:0xf
	v_fmac_f32_dpp v192, v12, v110 row_shl:15 row_mask:0xf bank_mask:0xf
	v_fmac_f32_dpp v193, v13, v111 row_shl:15 row_mask:0xf bank_mask:0xf
	v_fmac_f32_dpp v194, v14, v112 row_shl:15 row_mask:0xf bank_mask:0xf
	v_fmac_f32_dpp v195, v15, v113 row_shl:15 row_mask:0xf bank_mask:0xf
	v_fmac_f32_dpp v188, v24, v154 row_shl:14 row_mask:0xf bank_mask:0xf
	v_fmac_f32_dpp v189, v25, v155 row_shl:14 row_mask:0xf bank_mask:0xf
	v_fmac_f32_dpp v190, v26, v156 row_shl:14 row_mask:0xf bank_mask:0xf
	v_fmac_f32_dpp v191, v27, v157 row_shl:14 row_mask:0xf bank_mask:0xf
	v_fmac_f32_dpp v192, v12, v118 row_shl:14 row_mask:0xf bank_mask:0xf
	v_fmac_f32_dpp v193, v13, v119 row_shl:14 row_mask:0xf bank_mask:0xf
	v_fmac_f32_dpp v194, v14, v120 row_shl:14 row_mask:0xf bank_mask:0xf
	v_fmac_f32_dpp v195, v15, v121 row_shl:14 row_mask:0xf bank_mask:0xf
	v_pk_mul_f32 v[196:197], v[188:189], v[216:217] op_sel_hi:[1,0]
	v_pk_mul_f32 v[198:199], v[190:191], v[216:217] op_sel_hi:[1,0]
	v_exp_f32_e32 v196, v196
	v_exp_f32_e32 v197, v197
	v_exp_f32_e32 v198, v198
	v_exp_f32_e32 v199, v199
	v_pk_add_f32 v[196:197], v[196:197], v[214:215] op_sel_hi:[1,0]
	v_pk_add_f32 v[198:199], v[198:199], v[214:215] op_sel_hi:[1,0]
	v_rcp_f32_e32 v196, v196
	v_rcp_f32_e32 v197, v197
	v_rcp_f32_e32 v198, v198
	v_rcp_f32_e32 v199, v199
	v_pk_mul_f32 v[188:189], v[188:189], v[196:197]
	v_pk_mul_f32 v[190:191], v[190:191], v[198:199]
	v_pk_mul_f32 v[188:189], v[188:189], v[192:193]
	v_pk_mul_f32 v[190:191], v[190:191], v[194:195]
	v_cvt_pk_bf16_f32 v124, v188, v189
	v_cvt_pk_bf16_f32 v125, v190, v191
	v_add_u32_e32 v213, 0x108000, v215
	global_store_dwordx4 v213, v[122:125], s[96:97]
	v_pk_fma_f32 v[188:189], v[4:5], v[134:135], v[130:131]
	v_pk_fma_f32 v[190:191], v[6:7], v[136:137], v[132:133]
	v_pk_fma_f32 v[192:193], v[0:1], v[204:205], v[208:209]
	v_pk_fma_f32 v[194:195], v[2:3], v[206:207], v[210:211]
	v_fmac_f32_dpp v188, v4, v142 row_shr:1 row_mask:0xf bank_mask:0xf
	v_fmac_f32_dpp v189, v5, v143 row_shr:1 row_mask:0xf bank_mask:0xf
	v_fmac_f32_dpp v190, v6, v144 row_shr:1 row_mask:0xf bank_mask:0xf
	v_fmac_f32_dpp v191, v7, v145 row_shr:1 row_mask:0xf bank_mask:0xf
	v_fmac_f32_dpp v192, v0, v110 row_shr:1 row_mask:0xf bank_mask:0xf
	v_fmac_f32_dpp v193, v1, v111 row_shr:1 row_mask:0xf bank_mask:0xf
	v_fmac_f32_dpp v194, v2, v112 row_shr:1 row_mask:0xf bank_mask:0xf
	v_fmac_f32_dpp v195, v3, v113 row_shr:1 row_mask:0xf bank_mask:0xf
	v_fmac_f32_dpp v188, v4, v154 row_shr:2 row_mask:0xf bank_mask:0xf
	v_fmac_f32_dpp v189, v5, v155 row_shr:2 row_mask:0xf bank_mask:0xf
	v_fmac_f32_dpp v190, v6, v156 row_shr:2 row_mask:0xf bank_mask:0xf
	v_fmac_f32_dpp v191, v7, v157 row_shr:2 row_mask:0xf bank_mask:0xf
	v_fmac_f32_dpp v192, v0, v118 row_shr:2 row_mask:0xf bank_mask:0xf
	v_fmac_f32_dpp v193, v1, v119 row_shr:2 row_mask:0xf bank_mask:0xf
	v_fmac_f32_dpp v194, v2, v120 row_shr:2 row_mask:0xf bank_mask:0xf
	v_fmac_f32_dpp v195, v3, v121 row_shr:2 row_mask:0xf bank_mask:0xf
	v_fmac_f32_dpp v188, v20, v142 row_shl:15 row_mask:0xf bank_mask:0xf
	v_fmac_f32_dpp v189, v21, v143 row_shl:15 row_mask:0xf bank_mask:0xf
	v_fmac_f32_dpp v190, v22, v144 row_shl:15 row_mask:0xf bank_mask:0xf
	v_fmac_f32_dpp v191, v23, v145 row_shl:15 row_mask:0xf bank_mask:0xf
	v_fmac_f32_dpp v192, v8, v110 row_shl:15 row_mask:0xf bank_mask:0xf
	v_fmac_f32_dpp v193, v9, v111 row_shl:15 row_mask:0xf bank_mask:0xf
	v_fmac_f32_dpp v194, v10, v112 row_shl:15 row_mask:0xf bank_mask:0xf
	v_fmac_f32_dpp v195, v11, v113 row_shl:15 row_mask:0xf bank_mask:0xf
	v_fmac_f32_dpp v188, v20, v154 row_shl:14 row_mask:0xf bank_mask:0xf
	v_fmac_f32_dpp v189, v21, v155 row_shl:14 row_mask:0xf bank_mask:0xf
	v_fmac_f32_dpp v190, v22, v156 row_shl:14 row_mask:0xf bank_mask:0xf
	v_fmac_f32_dpp v191, v23, v157 row_shl:14 row_mask:0xf bank_mask:0xf
	v_fmac_f32_dpp v192, v8, v118 row_shl:14 row_mask:0xf bank_mask:0xf
	v_fmac_f32_dpp v193, v9, v119 row_shl:14 row_mask:0xf bank_mask:0xf
	v_fmac_f32_dpp v194, v10, v120 row_shl:14 row_mask:0xf bank_mask:0xf
	v_fmac_f32_dpp v195, v11, v121 row_shl:14 row_mask:0xf bank_mask:0xf
	v_pk_mul_f32 v[196:197], v[188:189], v[216:217] op_sel_hi:[1,0]
	v_pk_mul_f32 v[198:199], v[190:191], v[216:217] op_sel_hi:[1,0]
	v_exp_f32_e32 v196, v196
	v_exp_f32_e32 v197, v197
	v_exp_f32_e32 v198, v198
	v_exp_f32_e32 v199, v199
	v_pk_add_f32 v[196:197], v[196:197], v[214:215] op_sel_hi:[1,0]
	v_pk_add_f32 v[198:199], v[198:199], v[214:215] op_sel_hi:[1,0]
	v_rcp_f32_e32 v196, v196
	v_rcp_f32_e32 v197, v197
	v_rcp_f32_e32 v198, v198
	v_rcp_f32_e32 v199, v199
	v_pk_mul_f32 v[188:189], v[188:189], v[196:197]
	v_pk_mul_f32 v[190:191], v[190:191], v[198:199]
	v_pk_mul_f32 v[188:189], v[188:189], v[192:193]
	v_pk_mul_f32 v[190:191], v[190:191], v[194:195]
	v_cvt_pk_bf16_f32 v116, v188, v189
	v_cvt_pk_bf16_f32 v117, v190, v191
	v_add_u32_e32 v213, 0x134000, v215
	global_store_dwordx4 v213, v[114:117], s[96:97]
	s_branch .LBB0_359

.LBB0_840:
	ds_read_b128 v[76:79], v171
	ds_read_b128 v[80:83], v220
	ds_read_b128 v[84:87], v171 offset:2048
	ds_read_b128 v[88:91], v220 offset:2048
	s_add_u32 s10, s8, 0x100
	s_addc_u32 s11, s9, 0
	s_cmp_eq_u32 s67, 28
	s_cselect_b32 s43, s33, s11
	s_cselect_b32 s42, s37, s10
	s_cselect_b32 s13, s35, s66
	s_cselect_b32 s12, s64, s65
	s_add_i32 m0, s48, 0xc000
	ds_read_b128 v[92:95], v173
	ds_read_b128 v[96:99], v221
	ds_read_b128 v[100:103], v173 offset:2048
	ds_read_b128 v[104:107], v221 offset:2048
	ds_read_b128 v[188:191], v173 offset:4096
	ds_read_b128 v[192:195], v221 offset:4096
	ds_read_b128 v[196:199], v173 offset:6144
	ds_read_b128 v[200:203], v221 offset:6144
	global_load_lds_dwordx4 v180, s[8:9]
	s_add_i32 m0, s48, 0xe000
	s_nop 0
	global_load_lds_dwordx4 v182, s[8:9]
	s_waitcnt lgkmcnt(8)
	s_barrier
	s_waitcnt lgkmcnt(0)
	s_setprio 1
	s_waitcnt lgkmcnt(0)
	v_mfma_f32_16x16x32_bf16 v[158:161], v[76:79], v[92:95], v[158:161]
	v_mfma_f32_16x16x32_bf16 v[158:161], v[80:83], v[96:99], v[158:161]
	v_mfma_f32_16x16x32_bf16 v[60:63], v[88:91], v[96:99], v[60:63]
	v_mfma_f32_16x16x32_bf16 v[60:63], v[84:87], v[92:95], v[60:63]
	v_mfma_f32_16x16x32_bf16 v[52:55], v[84:87], v[100:103], v[52:55]
	v_mfma_f32_16x16x32_bf16 v[52:55], v[88:91], v[104:107], v[52:55]
	v_mfma_f32_16x16x32_bf16 v[150:153], v[80:83], v[104:107], v[150:153]
	v_mfma_f32_16x16x32_bf16 v[150:153], v[76:79], v[100:103], v[150:153]
	v_mfma_f32_16x16x32_bf16 v[146:149], v[76:79], v[188:191], v[146:149]
	v_mfma_f32_16x16x32_bf16 v[146:149], v[80:83], v[192:195], v[146:149]
	v_mfma_f32_16x16x32_bf16 v[48:51], v[88:91], v[192:195], v[48:51]
	v_mfma_f32_16x16x32_bf16 v[48:51], v[84:87], v[188:191], v[48:51]
	v_mfma_f32_16x16x32_bf16 v[40:43], v[84:87], v[196:199], v[40:43]
	v_mfma_f32_16x16x32_bf16 v[40:43], v[88:91], v[200:203], v[40:43]
	v_mfma_f32_16x16x32_bf16 v[138:141], v[80:83], v[200:203], v[138:141]
	v_mfma_f32_16x16x32_bf16 v[138:141], v[76:79], v[196:199], v[138:141]
	s_setprio 0
	s_barrier
	s_add_i32 s8, s60, s46
	s_add_u32 s98, s12, s18
	s_addc_u32 s99, s13, s19
	s_mov_b32 m0, s8
	ds_read_b128 v[204:207], v175
	ds_read_b128 v[208:211], v238
	ds_read_b128 v[212:215], v175 offset:2048
	ds_read_b128 v[216:219], v238 offset:2048
	global_load_lds_dwordx4 v164, s[12:13]
	s_add_i32 m0, s8, 0x2000
	s_nop 0
	global_load_lds_dwordx4 v166, s[12:13]
	s_barrier
	s_waitcnt lgkmcnt(0)
	s_setprio 1
	s_waitcnt lgkmcnt(0)
	v_mfma_f32_16x16x32_bf16 v[154:157], v[204:207], v[92:95], v[154:157]
	v_mfma_f32_16x16x32_bf16 v[154:157], v[208:211], v[96:99], v[154:157]
	v_mfma_f32_16x16x32_bf16 v[56:59], v[216:219], v[96:99], v[56:59]
	v_mfma_f32_16x16x32_bf16 v[56:59], v[212:215], v[92:95], v[56:59]
	v_mfma_f32_16x16x32_bf16 v[44:47], v[212:215], v[100:103], v[44:47]
	v_mfma_f32_16x16x32_bf16 v[44:47], v[216:219], v[104:107], v[44:47]
	v_mfma_f32_16x16x32_bf16 v[36:39], v[216:219], v[192:195], v[36:39]
	v_mfma_f32_16x16x32_bf16 v[36:39], v[212:215], v[188:191], v[36:39]
	v_mfma_f32_16x16x32_bf16 v[32:35], v[212:215], v[196:199], v[32:35]
	v_mfma_f32_16x16x32_bf16 v[32:35], v[216:219], v[200:203], v[32:35]
	v_mfma_f32_16x16x32_bf16 v[92:95], v[204:207], v[100:103], v[142:145]
	v_mfma_f32_16x16x32_bf16 v[92:95], v[208:211], v[104:107], v[92:95]
	v_mfma_f32_16x16x32_bf16 v[96:99], v[208:211], v[192:195], v[134:137]
	v_mfma_f32_16x16x32_bf16 v[96:99], v[204:207], v[188:191], v[96:99]
	v_mfma_f32_16x16x32_bf16 v[100:103], v[204:207], v[196:199], v[130:133]
	v_mfma_f32_16x16x32_bf16 v[100:103], v[208:211], v[200:203], v[100:103]
	s_setprio 0
	s_mov_b32 m0, s48
	s_add_u32 s100, s42, s18
	s_addc_u32 s101, s43, s19
	s_barrier
	ds_read_b128 v[104:107], v173 offset:16384
	ds_read_b128 v[130:133], v221 offset:16384
	ds_read_b128 v[134:137], v173 offset:18432
	ds_read_b128 v[142:145], v221 offset:18432
	ds_read_b128 v[188:191], v173 offset:20480
	ds_read_b128 v[192:195], v221 offset:20480
	ds_read_b128 v[196:199], v173 offset:22528
	ds_read_b128 v[200:203], v221 offset:22528
	global_load_lds_dwordx4 v178, s[42:43]
	s_mov_b32 m0, s49
	s_nop 0
	global_load_lds_dwordx4 v176, s[42:43]
	s_barrier
	s_waitcnt lgkmcnt(0)
	s_setprio 1
	s_waitcnt lgkmcnt(0)
	v_mfma_f32_16x16x32_bf16 v[126:129], v[76:79], v[104:107], v[126:129]
	v_mfma_f32_16x16x32_bf16 v[126:129], v[80:83], v[130:133], v[126:129]
	v_mfma_f32_16x16x32_bf16 v[28:31], v[88:91], v[130:133], v[28:31]
	v_mfma_f32_16x16x32_bf16 v[28:31], v[84:87], v[104:107], v[28:31]
	v_mfma_f32_16x16x32_bf16 v[24:27], v[84:87], v[134:137], v[24:27]
	v_mfma_f32_16x16x32_bf16 v[24:27], v[88:91], v[142:145], v[24:27]
	v_mfma_f32_16x16x32_bf16 v[122:125], v[80:83], v[142:145], v[122:125]
	v_mfma_f32_16x16x32_bf16 v[122:125], v[76:79], v[134:137], v[122:125]
	v_mfma_f32_16x16x32_bf16 v[114:117], v[76:79], v[188:191], v[114:117]
	v_mfma_f32_16x16x32_bf16 v[114:117], v[80:83], v[192:195], v[114:117]
	v_mfma_f32_16x16x32_bf16 v[20:23], v[88:91], v[192:195], v[20:23]
	v_mfma_f32_16x16x32_bf16 v[20:23], v[84:87], v[188:191], v[20:23]
	v_mfma_f32_16x16x32_bf16 v[4:7], v[84:87], v[196:199], v[4:7]
	v_mfma_f32_16x16x32_bf16 v[4:7], v[88:91], v[200:203], v[4:7]
	v_mfma_f32_16x16x32_bf16 v[72:75], v[80:83], v[200:203], v[72:75]
	v_mfma_f32_16x16x32_bf16 v[72:75], v[76:79], v[196:199], v[72:75]
	s_setprio 0
	s_barrier
	s_add_u32 s8, s12, 0x1600000
	s_addc_u32 s9, s13, 0
	s_add_i32 s68, s61, s46
	s_mov_b32 m0, s68
	s_nop 0
	global_load_lds_dwordx4 v164, s[8:9]
	s_add_i32 m0, s68, 0x2000
	s_nop 0
	global_load_lds_dwordx4 v166, s[8:9]
	s_waitcnt vmcnt(6)
	s_barrier
	s_setprio 1
	v_mfma_f32_16x16x32_bf16 v[16:19], v[212:215], v[104:107], v[16:19]
	v_mfma_f32_16x16x32_bf16 v[16:19], v[216:219], v[130:133], v[16:19]
	v_mfma_f32_16x16x32_bf16 v[12:15], v[216:219], v[142:145], v[12:15]
	v_mfma_f32_16x16x32_bf16 v[12:15], v[212:215], v[134:137], v[12:15]
	v_mfma_f32_16x16x32_bf16 v[8:11], v[212:215], v[188:191], v[8:11]
	v_mfma_f32_16x16x32_bf16 v[8:11], v[216:219], v[192:195], v[8:11]
	v_mfma_f32_16x16x32_bf16 v[68:71], v[208:211], v[192:195], v[68:71]
	v_mfma_f32_16x16x32_bf16 v[68:71], v[204:207], v[188:191], v[68:71]
	v_mfma_f32_16x16x32_bf16 v[64:67], v[204:207], v[196:199], v[64:67]
	v_mfma_f32_16x16x32_bf16 v[64:67], v[208:211], v[200:203], v[64:67]
	v_mfma_f32_16x16x32_bf16 v[0:3], v[216:219], v[200:203], v[0:3]
	v_mfma_f32_16x16x32_bf16 v[0:3], v[212:215], v[196:199], v[0:3]
	v_mfma_f32_16x16x32_bf16 v[76:79], v[204:207], v[104:107], v[118:121]
	v_mfma_f32_16x16x32_bf16 v[76:79], v[208:211], v[130:133], v[76:79]
	v_mfma_f32_16x16x32_bf16 v[80:83], v[208:211], v[142:145], v[110:113]
	v_mfma_f32_16x16x32_bf16 v[80:83], v[204:207], v[134:137], v[80:83]
	s_setprio 0
	s_add_i32 s68, 0, 0x18000
	s_barrier
	ds_read_b128 v[84:87], v239
	ds_read_b128 v[88:91], v240
	ds_read_b128 v[104:107], v239 offset:2048
	ds_read_b128 v[108:111], v240 offset:2048
	s_add_u32 s8, s42, 0x40000
	s_addc_u32 s9, s43, 0
	s_mov_b32 m0, s50
	ds_read_b128 v[118:121], v173 offset:32768
	ds_read_b128 v[130:133], v221 offset:32768
	ds_read_b128 v[134:137], v173 offset:34816
	ds_read_b128 v[188:191], v221 offset:34816
	ds_read_b128 v[192:195], v173 offset:36864
	ds_read_b128 v[196:199], v221 offset:36864
	ds_read_b128 v[200:203], v173 offset:38912
	ds_read_b128 v[204:207], v221 offset:38912
	global_load_lds_dwordx4 v178, s[8:9]
	s_mov_b32 m0, s51
	s_nop 0
	global_load_lds_dwordx4 v176, s[8:9]
	s_waitcnt lgkmcnt(8)
	s_barrier
	s_waitcnt lgkmcnt(0)
	s_setprio 1
	s_waitcnt lgkmcnt(0)
	v_mfma_f32_16x16x32_bf16 v[142:145], v[84:87], v[118:121], v[158:161]
	v_mfma_f32_16x16x32_bf16 v[158:161], v[88:91], v[130:133], v[142:145]
	v_mfma_f32_16x16x32_bf16 v[60:63], v[108:111], v[130:133], v[60:63]
	v_mfma_f32_16x16x32_bf16 v[60:63], v[104:107], v[118:121], v[60:63]
	v_mfma_f32_16x16x32_bf16 v[52:55], v[104:107], v[134:137], v[52:55]
	v_mfma_f32_16x16x32_bf16 v[52:55], v[108:111], v[188:191], v[52:55]
	v_mfma_f32_16x16x32_bf16 v[48:51], v[108:111], v[196:199], v[48:51]
	v_mfma_f32_16x16x32_bf16 v[48:51], v[104:107], v[192:195], v[48:51]
	v_mfma_f32_16x16x32_bf16 v[40:43], v[104:107], v[200:203], v[40:43]
	v_mfma_f32_16x16x32_bf16 v[40:43], v[108:111], v[204:207], v[40:43]
	v_mfma_f32_16x16x32_bf16 v[138:141], v[88:91], v[204:207], v[138:141]
	v_mfma_f32_16x16x32_bf16 v[138:141], v[84:87], v[200:203], v[138:141]
	v_mfma_f32_16x16x32_bf16 v[142:145], v[84:87], v[134:137], v[150:153]
	v_mfma_f32_16x16x32_bf16 v[150:153], v[88:91], v[188:191], v[142:145]
	v_mfma_f32_16x16x32_bf16 v[142:145], v[84:87], v[192:195], v[146:149]
	v_mfma_f32_16x16x32_bf16 v[146:149], v[88:91], v[196:199], v[142:145]
	s_setprio 0
	s_barrier
	s_add_i32 s42, 0, 0x1c000
	s_add_i32 s8, s68, s46
	ds_read_b128 v[208:211], v241
	ds_read_b128 v[212:215], v242
	ds_read_b128 v[216:219], v241 offset:2048
	ds_read_b128 v[234:237], v242 offset:2048
	s_mov_b32 m0, s8
	s_nop 0
	global_load_lds_dwordx4 v164, s[98:99]
	s_add_i32 m0, s8, 0x2000
	s_nop 0
	global_load_lds_dwordx4 v166, s[98:99]
	s_barrier
	s_waitcnt lgkmcnt(0)
	s_setprio 1
	s_waitcnt lgkmcnt(0)
	v_mfma_f32_16x16x32_bf16 v[142:145], v[208:211], v[118:121], v[154:157]
	v_mfma_f32_16x16x32_bf16 v[154:157], v[212:215], v[130:133], v[142:145]
	v_mfma_f32_16x16x32_bf16 v[56:59], v[234:237], v[130:133], v[56:59]
	v_mfma_f32_16x16x32_bf16 v[56:59], v[216:219], v[118:121], v[56:59]
	v_mfma_f32_16x16x32_bf16 v[44:47], v[216:219], v[134:137], v[44:47]
	v_mfma_f32_16x16x32_bf16 v[44:47], v[234:237], v[188:191], v[44:47]
	v_mfma_f32_16x16x32_bf16 v[36:39], v[234:237], v[196:199], v[36:39]
	v_mfma_f32_16x16x32_bf16 v[36:39], v[216:219], v[192:195], v[36:39]
	v_mfma_f32_16x16x32_bf16 v[32:35], v[216:219], v[200:203], v[32:35]
	v_mfma_f32_16x16x32_bf16 v[32:35], v[234:237], v[204:207], v[32:35]
	v_mfma_f32_16x16x32_bf16 v[92:95], v[208:211], v[134:137], v[92:95]
	v_mfma_f32_16x16x32_bf16 v[142:145], v[212:215], v[188:191], v[92:95]
	v_mfma_f32_16x16x32_bf16 v[92:95], v[208:211], v[192:195], v[96:99]
	v_mfma_f32_16x16x32_bf16 v[134:137], v[212:215], v[196:199], v[92:95]
	v_mfma_f32_16x16x32_bf16 v[92:95], v[208:211], v[200:203], v[100:103]
	v_mfma_f32_16x16x32_bf16 v[130:133], v[212:215], v[204:207], v[92:95]
	s_setprio 0
	s_mov_b32 m0, s54
	s_barrier
	ds_read_b128 v[92:95], v173 offset:49152
	ds_read_b128 v[96:99], v221 offset:49152
	ds_read_b128 v[100:103], v173 offset:51200
	ds_read_b128 v[188:191], v221 offset:51200
	ds_read_b128 v[192:195], v173 offset:53248
	ds_read_b128 v[196:199], v221 offset:53248
	ds_read_b128 v[200:203], v173 offset:55296
	ds_read_b128 v[204:207], v221 offset:55296
	global_load_lds_dwordx4 v178, s[100:101]
	s_mov_b32 m0, s55
	s_nop 0
	global_load_lds_dwordx4 v176, s[100:101]
	s_barrier
	s_waitcnt lgkmcnt(0)
	s_setprio 1
	s_waitcnt lgkmcnt(0)
	v_mfma_f32_16x16x32_bf16 v[118:121], v[84:87], v[92:95], v[126:129]
	v_mfma_f32_16x16x32_bf16 v[126:129], v[88:91], v[96:99], v[118:121]
	v_mfma_f32_16x16x32_bf16 v[28:31], v[108:111], v[96:99], v[28:31]
	v_mfma_f32_16x16x32_bf16 v[28:31], v[104:107], v[92:95], v[28:31]
	v_mfma_f32_16x16x32_bf16 v[24:27], v[104:107], v[100:103], v[24:27]
	v_mfma_f32_16x16x32_bf16 v[24:27], v[108:111], v[188:191], v[24:27]
	v_mfma_f32_16x16x32_bf16 v[20:23], v[108:111], v[196:199], v[20:23]
	v_mfma_f32_16x16x32_bf16 v[20:23], v[104:107], v[192:195], v[20:23]
	v_mfma_f32_16x16x32_bf16 v[112:115], v[84:87], v[192:195], v[114:117]
	v_mfma_f32_16x16x32_bf16 v[114:117], v[88:91], v[196:199], v[112:115]
	v_mfma_f32_16x16x32_bf16 v[72:75], v[88:91], v[204:207], v[72:75]
	v_mfma_f32_16x16x32_bf16 v[72:75], v[84:87], v[200:203], v[72:75]
	v_mfma_f32_16x16x32_bf16 v[118:121], v[84:87], v[100:103], v[122:125]
	v_mfma_f32_16x16x32_bf16 v[122:125], v[88:91], v[188:191], v[118:121]
	v_mfma_f32_16x16x32_bf16 v[4:7], v[104:107], v[200:203], v[4:7]
	v_mfma_f32_16x16x32_bf16 v[4:7], v[108:111], v[204:207], v[4:7]
	s_setprio 0
	s_barrier
	s_add_u32 s8, s12, 0x1600080
	s_addc_u32 s9, s13, 0
	s_add_i32 s12, s42, s46
	s_mov_b32 m0, s12
	s_nop 0
	global_load_lds_dwordx4 v164, s[8:9]
	s_add_i32 m0, s12, 0x2000
	s_nop 0
	global_load_lds_dwordx4 v166, s[8:9]
	s_waitcnt vmcnt(6)
	s_barrier
	s_setprio 1
	v_mfma_f32_16x16x32_bf16 v[76:79], v[208:211], v[92:95], v[76:79]
	v_mfma_f32_16x16x32_bf16 v[118:121], v[212:215], v[96:99], v[76:79]
	v_mfma_f32_16x16x32_bf16 v[16:19], v[234:237], v[96:99], v[16:19]
	v_mfma_f32_16x16x32_bf16 v[16:19], v[216:219], v[92:95], v[16:19]
	v_mfma_f32_16x16x32_bf16 v[12:15], v[216:219], v[100:103], v[12:15]
	v_mfma_f32_16x16x32_bf16 v[12:15], v[234:237], v[188:191], v[12:15]
	v_mfma_f32_16x16x32_bf16 v[8:11], v[234:237], v[196:199], v[8:11]
	v_mfma_f32_16x16x32_bf16 v[8:11], v[216:219], v[192:195], v[8:11]
	v_mfma_f32_16x16x32_bf16 v[68:71], v[208:211], v[192:195], v[68:71]
	v_mfma_f32_16x16x32_bf16 v[68:71], v[212:215], v[196:199], v[68:71]
	v_mfma_f32_16x16x32_bf16 v[64:67], v[212:215], v[204:207], v[64:67]
	v_mfma_f32_16x16x32_bf16 v[64:67], v[208:211], v[200:203], v[64:67]
	v_mfma_f32_16x16x32_bf16 v[76:79], v[208:211], v[100:103], v[80:83]
	v_mfma_f32_16x16x32_bf16 v[110:113], v[212:215], v[188:191], v[76:79]
	v_mfma_f32_16x16x32_bf16 v[0:3], v[216:219], v[200:203], v[0:3]
	v_mfma_f32_16x16x32_bf16 v[0:3], v[234:237], v[204:207], v[0:3]
	s_setprio 0
	s_add_i32 s67, s67, 2
	s_add_u32 s65, s65, 0x100
	s_addc_u32 s66, s66, 0
	s_cmp_gt_u32 s67, 29
	s_mov_b64 s[8:9], s[10:11]
	s_barrier
	s_cbranch_scc0 .LBB0_840
	s_cmp_eq_u32 s52, 1
	s_cbranch_scc1 .Lfs8_first
	s_lshl_b32 s8, s0, 8
	s_add_i32 s8, s8, s58
	s_lshl_b32 s9, s1, 7
	s_add_i32 s9, s9, s53
	s_lshl_b32 s10, s0, 3
	s_lshr_b32 s11, s58, 5
	s_add_i32 s10, s10, s11
	v_add_u32_e32 v200, s8, v163
	v_lshlrev_b32_e32 v213, 2, v200
	v_lshl_add_u32 v201, v225, 3, s9
	v_lshlrev_b32_e32 v212, 2, v201
	v_lshrrev_b32_e32 v109, 6, v222
	s_and_b32 s9, s52, 1
	v_readfirstlane_b32 s11, v109
	s_mul_i32 s9, s9, 0x3000
	s_mul_i32 s11, s11, 0x600
	s_add_i32 s9, s9, s11
	s_add_i32 s9, s9, 0x21040
	s_xor_b32 s11, s52, 1
	s_and_b32 s11, s11, 1
	s_mul_i32 s11, s11, 0x3000
	v_mul_u32_u24_e32 v109, 0x600, v109
	v_add_u32_e32 v109, s11, v109
	v_add_u32_e32 v109, 0x21040, v109
	v_lshl_add_u32 v213, v163, 2, v109
	ds_read_b32 v188, v213
	ds_read_b32 v189, v213 offset:64
	ds_read_b32 v190, v213 offset:128
	ds_read_b32 v191, v213 offset:192
	ds_read_b32 v192, v213 offset:256
	ds_read_b32 v193, v213 offset:320
	ds_read_b32 v194, v213 offset:384
	ds_read_b32 v195, v213 offset:448
	v_lshl_add_u32 v109, v225, 5, v109
	v_add_u32_e32 v109, 512, v109
	ds_read_b128 v[76:79], v109 offset:0
	ds_read_b128 v[80:83], v109 offset:128
	ds_read_b128 v[84:87], v109 offset:256
	ds_read_b128 v[88:91], v109 offset:384
	ds_read_b128 v[92:95], v109 offset:512
	ds_read_b128 v[96:99], v109 offset:640
	ds_read_b128 v[100:103], v109 offset:768
	ds_read_b128 v[104:107], v109 offset:896
	v_mul_u32_u24_e32 v215, 0x2c00, v200
	v_lshl_add_u32 v215, v201, 1, v215
	v_add_u32_e32 v213, s10, v163
	v_mul_u32_u24_e32 v217, 0xb000, v213
	v_add_u32_e32 v217, v217, v212
	v_cmp_lt_u32_e64 s[10:11], 13, v163
	v_cmp_lt_u32_e32 vcc, 1, v163
	v_mov_b32_e32 v214, 1.0
	v_mov_b32_e32 v216, 0xbfb8aa3b
	v_mov_b32_e32 v108, 0x3727c5ac
	s_waitcnt lgkmcnt(0)
	v_fmamk_f32 v188, v188, 0x3a000000, v108
	v_fmamk_f32 v189, v189, 0x3a000000, v108
	v_fmamk_f32 v190, v190, 0x3a000000, v108
	v_fmamk_f32 v191, v191, 0x3a000000, v108
	v_fmamk_f32 v192, v192, 0x3a000000, v108
	v_fmamk_f32 v193, v193, 0x3a000000, v108
	v_fmamk_f32 v194, v194, 0x3a000000, v108
	v_fmamk_f32 v195, v195, 0x3a000000, v108
	v_rsq_f32_e32 v188, v188
	v_rsq_f32_e32 v189, v189
	v_rsq_f32_e32 v190, v190
	v_rsq_f32_e32 v191, v191
	v_rsq_f32_e32 v192, v192
	v_rsq_f32_e32 v193, v193
	v_rsq_f32_e32 v194, v194
	v_rsq_f32_e32 v195, v195
	v_pk_mul_f32 v[158:159], v[158:159], v[188:189] op_sel_hi:[1,0]
	v_pk_mul_f32 v[160:161], v[160:161], v[188:189] op_sel_hi:[1,0]
	v_pk_mul_f32 v[60:61], v[60:61], v[188:189] op_sel_hi:[1,0]
	v_pk_mul_f32 v[62:63], v[62:63], v[188:189] op_sel_hi:[1,0]
	v_pk_mul_f32 v[154:155], v[154:155], v[188:189] op_sel_hi:[1,0]
	v_pk_mul_f32 v[156:157], v[156:157], v[188:189] op_sel_hi:[1,0]
	v_pk_mul_f32 v[56:57], v[56:57], v[188:189] op_sel_hi:[1,0]
	v_pk_mul_f32 v[58:59], v[58:59], v[188:189] op_sel_hi:[1,0]
	v_pk_mul_f32 v[150:151], v[150:151], v[188:189] op_sel:[0,1] op_sel_hi:[1,1]
	v_pk_mul_f32 v[152:153], v[152:153], v[188:189] op_sel:[0,1] op_sel_hi:[1,1]
	v_pk_mul_f32 v[52:53], v[52:53], v[188:189] op_sel:[0,1] op_sel_hi:[1,1]
	v_pk_mul_f32 v[54:55], v[54:55], v[188:189] op_sel:[0,1] op_sel_hi:[1,1]
	v_pk_mul_f32 v[142:143], v[142:143], v[188:189] op_sel:[0,1] op_sel_hi:[1,1]
	v_pk_mul_f32 v[144:145], v[144:145], v[188:189] op_sel:[0,1] op_sel_hi:[1,1]
	v_pk_mul_f32 v[44:45], v[44:45], v[188:189] op_sel:[0,1] op_sel_hi:[1,1]
	v_pk_mul_f32 v[46:47], v[46:47], v[188:189] op_sel:[0,1] op_sel_hi:[1,1]
	v_pk_mul_f32 v[146:147], v[146:147], v[190:191] op_sel_hi:[1,0]
	v_pk_mul_f32 v[148:149], v[148:149], v[190:191] op_sel_hi:[1,0]
	v_pk_mul_f32 v[48:49], v[48:49], v[190:191] op_sel_hi:[1,0]
	v_pk_mul_f32 v[50:51], v[50:51], v[190:191] op_sel_hi:[1,0]
	v_pk_mul_f32 v[134:135], v[134:135], v[190:191] op_sel_hi:[1,0]
	v_pk_mul_f32 v[136:137], v[136:137], v[190:191] op_sel_hi:[1,0]
	v_pk_mul_f32 v[36:37], v[36:37], v[190:191] op_sel_hi:[1,0]
	v_pk_mul_f32 v[38:39], v[38:39], v[190:191] op_sel_hi:[1,0]
	v_pk_mul_f32 v[138:139], v[138:139], v[190:191] op_sel:[0,1] op_sel_hi:[1,1]
	v_pk_mul_f32 v[140:141], v[140:141], v[190:191] op_sel:[0,1] op_sel_hi:[1,1]
	v_pk_mul_f32 v[40:41], v[40:41], v[190:191] op_sel:[0,1] op_sel_hi:[1,1]
	v_pk_mul_f32 v[42:43], v[42:43], v[190:191] op_sel:[0,1] op_sel_hi:[1,1]
	v_pk_mul_f32 v[130:131], v[130:131], v[190:191] op_sel:[0,1] op_sel_hi:[1,1]
	v_pk_mul_f32 v[132:133], v[132:133], v[190:191] op_sel:[0,1] op_sel_hi:[1,1]
	v_pk_mul_f32 v[32:33], v[32:33], v[190:191] op_sel:[0,1] op_sel_hi:[1,1]
	v_pk_mul_f32 v[34:35], v[34:35], v[190:191] op_sel:[0,1] op_sel_hi:[1,1]
	v_pk_mul_f32 v[126:127], v[126:127], v[192:193] op_sel_hi:[1,0]
	v_pk_mul_f32 v[128:129], v[128:129], v[192:193] op_sel_hi:[1,0]
	v_pk_mul_f32 v[28:29], v[28:29], v[192:193] op_sel_hi:[1,0]
	v_pk_mul_f32 v[30:31], v[30:31], v[192:193] op_sel_hi:[1,0]
	v_pk_mul_f32 v[118:119], v[118:119], v[192:193] op_sel_hi:[1,0]
	v_pk_mul_f32 v[120:121], v[120:121], v[192:193] op_sel_hi:[1,0]
	v_pk_mul_f32 v[16:17], v[16:17], v[192:193] op_sel_hi:[1,0]
	v_pk_mul_f32 v[18:19], v[18:19], v[192:193] op_sel_hi:[1,0]
	v_pk_mul_f32 v[122:123], v[122:123], v[192:193] op_sel:[0,1] op_sel_hi:[1,1]
	v_pk_mul_f32 v[124:125], v[124:125], v[192:193] op_sel:[0,1] op_sel_hi:[1,1]
	v_pk_mul_f32 v[24:25], v[24:25], v[192:193] op_sel:[0,1] op_sel_hi:[1,1]
	v_pk_mul_f32 v[26:27], v[26:27], v[192:193] op_sel:[0,1] op_sel_hi:[1,1]
	v_pk_mul_f32 v[110:111], v[110:111], v[192:193] op_sel:[0,1] op_sel_hi:[1,1]
	v_pk_mul_f32 v[112:113], v[112:113], v[192:193] op_sel:[0,1] op_sel_hi:[1,1]
	v_pk_mul_f32 v[12:13], v[12:13], v[192:193] op_sel:[0,1] op_sel_hi:[1,1]
	v_pk_mul_f32 v[14:15], v[14:15], v[192:193] op_sel:[0,1] op_sel_hi:[1,1]
	v_pk_mul_f32 v[114:115], v[114:115], v[194:195] op_sel_hi:[1,0]
	v_pk_mul_f32 v[116:117], v[116:117], v[194:195] op_sel_hi:[1,0]
	v_pk_mul_f32 v[20:21], v[20:21], v[194:195] op_sel_hi:[1,0]
	v_pk_mul_f32 v[22:23], v[22:23], v[194:195] op_sel_hi:[1,0]
	v_pk_mul_f32 v[68:69], v[68:69], v[194:195] op_sel_hi:[1,0]
	v_pk_mul_f32 v[70:71], v[70:71], v[194:195] op_sel_hi:[1,0]
	v_pk_mul_f32 v[8:9], v[8:9], v[194:195] op_sel_hi:[1,0]
	v_pk_mul_f32 v[10:11], v[10:11], v[194:195] op_sel_hi:[1,0]
	v_pk_mul_f32 v[72:73], v[72:73], v[194:195] op_sel:[0,1] op_sel_hi:[1,1]
	v_pk_mul_f32 v[74:75], v[74:75], v[194:195] op_sel:[0,1] op_sel_hi:[1,1]
	v_pk_mul_f32 v[4:5], v[4:5], v[194:195] op_sel:[0,1] op_sel_hi:[1,1]
	v_pk_mul_f32 v[6:7], v[6:7], v[194:195] op_sel:[0,1] op_sel_hi:[1,1]
	v_pk_mul_f32 v[64:65], v[64:65], v[194:195] op_sel:[0,1] op_sel_hi:[1,1]
	v_pk_mul_f32 v[66:67], v[66:67], v[194:195] op_sel:[0,1] op_sel_hi:[1,1]
	v_pk_mul_f32 v[0:1], v[0:1], v[194:195] op_sel:[0,1] op_sel_hi:[1,1]
	v_pk_mul_f32 v[2:3], v[2:3], v[194:195] op_sel:[0,1] op_sel_hi:[1,1]
	v_cmp_gt_u32_e32 vcc, 2, v163
	s_nop 1
	s_mov_b64 exec, vcc
	v_add_u32_e32 v213, 0x5800, v217
	global_store_dwordx4 v217, v[158:161], s[70:71]
	global_store_dwordx4 v213, v[154:157], s[70:71]
	global_store_dwordx4 v217, v[60:63], s[70:71] offset:16
	global_store_dwordx4 v213, v[56:59], s[70:71] offset:16
	s_mov_b64 exec, s[10:11]
	v_add_u32_e32 v213, 0xfff7c000, v217
	global_store_dwordx4 v213, v[72:75], s[70:71]
	global_store_dwordx4 v213, v[4:7], s[70:71] offset:16
	v_add_u32_e32 v213, 0xfff81800, v217
	global_store_dwordx4 v213, v[64:67], s[70:71]
	global_store_dwordx4 v213, v[0:3], s[70:71] offset:16
	s_mov_b64 exec, -1
	v_cmp_lt_u32_e32 vcc, 1, v163
	s_cmp_lg_u64 s[6:7], 0
	s_cselect_b32 s8, s0, s36
	s_cselect_b32 s10, s1, s34
	s_lshl_b32 s8, s8, 8
	s_add_i32 s8, s8, s58
	s_lshl_b32 s10, s10, 7
	s_add_i32 s10, s10, s53
	v_and_b32_e32 v213, 63, v222
	v_add_u32_e32 v188, s8, v213
	v_lshlrev_b32_e32 v188, 2, v188
	s_mov_b32 m0, s9
	v_add_u32_e32 v189, 0x100, v188
	global_load_lds_dword v188, s[4:5]
	s_add_i32 m0, s9, 0x100
	v_and_b32_e32 v190, 7, v213
	global_load_lds_dword v189, s[4:5]
	v_lshrrev_b32_e32 v191, 3, v213
	v_lshlrev_b32_e32 v190, 4, v190
	s_lshl_b32 s10, s10, 2
	v_add_u32_e32 v190, s10, v190
	v_lshrrev_b32_e32 v192, 2, v191
	v_and_b32_e32 v191, 3, v191
	v_mul_u32_u24_e32 v192, 0x5800, v192
	v_add_u32_e32 v190, v190, v192
	v_mul_u32_u24_e32 v192, 0xb000, v191
	v_add_u32_e32 v192, v192, v190
	v_add_u32_e32 v192, 0x21000, v192
	v_add_u32_e32 v190, 0xb000, v190
	s_add_i32 m0, s9, 0x200
	s_mov_b32 s10, 0xff000000
	s_mov_b32 s11, 0xff000000
	s_andn2_b64 exec, exec, s[10:11]
	global_load_lds_dwordx4 v192, s[82:83]
	s_mov_b64 exec, s[10:11]
	global_load_lds_dwordx4 v190, s[84:85]
	s_mov_b64 exec, -1
	ds_read_b128 v[204:207], v109 offset:784
	ds_read_b128 v[208:211], v109 offset:912
	s_waitcnt lgkmcnt(0)
	v_pk_fma_f32 v[188:189], v[158:159], v[84:85], v[88:89]
	v_pk_fma_f32 v[190:191], v[160:161], v[86:87], v[90:91]
	v_pk_fma_f32 v[192:193], v[154:155], v[100:101], v[104:105]
	v_pk_fma_f32 v[194:195], v[156:157], v[102:103], v[106:107]
	v_fmac_f32_dpp v188, v158, v80 row_shr:1 row_mask:0xf bank_mask:0xf
	v_fmac_f32_dpp v189, v159, v81 row_shr:1 row_mask:0xf bank_mask:0xf
	v_fmac_f32_dpp v190, v160, v82 row_shr:1 row_mask:0xf bank_mask:0xf
	v_fmac_f32_dpp v191, v161, v83 row_shr:1 row_mask:0xf bank_mask:0xf
	v_fmac_f32_dpp v192, v154, v96 row_shr:1 row_mask:0xf bank_mask:0xf
	v_fmac_f32_dpp v193, v155, v97 row_shr:1 row_mask:0xf bank_mask:0xf
	v_fmac_f32_dpp v194, v156, v98 row_shr:1 row_mask:0xf bank_mask:0xf
	v_fmac_f32_dpp v195, v157, v99 row_shr:1 row_mask:0xf bank_mask:0xf
	v_fmac_f32_dpp v188, v158, v76 row_shr:2 row_mask:0xf bank_mask:0xf
	v_fmac_f32_dpp v189, v159, v77 row_shr:2 row_mask:0xf bank_mask:0xf
	v_fmac_f32_dpp v190, v160, v78 row_shr:2 row_mask:0xf bank_mask:0xf
	v_fmac_f32_dpp v191, v161, v79 row_shr:2 row_mask:0xf bank_mask:0xf
	v_fmac_f32_dpp v192, v154, v92 row_shr:2 row_mask:0xf bank_mask:0xf
	v_fmac_f32_dpp v193, v155, v93 row_shr:2 row_mask:0xf bank_mask:0xf
	v_fmac_f32_dpp v194, v156, v94 row_shr:2 row_mask:0xf bank_mask:0xf
	v_fmac_f32_dpp v195, v157, v95 row_shr:2 row_mask:0xf bank_mask:0xf
	v_pk_mul_f32 v[196:197], v[188:189], v[216:217] op_sel_hi:[1,0]
	v_pk_mul_f32 v[198:199], v[190:191], v[216:217] op_sel_hi:[1,0]
	v_exp_f32_e32 v196, v196
	v_exp_f32_e32 v197, v197
	v_exp_f32_e32 v198, v198
	v_exp_f32_e32 v199, v199
	v_pk_add_f32 v[196:197], v[196:197], v[214:215] op_sel_hi:[1,0]
	v_pk_add_f32 v[198:199], v[198:199], v[214:215] op_sel_hi:[1,0]
	v_rcp_f32_e32 v196, v196
	v_rcp_f32_e32 v197, v197
	v_rcp_f32_e32 v198, v198
	v_rcp_f32_e32 v199, v199
	v_pk_mul_f32 v[188:189], v[188:189], v[196:197]
	v_pk_mul_f32 v[190:191], v[190:191], v[198:199]
	v_pk_mul_f32 v[188:189], v[188:189], v[192:193]
	v_pk_mul_f32 v[190:191], v[190:191], v[194:195]
	v_cvt_pk_bf16_f32 v200, v188, v189
	v_cvt_pk_bf16_f32 v201, v190, v191
	v_pk_fma_f32 v[188:189], v[150:151], v[84:85], v[88:89]
	v_pk_fma_f32 v[190:191], v[152:153], v[86:87], v[90:91]
	v_pk_fma_f32 v[192:193], v[142:143], v[100:101], v[104:105]
	v_pk_fma_f32 v[194:195], v[144:145], v[102:103], v[106:107]
	v_fmac_f32_dpp v188, v150, v80 row_shr:1 row_mask:0xf bank_mask:0xf
	v_fmac_f32_dpp v189, v151, v81 row_shr:1 row_mask:0xf bank_mask:0xf
	v_fmac_f32_dpp v190, v152, v82 row_shr:1 row_mask:0xf bank_mask:0xf
	v_fmac_f32_dpp v191, v153, v83 row_shr:1 row_mask:0xf bank_mask:0xf
	v_fmac_f32_dpp v192, v142, v96 row_shr:1 row_mask:0xf bank_mask:0xf
	v_fmac_f32_dpp v193, v143, v97 row_shr:1 row_mask:0xf bank_mask:0xf
	v_fmac_f32_dpp v194, v144, v98 row_shr:1 row_mask:0xf bank_mask:0xf
	v_fmac_f32_dpp v195, v145, v99 row_shr:1 row_mask:0xf bank_mask:0xf
	v_fmac_f32_dpp v188, v150, v76 row_shr:2 row_mask:0xf bank_mask:0xf
	v_fmac_f32_dpp v189, v151, v77 row_shr:2 row_mask:0xf bank_mask:0xf
	v_fmac_f32_dpp v190, v152, v78 row_shr:2 row_mask:0xf bank_mask:0xf
	v_fmac_f32_dpp v191, v153, v79 row_shr:2 row_mask:0xf bank_mask:0xf
	v_fmac_f32_dpp v192, v142, v92 row_shr:2 row_mask:0xf bank_mask:0xf
	v_fmac_f32_dpp v193, v143, v93 row_shr:2 row_mask:0xf bank_mask:0xf
	v_fmac_f32_dpp v194, v144, v94 row_shr:2 row_mask:0xf bank_mask:0xf
	v_fmac_f32_dpp v195, v145, v95 row_shr:2 row_mask:0xf bank_mask:0xf
	v_fmac_f32_dpp v188, v158, v80 row_shl:15 row_mask:0xf bank_mask:0xf
	v_fmac_f32_dpp v189, v159, v81 row_shl:15 row_mask:0xf bank_mask:0xf
	v_fmac_f32_dpp v190, v160, v82 row_shl:15 row_mask:0xf bank_mask:0xf
	v_fmac_f32_dpp v191, v161, v83 row_shl:15 row_mask:0xf bank_mask:0xf
	v_fmac_f32_dpp v192, v154, v96 row_shl:15 row_mask:0xf bank_mask:0xf
	v_fmac_f32_dpp v193, v155, v97 row_shl:15 row_mask:0xf bank_mask:0xf
	v_fmac_f32_dpp v194, v156, v98 row_shl:15 row_mask:0xf bank_mask:0xf
	v_fmac_f32_dpp v195, v157, v99 row_shl:15 row_mask:0xf bank_mask:0xf
	v_fmac_f32_dpp v188, v158, v76 row_shl:14 row_mask:0xf bank_mask:0xf
	v_fmac_f32_dpp v189, v159, v77 row_shl:14 row_mask:0xf bank_mask:0xf
	v_fmac_f32_dpp v190, v160, v78 row_shl:14 row_mask:0xf bank_mask:0xf
	v_fmac_f32_dpp v191, v161, v79 row_shl:14 row_mask:0xf bank_mask:0xf
	v_fmac_f32_dpp v192, v154, v92 row_shl:14 row_mask:0xf bank_mask:0xf
	v_fmac_f32_dpp v193, v155, v93 row_shl:14 row_mask:0xf bank_mask:0xf
	v_fmac_f32_dpp v194, v156, v94 row_shl:14 row_mask:0xf bank_mask:0xf
	v_fmac_f32_dpp v195, v157, v95 row_shl:14 row_mask:0xf bank_mask:0xf
	v_pk_mul_f32 v[196:197], v[188:189], v[216:217] op_sel_hi:[1,0]
	v_pk_mul_f32 v[198:199], v[190:191], v[216:217] op_sel_hi:[1,0]
	v_exp_f32_e32 v196, v196
	v_exp_f32_e32 v197, v197
	v_exp_f32_e32 v198, v198
	v_exp_f32_e32 v199, v199
	v_pk_add_f32 v[196:197], v[196:197], v[214:215] op_sel_hi:[1,0]
	v_pk_add_f32 v[198:199], v[198:199], v[214:215] op_sel_hi:[1,0]
	v_rcp_f32_e32 v196, v196
	v_rcp_f32_e32 v197, v197
	v_rcp_f32_e32 v198, v198
	v_rcp_f32_e32 v199, v199
	v_pk_mul_f32 v[188:189], v[188:189], v[196:197]
	v_pk_mul_f32 v[190:191], v[190:191], v[198:199]
	v_pk_mul_f32 v[188:189], v[188:189], v[192:193]
	v_pk_mul_f32 v[190:191], v[190:191], v[194:195]
	v_cvt_pk_bf16_f32 v158, v188, v189
	v_cvt_pk_bf16_f32 v159, v190, v191
	ds_read_b128 v[154:157], v109 offset:16
	v_pk_fma_f32 v[188:189], v[146:147], v[84:85], v[88:89]
	v_pk_fma_f32 v[190:191], v[148:149], v[86:87], v[90:91]
	v_pk_fma_f32 v[192:193], v[134:135], v[100:101], v[104:105]
	v_pk_fma_f32 v[194:195], v[136:137], v[102:103], v[106:107]
	v_fmac_f32_dpp v188, v146, v80 row_shr:1 row_mask:0xf bank_mask:0xf
	v_fmac_f32_dpp v189, v147, v81 row_shr:1 row_mask:0xf bank_mask:0xf
	v_fmac_f32_dpp v190, v148, v82 row_shr:1 row_mask:0xf bank_mask:0xf
	v_fmac_f32_dpp v191, v149, v83 row_shr:1 row_mask:0xf bank_mask:0xf
	v_fmac_f32_dpp v192, v134, v96 row_shr:1 row_mask:0xf bank_mask:0xf
	v_fmac_f32_dpp v193, v135, v97 row_shr:1 row_mask:0xf bank_mask:0xf
	v_fmac_f32_dpp v194, v136, v98 row_shr:1 row_mask:0xf bank_mask:0xf
	v_fmac_f32_dpp v195, v137, v99 row_shr:1 row_mask:0xf bank_mask:0xf
	v_fmac_f32_dpp v188, v146, v76 row_shr:2 row_mask:0xf bank_mask:0xf
	v_fmac_f32_dpp v189, v147, v77 row_shr:2 row_mask:0xf bank_mask:0xf
	v_fmac_f32_dpp v190, v148, v78 row_shr:2 row_mask:0xf bank_mask:0xf
	v_fmac_f32_dpp v191, v149, v79 row_shr:2 row_mask:0xf bank_mask:0xf
	v_fmac_f32_dpp v192, v134, v92 row_shr:2 row_mask:0xf bank_mask:0xf
	v_fmac_f32_dpp v193, v135, v93 row_shr:2 row_mask:0xf bank_mask:0xf
	v_fmac_f32_dpp v194, v136, v94 row_shr:2 row_mask:0xf bank_mask:0xf
	v_fmac_f32_dpp v195, v137, v95 row_shr:2 row_mask:0xf bank_mask:0xf
	v_fmac_f32_dpp v188, v150, v80 row_shl:15 row_mask:0xf bank_mask:0xf
	v_fmac_f32_dpp v189, v151, v81 row_shl:15 row_mask:0xf bank_mask:0xf
	v_fmac_f32_dpp v190, v152, v82 row_shl:15 row_mask:0xf bank_mask:0xf
	v_fmac_f32_dpp v191, v153, v83 row_shl:15 row_mask:0xf bank_mask:0xf
	v_fmac_f32_dpp v192, v142, v96 row_shl:15 row_mask:0xf bank_mask:0xf
	v_fmac_f32_dpp v193, v143, v97 row_shl:15 row_mask:0xf bank_mask:0xf
	v_fmac_f32_dpp v194, v144, v98 row_shl:15 row_mask:0xf bank_mask:0xf
	v_fmac_f32_dpp v195, v145, v99 row_shl:15 row_mask:0xf bank_mask:0xf
	v_fmac_f32_dpp v188, v150, v76 row_shl:14 row_mask:0xf bank_mask:0xf
	v_fmac_f32_dpp v189, v151, v77 row_shl:14 row_mask:0xf bank_mask:0xf
	v_fmac_f32_dpp v190, v152, v78 row_shl:14 row_mask:0xf bank_mask:0xf
	v_fmac_f32_dpp v191, v153, v79 row_shl:14 row_mask:0xf bank_mask:0xf
	v_fmac_f32_dpp v192, v142, v92 row_shl:14 row_mask:0xf bank_mask:0xf
	v_fmac_f32_dpp v193, v143, v93 row_shl:14 row_mask:0xf bank_mask:0xf
	v_fmac_f32_dpp v194, v144, v94 row_shl:14 row_mask:0xf bank_mask:0xf
	v_fmac_f32_dpp v195, v145, v95 row_shl:14 row_mask:0xf bank_mask:0xf
	v_pk_mul_f32 v[196:197], v[188:189], v[216:217] op_sel_hi:[1,0]
	v_pk_mul_f32 v[198:199], v[190:191], v[216:217] op_sel_hi:[1,0]
	v_exp_f32_e32 v196, v196
	v_exp_f32_e32 v197, v197
	v_exp_f32_e32 v198, v198
	v_exp_f32_e32 v199, v199
	v_pk_add_f32 v[196:197], v[196:197], v[214:215] op_sel_hi:[1,0]
	v_pk_add_f32 v[198:199], v[198:199], v[214:215] op_sel_hi:[1,0]
	v_rcp_f32_e32 v196, v196
	v_rcp_f32_e32 v197, v197
	v_rcp_f32_e32 v198, v198
	v_rcp_f32_e32 v199, v199
	v_pk_mul_f32 v[188:189], v[188:189], v[196:197]
	v_pk_mul_f32 v[190:191], v[190:191], v[198:199]
	v_pk_mul_f32 v[188:189], v[188:189], v[192:193]
	v_pk_mul_f32 v[190:191], v[190:191], v[194:195]
	v_cvt_pk_bf16_f32 v150, v188, v189
	v_cvt_pk_bf16_f32 v151, v190, v191
	ds_read_b128 v[142:145], v109 offset:144
	v_pk_fma_f32 v[188:189], v[138:139], v[84:85], v[88:89]
	v_pk_fma_f32 v[190:191], v[140:141], v[86:87], v[90:91]
	v_pk_fma_f32 v[192:193], v[130:131], v[100:101], v[104:105]
	v_pk_fma_f32 v[194:195], v[132:133], v[102:103], v[106:107]
	v_fmac_f32_dpp v188, v138, v80 row_shr:1 row_mask:0xf bank_mask:0xf
	v_fmac_f32_dpp v189, v139, v81 row_shr:1 row_mask:0xf bank_mask:0xf
	v_fmac_f32_dpp v190, v140, v82 row_shr:1 row_mask:0xf bank_mask:0xf
	v_fmac_f32_dpp v191, v141, v83 row_shr:1 row_mask:0xf bank_mask:0xf
	v_fmac_f32_dpp v192, v130, v96 row_shr:1 row_mask:0xf bank_mask:0xf
	v_fmac_f32_dpp v193, v131, v97 row_shr:1 row_mask:0xf bank_mask:0xf
	v_fmac_f32_dpp v194, v132, v98 row_shr:1 row_mask:0xf bank_mask:0xf
	v_fmac_f32_dpp v195, v133, v99 row_shr:1 row_mask:0xf bank_mask:0xf
	v_fmac_f32_dpp v188, v138, v76 row_shr:2 row_mask:0xf bank_mask:0xf
	v_fmac_f32_dpp v189, v139, v77 row_shr:2 row_mask:0xf bank_mask:0xf
	v_fmac_f32_dpp v190, v140, v78 row_shr:2 row_mask:0xf bank_mask:0xf
	v_fmac_f32_dpp v191, v141, v79 row_shr:2 row_mask:0xf bank_mask:0xf
	v_fmac_f32_dpp v192, v130, v92 row_shr:2 row_mask:0xf bank_mask:0xf
	v_fmac_f32_dpp v193, v131, v93 row_shr:2 row_mask:0xf bank_mask:0xf
	v_fmac_f32_dpp v194, v132, v94 row_shr:2 row_mask:0xf bank_mask:0xf
	v_fmac_f32_dpp v195, v133, v95 row_shr:2 row_mask:0xf bank_mask:0xf
	v_fmac_f32_dpp v188, v146, v80 row_shl:15 row_mask:0xf bank_mask:0xf
	v_fmac_f32_dpp v189, v147, v81 row_shl:15 row_mask:0xf bank_mask:0xf
	v_fmac_f32_dpp v190, v148, v82 row_shl:15 row_mask:0xf bank_mask:0xf
	v_fmac_f32_dpp v191, v149, v83 row_shl:15 row_mask:0xf bank_mask:0xf
	v_fmac_f32_dpp v192, v134, v96 row_shl:15 row_mask:0xf bank_mask:0xf
	v_fmac_f32_dpp v193, v135, v97 row_shl:15 row_mask:0xf bank_mask:0xf
	v_fmac_f32_dpp v194, v136, v98 row_shl:15 row_mask:0xf bank_mask:0xf
	v_fmac_f32_dpp v195, v137, v99 row_shl:15 row_mask:0xf bank_mask:0xf
	v_fmac_f32_dpp v188, v146, v76 row_shl:14 row_mask:0xf bank_mask:0xf
	v_fmac_f32_dpp v189, v147, v77 row_shl:14 row_mask:0xf bank_mask:0xf
	v_fmac_f32_dpp v190, v148, v78 row_shl:14 row_mask:0xf bank_mask:0xf
	v_fmac_f32_dpp v191, v149, v79 row_shl:14 row_mask:0xf bank_mask:0xf
	v_fmac_f32_dpp v192, v134, v92 row_shl:14 row_mask:0xf bank_mask:0xf
	v_fmac_f32_dpp v193, v135, v93 row_shl:14 row_mask:0xf bank_mask:0xf
	v_fmac_f32_dpp v194, v136, v94 row_shl:14 row_mask:0xf bank_mask:0xf
	v_fmac_f32_dpp v195, v137, v95 row_shl:14 row_mask:0xf bank_mask:0xf
	v_pk_mul_f32 v[196:197], v[188:189], v[216:217] op_sel_hi:[1,0]
	v_pk_mul_f32 v[198:199], v[190:191], v[216:217] op_sel_hi:[1,0]
	v_exp_f32_e32 v196, v196
	v_exp_f32_e32 v197, v197
	v_exp_f32_e32 v198, v198
	v_exp_f32_e32 v199, v199
	v_pk_add_f32 v[196:197], v[196:197], v[214:215] op_sel_hi:[1,0]
	v_pk_add_f32 v[198:199], v[198:199], v[214:215] op_sel_hi:[1,0]
	v_rcp_f32_e32 v196, v196
	v_rcp_f32_e32 v197, v197
	v_rcp_f32_e32 v198, v198
	v_rcp_f32_e32 v199, v199
	v_pk_mul_f32 v[188:189], v[188:189], v[196:197]
	v_pk_mul_f32 v[190:191], v[190:191], v[198:199]
	v_pk_mul_f32 v[188:189], v[188:189], v[192:193]
	v_pk_mul_f32 v[190:191], v[190:191], v[194:195]
	v_cvt_pk_bf16_f32 v146, v188, v189
	v_cvt_pk_bf16_f32 v147, v190, v191
	ds_read_b128 v[134:137], v109 offset:272
	v_pk_fma_f32 v[188:189], v[126:127], v[84:85], v[88:89]
	v_pk_fma_f32 v[190:191], v[128:129], v[86:87], v[90:91]
	v_pk_fma_f32 v[192:193], v[118:119], v[100:101], v[104:105]
	v_pk_fma_f32 v[194:195], v[120:121], v[102:103], v[106:107]
	v_fmac_f32_dpp v188, v126, v80 row_shr:1 row_mask:0xf bank_mask:0xf
	v_fmac_f32_dpp v189, v127, v81 row_shr:1 row_mask:0xf bank_mask:0xf
	v_fmac_f32_dpp v190, v128, v82 row_shr:1 row_mask:0xf bank_mask:0xf
	v_fmac_f32_dpp v191, v129, v83 row_shr:1 row_mask:0xf bank_mask:0xf
	v_fmac_f32_dpp v192, v118, v96 row_shr:1 row_mask:0xf bank_mask:0xf
	v_fmac_f32_dpp v193, v119, v97 row_shr:1 row_mask:0xf bank_mask:0xf
	v_fmac_f32_dpp v194, v120, v98 row_shr:1 row_mask:0xf bank_mask:0xf
	v_fmac_f32_dpp v195, v121, v99 row_shr:1 row_mask:0xf bank_mask:0xf
	v_fmac_f32_dpp v188, v126, v76 row_shr:2 row_mask:0xf bank_mask:0xf
	v_fmac_f32_dpp v189, v127, v77 row_shr:2 row_mask:0xf bank_mask:0xf
	v_fmac_f32_dpp v190, v128, v78 row_shr:2 row_mask:0xf bank_mask:0xf
	v_fmac_f32_dpp v191, v129, v79 row_shr:2 row_mask:0xf bank_mask:0xf
	v_fmac_f32_dpp v192, v118, v92 row_shr:2 row_mask:0xf bank_mask:0xf
	v_fmac_f32_dpp v193, v119, v93 row_shr:2 row_mask:0xf bank_mask:0xf
	v_fmac_f32_dpp v194, v120, v94 row_shr:2 row_mask:0xf bank_mask:0xf
	v_fmac_f32_dpp v195, v121, v95 row_shr:2 row_mask:0xf bank_mask:0xf
	v_fmac_f32_dpp v188, v138, v80 row_shl:15 row_mask:0xf bank_mask:0xf
	v_fmac_f32_dpp v189, v139, v81 row_shl:15 row_mask:0xf bank_mask:0xf
	v_fmac_f32_dpp v190, v140, v82 row_shl:15 row_mask:0xf bank_mask:0xf
	v_fmac_f32_dpp v191, v141, v83 row_shl:15 row_mask:0xf bank_mask:0xf
	v_fmac_f32_dpp v192, v130, v96 row_shl:15 row_mask:0xf bank_mask:0xf
	v_fmac_f32_dpp v193, v131, v97 row_shl:15 row_mask:0xf bank_mask:0xf
	v_fmac_f32_dpp v194, v132, v98 row_shl:15 row_mask:0xf bank_mask:0xf
	v_fmac_f32_dpp v195, v133, v99 row_shl:15 row_mask:0xf bank_mask:0xf
	v_fmac_f32_dpp v188, v138, v76 row_shl:14 row_mask:0xf bank_mask:0xf
	v_fmac_f32_dpp v189, v139, v77 row_shl:14 row_mask:0xf bank_mask:0xf
	v_fmac_f32_dpp v190, v140, v78 row_shl:14 row_mask:0xf bank_mask:0xf
	v_fmac_f32_dpp v191, v141, v79 row_shl:14 row_mask:0xf bank_mask:0xf
	v_fmac_f32_dpp v192, v130, v92 row_shl:14 row_mask:0xf bank_mask:0xf
	v_fmac_f32_dpp v193, v131, v93 row_shl:14 row_mask:0xf bank_mask:0xf
	v_fmac_f32_dpp v194, v132, v94 row_shl:14 row_mask:0xf bank_mask:0xf
	v_fmac_f32_dpp v195, v133, v95 row_shl:14 row_mask:0xf bank_mask:0xf
	v_pk_mul_f32 v[196:197], v[188:189], v[216:217] op_sel_hi:[1,0]
	v_pk_mul_f32 v[198:199], v[190:191], v[216:217] op_sel_hi:[1,0]
	v_exp_f32_e32 v196, v196
	v_exp_f32_e32 v197, v197
	v_exp_f32_e32 v198, v198
	v_exp_f32_e32 v199, v199
	v_pk_add_f32 v[196:197], v[196:197], v[214:215] op_sel_hi:[1,0]
	v_pk_add_f32 v[198:199], v[198:199], v[214:215] op_sel_hi:[1,0]
	v_rcp_f32_e32 v196, v196
	v_rcp_f32_e32 v197, v197
	v_rcp_f32_e32 v198, v198
	v_rcp_f32_e32 v199, v199
	v_pk_mul_f32 v[188:189], v[188:189], v[196:197]
	v_pk_mul_f32 v[190:191], v[190:191], v[198:199]
	v_pk_mul_f32 v[188:189], v[188:189], v[192:193]
	v_pk_mul_f32 v[190:191], v[190:191], v[194:195]
	v_cvt_pk_bf16_f32 v138, v188, v189
	v_cvt_pk_bf16_f32 v139, v190, v191
	ds_read_b128 v[130:133], v109 offset:400
	v_pk_fma_f32 v[188:189], v[122:123], v[84:85], v[88:89]
	v_pk_fma_f32 v[190:191], v[124:125], v[86:87], v[90:91]
	v_pk_fma_f32 v[192:193], v[110:111], v[100:101], v[104:105]
	v_pk_fma_f32 v[194:195], v[112:113], v[102:103], v[106:107]
	v_fmac_f32_dpp v188, v122, v80 row_shr:1 row_mask:0xf bank_mask:0xf
	v_fmac_f32_dpp v189, v123, v81 row_shr:1 row_mask:0xf bank_mask:0xf
	v_fmac_f32_dpp v190, v124, v82 row_shr:1 row_mask:0xf bank_mask:0xf
	v_fmac_f32_dpp v191, v125, v83 row_shr:1 row_mask:0xf bank_mask:0xf
	v_fmac_f32_dpp v192, v110, v96 row_shr:1 row_mask:0xf bank_mask:0xf
	v_fmac_f32_dpp v193, v111, v97 row_shr:1 row_mask:0xf bank_mask:0xf
	v_fmac_f32_dpp v194, v112, v98 row_shr:1 row_mask:0xf bank_mask:0xf
	v_fmac_f32_dpp v195, v113, v99 row_shr:1 row_mask:0xf bank_mask:0xf
	v_fmac_f32_dpp v188, v122, v76 row_shr:2 row_mask:0xf bank_mask:0xf
	v_fmac_f32_dpp v189, v123, v77 row_shr:2 row_mask:0xf bank_mask:0xf
	v_fmac_f32_dpp v190, v124, v78 row_shr:2 row_mask:0xf bank_mask:0xf
	v_fmac_f32_dpp v191, v125, v79 row_shr:2 row_mask:0xf bank_mask:0xf
	v_fmac_f32_dpp v192, v110, v92 row_shr:2 row_mask:0xf bank_mask:0xf
	v_fmac_f32_dpp v193, v111, v93 row_shr:2 row_mask:0xf bank_mask:0xf
	v_fmac_f32_dpp v194, v112, v94 row_shr:2 row_mask:0xf bank_mask:0xf
	v_fmac_f32_dpp v195, v113, v95 row_shr:2 row_mask:0xf bank_mask:0xf
	v_fmac_f32_dpp v188, v126, v80 row_shl:15 row_mask:0xf bank_mask:0xf
	v_fmac_f32_dpp v189, v127, v81 row_shl:15 row_mask:0xf bank_mask:0xf
	v_fmac_f32_dpp v190, v128, v82 row_shl:15 row_mask:0xf bank_mask:0xf
	v_fmac_f32_dpp v191, v129, v83 row_shl:15 row_mask:0xf bank_mask:0xf
	v_fmac_f32_dpp v192, v118, v96 row_shl:15 row_mask:0xf bank_mask:0xf
	v_fmac_f32_dpp v193, v119, v97 row_shl:15 row_mask:0xf bank_mask:0xf
	v_fmac_f32_dpp v194, v120, v98 row_shl:15 row_mask:0xf bank_mask:0xf
	v_fmac_f32_dpp v195, v121, v99 row_shl:15 row_mask:0xf bank_mask:0xf
	v_fmac_f32_dpp v188, v126, v76 row_shl:14 row_mask:0xf bank_mask:0xf
	v_fmac_f32_dpp v189, v127, v77 row_shl:14 row_mask:0xf bank_mask:0xf
	v_fmac_f32_dpp v190, v128, v78 row_shl:14 row_mask:0xf bank_mask:0xf
	v_fmac_f32_dpp v191, v129, v79 row_shl:14 row_mask:0xf bank_mask:0xf
	v_fmac_f32_dpp v192, v118, v92 row_shl:14 row_mask:0xf bank_mask:0xf
	v_fmac_f32_dpp v193, v119, v93 row_shl:14 row_mask:0xf bank_mask:0xf
	v_fmac_f32_dpp v194, v120, v94 row_shl:14 row_mask:0xf bank_mask:0xf
	v_fmac_f32_dpp v195, v121, v95 row_shl:14 row_mask:0xf bank_mask:0xf
	v_pk_mul_f32 v[196:197], v[188:189], v[216:217] op_sel_hi:[1,0]
	v_pk_mul_f32 v[198:199], v[190:191], v[216:217] op_sel_hi:[1,0]
	v_exp_f32_e32 v196, v196
	v_exp_f32_e32 v197, v197
	v_exp_f32_e32 v198, v198
	v_exp_f32_e32 v199, v199
	v_pk_add_f32 v[196:197], v[196:197], v[214:215] op_sel_hi:[1,0]
	v_pk_add_f32 v[198:199], v[198:199], v[214:215] op_sel_hi:[1,0]
	v_rcp_f32_e32 v196, v196
	v_rcp_f32_e32 v197, v197
	v_rcp_f32_e32 v198, v198
	v_rcp_f32_e32 v199, v199
	v_pk_mul_f32 v[188:189], v[188:189], v[196:197]
	v_pk_mul_f32 v[190:191], v[190:191], v[198:199]
	v_pk_mul_f32 v[188:189], v[188:189], v[192:193]
	v_pk_mul_f32 v[190:191], v[190:191], v[194:195]
	v_cvt_pk_bf16_f32 v126, v188, v189
	v_cvt_pk_bf16_f32 v127, v190, v191
	ds_read_b128 v[118:121], v109 offset:528
	v_pk_fma_f32 v[188:189], v[114:115], v[84:85], v[88:89]
	v_pk_fma_f32 v[190:191], v[116:117], v[86:87], v[90:91]
	v_pk_fma_f32 v[192:193], v[68:69], v[100:101], v[104:105]
	v_pk_fma_f32 v[194:195], v[70:71], v[102:103], v[106:107]
	v_fmac_f32_dpp v188, v114, v80 row_shr:1 row_mask:0xf bank_mask:0xf
	v_fmac_f32_dpp v189, v115, v81 row_shr:1 row_mask:0xf bank_mask:0xf
	v_fmac_f32_dpp v190, v116, v82 row_shr:1 row_mask:0xf bank_mask:0xf
	v_fmac_f32_dpp v191, v117, v83 row_shr:1 row_mask:0xf bank_mask:0xf
	v_fmac_f32_dpp v192, v68, v96 row_shr:1 row_mask:0xf bank_mask:0xf
	v_fmac_f32_dpp v193, v69, v97 row_shr:1 row_mask:0xf bank_mask:0xf
	v_fmac_f32_dpp v194, v70, v98 row_shr:1 row_mask:0xf bank_mask:0xf
	v_fmac_f32_dpp v195, v71, v99 row_shr:1 row_mask:0xf bank_mask:0xf
	v_fmac_f32_dpp v188, v114, v76 row_shr:2 row_mask:0xf bank_mask:0xf
	v_fmac_f32_dpp v189, v115, v77 row_shr:2 row_mask:0xf bank_mask:0xf
	v_fmac_f32_dpp v190, v116, v78 row_shr:2 row_mask:0xf bank_mask:0xf
	v_fmac_f32_dpp v191, v117, v79 row_shr:2 row_mask:0xf bank_mask:0xf
	v_fmac_f32_dpp v192, v68, v92 row_shr:2 row_mask:0xf bank_mask:0xf
	v_fmac_f32_dpp v193, v69, v93 row_shr:2 row_mask:0xf bank_mask:0xf
	v_fmac_f32_dpp v194, v70, v94 row_shr:2 row_mask:0xf bank_mask:0xf
	v_fmac_f32_dpp v195, v71, v95 row_shr:2 row_mask:0xf bank_mask:0xf
	v_fmac_f32_dpp v188, v122, v80 row_shl:15 row_mask:0xf bank_mask:0xf
	v_fmac_f32_dpp v189, v123, v81 row_shl:15 row_mask:0xf bank_mask:0xf
	v_fmac_f32_dpp v190, v124, v82 row_shl:15 row_mask:0xf bank_mask:0xf
	v_fmac_f32_dpp v191, v125, v83 row_shl:15 row_mask:0xf bank_mask:0xf
	v_fmac_f32_dpp v192, v110, v96 row_shl:15 row_mask:0xf bank_mask:0xf
	v_fmac_f32_dpp v193, v111, v97 row_shl:15 row_mask:0xf bank_mask:0xf
	v_fmac_f32_dpp v194, v112, v98 row_shl:15 row_mask:0xf bank_mask:0xf
	v_fmac_f32_dpp v195, v113, v99 row_shl:15 row_mask:0xf bank_mask:0xf
	v_fmac_f32_dpp v188, v122, v76 row_shl:14 row_mask:0xf bank_mask:0xf
	v_fmac_f32_dpp v189, v123, v77 row_shl:14 row_mask:0xf bank_mask:0xf
	v_fmac_f32_dpp v190, v124, v78 row_shl:14 row_mask:0xf bank_mask:0xf
	v_fmac_f32_dpp v191, v125, v79 row_shl:14 row_mask:0xf bank_mask:0xf
	v_fmac_f32_dpp v192, v110, v92 row_shl:14 row_mask:0xf bank_mask:0xf
	v_fmac_f32_dpp v193, v111, v93 row_shl:14 row_mask:0xf bank_mask:0xf
	v_fmac_f32_dpp v194, v112, v94 row_shl:14 row_mask:0xf bank_mask:0xf
	v_fmac_f32_dpp v195, v113, v95 row_shl:14 row_mask:0xf bank_mask:0xf
	v_pk_mul_f32 v[196:197], v[188:189], v[216:217] op_sel_hi:[1,0]
	v_pk_mul_f32 v[198:199], v[190:191], v[216:217] op_sel_hi:[1,0]
	v_exp_f32_e32 v196, v196
	v_exp_f32_e32 v197, v197
	v_exp_f32_e32 v198, v198
	v_exp_f32_e32 v199, v199
	v_pk_add_f32 v[196:197], v[196:197], v[214:215] op_sel_hi:[1,0]
	v_pk_add_f32 v[198:199], v[198:199], v[214:215] op_sel_hi:[1,0]
	v_rcp_f32_e32 v196, v196
	v_rcp_f32_e32 v197, v197
	v_rcp_f32_e32 v198, v198
	v_rcp_f32_e32 v199, v199
	v_pk_mul_f32 v[188:189], v[188:189], v[196:197]
	v_pk_mul_f32 v[190:191], v[190:191], v[198:199]
	v_pk_mul_f32 v[188:189], v[188:189], v[192:193]
	v_pk_mul_f32 v[190:191], v[190:191], v[194:195]
	v_cvt_pk_bf16_f32 v122, v188, v189
	v_cvt_pk_bf16_f32 v123, v190, v191
	ds_read_b128 v[110:113], v109 offset:656
	v_pk_fma_f32 v[188:189], v[72:73], v[84:85], v[88:89]
	v_pk_fma_f32 v[190:191], v[74:75], v[86:87], v[90:91]
	v_pk_fma_f32 v[192:193], v[64:65], v[100:101], v[104:105]
	v_pk_fma_f32 v[194:195], v[66:67], v[102:103], v[106:107]
	v_fmac_f32_dpp v188, v72, v80 row_shr:1 row_mask:0xf bank_mask:0xf
	v_fmac_f32_dpp v189, v73, v81 row_shr:1 row_mask:0xf bank_mask:0xf
	v_fmac_f32_dpp v190, v74, v82 row_shr:1 row_mask:0xf bank_mask:0xf
	v_fmac_f32_dpp v191, v75, v83 row_shr:1 row_mask:0xf bank_mask:0xf
	v_fmac_f32_dpp v192, v64, v96 row_shr:1 row_mask:0xf bank_mask:0xf
	v_fmac_f32_dpp v193, v65, v97 row_shr:1 row_mask:0xf bank_mask:0xf
	v_fmac_f32_dpp v194, v66, v98 row_shr:1 row_mask:0xf bank_mask:0xf
	v_fmac_f32_dpp v195, v67, v99 row_shr:1 row_mask:0xf bank_mask:0xf
	v_fmac_f32_dpp v188, v72, v76 row_shr:2 row_mask:0xf bank_mask:0xf
	v_fmac_f32_dpp v189, v73, v77 row_shr:2 row_mask:0xf bank_mask:0xf
	v_fmac_f32_dpp v190, v74, v78 row_shr:2 row_mask:0xf bank_mask:0xf
	v_fmac_f32_dpp v191, v75, v79 row_shr:2 row_mask:0xf bank_mask:0xf
	v_fmac_f32_dpp v192, v64, v92 row_shr:2 row_mask:0xf bank_mask:0xf
	v_fmac_f32_dpp v193, v65, v93 row_shr:2 row_mask:0xf bank_mask:0xf
	v_fmac_f32_dpp v194, v66, v94 row_shr:2 row_mask:0xf bank_mask:0xf
	v_fmac_f32_dpp v195, v67, v95 row_shr:2 row_mask:0xf bank_mask:0xf
	v_fmac_f32_dpp v188, v114, v80 row_shl:15 row_mask:0xf bank_mask:0xf
	v_fmac_f32_dpp v189, v115, v81 row_shl:15 row_mask:0xf bank_mask:0xf
	v_fmac_f32_dpp v190, v116, v82 row_shl:15 row_mask:0xf bank_mask:0xf
	v_fmac_f32_dpp v191, v117, v83 row_shl:15 row_mask:0xf bank_mask:0xf
	v_fmac_f32_dpp v192, v68, v96 row_shl:15 row_mask:0xf bank_mask:0xf
	v_fmac_f32_dpp v193, v69, v97 row_shl:15 row_mask:0xf bank_mask:0xf
	v_fmac_f32_dpp v194, v70, v98 row_shl:15 row_mask:0xf bank_mask:0xf
	v_fmac_f32_dpp v195, v71, v99 row_shl:15 row_mask:0xf bank_mask:0xf
	v_fmac_f32_dpp v188, v114, v76 row_shl:14 row_mask:0xf bank_mask:0xf
	v_fmac_f32_dpp v189, v115, v77 row_shl:14 row_mask:0xf bank_mask:0xf
	v_fmac_f32_dpp v190, v116, v78 row_shl:14 row_mask:0xf bank_mask:0xf
	v_fmac_f32_dpp v191, v117, v79 row_shl:14 row_mask:0xf bank_mask:0xf
	v_fmac_f32_dpp v192, v68, v92 row_shl:14 row_mask:0xf bank_mask:0xf
	v_fmac_f32_dpp v193, v69, v93 row_shl:14 row_mask:0xf bank_mask:0xf
	v_fmac_f32_dpp v194, v70, v94 row_shl:14 row_mask:0xf bank_mask:0xf
	v_fmac_f32_dpp v195, v71, v95 row_shl:14 row_mask:0xf bank_mask:0xf
	v_pk_mul_f32 v[196:197], v[188:189], v[216:217] op_sel_hi:[1,0]
	v_pk_mul_f32 v[198:199], v[190:191], v[216:217] op_sel_hi:[1,0]
	v_exp_f32_e32 v196, v196
	v_exp_f32_e32 v197, v197
	v_exp_f32_e32 v198, v198
	v_exp_f32_e32 v199, v199
	v_pk_add_f32 v[196:197], v[196:197], v[214:215] op_sel_hi:[1,0]
	v_pk_add_f32 v[198:199], v[198:199], v[214:215] op_sel_hi:[1,0]
	v_rcp_f32_e32 v196, v196
	v_rcp_f32_e32 v197, v197
	v_rcp_f32_e32 v198, v198
	v_rcp_f32_e32 v199, v199
	v_pk_mul_f32 v[188:189], v[188:189], v[196:197]
	v_pk_mul_f32 v[190:191], v[190:191], v[198:199]
	v_pk_mul_f32 v[188:189], v[188:189], v[192:193]
	v_pk_mul_f32 v[190:191], v[190:191], v[194:195]
	v_cvt_pk_bf16_f32 v114, v188, v189
	v_cvt_pk_bf16_f32 v115, v190, v191
	s_waitcnt lgkmcnt(0)
	v_pk_fma_f32 v[188:189], v[60:61], v[134:135], v[130:131]
	v_pk_fma_f32 v[190:191], v[62:63], v[136:137], v[132:133]
	v_pk_fma_f32 v[192:193], v[56:57], v[204:205], v[208:209]
	v_pk_fma_f32 v[194:195], v[58:59], v[206:207], v[210:211]
	v_fmac_f32_dpp v188, v60, v142 row_shr:1 row_mask:0xf bank_mask:0xf
	v_fmac_f32_dpp v189, v61, v143 row_shr:1 row_mask:0xf bank_mask:0xf
	v_fmac_f32_dpp v190, v62, v144 row_shr:1 row_mask:0xf bank_mask:0xf
	v_fmac_f32_dpp v191, v63, v145 row_shr:1 row_mask:0xf bank_mask:0xf
	v_fmac_f32_dpp v192, v56, v110 row_shr:1 row_mask:0xf bank_mask:0xf
	v_fmac_f32_dpp v193, v57, v111 row_shr:1 row_mask:0xf bank_mask:0xf
	v_fmac_f32_dpp v194, v58, v112 row_shr:1 row_mask:0xf bank_mask:0xf
	v_fmac_f32_dpp v195, v59, v113 row_shr:1 row_mask:0xf bank_mask:0xf
	v_fmac_f32_dpp v188, v60, v154 row_shr:2 row_mask:0xf bank_mask:0xf
	v_fmac_f32_dpp v189, v61, v155 row_shr:2 row_mask:0xf bank_mask:0xf
	v_fmac_f32_dpp v190, v62, v156 row_shr:2 row_mask:0xf bank_mask:0xf
	v_fmac_f32_dpp v191, v63, v157 row_shr:2 row_mask:0xf bank_mask:0xf
	v_fmac_f32_dpp v192, v56, v118 row_shr:2 row_mask:0xf bank_mask:0xf
	v_fmac_f32_dpp v193, v57, v119 row_shr:2 row_mask:0xf bank_mask:0xf
	v_fmac_f32_dpp v194, v58, v120 row_shr:2 row_mask:0xf bank_mask:0xf
	v_fmac_f32_dpp v195, v59, v121 row_shr:2 row_mask:0xf bank_mask:0xf
	v_pk_mul_f32 v[196:197], v[188:189], v[216:217] op_sel_hi:[1,0]
	v_pk_mul_f32 v[198:199], v[190:191], v[216:217] op_sel_hi:[1,0]
	v_exp_f32_e32 v196, v196
	v_exp_f32_e32 v197, v197
	v_exp_f32_e32 v198, v198
	v_exp_f32_e32 v199, v199
	v_pk_add_f32 v[196:197], v[196:197], v[214:215] op_sel_hi:[1,0]
	v_pk_add_f32 v[198:199], v[198:199], v[214:215] op_sel_hi:[1,0]
	v_rcp_f32_e32 v196, v196
	v_rcp_f32_e32 v197, v197
	v_rcp_f32_e32 v198, v198
	v_rcp_f32_e32 v199, v199
	v_pk_mul_f32 v[188:189], v[188:189], v[196:197]
	v_pk_mul_f32 v[190:191], v[190:191], v[198:199]
	v_pk_mul_f32 v[188:189], v[188:189], v[192:193]
	v_pk_mul_f32 v[190:191], v[190:191], v[194:195]
	v_cvt_pk_bf16_f32 v202, v188, v189
	v_cvt_pk_bf16_f32 v203, v190, v191
	s_mov_b64 exec, vcc
	global_store_dwordx4 v215, v[200:203], s[96:97]
	s_mov_b64 exec, -1
	v_pk_fma_f32 v[188:189], v[52:53], v[134:135], v[130:131]
	v_pk_fma_f32 v[190:191], v[54:55], v[136:137], v[132:133]
	v_pk_fma_f32 v[192:193], v[44:45], v[204:205], v[208:209]
	v_pk_fma_f32 v[194:195], v[46:47], v[206:207], v[210:211]
	v_fmac_f32_dpp v188, v52, v142 row_shr:1 row_mask:0xf bank_mask:0xf
	v_fmac_f32_dpp v189, v53, v143 row_shr:1 row_mask:0xf bank_mask:0xf
	v_fmac_f32_dpp v190, v54, v144 row_shr:1 row_mask:0xf bank_mask:0xf
	v_fmac_f32_dpp v191, v55, v145 row_shr:1 row_mask:0xf bank_mask:0xf
	v_fmac_f32_dpp v192, v44, v110 row_shr:1 row_mask:0xf bank_mask:0xf
	v_fmac_f32_dpp v193, v45, v111 row_shr:1 row_mask:0xf bank_mask:0xf
	v_fmac_f32_dpp v194, v46, v112 row_shr:1 row_mask:0xf bank_mask:0xf
	v_fmac_f32_dpp v195, v47, v113 row_shr:1 row_mask:0xf bank_mask:0xf
	v_fmac_f32_dpp v188, v52, v154 row_shr:2 row_mask:0xf bank_mask:0xf
	v_fmac_f32_dpp v189, v53, v155 row_shr:2 row_mask:0xf bank_mask:0xf
	v_fmac_f32_dpp v190, v54, v156 row_shr:2 row_mask:0xf bank_mask:0xf
	v_fmac_f32_dpp v191, v55, v157 row_shr:2 row_mask:0xf bank_mask:0xf
	v_fmac_f32_dpp v192, v44, v118 row_shr:2 row_mask:0xf bank_mask:0xf
	v_fmac_f32_dpp v193, v45, v119 row_shr:2 row_mask:0xf bank_mask:0xf
	v_fmac_f32_dpp v194, v46, v120 row_shr:2 row_mask:0xf bank_mask:0xf
	v_fmac_f32_dpp v195, v47, v121 row_shr:2 row_mask:0xf bank_mask:0xf
	v_fmac_f32_dpp v188, v60, v142 row_shl:15 row_mask:0xf bank_mask:0xf
	v_fmac_f32_dpp v189, v61, v143 row_shl:15 row_mask:0xf bank_mask:0xf
	v_fmac_f32_dpp v190, v62, v144 row_shl:15 row_mask:0xf bank_mask:0xf
	v_fmac_f32_dpp v191, v63, v145 row_shl:15 row_mask:0xf bank_mask:0xf
	v_fmac_f32_dpp v192, v56, v110 row_shl:15 row_mask:0xf bank_mask:0xf
	v_fmac_f32_dpp v193, v57, v111 row_shl:15 row_mask:0xf bank_mask:0xf
	v_fmac_f32_dpp v194, v58, v112 row_shl:15 row_mask:0xf bank_mask:0xf
	v_fmac_f32_dpp v195, v59, v113 row_shl:15 row_mask:0xf bank_mask:0xf
	v_fmac_f32_dpp v188, v60, v154 row_shl:14 row_mask:0xf bank_mask:0xf
	v_fmac_f32_dpp v189, v61, v155 row_shl:14 row_mask:0xf bank_mask:0xf
	v_fmac_f32_dpp v190, v62, v156 row_shl:14 row_mask:0xf bank_mask:0xf
	v_fmac_f32_dpp v191, v63, v157 row_shl:14 row_mask:0xf bank_mask:0xf
	v_fmac_f32_dpp v192, v56, v118 row_shl:14 row_mask:0xf bank_mask:0xf
	v_fmac_f32_dpp v193, v57, v119 row_shl:14 row_mask:0xf bank_mask:0xf
	v_fmac_f32_dpp v194, v58, v120 row_shl:14 row_mask:0xf bank_mask:0xf
	v_fmac_f32_dpp v195, v59, v121 row_shl:14 row_mask:0xf bank_mask:0xf
	v_pk_mul_f32 v[196:197], v[188:189], v[216:217] op_sel_hi:[1,0]
	v_pk_mul_f32 v[198:199], v[190:191], v[216:217] op_sel_hi:[1,0]
	v_exp_f32_e32 v196, v196
	v_exp_f32_e32 v197, v197
	v_exp_f32_e32 v198, v198
	v_exp_f32_e32 v199, v199
	v_pk_add_f32 v[196:197], v[196:197], v[214:215] op_sel_hi:[1,0]
	v_pk_add_f32 v[198:199], v[198:199], v[214:215] op_sel_hi:[1,0]
	v_rcp_f32_e32 v196, v196
	v_rcp_f32_e32 v197, v197
	v_rcp_f32_e32 v198, v198
	v_rcp_f32_e32 v199, v199
	v_pk_mul_f32 v[188:189], v[188:189], v[196:197]
	v_pk_mul_f32 v[190:191], v[190:191], v[198:199]
	v_pk_mul_f32 v[188:189], v[188:189], v[192:193]
	v_pk_mul_f32 v[190:191], v[190:191], v[194:195]
	v_cvt_pk_bf16_f32 v160, v188, v189
	v_cvt_pk_bf16_f32 v161, v190, v191
	v_add_u32_e32 v213, 0x2c000, v215
	global_store_dwordx4 v213, v[158:161], s[96:97]
	v_pk_fma_f32 v[188:189], v[48:49], v[134:135], v[130:131]
	v_pk_fma_f32 v[190:191], v[50:51], v[136:137], v[132:133]
	v_pk_fma_f32 v[192:193], v[36:37], v[204:205], v[208:209]
	v_pk_fma_f32 v[194:195], v[38:39], v[206:207], v[210:211]
	v_fmac_f32_dpp v188, v48, v142 row_shr:1 row_mask:0xf bank_mask:0xf
	v_fmac_f32_dpp v189, v49, v143 row_shr:1 row_mask:0xf bank_mask:0xf
	v_fmac_f32_dpp v190, v50, v144 row_shr:1 row_mask:0xf bank_mask:0xf
	v_fmac_f32_dpp v191, v51, v145 row_shr:1 row_mask:0xf bank_mask:0xf
	v_fmac_f32_dpp v192, v36, v110 row_shr:1 row_mask:0xf bank_mask:0xf
	v_fmac_f32_dpp v193, v37, v111 row_shr:1 row_mask:0xf bank_mask:0xf
	v_fmac_f32_dpp v194, v38, v112 row_shr:1 row_mask:0xf bank_mask:0xf
	v_fmac_f32_dpp v195, v39, v113 row_shr:1 row_mask:0xf bank_mask:0xf
	v_fmac_f32_dpp v188, v48, v154 row_shr:2 row_mask:0xf bank_mask:0xf
	v_fmac_f32_dpp v189, v49, v155 row_shr:2 row_mask:0xf bank_mask:0xf
	v_fmac_f32_dpp v190, v50, v156 row_shr:2 row_mask:0xf bank_mask:0xf
	v_fmac_f32_dpp v191, v51, v157 row_shr:2 row_mask:0xf bank_mask:0xf
	v_fmac_f32_dpp v192, v36, v118 row_shr:2 row_mask:0xf bank_mask:0xf
	v_fmac_f32_dpp v193, v37, v119 row_shr:2 row_mask:0xf bank_mask:0xf
	v_fmac_f32_dpp v194, v38, v120 row_shr:2 row_mask:0xf bank_mask:0xf
	v_fmac_f32_dpp v195, v39, v121 row_shr:2 row_mask:0xf bank_mask:0xf
	v_fmac_f32_dpp v188, v52, v142 row_shl:15 row_mask:0xf bank_mask:0xf
	v_fmac_f32_dpp v189, v53, v143 row_shl:15 row_mask:0xf bank_mask:0xf
	v_fmac_f32_dpp v190, v54, v144 row_shl:15 row_mask:0xf bank_mask:0xf
	v_fmac_f32_dpp v191, v55, v145 row_shl:15 row_mask:0xf bank_mask:0xf
	v_fmac_f32_dpp v192, v44, v110 row_shl:15 row_mask:0xf bank_mask:0xf
	v_fmac_f32_dpp v193, v45, v111 row_shl:15 row_mask:0xf bank_mask:0xf
	v_fmac_f32_dpp v194, v46, v112 row_shl:15 row_mask:0xf bank_mask:0xf
	v_fmac_f32_dpp v195, v47, v113 row_shl:15 row_mask:0xf bank_mask:0xf
	v_fmac_f32_dpp v188, v52, v154 row_shl:14 row_mask:0xf bank_mask:0xf
	v_fmac_f32_dpp v189, v53, v155 row_shl:14 row_mask:0xf bank_mask:0xf
	v_fmac_f32_dpp v190, v54, v156 row_shl:14 row_mask:0xf bank_mask:0xf
	v_fmac_f32_dpp v191, v55, v157 row_shl:14 row_mask:0xf bank_mask:0xf
	v_fmac_f32_dpp v192, v44, v118 row_shl:14 row_mask:0xf bank_mask:0xf
	v_fmac_f32_dpp v193, v45, v119 row_shl:14 row_mask:0xf bank_mask:0xf
	v_fmac_f32_dpp v194, v46, v120 row_shl:14 row_mask:0xf bank_mask:0xf
	v_fmac_f32_dpp v195, v47, v121 row_shl:14 row_mask:0xf bank_mask:0xf
	v_pk_mul_f32 v[196:197], v[188:189], v[216:217] op_sel_hi:[1,0]
	v_pk_mul_f32 v[198:199], v[190:191], v[216:217] op_sel_hi:[1,0]
	v_exp_f32_e32 v196, v196
	v_exp_f32_e32 v197, v197
	v_exp_f32_e32 v198, v198
	v_exp_f32_e32 v199, v199
	v_pk_add_f32 v[196:197], v[196:197], v[214:215] op_sel_hi:[1,0]
	v_pk_add_f32 v[198:199], v[198:199], v[214:215] op_sel_hi:[1,0]
	v_rcp_f32_e32 v196, v196
	v_rcp_f32_e32 v197, v197
	v_rcp_f32_e32 v198, v198
	v_rcp_f32_e32 v199, v199
	v_pk_mul_f32 v[188:189], v[188:189], v[196:197]
	v_pk_mul_f32 v[190:191], v[190:191], v[198:199]
	v_pk_mul_f32 v[188:189], v[188:189], v[192:193]
	v_pk_mul_f32 v[190:191], v[190:191], v[194:195]
	v_cvt_pk_bf16_f32 v152, v188, v189
	v_cvt_pk_bf16_f32 v153, v190, v191
	v_add_u32_e32 v213, 0x58000, v215
	global_store_dwordx4 v213, v[150:153], s[96:97]
	v_pk_fma_f32 v[188:189], v[40:41], v[134:135], v[130:131]
	v_pk_fma_f32 v[190:191], v[42:43], v[136:137], v[132:133]
	v_pk_fma_f32 v[192:193], v[32:33], v[204:205], v[208:209]
	v_pk_fma_f32 v[194:195], v[34:35], v[206:207], v[210:211]
	v_fmac_f32_dpp v188, v40, v142 row_shr:1 row_mask:0xf bank_mask:0xf
	v_fmac_f32_dpp v189, v41, v143 row_shr:1 row_mask:0xf bank_mask:0xf
	v_fmac_f32_dpp v190, v42, v144 row_shr:1 row_mask:0xf bank_mask:0xf
	v_fmac_f32_dpp v191, v43, v145 row_shr:1 row_mask:0xf bank_mask:0xf
	v_fmac_f32_dpp v192, v32, v110 row_shr:1 row_mask:0xf bank_mask:0xf
	v_fmac_f32_dpp v193, v33, v111 row_shr:1 row_mask:0xf bank_mask:0xf
	v_fmac_f32_dpp v194, v34, v112 row_shr:1 row_mask:0xf bank_mask:0xf
	v_fmac_f32_dpp v195, v35, v113 row_shr:1 row_mask:0xf bank_mask:0xf
	v_fmac_f32_dpp v188, v40, v154 row_shr:2 row_mask:0xf bank_mask:0xf
	v_fmac_f32_dpp v189, v41, v155 row_shr:2 row_mask:0xf bank_mask:0xf
	v_fmac_f32_dpp v190, v42, v156 row_shr:2 row_mask:0xf bank_mask:0xf
	v_fmac_f32_dpp v191, v43, v157 row_shr:2 row_mask:0xf bank_mask:0xf
	v_fmac_f32_dpp v192, v32, v118 row_shr:2 row_mask:0xf bank_mask:0xf
	v_fmac_f32_dpp v193, v33, v119 row_shr:2 row_mask:0xf bank_mask:0xf
	v_fmac_f32_dpp v194, v34, v120 row_shr:2 row_mask:0xf bank_mask:0xf
	v_fmac_f32_dpp v195, v35, v121 row_shr:2 row_mask:0xf bank_mask:0xf
	v_fmac_f32_dpp v188, v48, v142 row_shl:15 row_mask:0xf bank_mask:0xf
	v_fmac_f32_dpp v189, v49, v143 row_shl:15 row_mask:0xf bank_mask:0xf
	v_fmac_f32_dpp v190, v50, v144 row_shl:15 row_mask:0xf bank_mask:0xf
	v_fmac_f32_dpp v191, v51, v145 row_shl:15 row_mask:0xf bank_mask:0xf
	v_fmac_f32_dpp v192, v36, v110 row_shl:15 row_mask:0xf bank_mask:0xf
	v_fmac_f32_dpp v193, v37, v111 row_shl:15 row_mask:0xf bank_mask:0xf
	v_fmac_f32_dpp v194, v38, v112 row_shl:15 row_mask:0xf bank_mask:0xf
	v_fmac_f32_dpp v195, v39, v113 row_shl:15 row_mask:0xf bank_mask:0xf
	v_fmac_f32_dpp v188, v48, v154 row_shl:14 row_mask:0xf bank_mask:0xf
	v_fmac_f32_dpp v189, v49, v155 row_shl:14 row_mask:0xf bank_mask:0xf
	v_fmac_f32_dpp v190, v50, v156 row_shl:14 row_mask:0xf bank_mask:0xf
	v_fmac_f32_dpp v191, v51, v157 row_shl:14 row_mask:0xf bank_mask:0xf
	v_fmac_f32_dpp v192, v36, v118 row_shl:14 row_mask:0xf bank_mask:0xf
	v_fmac_f32_dpp v193, v37, v119 row_shl:14 row_mask:0xf bank_mask:0xf
	v_fmac_f32_dpp v194, v38, v120 row_shl:14 row_mask:0xf bank_mask:0xf
	v_fmac_f32_dpp v195, v39, v121 row_shl:14 row_mask:0xf bank_mask:0xf
	v_pk_mul_f32 v[196:197], v[188:189], v[216:217] op_sel_hi:[1,0]
	v_pk_mul_f32 v[198:199], v[190:191], v[216:217] op_sel_hi:[1,0]
	v_exp_f32_e32 v196, v196
	v_exp_f32_e32 v197, v197
	v_exp_f32_e32 v198, v198
	v_exp_f32_e32 v199, v199
	v_pk_add_f32 v[196:197], v[196:197], v[214:215] op_sel_hi:[1,0]
	v_pk_add_f32 v[198:199], v[198:199], v[214:215] op_sel_hi:[1,0]
	v_rcp_f32_e32 v196, v196
	v_rcp_f32_e32 v197, v197
	v_rcp_f32_e32 v198, v198
	v_rcp_f32_e32 v199, v199
	v_pk_mul_f32 v[188:189], v[188:189], v[196:197]
	v_pk_mul_f32 v[190:191], v[190:191], v[198:199]
	v_pk_mul_f32 v[188:189], v[188:189], v[192:193]
	v_pk_mul_f32 v[190:191], v[190:191], v[194:195]
	v_cvt_pk_bf16_f32 v148, v188, v189
	v_cvt_pk_bf16_f32 v149, v190, v191
	v_add_u32_e32 v213, 0x84000, v215
	global_store_dwordx4 v213, v[146:149], s[96:97]
	v_pk_fma_f32 v[188:189], v[28:29], v[134:135], v[130:131]
	v_pk_fma_f32 v[190:191], v[30:31], v[136:137], v[132:133]
	v_pk_fma_f32 v[192:193], v[16:17], v[204:205], v[208:209]
	v_pk_fma_f32 v[194:195], v[18:19], v[206:207], v[210:211]
	v_fmac_f32_dpp v188, v28, v142 row_shr:1 row_mask:0xf bank_mask:0xf
	v_fmac_f32_dpp v189, v29, v143 row_shr:1 row_mask:0xf bank_mask:0xf
	v_fmac_f32_dpp v190, v30, v144 row_shr:1 row_mask:0xf bank_mask:0xf
	v_fmac_f32_dpp v191, v31, v145 row_shr:1 row_mask:0xf bank_mask:0xf
	v_fmac_f32_dpp v192, v16, v110 row_shr:1 row_mask:0xf bank_mask:0xf
	v_fmac_f32_dpp v193, v17, v111 row_shr:1 row_mask:0xf bank_mask:0xf
	v_fmac_f32_dpp v194, v18, v112 row_shr:1 row_mask:0xf bank_mask:0xf
	v_fmac_f32_dpp v195, v19, v113 row_shr:1 row_mask:0xf bank_mask:0xf
	v_fmac_f32_dpp v188, v28, v154 row_shr:2 row_mask:0xf bank_mask:0xf
	v_fmac_f32_dpp v189, v29, v155 row_shr:2 row_mask:0xf bank_mask:0xf
	v_fmac_f32_dpp v190, v30, v156 row_shr:2 row_mask:0xf bank_mask:0xf
	v_fmac_f32_dpp v191, v31, v157 row_shr:2 row_mask:0xf bank_mask:0xf
	v_fmac_f32_dpp v192, v16, v118 row_shr:2 row_mask:0xf bank_mask:0xf
	v_fmac_f32_dpp v193, v17, v119 row_shr:2 row_mask:0xf bank_mask:0xf
	v_fmac_f32_dpp v194, v18, v120 row_shr:2 row_mask:0xf bank_mask:0xf
	v_fmac_f32_dpp v195, v19, v121 row_shr:2 row_mask:0xf bank_mask:0xf
	v_fmac_f32_dpp v188, v40, v142 row_shl:15 row_mask:0xf bank_mask:0xf
	v_fmac_f32_dpp v189, v41, v143 row_shl:15 row_mask:0xf bank_mask:0xf
	v_fmac_f32_dpp v190, v42, v144 row_shl:15 row_mask:0xf bank_mask:0xf
	v_fmac_f32_dpp v191, v43, v145 row_shl:15 row_mask:0xf bank_mask:0xf
	v_fmac_f32_dpp v192, v32, v110 row_shl:15 row_mask:0xf bank_mask:0xf
	v_fmac_f32_dpp v193, v33, v111 row_shl:15 row_mask:0xf bank_mask:0xf
	v_fmac_f32_dpp v194, v34, v112 row_shl:15 row_mask:0xf bank_mask:0xf
	v_fmac_f32_dpp v195, v35, v113 row_shl:15 row_mask:0xf bank_mask:0xf
	v_fmac_f32_dpp v188, v40, v154 row_shl:14 row_mask:0xf bank_mask:0xf
	v_fmac_f32_dpp v189, v41, v155 row_shl:14 row_mask:0xf bank_mask:0xf
	v_fmac_f32_dpp v190, v42, v156 row_shl:14 row_mask:0xf bank_mask:0xf
	v_fmac_f32_dpp v191, v43, v157 row_shl:14 row_mask:0xf bank_mask:0xf
	v_fmac_f32_dpp v192, v32, v118 row_shl:14 row_mask:0xf bank_mask:0xf
	v_fmac_f32_dpp v193, v33, v119 row_shl:14 row_mask:0xf bank_mask:0xf
	v_fmac_f32_dpp v194, v34, v120 row_shl:14 row_mask:0xf bank_mask:0xf
	v_fmac_f32_dpp v195, v35, v121 row_shl:14 row_mask:0xf bank_mask:0xf
	v_pk_mul_f32 v[196:197], v[188:189], v[216:217] op_sel_hi:[1,0]
	v_pk_mul_f32 v[198:199], v[190:191], v[216:217] op_sel_hi:[1,0]
	v_exp_f32_e32 v196, v196
	v_exp_f32_e32 v197, v197
	v_exp_f32_e32 v198, v198
	v_exp_f32_e32 v199, v199
	v_pk_add_f32 v[196:197], v[196:197], v[214:215] op_sel_hi:[1,0]
	v_pk_add_f32 v[198:199], v[198:199], v[214:215] op_sel_hi:[1,0]
	v_rcp_f32_e32 v196, v196
	v_rcp_f32_e32 v197, v197
	v_rcp_f32_e32 v198, v198
	v_rcp_f32_e32 v199, v199
	v_pk_mul_f32 v[188:189], v[188:189], v[196:197]
	v_pk_mul_f32 v[190:191], v[190:191], v[198:199]
	v_pk_mul_f32 v[188:189], v[188:189], v[192:193]
	v_pk_mul_f32 v[190:191], v[190:191], v[194:195]
	v_cvt_pk_bf16_f32 v140, v188, v189
	v_cvt_pk_bf16_f32 v141, v190, v191
	v_add_u32_e32 v213, 0xb0000, v215
	global_store_dwordx4 v213, v[138:141], s[96:97]
	v_pk_fma_f32 v[188:189], v[24:25], v[134:135], v[130:131]
	v_pk_fma_f32 v[190:191], v[26:27], v[136:137], v[132:133]
	v_pk_fma_f32 v[192:193], v[12:13], v[204:205], v[208:209]
	v_pk_fma_f32 v[194:195], v[14:15], v[206:207], v[210:211]
	v_fmac_f32_dpp v188, v24, v142 row_shr:1 row_mask:0xf bank_mask:0xf
	v_fmac_f32_dpp v189, v25, v143 row_shr:1 row_mask:0xf bank_mask:0xf
	v_fmac_f32_dpp v190, v26, v144 row_shr:1 row_mask:0xf bank_mask:0xf
	v_fmac_f32_dpp v191, v27, v145 row_shr:1 row_mask:0xf bank_mask:0xf
	v_fmac_f32_dpp v192, v12, v110 row_shr:1 row_mask:0xf bank_mask:0xf
	v_fmac_f32_dpp v193, v13, v111 row_shr:1 row_mask:0xf bank_mask:0xf
	v_fmac_f32_dpp v194, v14, v112 row_shr:1 row_mask:0xf bank_mask:0xf
	v_fmac_f32_dpp v195, v15, v113 row_shr:1 row_mask:0xf bank_mask:0xf
	v_fmac_f32_dpp v188, v24, v154 row_shr:2 row_mask:0xf bank_mask:0xf
	v_fmac_f32_dpp v189, v25, v155 row_shr:2 row_mask:0xf bank_mask:0xf
	v_fmac_f32_dpp v190, v26, v156 row_shr:2 row_mask:0xf bank_mask:0xf
	v_fmac_f32_dpp v191, v27, v157 row_shr:2 row_mask:0xf bank_mask:0xf
	v_fmac_f32_dpp v192, v12, v118 row_shr:2 row_mask:0xf bank_mask:0xf
	v_fmac_f32_dpp v193, v13, v119 row_shr:2 row_mask:0xf bank_mask:0xf
	v_fmac_f32_dpp v194, v14, v120 row_shr:2 row_mask:0xf bank_mask:0xf
	v_fmac_f32_dpp v195, v15, v121 row_shr:2 row_mask:0xf bank_mask:0xf
	v_fmac_f32_dpp v188, v28, v142 row_shl:15 row_mask:0xf bank_mask:0xf
	v_fmac_f32_dpp v189, v29, v143 row_shl:15 row_mask:0xf bank_mask:0xf
	v_fmac_f32_dpp v190, v30, v144 row_shl:15 row_mask:0xf bank_mask:0xf
	v_fmac_f32_dpp v191, v31, v145 row_shl:15 row_mask:0xf bank_mask:0xf
	v_fmac_f32_dpp v192, v16, v110 row_shl:15 row_mask:0xf bank_mask:0xf
	v_fmac_f32_dpp v193, v17, v111 row_shl:15 row_mask:0xf bank_mask:0xf
	v_fmac_f32_dpp v194, v18, v112 row_shl:15 row_mask:0xf bank_mask:0xf
	v_fmac_f32_dpp v195, v19, v113 row_shl:15 row_mask:0xf bank_mask:0xf
	v_fmac_f32_dpp v188, v28, v154 row_shl:14 row_mask:0xf bank_mask:0xf
	v_fmac_f32_dpp v189, v29, v155 row_shl:14 row_mask:0xf bank_mask:0xf
	v_fmac_f32_dpp v190, v30, v156 row_shl:14 row_mask:0xf bank_mask:0xf
	v_fmac_f32_dpp v191, v31, v157 row_shl:14 row_mask:0xf bank_mask:0xf
	v_fmac_f32_dpp v192, v16, v118 row_shl:14 row_mask:0xf bank_mask:0xf
	v_fmac_f32_dpp v193, v17, v119 row_shl:14 row_mask:0xf bank_mask:0xf
	v_fmac_f32_dpp v194, v18, v120 row_shl:14 row_mask:0xf bank_mask:0xf
	v_fmac_f32_dpp v195, v19, v121 row_shl:14 row_mask:0xf bank_mask:0xf
	v_pk_mul_f32 v[196:197], v[188:189], v[216:217] op_sel_hi:[1,0]
	v_pk_mul_f32 v[198:199], v[190:191], v[216:217] op_sel_hi:[1,0]
	v_exp_f32_e32 v196, v196
	v_exp_f32_e32 v197, v197
	v_exp_f32_e32 v198, v198
	v_exp_f32_e32 v199, v199
	v_pk_add_f32 v[196:197], v[196:197], v[214:215] op_sel_hi:[1,0]
	v_pk_add_f32 v[198:199], v[198:199], v[214:215] op_sel_hi:[1,0]
	v_rcp_f32_e32 v196, v196
	v_rcp_f32_e32 v197, v197
	v_rcp_f32_e32 v198, v198
	v_rcp_f32_e32 v199, v199
	v_pk_mul_f32 v[188:189], v[188:189], v[196:197]
	v_pk_mul_f32 v[190:191], v[190:191], v[198:199]
	v_pk_mul_f32 v[188:189], v[188:189], v[192:193]
	v_pk_mul_f32 v[190:191], v[190:191], v[194:195]
	v_cvt_pk_bf16_f32 v128, v188, v189
	v_cvt_pk_bf16_f32 v129, v190, v191
	v_add_u32_e32 v213, 0xdc000, v215
	global_store_dwordx4 v213, v[126:129], s[96:97]
	v_pk_fma_f32 v[188:189], v[20:21], v[134:135], v[130:131]
	v_pk_fma_f32 v[190:191], v[22:23], v[136:137], v[132:133]
	v_pk_fma_f32 v[192:193], v[8:9], v[204:205], v[208:209]
	v_pk_fma_f32 v[194:195], v[10:11], v[206:207], v[210:211]
	v_fmac_f32_dpp v188, v20, v142 row_shr:1 row_mask:0xf bank_mask:0xf
	v_fmac_f32_dpp v189, v21, v143 row_shr:1 row_mask:0xf bank_mask:0xf
	v_fmac_f32_dpp v190, v22, v144 row_shr:1 row_mask:0xf bank_mask:0xf
	v_fmac_f32_dpp v191, v23, v145 row_shr:1 row_mask:0xf bank_mask:0xf
	v_fmac_f32_dpp v192, v8, v110 row_shr:1 row_mask:0xf bank_mask:0xf
	v_fmac_f32_dpp v193, v9, v111 row_shr:1 row_mask:0xf bank_mask:0xf
	v_fmac_f32_dpp v194, v10, v112 row_shr:1 row_mask:0xf bank_mask:0xf
	v_fmac_f32_dpp v195, v11, v113 row_shr:1 row_mask:0xf bank_mask:0xf
	v_fmac_f32_dpp v188, v20, v154 row_shr:2 row_mask:0xf bank_mask:0xf
	v_fmac_f32_dpp v189, v21, v155 row_shr:2 row_mask:0xf bank_mask:0xf
	v_fmac_f32_dpp v190, v22, v156 row_shr:2 row_mask:0xf bank_mask:0xf
	v_fmac_f32_dpp v191, v23, v157 row_shr:2 row_mask:0xf bank_mask:0xf
	v_fmac_f32_dpp v192, v8, v118 row_shr:2 row_mask:0xf bank_mask:0xf
	v_fmac_f32_dpp v193, v9, v119 row_shr:2 row_mask:0xf bank_mask:0xf
	v_fmac_f32_dpp v194, v10, v120 row_shr:2 row_mask:0xf bank_mask:0xf
	v_fmac_f32_dpp v195, v11, v121 row_shr:2 row_mask:0xf bank_mask:0xf
	v_fmac_f32_dpp v188, v24, v142 row_shl:15 row_mask:0xf bank_mask:0xf
	v_fmac_f32_dpp v189, v25, v143 row_shl:15 row_mask:0xf bank_mask:0xf
	v_fmac_f32_dpp v190, v26, v144 row_shl:15 row_mask:0xf bank_mask:0xf
	v_fmac_f32_dpp v191, v27, v145 row_shl:15 row_mask:0xf bank_mask:0xf
	v_fmac_f32_dpp v192, v12, v110 row_shl:15 row_mask:0xf bank_mask:0xf
	v_fmac_f32_dpp v193, v13, v111 row_shl:15 row_mask:0xf bank_mask:0xf
	v_fmac_f32_dpp v194, v14, v112 row_shl:15 row_mask:0xf bank_mask:0xf
	v_fmac_f32_dpp v195, v15, v113 row_shl:15 row_mask:0xf bank_mask:0xf
	v_fmac_f32_dpp v188, v24, v154 row_shl:14 row_mask:0xf bank_mask:0xf
	v_fmac_f32_dpp v189, v25, v155 row_shl:14 row_mask:0xf bank_mask:0xf
	v_fmac_f32_dpp v190, v26, v156 row_shl:14 row_mask:0xf bank_mask:0xf
	v_fmac_f32_dpp v191, v27, v157 row_shl:14 row_mask:0xf bank_mask:0xf
	v_fmac_f32_dpp v192, v12, v118 row_shl:14 row_mask:0xf bank_mask:0xf
	v_fmac_f32_dpp v193, v13, v119 row_shl:14 row_mask:0xf bank_mask:0xf
	v_fmac_f32_dpp v194, v14, v120 row_shl:14 row_mask:0xf bank_mask:0xf
	v_fmac_f32_dpp v195, v15, v121 row_shl:14 row_mask:0xf bank_mask:0xf
	v_pk_mul_f32 v[196:197], v[188:189], v[216:217] op_sel_hi:[1,0]
	v_pk_mul_f32 v[198:199], v[190:191], v[216:217] op_sel_hi:[1,0]
	v_exp_f32_e32 v196, v196
	v_exp_f32_e32 v197, v197
	v_exp_f32_e32 v198, v198
	v_exp_f32_e32 v199, v199
	v_pk_add_f32 v[196:197], v[196:197], v[214:215] op_sel_hi:[1,0]
	v_pk_add_f32 v[198:199], v[198:199], v[214:215] op_sel_hi:[1,0]
	v_rcp_f32_e32 v196, v196
	v_rcp_f32_e32 v197, v197
	v_rcp_f32_e32 v198, v198
	v_rcp_f32_e32 v199, v199
	v_pk_mul_f32 v[188:189], v[188:189], v[196:197]
	v_pk_mul_f32 v[190:191], v[190:191], v[198:199]
	v_pk_mul_f32 v[188:189], v[188:189], v[192:193]
	v_pk_mul_f32 v[190:191], v[190:191], v[194:195]
	v_cvt_pk_bf16_f32 v124, v188, v189
	v_cvt_pk_bf16_f32 v125, v190, v191
	v_add_u32_e32 v213, 0x108000, v215
	global_store_dwordx4 v213, v[122:125], s[96:97]
	v_pk_fma_f32 v[188:189], v[4:5], v[134:135], v[130:131]
	v_pk_fma_f32 v[190:191], v[6:7], v[136:137], v[132:133]
	v_pk_fma_f32 v[192:193], v[0:1], v[204:205], v[208:209]
	v_pk_fma_f32 v[194:195], v[2:3], v[206:207], v[210:211]
	v_fmac_f32_dpp v188, v4, v142 row_shr:1 row_mask:0xf bank_mask:0xf
	v_fmac_f32_dpp v189, v5, v143 row_shr:1 row_mask:0xf bank_mask:0xf
	v_fmac_f32_dpp v190, v6, v144 row_shr:1 row_mask:0xf bank_mask:0xf
	v_fmac_f32_dpp v191, v7, v145 row_shr:1 row_mask:0xf bank_mask:0xf
	v_fmac_f32_dpp v192, v0, v110 row_shr:1 row_mask:0xf bank_mask:0xf
	v_fmac_f32_dpp v193, v1, v111 row_shr:1 row_mask:0xf bank_mask:0xf
	v_fmac_f32_dpp v194, v2, v112 row_shr:1 row_mask:0xf bank_mask:0xf
	v_fmac_f32_dpp v195, v3, v113 row_shr:1 row_mask:0xf bank_mask:0xf
	v_fmac_f32_dpp v188, v4, v154 row_shr:2 row_mask:0xf bank_mask:0xf
	v_fmac_f32_dpp v189, v5, v155 row_shr:2 row_mask:0xf bank_mask:0xf
	v_fmac_f32_dpp v190, v6, v156 row_shr:2 row_mask:0xf bank_mask:0xf
	v_fmac_f32_dpp v191, v7, v157 row_shr:2 row_mask:0xf bank_mask:0xf
	v_fmac_f32_dpp v192, v0, v118 row_shr:2 row_mask:0xf bank_mask:0xf
	v_fmac_f32_dpp v193, v1, v119 row_shr:2 row_mask:0xf bank_mask:0xf
	v_fmac_f32_dpp v194, v2, v120 row_shr:2 row_mask:0xf bank_mask:0xf
	v_fmac_f32_dpp v195, v3, v121 row_shr:2 row_mask:0xf bank_mask:0xf
	v_fmac_f32_dpp v188, v20, v142 row_shl:15 row_mask:0xf bank_mask:0xf
	v_fmac_f32_dpp v189, v21, v143 row_shl:15 row_mask:0xf bank_mask:0xf
	v_fmac_f32_dpp v190, v22, v144 row_shl:15 row_mask:0xf bank_mask:0xf
	v_fmac_f32_dpp v191, v23, v145 row_shl:15 row_mask:0xf bank_mask:0xf
	v_fmac_f32_dpp v192, v8, v110 row_shl:15 row_mask:0xf bank_mask:0xf
	v_fmac_f32_dpp v193, v9, v111 row_shl:15 row_mask:0xf bank_mask:0xf
	v_fmac_f32_dpp v194, v10, v112 row_shl:15 row_mask:0xf bank_mask:0xf
	v_fmac_f32_dpp v195, v11, v113 row_shl:15 row_mask:0xf bank_mask:0xf
	v_fmac_f32_dpp v188, v20, v154 row_shl:14 row_mask:0xf bank_mask:0xf
	v_fmac_f32_dpp v189, v21, v155 row_shl:14 row_mask:0xf bank_mask:0xf
	v_fmac_f32_dpp v190, v22, v156 row_shl:14 row_mask:0xf bank_mask:0xf
	v_fmac_f32_dpp v191, v23, v157 row_shl:14 row_mask:0xf bank_mask:0xf
	v_fmac_f32_dpp v192, v8, v118 row_shl:14 row_mask:0xf bank_mask:0xf
	v_fmac_f32_dpp v193, v9, v119 row_shl:14 row_mask:0xf bank_mask:0xf
	v_fmac_f32_dpp v194, v10, v120 row_shl:14 row_mask:0xf bank_mask:0xf
	v_fmac_f32_dpp v195, v11, v121 row_shl:14 row_mask:0xf bank_mask:0xf
	v_pk_mul_f32 v[196:197], v[188:189], v[216:217] op_sel_hi:[1,0]
	v_pk_mul_f32 v[198:199], v[190:191], v[216:217] op_sel_hi:[1,0]
	v_exp_f32_e32 v196, v196
	v_exp_f32_e32 v197, v197
	v_exp_f32_e32 v198, v198
	v_exp_f32_e32 v199, v199
	v_pk_add_f32 v[196:197], v[196:197], v[214:215] op_sel_hi:[1,0]
	v_pk_add_f32 v[198:199], v[198:199], v[214:215] op_sel_hi:[1,0]
	v_rcp_f32_e32 v196, v196
	v_rcp_f32_e32 v197, v197
	v_rcp_f32_e32 v198, v198
	v_rcp_f32_e32 v199, v199
	v_pk_mul_f32 v[188:189], v[188:189], v[196:197]
	v_pk_mul_f32 v[190:191], v[190:191], v[198:199]
	v_pk_mul_f32 v[188:189], v[188:189], v[192:193]
	v_pk_mul_f32 v[190:191], v[190:191], v[194:195]
	v_cvt_pk_bf16_f32 v116, v188, v189
	v_cvt_pk_bf16_f32 v117, v190, v191
	v_add_u32_e32 v213, 0x134000, v215
	global_store_dwordx4 v213, v[114:117], s[96:97]
	s_branch .LBB0_836
.Lfs8_first:
	s_lshl_b32 s8, s0, 8
	s_add_i32 s8, s8, s58
	s_lshl_b32 s9, s1, 7
	s_add_i32 s9, s9, s53
	s_lshl_b32 s10, s0, 3
	s_lshr_b32 s11, s58, 5
	s_add_i32 s10, s10, s11
	v_add_u32_e32 v200, s8, v163
	v_lshlrev_b32_e32 v213, 2, v200
	v_lshl_add_u32 v201, v225, 3, s9
	v_lshlrev_b32_e32 v212, 2, v201
	v_lshrrev_b32_e32 v109, 6, v222
	s_and_b32 s9, s52, 1
	v_readfirstlane_b32 s11, v109
	s_mul_i32 s9, s9, 0x3000
	s_mul_i32 s11, s11, 0x600
	s_add_i32 s9, s9, s11
	s_add_i32 s9, s9, 0x21040
	global_load_dword v188, v213, s[4:5]
	global_load_dword v189, v213, s[4:5] offset:64
	global_load_dword v190, v213, s[4:5] offset:128
	global_load_dword v191, v213, s[4:5] offset:192
	global_load_dword v192, v213, s[4:5] offset:256
	global_load_dword v193, v213, s[4:5] offset:320
	global_load_dword v194, v213, s[4:5] offset:384
	global_load_dword v195, v213, s[4:5] offset:448
	v_add_u32_e32 v213, 0x21000, v212
	global_load_dwordx4 v[76:79], v213, s[82:83]
	v_add_u32_e32 v213, 0x2c000, v212
	global_load_dwordx4 v[80:83], v213, s[82:83]
	v_add_u32_e32 v213, 0x37000, v212
	global_load_dwordx4 v[84:87], v213, s[82:83]
	v_add_u32_e32 v213, 0xb000, v212
	global_load_dwordx4 v[88:91], v213, s[84:85]
	v_add_u32_e32 v213, 0x26800, v212
	global_load_dwordx4 v[92:95], v213, s[82:83]
	v_add_u32_e32 v213, 0x31800, v212
	global_load_dwordx4 v[96:99], v213, s[82:83]
	v_add_u32_e32 v213, 0x3c800, v212
	global_load_dwordx4 v[100:103], v213, s[82:83]
	v_add_u32_e32 v213, 0x10800, v212
	global_load_dwordx4 v[104:107], v213, s[84:85]
	v_mul_u32_u24_e32 v215, 0x2c00, v200
	v_lshl_add_u32 v215, v201, 1, v215
	v_add_u32_e32 v213, s10, v163
	v_mul_u32_u24_e32 v217, 0xb000, v213
	v_add_u32_e32 v217, v217, v212
	v_cmp_lt_u32_e64 s[10:11], 13, v163
	v_cmp_lt_u32_e32 vcc, 1, v163
	v_mov_b32_e32 v214, 1.0
	v_mov_b32_e32 v216, 0xbfb8aa3b
	v_mov_b32_e32 v108, 0x3727c5ac
	s_waitcnt vmcnt(8)
	v_fmamk_f32 v188, v188, 0x3a000000, v108
	v_fmamk_f32 v189, v189, 0x3a000000, v108
	v_fmamk_f32 v190, v190, 0x3a000000, v108
	v_fmamk_f32 v191, v191, 0x3a000000, v108
	v_fmamk_f32 v192, v192, 0x3a000000, v108
	v_fmamk_f32 v193, v193, 0x3a000000, v108
	v_fmamk_f32 v194, v194, 0x3a000000, v108
	v_fmamk_f32 v195, v195, 0x3a000000, v108
	v_rsq_f32_e32 v188, v188
	v_rsq_f32_e32 v189, v189
	v_rsq_f32_e32 v190, v190
	v_rsq_f32_e32 v191, v191
	v_rsq_f32_e32 v192, v192
	v_rsq_f32_e32 v193, v193
	v_rsq_f32_e32 v194, v194
	v_rsq_f32_e32 v195, v195
	v_pk_mul_f32 v[158:159], v[158:159], v[188:189] op_sel_hi:[1,0]
	v_pk_mul_f32 v[160:161], v[160:161], v[188:189] op_sel_hi:[1,0]
	v_pk_mul_f32 v[60:61], v[60:61], v[188:189] op_sel_hi:[1,0]
	v_pk_mul_f32 v[62:63], v[62:63], v[188:189] op_sel_hi:[1,0]
	v_pk_mul_f32 v[154:155], v[154:155], v[188:189] op_sel_hi:[1,0]
	v_pk_mul_f32 v[156:157], v[156:157], v[188:189] op_sel_hi:[1,0]
	v_pk_mul_f32 v[56:57], v[56:57], v[188:189] op_sel_hi:[1,0]
	v_pk_mul_f32 v[58:59], v[58:59], v[188:189] op_sel_hi:[1,0]
	v_pk_mul_f32 v[150:151], v[150:151], v[188:189] op_sel:[0,1] op_sel_hi:[1,1]
	v_pk_mul_f32 v[152:153], v[152:153], v[188:189] op_sel:[0,1] op_sel_hi:[1,1]
	v_pk_mul_f32 v[52:53], v[52:53], v[188:189] op_sel:[0,1] op_sel_hi:[1,1]
	v_pk_mul_f32 v[54:55], v[54:55], v[188:189] op_sel:[0,1] op_sel_hi:[1,1]
	v_pk_mul_f32 v[142:143], v[142:143], v[188:189] op_sel:[0,1] op_sel_hi:[1,1]
	v_pk_mul_f32 v[144:145], v[144:145], v[188:189] op_sel:[0,1] op_sel_hi:[1,1]
	v_pk_mul_f32 v[44:45], v[44:45], v[188:189] op_sel:[0,1] op_sel_hi:[1,1]
	v_pk_mul_f32 v[46:47], v[46:47], v[188:189] op_sel:[0,1] op_sel_hi:[1,1]
	v_pk_mul_f32 v[146:147], v[146:147], v[190:191] op_sel_hi:[1,0]
	v_pk_mul_f32 v[148:149], v[148:149], v[190:191] op_sel_hi:[1,0]
	v_pk_mul_f32 v[48:49], v[48:49], v[190:191] op_sel_hi:[1,0]
	v_pk_mul_f32 v[50:51], v[50:51], v[190:191] op_sel_hi:[1,0]
	v_pk_mul_f32 v[134:135], v[134:135], v[190:191] op_sel_hi:[1,0]
	v_pk_mul_f32 v[136:137], v[136:137], v[190:191] op_sel_hi:[1,0]
	v_pk_mul_f32 v[36:37], v[36:37], v[190:191] op_sel_hi:[1,0]
	v_pk_mul_f32 v[38:39], v[38:39], v[190:191] op_sel_hi:[1,0]
	v_pk_mul_f32 v[138:139], v[138:139], v[190:191] op_sel:[0,1] op_sel_hi:[1,1]
	v_pk_mul_f32 v[140:141], v[140:141], v[190:191] op_sel:[0,1] op_sel_hi:[1,1]
	v_pk_mul_f32 v[40:41], v[40:41], v[190:191] op_sel:[0,1] op_sel_hi:[1,1]
	v_pk_mul_f32 v[42:43], v[42:43], v[190:191] op_sel:[0,1] op_sel_hi:[1,1]
	v_pk_mul_f32 v[130:131], v[130:131], v[190:191] op_sel:[0,1] op_sel_hi:[1,1]
	v_pk_mul_f32 v[132:133], v[132:133], v[190:191] op_sel:[0,1] op_sel_hi:[1,1]
	v_pk_mul_f32 v[32:33], v[32:33], v[190:191] op_sel:[0,1] op_sel_hi:[1,1]
	v_pk_mul_f32 v[34:35], v[34:35], v[190:191] op_sel:[0,1] op_sel_hi:[1,1]
	v_pk_mul_f32 v[126:127], v[126:127], v[192:193] op_sel_hi:[1,0]
	v_pk_mul_f32 v[128:129], v[128:129], v[192:193] op_sel_hi:[1,0]
	v_pk_mul_f32 v[28:29], v[28:29], v[192:193] op_sel_hi:[1,0]
	v_pk_mul_f32 v[30:31], v[30:31], v[192:193] op_sel_hi:[1,0]
	v_pk_mul_f32 v[118:119], v[118:119], v[192:193] op_sel_hi:[1,0]
	v_pk_mul_f32 v[120:121], v[120:121], v[192:193] op_sel_hi:[1,0]
	v_pk_mul_f32 v[16:17], v[16:17], v[192:193] op_sel_hi:[1,0]
	v_pk_mul_f32 v[18:19], v[18:19], v[192:193] op_sel_hi:[1,0]
	v_pk_mul_f32 v[122:123], v[122:123], v[192:193] op_sel:[0,1] op_sel_hi:[1,1]
	v_pk_mul_f32 v[124:125], v[124:125], v[192:193] op_sel:[0,1] op_sel_hi:[1,1]
	v_pk_mul_f32 v[24:25], v[24:25], v[192:193] op_sel:[0,1] op_sel_hi:[1,1]
	v_pk_mul_f32 v[26:27], v[26:27], v[192:193] op_sel:[0,1] op_sel_hi:[1,1]
	v_pk_mul_f32 v[110:111], v[110:111], v[192:193] op_sel:[0,1] op_sel_hi:[1,1]
	v_pk_mul_f32 v[112:113], v[112:113], v[192:193] op_sel:[0,1] op_sel_hi:[1,1]
	v_pk_mul_f32 v[12:13], v[12:13], v[192:193] op_sel:[0,1] op_sel_hi:[1,1]
	v_pk_mul_f32 v[14:15], v[14:15], v[192:193] op_sel:[0,1] op_sel_hi:[1,1]
	v_pk_mul_f32 v[114:115], v[114:115], v[194:195] op_sel_hi:[1,0]
	v_pk_mul_f32 v[116:117], v[116:117], v[194:195] op_sel_hi:[1,0]
	v_pk_mul_f32 v[20:21], v[20:21], v[194:195] op_sel_hi:[1,0]
	v_pk_mul_f32 v[22:23], v[22:23], v[194:195] op_sel_hi:[1,0]
	v_pk_mul_f32 v[68:69], v[68:69], v[194:195] op_sel_hi:[1,0]
	v_pk_mul_f32 v[70:71], v[70:71], v[194:195] op_sel_hi:[1,0]
	v_pk_mul_f32 v[8:9], v[8:9], v[194:195] op_sel_hi:[1,0]
	v_pk_mul_f32 v[10:11], v[10:11], v[194:195] op_sel_hi:[1,0]
	v_pk_mul_f32 v[72:73], v[72:73], v[194:195] op_sel:[0,1] op_sel_hi:[1,1]
	v_pk_mul_f32 v[74:75], v[74:75], v[194:195] op_sel:[0,1] op_sel_hi:[1,1]
	v_pk_mul_f32 v[4:5], v[4:5], v[194:195] op_sel:[0,1] op_sel_hi:[1,1]
	v_pk_mul_f32 v[6:7], v[6:7], v[194:195] op_sel:[0,1] op_sel_hi:[1,1]
	v_pk_mul_f32 v[64:65], v[64:65], v[194:195] op_sel:[0,1] op_sel_hi:[1,1]
	v_pk_mul_f32 v[66:67], v[66:67], v[194:195] op_sel:[0,1] op_sel_hi:[1,1]
	v_pk_mul_f32 v[0:1], v[0:1], v[194:195] op_sel:[0,1] op_sel_hi:[1,1]
	v_pk_mul_f32 v[2:3], v[2:3], v[194:195] op_sel:[0,1] op_sel_hi:[1,1]
	v_cmp_gt_u32_e32 vcc, 2, v163
	s_nop 1
	s_mov_b64 exec, vcc
	v_add_u32_e32 v213, 0x5800, v217
	global_store_dwordx4 v217, v[158:161], s[70:71]
	global_store_dwordx4 v213, v[154:157], s[70:71]
	global_store_dwordx4 v217, v[60:63], s[70:71] offset:16
	global_store_dwordx4 v213, v[56:59], s[70:71] offset:16
	s_mov_b64 exec, s[10:11]
	v_add_u32_e32 v213, 0xfff7c000, v217
	global_store_dwordx4 v213, v[72:75], s[70:71]
	global_store_dwordx4 v213, v[4:7], s[70:71] offset:16
	v_add_u32_e32 v213, 0xfff81800, v217
	global_store_dwordx4 v213, v[64:67], s[70:71]
	global_store_dwordx4 v213, v[0:3], s[70:71] offset:16
	s_mov_b64 exec, -1
	v_cmp_lt_u32_e32 vcc, 1, v163
	s_cmp_lg_u64 s[6:7], 0
	s_cselect_b32 s8, s0, s36
	s_cselect_b32 s10, s1, s34
	s_lshl_b32 s8, s8, 8
	s_add_i32 s8, s8, s58
	s_lshl_b32 s10, s10, 7
	s_add_i32 s10, s10, s53
	v_and_b32_e32 v213, 63, v222
	v_add_u32_e32 v188, s8, v213
	v_lshlrev_b32_e32 v188, 2, v188
	s_mov_b32 m0, s9
	v_add_u32_e32 v189, 0x100, v188
	global_load_lds_dword v188, s[4:5]
	s_add_i32 m0, s9, 0x100
	v_and_b32_e32 v190, 7, v213
	global_load_lds_dword v189, s[4:5]
	v_lshrrev_b32_e32 v191, 3, v213
	v_lshlrev_b32_e32 v190, 4, v190
	s_lshl_b32 s10, s10, 2
	v_add_u32_e32 v190, s10, v190
	v_lshrrev_b32_e32 v192, 2, v191
	v_and_b32_e32 v191, 3, v191
	v_mul_u32_u24_e32 v192, 0x5800, v192
	v_add_u32_e32 v190, v190, v192
	v_mul_u32_u24_e32 v192, 0xb000, v191
	v_add_u32_e32 v192, v192, v190
	v_add_u32_e32 v192, 0x21000, v192
	v_add_u32_e32 v190, 0xb000, v190
	s_add_i32 m0, s9, 0x200
	s_mov_b32 s10, 0xff000000
	s_mov_b32 s11, 0xff000000
	s_andn2_b64 exec, exec, s[10:11]
	global_load_lds_dwordx4 v192, s[82:83]
	s_mov_b64 exec, s[10:11]
	global_load_lds_dwordx4 v190, s[84:85]
	s_mov_b64 exec, -1
	v_add_u32_e32 v213, 0x3c800, v212
	global_load_dwordx4 v[204:207], v213, s[82:83] offset:16
	v_add_u32_e32 v213, 0x10800, v212
	global_load_dwordx4 v[208:211], v213, s[84:85] offset:16
	s_waitcnt vmcnt(14)
	v_pk_fma_f32 v[188:189], v[158:159], v[84:85], v[88:89]
	v_pk_fma_f32 v[190:191], v[160:161], v[86:87], v[90:91]
	v_pk_fma_f32 v[192:193], v[154:155], v[100:101], v[104:105]
	v_pk_fma_f32 v[194:195], v[156:157], v[102:103], v[106:107]
	v_fmac_f32_dpp v188, v158, v80 row_shr:1 row_mask:0xf bank_mask:0xf
	v_fmac_f32_dpp v189, v159, v81 row_shr:1 row_mask:0xf bank_mask:0xf
	v_fmac_f32_dpp v190, v160, v82 row_shr:1 row_mask:0xf bank_mask:0xf
	v_fmac_f32_dpp v191, v161, v83 row_shr:1 row_mask:0xf bank_mask:0xf
	v_fmac_f32_dpp v192, v154, v96 row_shr:1 row_mask:0xf bank_mask:0xf
	v_fmac_f32_dpp v193, v155, v97 row_shr:1 row_mask:0xf bank_mask:0xf
	v_fmac_f32_dpp v194, v156, v98 row_shr:1 row_mask:0xf bank_mask:0xf
	v_fmac_f32_dpp v195, v157, v99 row_shr:1 row_mask:0xf bank_mask:0xf
	v_fmac_f32_dpp v188, v158, v76 row_shr:2 row_mask:0xf bank_mask:0xf
	v_fmac_f32_dpp v189, v159, v77 row_shr:2 row_mask:0xf bank_mask:0xf
	v_fmac_f32_dpp v190, v160, v78 row_shr:2 row_mask:0xf bank_mask:0xf
	v_fmac_f32_dpp v191, v161, v79 row_shr:2 row_mask:0xf bank_mask:0xf
	v_fmac_f32_dpp v192, v154, v92 row_shr:2 row_mask:0xf bank_mask:0xf
	v_fmac_f32_dpp v193, v155, v93 row_shr:2 row_mask:0xf bank_mask:0xf
	v_fmac_f32_dpp v194, v156, v94 row_shr:2 row_mask:0xf bank_mask:0xf
	v_fmac_f32_dpp v195, v157, v95 row_shr:2 row_mask:0xf bank_mask:0xf
	v_pk_mul_f32 v[196:197], v[188:189], v[216:217] op_sel_hi:[1,0]
	v_pk_mul_f32 v[198:199], v[190:191], v[216:217] op_sel_hi:[1,0]
	v_exp_f32_e32 v196, v196
	v_exp_f32_e32 v197, v197
	v_exp_f32_e32 v198, v198
	v_exp_f32_e32 v199, v199
	v_pk_add_f32 v[196:197], v[196:197], v[214:215] op_sel_hi:[1,0]
	v_pk_add_f32 v[198:199], v[198:199], v[214:215] op_sel_hi:[1,0]
	v_rcp_f32_e32 v196, v196
	v_rcp_f32_e32 v197, v197
	v_rcp_f32_e32 v198, v198
	v_rcp_f32_e32 v199, v199
	v_pk_mul_f32 v[188:189], v[188:189], v[196:197]
	v_pk_mul_f32 v[190:191], v[190:191], v[198:199]
	v_pk_mul_f32 v[188:189], v[188:189], v[192:193]
	v_pk_mul_f32 v[190:191], v[190:191], v[194:195]
	v_cvt_pk_bf16_f32 v200, v188, v189
	v_cvt_pk_bf16_f32 v201, v190, v191
	v_pk_fma_f32 v[188:189], v[150:151], v[84:85], v[88:89]
	v_pk_fma_f32 v[190:191], v[152:153], v[86:87], v[90:91]
	v_pk_fma_f32 v[192:193], v[142:143], v[100:101], v[104:105]
	v_pk_fma_f32 v[194:195], v[144:145], v[102:103], v[106:107]
	v_fmac_f32_dpp v188, v150, v80 row_shr:1 row_mask:0xf bank_mask:0xf
	v_fmac_f32_dpp v189, v151, v81 row_shr:1 row_mask:0xf bank_mask:0xf
	v_fmac_f32_dpp v190, v152, v82 row_shr:1 row_mask:0xf bank_mask:0xf
	v_fmac_f32_dpp v191, v153, v83 row_shr:1 row_mask:0xf bank_mask:0xf
	v_fmac_f32_dpp v192, v142, v96 row_shr:1 row_mask:0xf bank_mask:0xf
	v_fmac_f32_dpp v193, v143, v97 row_shr:1 row_mask:0xf bank_mask:0xf
	v_fmac_f32_dpp v194, v144, v98 row_shr:1 row_mask:0xf bank_mask:0xf
	v_fmac_f32_dpp v195, v145, v99 row_shr:1 row_mask:0xf bank_mask:0xf
	v_fmac_f32_dpp v188, v150, v76 row_shr:2 row_mask:0xf bank_mask:0xf
	v_fmac_f32_dpp v189, v151, v77 row_shr:2 row_mask:0xf bank_mask:0xf
	v_fmac_f32_dpp v190, v152, v78 row_shr:2 row_mask:0xf bank_mask:0xf
	v_fmac_f32_dpp v191, v153, v79 row_shr:2 row_mask:0xf bank_mask:0xf
	v_fmac_f32_dpp v192, v142, v92 row_shr:2 row_mask:0xf bank_mask:0xf
	v_fmac_f32_dpp v193, v143, v93 row_shr:2 row_mask:0xf bank_mask:0xf
	v_fmac_f32_dpp v194, v144, v94 row_shr:2 row_mask:0xf bank_mask:0xf
	v_fmac_f32_dpp v195, v145, v95 row_shr:2 row_mask:0xf bank_mask:0xf
	v_fmac_f32_dpp v188, v158, v80 row_shl:15 row_mask:0xf bank_mask:0xf
	v_fmac_f32_dpp v189, v159, v81 row_shl:15 row_mask:0xf bank_mask:0xf
	v_fmac_f32_dpp v190, v160, v82 row_shl:15 row_mask:0xf bank_mask:0xf
	v_fmac_f32_dpp v191, v161, v83 row_shl:15 row_mask:0xf bank_mask:0xf
	v_fmac_f32_dpp v192, v154, v96 row_shl:15 row_mask:0xf bank_mask:0xf
	v_fmac_f32_dpp v193, v155, v97 row_shl:15 row_mask:0xf bank_mask:0xf
	v_fmac_f32_dpp v194, v156, v98 row_shl:15 row_mask:0xf bank_mask:0xf
	v_fmac_f32_dpp v195, v157, v99 row_shl:15 row_mask:0xf bank_mask:0xf
	v_fmac_f32_dpp v188, v158, v76 row_shl:14 row_mask:0xf bank_mask:0xf
	v_fmac_f32_dpp v189, v159, v77 row_shl:14 row_mask:0xf bank_mask:0xf
	v_fmac_f32_dpp v190, v160, v78 row_shl:14 row_mask:0xf bank_mask:0xf
	v_fmac_f32_dpp v191, v161, v79 row_shl:14 row_mask:0xf bank_mask:0xf
	v_fmac_f32_dpp v192, v154, v92 row_shl:14 row_mask:0xf bank_mask:0xf
	v_fmac_f32_dpp v193, v155, v93 row_shl:14 row_mask:0xf bank_mask:0xf
	v_fmac_f32_dpp v194, v156, v94 row_shl:14 row_mask:0xf bank_mask:0xf
	v_fmac_f32_dpp v195, v157, v95 row_shl:14 row_mask:0xf bank_mask:0xf
	v_pk_mul_f32 v[196:197], v[188:189], v[216:217] op_sel_hi:[1,0]
	v_pk_mul_f32 v[198:199], v[190:191], v[216:217] op_sel_hi:[1,0]
	v_exp_f32_e32 v196, v196
	v_exp_f32_e32 v197, v197
	v_exp_f32_e32 v198, v198
	v_exp_f32_e32 v199, v199
	v_pk_add_f32 v[196:197], v[196:197], v[214:215] op_sel_hi:[1,0]
	v_pk_add_f32 v[198:199], v[198:199], v[214:215] op_sel_hi:[1,0]
	v_rcp_f32_e32 v196, v196
	v_rcp_f32_e32 v197, v197
	v_rcp_f32_e32 v198, v198
	v_rcp_f32_e32 v199, v199
	v_pk_mul_f32 v[188:189], v[188:189], v[196:197]
	v_pk_mul_f32 v[190:191], v[190:191], v[198:199]
	v_pk_mul_f32 v[188:189], v[188:189], v[192:193]
	v_pk_mul_f32 v[190:191], v[190:191], v[194:195]
	v_cvt_pk_bf16_f32 v158, v188, v189
	v_cvt_pk_bf16_f32 v159, v190, v191
	v_add_u32_e32 v213, 0x21000, v212
	global_load_dwordx4 v[154:157], v213, s[82:83] offset:16
	v_pk_fma_f32 v[188:189], v[146:147], v[84:85], v[88:89]
	v_pk_fma_f32 v[190:191], v[148:149], v[86:87], v[90:91]
	v_pk_fma_f32 v[192:193], v[134:135], v[100:101], v[104:105]
	v_pk_fma_f32 v[194:195], v[136:137], v[102:103], v[106:107]
	v_fmac_f32_dpp v188, v146, v80 row_shr:1 row_mask:0xf bank_mask:0xf
	v_fmac_f32_dpp v189, v147, v81 row_shr:1 row_mask:0xf bank_mask:0xf
	v_fmac_f32_dpp v190, v148, v82 row_shr:1 row_mask:0xf bank_mask:0xf
	v_fmac_f32_dpp v191, v149, v83 row_shr:1 row_mask:0xf bank_mask:0xf
	v_fmac_f32_dpp v192, v134, v96 row_shr:1 row_mask:0xf bank_mask:0xf
	v_fmac_f32_dpp v193, v135, v97 row_shr:1 row_mask:0xf bank_mask:0xf
	v_fmac_f32_dpp v194, v136, v98 row_shr:1 row_mask:0xf bank_mask:0xf
	v_fmac_f32_dpp v195, v137, v99 row_shr:1 row_mask:0xf bank_mask:0xf
	v_fmac_f32_dpp v188, v146, v76 row_shr:2 row_mask:0xf bank_mask:0xf
	v_fmac_f32_dpp v189, v147, v77 row_shr:2 row_mask:0xf bank_mask:0xf
	v_fmac_f32_dpp v190, v148, v78 row_shr:2 row_mask:0xf bank_mask:0xf
	v_fmac_f32_dpp v191, v149, v79 row_shr:2 row_mask:0xf bank_mask:0xf
	v_fmac_f32_dpp v192, v134, v92 row_shr:2 row_mask:0xf bank_mask:0xf
	v_fmac_f32_dpp v193, v135, v93 row_shr:2 row_mask:0xf bank_mask:0xf
	v_fmac_f32_dpp v194, v136, v94 row_shr:2 row_mask:0xf bank_mask:0xf
	v_fmac_f32_dpp v195, v137, v95 row_shr:2 row_mask:0xf bank_mask:0xf
	v_fmac_f32_dpp v188, v150, v80 row_shl:15 row_mask:0xf bank_mask:0xf
	v_fmac_f32_dpp v189, v151, v81 row_shl:15 row_mask:0xf bank_mask:0xf
	v_fmac_f32_dpp v190, v152, v82 row_shl:15 row_mask:0xf bank_mask:0xf
	v_fmac_f32_dpp v191, v153, v83 row_shl:15 row_mask:0xf bank_mask:0xf
	v_fmac_f32_dpp v192, v142, v96 row_shl:15 row_mask:0xf bank_mask:0xf
	v_fmac_f32_dpp v193, v143, v97 row_shl:15 row_mask:0xf bank_mask:0xf
	v_fmac_f32_dpp v194, v144, v98 row_shl:15 row_mask:0xf bank_mask:0xf
	v_fmac_f32_dpp v195, v145, v99 row_shl:15 row_mask:0xf bank_mask:0xf
	v_fmac_f32_dpp v188, v150, v76 row_shl:14 row_mask:0xf bank_mask:0xf
	v_fmac_f32_dpp v189, v151, v77 row_shl:14 row_mask:0xf bank_mask:0xf
	v_fmac_f32_dpp v190, v152, v78 row_shl:14 row_mask:0xf bank_mask:0xf
	v_fmac_f32_dpp v191, v153, v79 row_shl:14 row_mask:0xf bank_mask:0xf
	v_fmac_f32_dpp v192, v142, v92 row_shl:14 row_mask:0xf bank_mask:0xf
	v_fmac_f32_dpp v193, v143, v93 row_shl:14 row_mask:0xf bank_mask:0xf
	v_fmac_f32_dpp v194, v144, v94 row_shl:14 row_mask:0xf bank_mask:0xf
	v_fmac_f32_dpp v195, v145, v95 row_shl:14 row_mask:0xf bank_mask:0xf
	v_pk_mul_f32 v[196:197], v[188:189], v[216:217] op_sel_hi:[1,0]
	v_pk_mul_f32 v[198:199], v[190:191], v[216:217] op_sel_hi:[1,0]
	v_exp_f32_e32 v196, v196
	v_exp_f32_e32 v197, v197
	v_exp_f32_e32 v198, v198
	v_exp_f32_e32 v199, v199
	v_pk_add_f32 v[196:197], v[196:197], v[214:215] op_sel_hi:[1,0]
	v_pk_add_f32 v[198:199], v[198:199], v[214:215] op_sel_hi:[1,0]
	v_rcp_f32_e32 v196, v196
	v_rcp_f32_e32 v197, v197
	v_rcp_f32_e32 v198, v198
	v_rcp_f32_e32 v199, v199
	v_pk_mul_f32 v[188:189], v[188:189], v[196:197]
	v_pk_mul_f32 v[190:191], v[190:191], v[198:199]
	v_pk_mul_f32 v[188:189], v[188:189], v[192:193]
	v_pk_mul_f32 v[190:191], v[190:191], v[194:195]
	v_cvt_pk_bf16_f32 v150, v188, v189
	v_cvt_pk_bf16_f32 v151, v190, v191
	v_add_u32_e32 v213, 0x2c000, v212
	global_load_dwordx4 v[142:145], v213, s[82:83] offset:16
	v_pk_fma_f32 v[188:189], v[138:139], v[84:85], v[88:89]
	v_pk_fma_f32 v[190:191], v[140:141], v[86:87], v[90:91]
	v_pk_fma_f32 v[192:193], v[130:131], v[100:101], v[104:105]
	v_pk_fma_f32 v[194:195], v[132:133], v[102:103], v[106:107]
	v_fmac_f32_dpp v188, v138, v80 row_shr:1 row_mask:0xf bank_mask:0xf
	v_fmac_f32_dpp v189, v139, v81 row_shr:1 row_mask:0xf bank_mask:0xf
	v_fmac_f32_dpp v190, v140, v82 row_shr:1 row_mask:0xf bank_mask:0xf
	v_fmac_f32_dpp v191, v141, v83 row_shr:1 row_mask:0xf bank_mask:0xf
	v_fmac_f32_dpp v192, v130, v96 row_shr:1 row_mask:0xf bank_mask:0xf
	v_fmac_f32_dpp v193, v131, v97 row_shr:1 row_mask:0xf bank_mask:0xf
	v_fmac_f32_dpp v194, v132, v98 row_shr:1 row_mask:0xf bank_mask:0xf
	v_fmac_f32_dpp v195, v133, v99 row_shr:1 row_mask:0xf bank_mask:0xf
	v_fmac_f32_dpp v188, v138, v76 row_shr:2 row_mask:0xf bank_mask:0xf
	v_fmac_f32_dpp v189, v139, v77 row_shr:2 row_mask:0xf bank_mask:0xf
	v_fmac_f32_dpp v190, v140, v78 row_shr:2 row_mask:0xf bank_mask:0xf
	v_fmac_f32_dpp v191, v141, v79 row_shr:2 row_mask:0xf bank_mask:0xf
	v_fmac_f32_dpp v192, v130, v92 row_shr:2 row_mask:0xf bank_mask:0xf
	v_fmac_f32_dpp v193, v131, v93 row_shr:2 row_mask:0xf bank_mask:0xf
	v_fmac_f32_dpp v194, v132, v94 row_shr:2 row_mask:0xf bank_mask:0xf
	v_fmac_f32_dpp v195, v133, v95 row_shr:2 row_mask:0xf bank_mask:0xf
	v_fmac_f32_dpp v188, v146, v80 row_shl:15 row_mask:0xf bank_mask:0xf
	v_fmac_f32_dpp v189, v147, v81 row_shl:15 row_mask:0xf bank_mask:0xf
	v_fmac_f32_dpp v190, v148, v82 row_shl:15 row_mask:0xf bank_mask:0xf
	v_fmac_f32_dpp v191, v149, v83 row_shl:15 row_mask:0xf bank_mask:0xf
	v_fmac_f32_dpp v192, v134, v96 row_shl:15 row_mask:0xf bank_mask:0xf
	v_fmac_f32_dpp v193, v135, v97 row_shl:15 row_mask:0xf bank_mask:0xf
	v_fmac_f32_dpp v194, v136, v98 row_shl:15 row_mask:0xf bank_mask:0xf
	v_fmac_f32_dpp v195, v137, v99 row_shl:15 row_mask:0xf bank_mask:0xf
	v_fmac_f32_dpp v188, v146, v76 row_shl:14 row_mask:0xf bank_mask:0xf
	v_fmac_f32_dpp v189, v147, v77 row_shl:14 row_mask:0xf bank_mask:0xf
	v_fmac_f32_dpp v190, v148, v78 row_shl:14 row_mask:0xf bank_mask:0xf
	v_fmac_f32_dpp v191, v149, v79 row_shl:14 row_mask:0xf bank_mask:0xf
	v_fmac_f32_dpp v192, v134, v92 row_shl:14 row_mask:0xf bank_mask:0xf
	v_fmac_f32_dpp v193, v135, v93 row_shl:14 row_mask:0xf bank_mask:0xf
	v_fmac_f32_dpp v194, v136, v94 row_shl:14 row_mask:0xf bank_mask:0xf
	v_fmac_f32_dpp v195, v137, v95 row_shl:14 row_mask:0xf bank_mask:0xf
	v_pk_mul_f32 v[196:197], v[188:189], v[216:217] op_sel_hi:[1,0]
	v_pk_mul_f32 v[198:199], v[190:191], v[216:217] op_sel_hi:[1,0]
	v_exp_f32_e32 v196, v196
	v_exp_f32_e32 v197, v197
	v_exp_f32_e32 v198, v198
	v_exp_f32_e32 v199, v199
	v_pk_add_f32 v[196:197], v[196:197], v[214:215] op_sel_hi:[1,0]
	v_pk_add_f32 v[198:199], v[198:199], v[214:215] op_sel_hi:[1,0]
	v_rcp_f32_e32 v196, v196
	v_rcp_f32_e32 v197, v197
	v_rcp_f32_e32 v198, v198
	v_rcp_f32_e32 v199, v199
	v_pk_mul_f32 v[188:189], v[188:189], v[196:197]
	v_pk_mul_f32 v[190:191], v[190:191], v[198:199]
	v_pk_mul_f32 v[188:189], v[188:189], v[192:193]
	v_pk_mul_f32 v[190:191], v[190:191], v[194:195]
	v_cvt_pk_bf16_f32 v146, v188, v189
	v_cvt_pk_bf16_f32 v147, v190, v191
	v_add_u32_e32 v213, 0x37000, v212
	global_load_dwordx4 v[134:137], v213, s[82:83] offset:16
	v_pk_fma_f32 v[188:189], v[126:127], v[84:85], v[88:89]
	v_pk_fma_f32 v[190:191], v[128:129], v[86:87], v[90:91]
	v_pk_fma_f32 v[192:193], v[118:119], v[100:101], v[104:105]
	v_pk_fma_f32 v[194:195], v[120:121], v[102:103], v[106:107]
	v_fmac_f32_dpp v188, v126, v80 row_shr:1 row_mask:0xf bank_mask:0xf
	v_fmac_f32_dpp v189, v127, v81 row_shr:1 row_mask:0xf bank_mask:0xf
	v_fmac_f32_dpp v190, v128, v82 row_shr:1 row_mask:0xf bank_mask:0xf
	v_fmac_f32_dpp v191, v129, v83 row_shr:1 row_mask:0xf bank_mask:0xf
	v_fmac_f32_dpp v192, v118, v96 row_shr:1 row_mask:0xf bank_mask:0xf
	v_fmac_f32_dpp v193, v119, v97 row_shr:1 row_mask:0xf bank_mask:0xf
	v_fmac_f32_dpp v194, v120, v98 row_shr:1 row_mask:0xf bank_mask:0xf
	v_fmac_f32_dpp v195, v121, v99 row_shr:1 row_mask:0xf bank_mask:0xf
	v_fmac_f32_dpp v188, v126, v76 row_shr:2 row_mask:0xf bank_mask:0xf
	v_fmac_f32_dpp v189, v127, v77 row_shr:2 row_mask:0xf bank_mask:0xf
	v_fmac_f32_dpp v190, v128, v78 row_shr:2 row_mask:0xf bank_mask:0xf
	v_fmac_f32_dpp v191, v129, v79 row_shr:2 row_mask:0xf bank_mask:0xf
	v_fmac_f32_dpp v192, v118, v92 row_shr:2 row_mask:0xf bank_mask:0xf
	v_fmac_f32_dpp v193, v119, v93 row_shr:2 row_mask:0xf bank_mask:0xf
	v_fmac_f32_dpp v194, v120, v94 row_shr:2 row_mask:0xf bank_mask:0xf
	v_fmac_f32_dpp v195, v121, v95 row_shr:2 row_mask:0xf bank_mask:0xf
	v_fmac_f32_dpp v188, v138, v80 row_shl:15 row_mask:0xf bank_mask:0xf
	v_fmac_f32_dpp v189, v139, v81 row_shl:15 row_mask:0xf bank_mask:0xf
	v_fmac_f32_dpp v190, v140, v82 row_shl:15 row_mask:0xf bank_mask:0xf
	v_fmac_f32_dpp v191, v141, v83 row_shl:15 row_mask:0xf bank_mask:0xf
	v_fmac_f32_dpp v192, v130, v96 row_shl:15 row_mask:0xf bank_mask:0xf
	v_fmac_f32_dpp v193, v131, v97 row_shl:15 row_mask:0xf bank_mask:0xf
	v_fmac_f32_dpp v194, v132, v98 row_shl:15 row_mask:0xf bank_mask:0xf
	v_fmac_f32_dpp v195, v133, v99 row_shl:15 row_mask:0xf bank_mask:0xf
	v_fmac_f32_dpp v188, v138, v76 row_shl:14 row_mask:0xf bank_mask:0xf
	v_fmac_f32_dpp v189, v139, v77 row_shl:14 row_mask:0xf bank_mask:0xf
	v_fmac_f32_dpp v190, v140, v78 row_shl:14 row_mask:0xf bank_mask:0xf
	v_fmac_f32_dpp v191, v141, v79 row_shl:14 row_mask:0xf bank_mask:0xf
	v_fmac_f32_dpp v192, v130, v92 row_shl:14 row_mask:0xf bank_mask:0xf
	v_fmac_f32_dpp v193, v131, v93 row_shl:14 row_mask:0xf bank_mask:0xf
	v_fmac_f32_dpp v194, v132, v94 row_shl:14 row_mask:0xf bank_mask:0xf
	v_fmac_f32_dpp v195, v133, v95 row_shl:14 row_mask:0xf bank_mask:0xf
	v_pk_mul_f32 v[196:197], v[188:189], v[216:217] op_sel_hi:[1,0]
	v_pk_mul_f32 v[198:199], v[190:191], v[216:217] op_sel_hi:[1,0]
	v_exp_f32_e32 v196, v196
	v_exp_f32_e32 v197, v197
	v_exp_f32_e32 v198, v198
	v_exp_f32_e32 v199, v199
	v_pk_add_f32 v[196:197], v[196:197], v[214:215] op_sel_hi:[1,0]
	v_pk_add_f32 v[198:199], v[198:199], v[214:215] op_sel_hi:[1,0]
	v_rcp_f32_e32 v196, v196
	v_rcp_f32_e32 v197, v197
	v_rcp_f32_e32 v198, v198
	v_rcp_f32_e32 v199, v199
	v_pk_mul_f32 v[188:189], v[188:189], v[196:197]
	v_pk_mul_f32 v[190:191], v[190:191], v[198:199]
	v_pk_mul_f32 v[188:189], v[188:189], v[192:193]
	v_pk_mul_f32 v[190:191], v[190:191], v[194:195]
	v_cvt_pk_bf16_f32 v138, v188, v189
	v_cvt_pk_bf16_f32 v139, v190, v191
	v_add_u32_e32 v213, 0xb000, v212
	global_load_dwordx4 v[130:133], v213, s[84:85] offset:16
	v_pk_fma_f32 v[188:189], v[122:123], v[84:85], v[88:89]
	v_pk_fma_f32 v[190:191], v[124:125], v[86:87], v[90:91]
	v_pk_fma_f32 v[192:193], v[110:111], v[100:101], v[104:105]
	v_pk_fma_f32 v[194:195], v[112:113], v[102:103], v[106:107]
	v_fmac_f32_dpp v188, v122, v80 row_shr:1 row_mask:0xf bank_mask:0xf
	v_fmac_f32_dpp v189, v123, v81 row_shr:1 row_mask:0xf bank_mask:0xf
	v_fmac_f32_dpp v190, v124, v82 row_shr:1 row_mask:0xf bank_mask:0xf
	v_fmac_f32_dpp v191, v125, v83 row_shr:1 row_mask:0xf bank_mask:0xf
	v_fmac_f32_dpp v192, v110, v96 row_shr:1 row_mask:0xf bank_mask:0xf
	v_fmac_f32_dpp v193, v111, v97 row_shr:1 row_mask:0xf bank_mask:0xf
	v_fmac_f32_dpp v194, v112, v98 row_shr:1 row_mask:0xf bank_mask:0xf
	v_fmac_f32_dpp v195, v113, v99 row_shr:1 row_mask:0xf bank_mask:0xf
	v_fmac_f32_dpp v188, v122, v76 row_shr:2 row_mask:0xf bank_mask:0xf
	v_fmac_f32_dpp v189, v123, v77 row_shr:2 row_mask:0xf bank_mask:0xf
	v_fmac_f32_dpp v190, v124, v78 row_shr:2 row_mask:0xf bank_mask:0xf
	v_fmac_f32_dpp v191, v125, v79 row_shr:2 row_mask:0xf bank_mask:0xf
	v_fmac_f32_dpp v192, v110, v92 row_shr:2 row_mask:0xf bank_mask:0xf
	v_fmac_f32_dpp v193, v111, v93 row_shr:2 row_mask:0xf bank_mask:0xf
	v_fmac_f32_dpp v194, v112, v94 row_shr:2 row_mask:0xf bank_mask:0xf
	v_fmac_f32_dpp v195, v113, v95 row_shr:2 row_mask:0xf bank_mask:0xf
	v_fmac_f32_dpp v188, v126, v80 row_shl:15 row_mask:0xf bank_mask:0xf
	v_fmac_f32_dpp v189, v127, v81 row_shl:15 row_mask:0xf bank_mask:0xf
	v_fmac_f32_dpp v190, v128, v82 row_shl:15 row_mask:0xf bank_mask:0xf
	v_fmac_f32_dpp v191, v129, v83 row_shl:15 row_mask:0xf bank_mask:0xf
	v_fmac_f32_dpp v192, v118, v96 row_shl:15 row_mask:0xf bank_mask:0xf
	v_fmac_f32_dpp v193, v119, v97 row_shl:15 row_mask:0xf bank_mask:0xf
	v_fmac_f32_dpp v194, v120, v98 row_shl:15 row_mask:0xf bank_mask:0xf
	v_fmac_f32_dpp v195, v121, v99 row_shl:15 row_mask:0xf bank_mask:0xf
	v_fmac_f32_dpp v188, v126, v76 row_shl:14 row_mask:0xf bank_mask:0xf
	v_fmac_f32_dpp v189, v127, v77 row_shl:14 row_mask:0xf bank_mask:0xf
	v_fmac_f32_dpp v190, v128, v78 row_shl:14 row_mask:0xf bank_mask:0xf
	v_fmac_f32_dpp v191, v129, v79 row_shl:14 row_mask:0xf bank_mask:0xf
	v_fmac_f32_dpp v192, v118, v92 row_shl:14 row_mask:0xf bank_mask:0xf
	v_fmac_f32_dpp v193, v119, v93 row_shl:14 row_mask:0xf bank_mask:0xf
	v_fmac_f32_dpp v194, v120, v94 row_shl:14 row_mask:0xf bank_mask:0xf
	v_fmac_f32_dpp v195, v121, v95 row_shl:14 row_mask:0xf bank_mask:0xf
	v_pk_mul_f32 v[196:197], v[188:189], v[216:217] op_sel_hi:[1,0]
	v_pk_mul_f32 v[198:199], v[190:191], v[216:217] op_sel_hi:[1,0]
	v_exp_f32_e32 v196, v196
	v_exp_f32_e32 v197, v197
	v_exp_f32_e32 v198, v198
	v_exp_f32_e32 v199, v199
	v_pk_add_f32 v[196:197], v[196:197], v[214:215] op_sel_hi:[1,0]
	v_pk_add_f32 v[198:199], v[198:199], v[214:215] op_sel_hi:[1,0]
	v_rcp_f32_e32 v196, v196
	v_rcp_f32_e32 v197, v197
	v_rcp_f32_e32 v198, v198
	v_rcp_f32_e32 v199, v199
	v_pk_mul_f32 v[188:189], v[188:189], v[196:197]
	v_pk_mul_f32 v[190:191], v[190:191], v[198:199]
	v_pk_mul_f32 v[188:189], v[188:189], v[192:193]
	v_pk_mul_f32 v[190:191], v[190:191], v[194:195]
	v_cvt_pk_bf16_f32 v126, v188, v189
	v_cvt_pk_bf16_f32 v127, v190, v191
	v_add_u32_e32 v213, 0x26800, v212
	global_load_dwordx4 v[118:121], v213, s[82:83] offset:16
	v_pk_fma_f32 v[188:189], v[114:115], v[84:85], v[88:89]
	v_pk_fma_f32 v[190:191], v[116:117], v[86:87], v[90:91]
	v_pk_fma_f32 v[192:193], v[68:69], v[100:101], v[104:105]
	v_pk_fma_f32 v[194:195], v[70:71], v[102:103], v[106:107]
	v_fmac_f32_dpp v188, v114, v80 row_shr:1 row_mask:0xf bank_mask:0xf
	v_fmac_f32_dpp v189, v115, v81 row_shr:1 row_mask:0xf bank_mask:0xf
	v_fmac_f32_dpp v190, v116, v82 row_shr:1 row_mask:0xf bank_mask:0xf
	v_fmac_f32_dpp v191, v117, v83 row_shr:1 row_mask:0xf bank_mask:0xf
	v_fmac_f32_dpp v192, v68, v96 row_shr:1 row_mask:0xf bank_mask:0xf
	v_fmac_f32_dpp v193, v69, v97 row_shr:1 row_mask:0xf bank_mask:0xf
	v_fmac_f32_dpp v194, v70, v98 row_shr:1 row_mask:0xf bank_mask:0xf
	v_fmac_f32_dpp v195, v71, v99 row_shr:1 row_mask:0xf bank_mask:0xf
	v_fmac_f32_dpp v188, v114, v76 row_shr:2 row_mask:0xf bank_mask:0xf
	v_fmac_f32_dpp v189, v115, v77 row_shr:2 row_mask:0xf bank_mask:0xf
	v_fmac_f32_dpp v190, v116, v78 row_shr:2 row_mask:0xf bank_mask:0xf
	v_fmac_f32_dpp v191, v117, v79 row_shr:2 row_mask:0xf bank_mask:0xf
	v_fmac_f32_dpp v192, v68, v92 row_shr:2 row_mask:0xf bank_mask:0xf
	v_fmac_f32_dpp v193, v69, v93 row_shr:2 row_mask:0xf bank_mask:0xf
	v_fmac_f32_dpp v194, v70, v94 row_shr:2 row_mask:0xf bank_mask:0xf
	v_fmac_f32_dpp v195, v71, v95 row_shr:2 row_mask:0xf bank_mask:0xf
	v_fmac_f32_dpp v188, v122, v80 row_shl:15 row_mask:0xf bank_mask:0xf
	v_fmac_f32_dpp v189, v123, v81 row_shl:15 row_mask:0xf bank_mask:0xf
	v_fmac_f32_dpp v190, v124, v82 row_shl:15 row_mask:0xf bank_mask:0xf
	v_fmac_f32_dpp v191, v125, v83 row_shl:15 row_mask:0xf bank_mask:0xf
	v_fmac_f32_dpp v192, v110, v96 row_shl:15 row_mask:0xf bank_mask:0xf
	v_fmac_f32_dpp v193, v111, v97 row_shl:15 row_mask:0xf bank_mask:0xf
	v_fmac_f32_dpp v194, v112, v98 row_shl:15 row_mask:0xf bank_mask:0xf
	v_fmac_f32_dpp v195, v113, v99 row_shl:15 row_mask:0xf bank_mask:0xf
	v_fmac_f32_dpp v188, v122, v76 row_shl:14 row_mask:0xf bank_mask:0xf
	v_fmac_f32_dpp v189, v123, v77 row_shl:14 row_mask:0xf bank_mask:0xf
	v_fmac_f32_dpp v190, v124, v78 row_shl:14 row_mask:0xf bank_mask:0xf
	v_fmac_f32_dpp v191, v125, v79 row_shl:14 row_mask:0xf bank_mask:0xf
	v_fmac_f32_dpp v192, v110, v92 row_shl:14 row_mask:0xf bank_mask:0xf
	v_fmac_f32_dpp v193, v111, v93 row_shl:14 row_mask:0xf bank_mask:0xf
	v_fmac_f32_dpp v194, v112, v94 row_shl:14 row_mask:0xf bank_mask:0xf
	v_fmac_f32_dpp v195, v113, v95 row_shl:14 row_mask:0xf bank_mask:0xf
	v_pk_mul_f32 v[196:197], v[188:189], v[216:217] op_sel_hi:[1,0]
	v_pk_mul_f32 v[198:199], v[190:191], v[216:217] op_sel_hi:[1,0]
	v_exp_f32_e32 v196, v196
	v_exp_f32_e32 v197, v197
	v_exp_f32_e32 v198, v198
	v_exp_f32_e32 v199, v199
	v_pk_add_f32 v[196:197], v[196:197], v[214:215] op_sel_hi:[1,0]
	v_pk_add_f32 v[198:199], v[198:199], v[214:215] op_sel_hi:[1,0]
	v_rcp_f32_e32 v196, v196
	v_rcp_f32_e32 v197, v197
	v_rcp_f32_e32 v198, v198
	v_rcp_f32_e32 v199, v199
	v_pk_mul_f32 v[188:189], v[188:189], v[196:197]
	v_pk_mul_f32 v[190:191], v[190:191], v[198:199]
	v_pk_mul_f32 v[188:189], v[188:189], v[192:193]
	v_pk_mul_f32 v[190:191], v[190:191], v[194:195]
	v_cvt_pk_bf16_f32 v122, v188, v189
	v_cvt_pk_bf16_f32 v123, v190, v191
	v_add_u32_e32 v213, 0x31800, v212
	global_load_dwordx4 v[110:113], v213, s[82:83] offset:16
	v_pk_fma_f32 v[188:189], v[72:73], v[84:85], v[88:89]
	v_pk_fma_f32 v[190:191], v[74:75], v[86:87], v[90:91]
	v_pk_fma_f32 v[192:193], v[64:65], v[100:101], v[104:105]
	v_pk_fma_f32 v[194:195], v[66:67], v[102:103], v[106:107]
	v_fmac_f32_dpp v188, v72, v80 row_shr:1 row_mask:0xf bank_mask:0xf
	v_fmac_f32_dpp v189, v73, v81 row_shr:1 row_mask:0xf bank_mask:0xf
	v_fmac_f32_dpp v190, v74, v82 row_shr:1 row_mask:0xf bank_mask:0xf
	v_fmac_f32_dpp v191, v75, v83 row_shr:1 row_mask:0xf bank_mask:0xf
	v_fmac_f32_dpp v192, v64, v96 row_shr:1 row_mask:0xf bank_mask:0xf
	v_fmac_f32_dpp v193, v65, v97 row_shr:1 row_mask:0xf bank_mask:0xf
	v_fmac_f32_dpp v194, v66, v98 row_shr:1 row_mask:0xf bank_mask:0xf
	v_fmac_f32_dpp v195, v67, v99 row_shr:1 row_mask:0xf bank_mask:0xf
	v_fmac_f32_dpp v188, v72, v76 row_shr:2 row_mask:0xf bank_mask:0xf
	v_fmac_f32_dpp v189, v73, v77 row_shr:2 row_mask:0xf bank_mask:0xf
	v_fmac_f32_dpp v190, v74, v78 row_shr:2 row_mask:0xf bank_mask:0xf
	v_fmac_f32_dpp v191, v75, v79 row_shr:2 row_mask:0xf bank_mask:0xf
	v_fmac_f32_dpp v192, v64, v92 row_shr:2 row_mask:0xf bank_mask:0xf
	v_fmac_f32_dpp v193, v65, v93 row_shr:2 row_mask:0xf bank_mask:0xf
	v_fmac_f32_dpp v194, v66, v94 row_shr:2 row_mask:0xf bank_mask:0xf
	v_fmac_f32_dpp v195, v67, v95 row_shr:2 row_mask:0xf bank_mask:0xf
	v_fmac_f32_dpp v188, v114, v80 row_shl:15 row_mask:0xf bank_mask:0xf
	v_fmac_f32_dpp v189, v115, v81 row_shl:15 row_mask:0xf bank_mask:0xf
	v_fmac_f32_dpp v190, v116, v82 row_shl:15 row_mask:0xf bank_mask:0xf
	v_fmac_f32_dpp v191, v117, v83 row_shl:15 row_mask:0xf bank_mask:0xf
	v_fmac_f32_dpp v192, v68, v96 row_shl:15 row_mask:0xf bank_mask:0xf
	v_fmac_f32_dpp v193, v69, v97 row_shl:15 row_mask:0xf bank_mask:0xf
	v_fmac_f32_dpp v194, v70, v98 row_shl:15 row_mask:0xf bank_mask:0xf
	v_fmac_f32_dpp v195, v71, v99 row_shl:15 row_mask:0xf bank_mask:0xf
	v_fmac_f32_dpp v188, v114, v76 row_shl:14 row_mask:0xf bank_mask:0xf
	v_fmac_f32_dpp v189, v115, v77 row_shl:14 row_mask:0xf bank_mask:0xf
	v_fmac_f32_dpp v190, v116, v78 row_shl:14 row_mask:0xf bank_mask:0xf
	v_fmac_f32_dpp v191, v117, v79 row_shl:14 row_mask:0xf bank_mask:0xf
	v_fmac_f32_dpp v192, v68, v92 row_shl:14 row_mask:0xf bank_mask:0xf
	v_fmac_f32_dpp v193, v69, v93 row_shl:14 row_mask:0xf bank_mask:0xf
	v_fmac_f32_dpp v194, v70, v94 row_shl:14 row_mask:0xf bank_mask:0xf
	v_fmac_f32_dpp v195, v71, v95 row_shl:14 row_mask:0xf bank_mask:0xf
	v_pk_mul_f32 v[196:197], v[188:189], v[216:217] op_sel_hi:[1,0]
	v_pk_mul_f32 v[198:199], v[190:191], v[216:217] op_sel_hi:[1,0]
	v_exp_f32_e32 v196, v196
	v_exp_f32_e32 v197, v197
	v_exp_f32_e32 v198, v198
	v_exp_f32_e32 v199, v199
	v_pk_add_f32 v[196:197], v[196:197], v[214:215] op_sel_hi:[1,0]
	v_pk_add_f32 v[198:199], v[198:199], v[214:215] op_sel_hi:[1,0]
	v_rcp_f32_e32 v196, v196
	v_rcp_f32_e32 v197, v197
	v_rcp_f32_e32 v198, v198
	v_rcp_f32_e32 v199, v199
	v_pk_mul_f32 v[188:189], v[188:189], v[196:197]
	v_pk_mul_f32 v[190:191], v[190:191], v[198:199]
	v_pk_mul_f32 v[188:189], v[188:189], v[192:193]
	v_pk_mul_f32 v[190:191], v[190:191], v[194:195]
	v_cvt_pk_bf16_f32 v114, v188, v189
	v_cvt_pk_bf16_f32 v115, v190, v191
	s_waitcnt vmcnt(0)
	v_pk_fma_f32 v[188:189], v[60:61], v[134:135], v[130:131]
	v_pk_fma_f32 v[190:191], v[62:63], v[136:137], v[132:133]
	v_pk_fma_f32 v[192:193], v[56:57], v[204:205], v[208:209]
	v_pk_fma_f32 v[194:195], v[58:59], v[206:207], v[210:211]
	v_fmac_f32_dpp v188, v60, v142 row_shr:1 row_mask:0xf bank_mask:0xf
	v_fmac_f32_dpp v189, v61, v143 row_shr:1 row_mask:0xf bank_mask:0xf
	v_fmac_f32_dpp v190, v62, v144 row_shr:1 row_mask:0xf bank_mask:0xf
	v_fmac_f32_dpp v191, v63, v145 row_shr:1 row_mask:0xf bank_mask:0xf
	v_fmac_f32_dpp v192, v56, v110 row_shr:1 row_mask:0xf bank_mask:0xf
	v_fmac_f32_dpp v193, v57, v111 row_shr:1 row_mask:0xf bank_mask:0xf
	v_fmac_f32_dpp v194, v58, v112 row_shr:1 row_mask:0xf bank_mask:0xf
	v_fmac_f32_dpp v195, v59, v113 row_shr:1 row_mask:0xf bank_mask:0xf
	v_fmac_f32_dpp v188, v60, v154 row_shr:2 row_mask:0xf bank_mask:0xf
	v_fmac_f32_dpp v189, v61, v155 row_shr:2 row_mask:0xf bank_mask:0xf
	v_fmac_f32_dpp v190, v62, v156 row_shr:2 row_mask:0xf bank_mask:0xf
	v_fmac_f32_dpp v191, v63, v157 row_shr:2 row_mask:0xf bank_mask:0xf
	v_fmac_f32_dpp v192, v56, v118 row_shr:2 row_mask:0xf bank_mask:0xf
	v_fmac_f32_dpp v193, v57, v119 row_shr:2 row_mask:0xf bank_mask:0xf
	v_fmac_f32_dpp v194, v58, v120 row_shr:2 row_mask:0xf bank_mask:0xf
	v_fmac_f32_dpp v195, v59, v121 row_shr:2 row_mask:0xf bank_mask:0xf
	v_pk_mul_f32 v[196:197], v[188:189], v[216:217] op_sel_hi:[1,0]
	v_pk_mul_f32 v[198:199], v[190:191], v[216:217] op_sel_hi:[1,0]
	v_exp_f32_e32 v196, v196
	v_exp_f32_e32 v197, v197
	v_exp_f32_e32 v198, v198
	v_exp_f32_e32 v199, v199
	v_pk_add_f32 v[196:197], v[196:197], v[214:215] op_sel_hi:[1,0]
	v_pk_add_f32 v[198:199], v[198:199], v[214:215] op_sel_hi:[1,0]
	v_rcp_f32_e32 v196, v196
	v_rcp_f32_e32 v197, v197
	v_rcp_f32_e32 v198, v198
	v_rcp_f32_e32 v199, v199
	v_pk_mul_f32 v[188:189], v[188:189], v[196:197]
	v_pk_mul_f32 v[190:191], v[190:191], v[198:199]
	v_pk_mul_f32 v[188:189], v[188:189], v[192:193]
	v_pk_mul_f32 v[190:191], v[190:191], v[194:195]
	v_cvt_pk_bf16_f32 v202, v188, v189
	v_cvt_pk_bf16_f32 v203, v190, v191
	s_mov_b64 exec, vcc
	global_store_dwordx4 v215, v[200:203], s[96:97]
	s_mov_b64 exec, -1
	v_pk_fma_f32 v[188:189], v[52:53], v[134:135], v[130:131]
	v_pk_fma_f32 v[190:191], v[54:55], v[136:137], v[132:133]
	v_pk_fma_f32 v[192:193], v[44:45], v[204:205], v[208:209]
	v_pk_fma_f32 v[194:195], v[46:47], v[206:207], v[210:211]
	v_fmac_f32_dpp v188, v52, v142 row_shr:1 row_mask:0xf bank_mask:0xf
	v_fmac_f32_dpp v189, v53, v143 row_shr:1 row_mask:0xf bank_mask:0xf
	v_fmac_f32_dpp v190, v54, v144 row_shr:1 row_mask:0xf bank_mask:0xf
	v_fmac_f32_dpp v191, v55, v145 row_shr:1 row_mask:0xf bank_mask:0xf
	v_fmac_f32_dpp v192, v44, v110 row_shr:1 row_mask:0xf bank_mask:0xf
	v_fmac_f32_dpp v193, v45, v111 row_shr:1 row_mask:0xf bank_mask:0xf
	v_fmac_f32_dpp v194, v46, v112 row_shr:1 row_mask:0xf bank_mask:0xf
	v_fmac_f32_dpp v195, v47, v113 row_shr:1 row_mask:0xf bank_mask:0xf
	v_fmac_f32_dpp v188, v52, v154 row_shr:2 row_mask:0xf bank_mask:0xf
	v_fmac_f32_dpp v189, v53, v155 row_shr:2 row_mask:0xf bank_mask:0xf
	v_fmac_f32_dpp v190, v54, v156 row_shr:2 row_mask:0xf bank_mask:0xf
	v_fmac_f32_dpp v191, v55, v157 row_shr:2 row_mask:0xf bank_mask:0xf
	v_fmac_f32_dpp v192, v44, v118 row_shr:2 row_mask:0xf bank_mask:0xf
	v_fmac_f32_dpp v193, v45, v119 row_shr:2 row_mask:0xf bank_mask:0xf
	v_fmac_f32_dpp v194, v46, v120 row_shr:2 row_mask:0xf bank_mask:0xf
	v_fmac_f32_dpp v195, v47, v121 row_shr:2 row_mask:0xf bank_mask:0xf
	v_fmac_f32_dpp v188, v60, v142 row_shl:15 row_mask:0xf bank_mask:0xf
	v_fmac_f32_dpp v189, v61, v143 row_shl:15 row_mask:0xf bank_mask:0xf
	v_fmac_f32_dpp v190, v62, v144 row_shl:15 row_mask:0xf bank_mask:0xf
	v_fmac_f32_dpp v191, v63, v145 row_shl:15 row_mask:0xf bank_mask:0xf
	v_fmac_f32_dpp v192, v56, v110 row_shl:15 row_mask:0xf bank_mask:0xf
	v_fmac_f32_dpp v193, v57, v111 row_shl:15 row_mask:0xf bank_mask:0xf
	v_fmac_f32_dpp v194, v58, v112 row_shl:15 row_mask:0xf bank_mask:0xf
	v_fmac_f32_dpp v195, v59, v113 row_shl:15 row_mask:0xf bank_mask:0xf
	v_fmac_f32_dpp v188, v60, v154 row_shl:14 row_mask:0xf bank_mask:0xf
	v_fmac_f32_dpp v189, v61, v155 row_shl:14 row_mask:0xf bank_mask:0xf
	v_fmac_f32_dpp v190, v62, v156 row_shl:14 row_mask:0xf bank_mask:0xf
	v_fmac_f32_dpp v191, v63, v157 row_shl:14 row_mask:0xf bank_mask:0xf
	v_fmac_f32_dpp v192, v56, v118 row_shl:14 row_mask:0xf bank_mask:0xf
	v_fmac_f32_dpp v193, v57, v119 row_shl:14 row_mask:0xf bank_mask:0xf
	v_fmac_f32_dpp v194, v58, v120 row_shl:14 row_mask:0xf bank_mask:0xf
	v_fmac_f32_dpp v195, v59, v121 row_shl:14 row_mask:0xf bank_mask:0xf
	v_pk_mul_f32 v[196:197], v[188:189], v[216:217] op_sel_hi:[1,0]
	v_pk_mul_f32 v[198:199], v[190:191], v[216:217] op_sel_hi:[1,0]
	v_exp_f32_e32 v196, v196
	v_exp_f32_e32 v197, v197
	v_exp_f32_e32 v198, v198
	v_exp_f32_e32 v199, v199
	v_pk_add_f32 v[196:197], v[196:197], v[214:215] op_sel_hi:[1,0]
	v_pk_add_f32 v[198:199], v[198:199], v[214:215] op_sel_hi:[1,0]
	v_rcp_f32_e32 v196, v196
	v_rcp_f32_e32 v197, v197
	v_rcp_f32_e32 v198, v198
	v_rcp_f32_e32 v199, v199
	v_pk_mul_f32 v[188:189], v[188:189], v[196:197]
	v_pk_mul_f32 v[190:191], v[190:191], v[198:199]
	v_pk_mul_f32 v[188:189], v[188:189], v[192:193]
	v_pk_mul_f32 v[190:191], v[190:191], v[194:195]
	v_cvt_pk_bf16_f32 v160, v188, v189
	v_cvt_pk_bf16_f32 v161, v190, v191
	v_add_u32_e32 v213, 0x2c000, v215
	global_store_dwordx4 v213, v[158:161], s[96:97]
	v_pk_fma_f32 v[188:189], v[48:49], v[134:135], v[130:131]
	v_pk_fma_f32 v[190:191], v[50:51], v[136:137], v[132:133]
	v_pk_fma_f32 v[192:193], v[36:37], v[204:205], v[208:209]
	v_pk_fma_f32 v[194:195], v[38:39], v[206:207], v[210:211]
	v_fmac_f32_dpp v188, v48, v142 row_shr:1 row_mask:0xf bank_mask:0xf
	v_fmac_f32_dpp v189, v49, v143 row_shr:1 row_mask:0xf bank_mask:0xf
	v_fmac_f32_dpp v190, v50, v144 row_shr:1 row_mask:0xf bank_mask:0xf
	v_fmac_f32_dpp v191, v51, v145 row_shr:1 row_mask:0xf bank_mask:0xf
	v_fmac_f32_dpp v192, v36, v110 row_shr:1 row_mask:0xf bank_mask:0xf
	v_fmac_f32_dpp v193, v37, v111 row_shr:1 row_mask:0xf bank_mask:0xf
	v_fmac_f32_dpp v194, v38, v112 row_shr:1 row_mask:0xf bank_mask:0xf
	v_fmac_f32_dpp v195, v39, v113 row_shr:1 row_mask:0xf bank_mask:0xf
	v_fmac_f32_dpp v188, v48, v154 row_shr:2 row_mask:0xf bank_mask:0xf
	v_fmac_f32_dpp v189, v49, v155 row_shr:2 row_mask:0xf bank_mask:0xf
	v_fmac_f32_dpp v190, v50, v156 row_shr:2 row_mask:0xf bank_mask:0xf
	v_fmac_f32_dpp v191, v51, v157 row_shr:2 row_mask:0xf bank_mask:0xf
	v_fmac_f32_dpp v192, v36, v118 row_shr:2 row_mask:0xf bank_mask:0xf
	v_fmac_f32_dpp v193, v37, v119 row_shr:2 row_mask:0xf bank_mask:0xf
	v_fmac_f32_dpp v194, v38, v120 row_shr:2 row_mask:0xf bank_mask:0xf
	v_fmac_f32_dpp v195, v39, v121 row_shr:2 row_mask:0xf bank_mask:0xf
	v_fmac_f32_dpp v188, v52, v142 row_shl:15 row_mask:0xf bank_mask:0xf
	v_fmac_f32_dpp v189, v53, v143 row_shl:15 row_mask:0xf bank_mask:0xf
	v_fmac_f32_dpp v190, v54, v144 row_shl:15 row_mask:0xf bank_mask:0xf
	v_fmac_f32_dpp v191, v55, v145 row_shl:15 row_mask:0xf bank_mask:0xf
	v_fmac_f32_dpp v192, v44, v110 row_shl:15 row_mask:0xf bank_mask:0xf
	v_fmac_f32_dpp v193, v45, v111 row_shl:15 row_mask:0xf bank_mask:0xf
	v_fmac_f32_dpp v194, v46, v112 row_shl:15 row_mask:0xf bank_mask:0xf
	v_fmac_f32_dpp v195, v47, v113 row_shl:15 row_mask:0xf bank_mask:0xf
	v_fmac_f32_dpp v188, v52, v154 row_shl:14 row_mask:0xf bank_mask:0xf
	v_fmac_f32_dpp v189, v53, v155 row_shl:14 row_mask:0xf bank_mask:0xf
	v_fmac_f32_dpp v190, v54, v156 row_shl:14 row_mask:0xf bank_mask:0xf
	v_fmac_f32_dpp v191, v55, v157 row_shl:14 row_mask:0xf bank_mask:0xf
	v_fmac_f32_dpp v192, v44, v118 row_shl:14 row_mask:0xf bank_mask:0xf
	v_fmac_f32_dpp v193, v45, v119 row_shl:14 row_mask:0xf bank_mask:0xf
	v_fmac_f32_dpp v194, v46, v120 row_shl:14 row_mask:0xf bank_mask:0xf
	v_fmac_f32_dpp v195, v47, v121 row_shl:14 row_mask:0xf bank_mask:0xf
	v_pk_mul_f32 v[196:197], v[188:189], v[216:217] op_sel_hi:[1,0]
	v_pk_mul_f32 v[198:199], v[190:191], v[216:217] op_sel_hi:[1,0]
	v_exp_f32_e32 v196, v196
	v_exp_f32_e32 v197, v197
	v_exp_f32_e32 v198, v198
	v_exp_f32_e32 v199, v199
	v_pk_add_f32 v[196:197], v[196:197], v[214:215] op_sel_hi:[1,0]
	v_pk_add_f32 v[198:199], v[198:199], v[214:215] op_sel_hi:[1,0]
	v_rcp_f32_e32 v196, v196
	v_rcp_f32_e32 v197, v197
	v_rcp_f32_e32 v198, v198
	v_rcp_f32_e32 v199, v199
	v_pk_mul_f32 v[188:189], v[188:189], v[196:197]
	v_pk_mul_f32 v[190:191], v[190:191], v[198:199]
	v_pk_mul_f32 v[188:189], v[188:189], v[192:193]
	v_pk_mul_f32 v[190:191], v[190:191], v[194:195]
	v_cvt_pk_bf16_f32 v152, v188, v189
	v_cvt_pk_bf16_f32 v153, v190, v191
	v_add_u32_e32 v213, 0x58000, v215
	global_store_dwordx4 v213, v[150:153], s[96:97]
	v_pk_fma_f32 v[188:189], v[40:41], v[134:135], v[130:131]
	v_pk_fma_f32 v[190:191], v[42:43], v[136:137], v[132:133]
	v_pk_fma_f32 v[192:193], v[32:33], v[204:205], v[208:209]
	v_pk_fma_f32 v[194:195], v[34:35], v[206:207], v[210:211]
	v_fmac_f32_dpp v188, v40, v142 row_shr:1 row_mask:0xf bank_mask:0xf
	v_fmac_f32_dpp v189, v41, v143 row_shr:1 row_mask:0xf bank_mask:0xf
	v_fmac_f32_dpp v190, v42, v144 row_shr:1 row_mask:0xf bank_mask:0xf
	v_fmac_f32_dpp v191, v43, v145 row_shr:1 row_mask:0xf bank_mask:0xf
	v_fmac_f32_dpp v192, v32, v110 row_shr:1 row_mask:0xf bank_mask:0xf
	v_fmac_f32_dpp v193, v33, v111 row_shr:1 row_mask:0xf bank_mask:0xf
	v_fmac_f32_dpp v194, v34, v112 row_shr:1 row_mask:0xf bank_mask:0xf
	v_fmac_f32_dpp v195, v35, v113 row_shr:1 row_mask:0xf bank_mask:0xf
	v_fmac_f32_dpp v188, v40, v154 row_shr:2 row_mask:0xf bank_mask:0xf
	v_fmac_f32_dpp v189, v41, v155 row_shr:2 row_mask:0xf bank_mask:0xf
	v_fmac_f32_dpp v190, v42, v156 row_shr:2 row_mask:0xf bank_mask:0xf
	v_fmac_f32_dpp v191, v43, v157 row_shr:2 row_mask:0xf bank_mask:0xf
	v_fmac_f32_dpp v192, v32, v118 row_shr:2 row_mask:0xf bank_mask:0xf
	v_fmac_f32_dpp v193, v33, v119 row_shr:2 row_mask:0xf bank_mask:0xf
	v_fmac_f32_dpp v194, v34, v120 row_shr:2 row_mask:0xf bank_mask:0xf
	v_fmac_f32_dpp v195, v35, v121 row_shr:2 row_mask:0xf bank_mask:0xf
	v_fmac_f32_dpp v188, v48, v142 row_shl:15 row_mask:0xf bank_mask:0xf
	v_fmac_f32_dpp v189, v49, v143 row_shl:15 row_mask:0xf bank_mask:0xf
	v_fmac_f32_dpp v190, v50, v144 row_shl:15 row_mask:0xf bank_mask:0xf
	v_fmac_f32_dpp v191, v51, v145 row_shl:15 row_mask:0xf bank_mask:0xf
	v_fmac_f32_dpp v192, v36, v110 row_shl:15 row_mask:0xf bank_mask:0xf
	v_fmac_f32_dpp v193, v37, v111 row_shl:15 row_mask:0xf bank_mask:0xf
	v_fmac_f32_dpp v194, v38, v112 row_shl:15 row_mask:0xf bank_mask:0xf
	v_fmac_f32_dpp v195, v39, v113 row_shl:15 row_mask:0xf bank_mask:0xf
	v_fmac_f32_dpp v188, v48, v154 row_shl:14 row_mask:0xf bank_mask:0xf
	v_fmac_f32_dpp v189, v49, v155 row_shl:14 row_mask:0xf bank_mask:0xf
	v_fmac_f32_dpp v190, v50, v156 row_shl:14 row_mask:0xf bank_mask:0xf
	v_fmac_f32_dpp v191, v51, v157 row_shl:14 row_mask:0xf bank_mask:0xf
	v_fmac_f32_dpp v192, v36, v118 row_shl:14 row_mask:0xf bank_mask:0xf
	v_fmac_f32_dpp v193, v37, v119 row_shl:14 row_mask:0xf bank_mask:0xf
	v_fmac_f32_dpp v194, v38, v120 row_shl:14 row_mask:0xf bank_mask:0xf
	v_fmac_f32_dpp v195, v39, v121 row_shl:14 row_mask:0xf bank_mask:0xf
	v_pk_mul_f32 v[196:197], v[188:189], v[216:217] op_sel_hi:[1,0]
	v_pk_mul_f32 v[198:199], v[190:191], v[216:217] op_sel_hi:[1,0]
	v_exp_f32_e32 v196, v196
	v_exp_f32_e32 v197, v197
	v_exp_f32_e32 v198, v198
	v_exp_f32_e32 v199, v199
	v_pk_add_f32 v[196:197], v[196:197], v[214:215] op_sel_hi:[1,0]
	v_pk_add_f32 v[198:199], v[198:199], v[214:215] op_sel_hi:[1,0]
	v_rcp_f32_e32 v196, v196
	v_rcp_f32_e32 v197, v197
	v_rcp_f32_e32 v198, v198
	v_rcp_f32_e32 v199, v199
	v_pk_mul_f32 v[188:189], v[188:189], v[196:197]
	v_pk_mul_f32 v[190:191], v[190:191], v[198:199]
	v_pk_mul_f32 v[188:189], v[188:189], v[192:193]
	v_pk_mul_f32 v[190:191], v[190:191], v[194:195]
	v_cvt_pk_bf16_f32 v148, v188, v189
	v_cvt_pk_bf16_f32 v149, v190, v191
	v_add_u32_e32 v213, 0x84000, v215
	global_store_dwordx4 v213, v[146:149], s[96:97]
	v_pk_fma_f32 v[188:189], v[28:29], v[134:135], v[130:131]
	v_pk_fma_f32 v[190:191], v[30:31], v[136:137], v[132:133]
	v_pk_fma_f32 v[192:193], v[16:17], v[204:205], v[208:209]
	v_pk_fma_f32 v[194:195], v[18:19], v[206:207], v[210:211]
	v_fmac_f32_dpp v188, v28, v142 row_shr:1 row_mask:0xf bank_mask:0xf
	v_fmac_f32_dpp v189, v29, v143 row_shr:1 row_mask:0xf bank_mask:0xf
	v_fmac_f32_dpp v190, v30, v144 row_shr:1 row_mask:0xf bank_mask:0xf
	v_fmac_f32_dpp v191, v31, v145 row_shr:1 row_mask:0xf bank_mask:0xf
	v_fmac_f32_dpp v192, v16, v110 row_shr:1 row_mask:0xf bank_mask:0xf
	v_fmac_f32_dpp v193, v17, v111 row_shr:1 row_mask:0xf bank_mask:0xf
	v_fmac_f32_dpp v194, v18, v112 row_shr:1 row_mask:0xf bank_mask:0xf
	v_fmac_f32_dpp v195, v19, v113 row_shr:1 row_mask:0xf bank_mask:0xf
	v_fmac_f32_dpp v188, v28, v154 row_shr:2 row_mask:0xf bank_mask:0xf
	v_fmac_f32_dpp v189, v29, v155 row_shr:2 row_mask:0xf bank_mask:0xf
	v_fmac_f32_dpp v190, v30, v156 row_shr:2 row_mask:0xf bank_mask:0xf
	v_fmac_f32_dpp v191, v31, v157 row_shr:2 row_mask:0xf bank_mask:0xf
	v_fmac_f32_dpp v192, v16, v118 row_shr:2 row_mask:0xf bank_mask:0xf
	v_fmac_f32_dpp v193, v17, v119 row_shr:2 row_mask:0xf bank_mask:0xf
	v_fmac_f32_dpp v194, v18, v120 row_shr:2 row_mask:0xf bank_mask:0xf
	v_fmac_f32_dpp v195, v19, v121 row_shr:2 row_mask:0xf bank_mask:0xf
	v_fmac_f32_dpp v188, v40, v142 row_shl:15 row_mask:0xf bank_mask:0xf
	v_fmac_f32_dpp v189, v41, v143 row_shl:15 row_mask:0xf bank_mask:0xf
	v_fmac_f32_dpp v190, v42, v144 row_shl:15 row_mask:0xf bank_mask:0xf
	v_fmac_f32_dpp v191, v43, v145 row_shl:15 row_mask:0xf bank_mask:0xf
	v_fmac_f32_dpp v192, v32, v110 row_shl:15 row_mask:0xf bank_mask:0xf
	v_fmac_f32_dpp v193, v33, v111 row_shl:15 row_mask:0xf bank_mask:0xf
	v_fmac_f32_dpp v194, v34, v112 row_shl:15 row_mask:0xf bank_mask:0xf
	v_fmac_f32_dpp v195, v35, v113 row_shl:15 row_mask:0xf bank_mask:0xf
	v_fmac_f32_dpp v188, v40, v154 row_shl:14 row_mask:0xf bank_mask:0xf
	v_fmac_f32_dpp v189, v41, v155 row_shl:14 row_mask:0xf bank_mask:0xf
	v_fmac_f32_dpp v190, v42, v156 row_shl:14 row_mask:0xf bank_mask:0xf
	v_fmac_f32_dpp v191, v43, v157 row_shl:14 row_mask:0xf bank_mask:0xf
	v_fmac_f32_dpp v192, v32, v118 row_shl:14 row_mask:0xf bank_mask:0xf
	v_fmac_f32_dpp v193, v33, v119 row_shl:14 row_mask:0xf bank_mask:0xf
	v_fmac_f32_dpp v194, v34, v120 row_shl:14 row_mask:0xf bank_mask:0xf
	v_fmac_f32_dpp v195, v35, v121 row_shl:14 row_mask:0xf bank_mask:0xf
	v_pk_mul_f32 v[196:197], v[188:189], v[216:217] op_sel_hi:[1,0]
	v_pk_mul_f32 v[198:199], v[190:191], v[216:217] op_sel_hi:[1,0]
	v_exp_f32_e32 v196, v196
	v_exp_f32_e32 v197, v197
	v_exp_f32_e32 v198, v198
	v_exp_f32_e32 v199, v199
	v_pk_add_f32 v[196:197], v[196:197], v[214:215] op_sel_hi:[1,0]
	v_pk_add_f32 v[198:199], v[198:199], v[214:215] op_sel_hi:[1,0]
	v_rcp_f32_e32 v196, v196
	v_rcp_f32_e32 v197, v197
	v_rcp_f32_e32 v198, v198
	v_rcp_f32_e32 v199, v199
	v_pk_mul_f32 v[188:189], v[188:189], v[196:197]
	v_pk_mul_f32 v[190:191], v[190:191], v[198:199]
	v_pk_mul_f32 v[188:189], v[188:189], v[192:193]
	v_pk_mul_f32 v[190:191], v[190:191], v[194:195]
	v_cvt_pk_bf16_f32 v140, v188, v189
	v_cvt_pk_bf16_f32 v141, v190, v191
	v_add_u32_e32 v213, 0xb0000, v215
	global_store_dwordx4 v213, v[138:141], s[96:97]
	v_pk_fma_f32 v[188:189], v[24:25], v[134:135], v[130:131]
	v_pk_fma_f32 v[190:191], v[26:27], v[136:137], v[132:133]
	v_pk_fma_f32 v[192:193], v[12:13], v[204:205], v[208:209]
	v_pk_fma_f32 v[194:195], v[14:15], v[206:207], v[210:211]
	v_fmac_f32_dpp v188, v24, v142 row_shr:1 row_mask:0xf bank_mask:0xf
	v_fmac_f32_dpp v189, v25, v143 row_shr:1 row_mask:0xf bank_mask:0xf
	v_fmac_f32_dpp v190, v26, v144 row_shr:1 row_mask:0xf bank_mask:0xf
	v_fmac_f32_dpp v191, v27, v145 row_shr:1 row_mask:0xf bank_mask:0xf
	v_fmac_f32_dpp v192, v12, v110 row_shr:1 row_mask:0xf bank_mask:0xf
	v_fmac_f32_dpp v193, v13, v111 row_shr:1 row_mask:0xf bank_mask:0xf
	v_fmac_f32_dpp v194, v14, v112 row_shr:1 row_mask:0xf bank_mask:0xf
	v_fmac_f32_dpp v195, v15, v113 row_shr:1 row_mask:0xf bank_mask:0xf
	v_fmac_f32_dpp v188, v24, v154 row_shr:2 row_mask:0xf bank_mask:0xf
	v_fmac_f32_dpp v189, v25, v155 row_shr:2 row_mask:0xf bank_mask:0xf
	v_fmac_f32_dpp v190, v26, v156 row_shr:2 row_mask:0xf bank_mask:0xf
	v_fmac_f32_dpp v191, v27, v157 row_shr:2 row_mask:0xf bank_mask:0xf
	v_fmac_f32_dpp v192, v12, v118 row_shr:2 row_mask:0xf bank_mask:0xf
	v_fmac_f32_dpp v193, v13, v119 row_shr:2 row_mask:0xf bank_mask:0xf
	v_fmac_f32_dpp v194, v14, v120 row_shr:2 row_mask:0xf bank_mask:0xf
	v_fmac_f32_dpp v195, v15, v121 row_shr:2 row_mask:0xf bank_mask:0xf
	v_fmac_f32_dpp v188, v28, v142 row_shl:15 row_mask:0xf bank_mask:0xf
	v_fmac_f32_dpp v189, v29, v143 row_shl:15 row_mask:0xf bank_mask:0xf
	v_fmac_f32_dpp v190, v30, v144 row_shl:15 row_mask:0xf bank_mask:0xf
	v_fmac_f32_dpp v191, v31, v145 row_shl:15 row_mask:0xf bank_mask:0xf
	v_fmac_f32_dpp v192, v16, v110 row_shl:15 row_mask:0xf bank_mask:0xf
	v_fmac_f32_dpp v193, v17, v111 row_shl:15 row_mask:0xf bank_mask:0xf
	v_fmac_f32_dpp v194, v18, v112 row_shl:15 row_mask:0xf bank_mask:0xf
	v_fmac_f32_dpp v195, v19, v113 row_shl:15 row_mask:0xf bank_mask:0xf
	v_fmac_f32_dpp v188, v28, v154 row_shl:14 row_mask:0xf bank_mask:0xf
	v_fmac_f32_dpp v189, v29, v155 row_shl:14 row_mask:0xf bank_mask:0xf
	v_fmac_f32_dpp v190, v30, v156 row_shl:14 row_mask:0xf bank_mask:0xf
	v_fmac_f32_dpp v191, v31, v157 row_shl:14 row_mask:0xf bank_mask:0xf
	v_fmac_f32_dpp v192, v16, v118 row_shl:14 row_mask:0xf bank_mask:0xf
	v_fmac_f32_dpp v193, v17, v119 row_shl:14 row_mask:0xf bank_mask:0xf
	v_fmac_f32_dpp v194, v18, v120 row_shl:14 row_mask:0xf bank_mask:0xf
	v_fmac_f32_dpp v195, v19, v121 row_shl:14 row_mask:0xf bank_mask:0xf
	v_pk_mul_f32 v[196:197], v[188:189], v[216:217] op_sel_hi:[1,0]
	v_pk_mul_f32 v[198:199], v[190:191], v[216:217] op_sel_hi:[1,0]
	v_exp_f32_e32 v196, v196
	v_exp_f32_e32 v197, v197
	v_exp_f32_e32 v198, v198
	v_exp_f32_e32 v199, v199
	v_pk_add_f32 v[196:197], v[196:197], v[214:215] op_sel_hi:[1,0]
	v_pk_add_f32 v[198:199], v[198:199], v[214:215] op_sel_hi:[1,0]
	v_rcp_f32_e32 v196, v196
	v_rcp_f32_e32 v197, v197
	v_rcp_f32_e32 v198, v198
	v_rcp_f32_e32 v199, v199
	v_pk_mul_f32 v[188:189], v[188:189], v[196:197]
	v_pk_mul_f32 v[190:191], v[190:191], v[198:199]
	v_pk_mul_f32 v[188:189], v[188:189], v[192:193]
	v_pk_mul_f32 v[190:191], v[190:191], v[194:195]
	v_cvt_pk_bf16_f32 v128, v188, v189
	v_cvt_pk_bf16_f32 v129, v190, v191
	v_add_u32_e32 v213, 0xdc000, v215
	global_store_dwordx4 v213, v[126:129], s[96:97]
	v_pk_fma_f32 v[188:189], v[20:21], v[134:135], v[130:131]
	v_pk_fma_f32 v[190:191], v[22:23], v[136:137], v[132:133]
	v_pk_fma_f32 v[192:193], v[8:9], v[204:205], v[208:209]
	v_pk_fma_f32 v[194:195], v[10:11], v[206:207], v[210:211]
	v_fmac_f32_dpp v188, v20, v142 row_shr:1 row_mask:0xf bank_mask:0xf
	v_fmac_f32_dpp v189, v21, v143 row_shr:1 row_mask:0xf bank_mask:0xf
	v_fmac_f32_dpp v190, v22, v144 row_shr:1 row_mask:0xf bank_mask:0xf
	v_fmac_f32_dpp v191, v23, v145 row_shr:1 row_mask:0xf bank_mask:0xf
	v_fmac_f32_dpp v192, v8, v110 row_shr:1 row_mask:0xf bank_mask:0xf
	v_fmac_f32_dpp v193, v9, v111 row_shr:1 row_mask:0xf bank_mask:0xf
	v_fmac_f32_dpp v194, v10, v112 row_shr:1 row_mask:0xf bank_mask:0xf
	v_fmac_f32_dpp v195, v11, v113 row_shr:1 row_mask:0xf bank_mask:0xf
	v_fmac_f32_dpp v188, v20, v154 row_shr:2 row_mask:0xf bank_mask:0xf
	v_fmac_f32_dpp v189, v21, v155 row_shr:2 row_mask:0xf bank_mask:0xf
	v_fmac_f32_dpp v190, v22, v156 row_shr:2 row_mask:0xf bank_mask:0xf
	v_fmac_f32_dpp v191, v23, v157 row_shr:2 row_mask:0xf bank_mask:0xf
	v_fmac_f32_dpp v192, v8, v118 row_shr:2 row_mask:0xf bank_mask:0xf
	v_fmac_f32_dpp v193, v9, v119 row_shr:2 row_mask:0xf bank_mask:0xf
	v_fmac_f32_dpp v194, v10, v120 row_shr:2 row_mask:0xf bank_mask:0xf
	v_fmac_f32_dpp v195, v11, v121 row_shr:2 row_mask:0xf bank_mask:0xf
	v_fmac_f32_dpp v188, v24, v142 row_shl:15 row_mask:0xf bank_mask:0xf
	v_fmac_f32_dpp v189, v25, v143 row_shl:15 row_mask:0xf bank_mask:0xf
	v_fmac_f32_dpp v190, v26, v144 row_shl:15 row_mask:0xf bank_mask:0xf
	v_fmac_f32_dpp v191, v27, v145 row_shl:15 row_mask:0xf bank_mask:0xf
	v_fmac_f32_dpp v192, v12, v110 row_shl:15 row_mask:0xf bank_mask:0xf
	v_fmac_f32_dpp v193, v13, v111 row_shl:15 row_mask:0xf bank_mask:0xf
	v_fmac_f32_dpp v194, v14, v112 row_shl:15 row_mask:0xf bank_mask:0xf
	v_fmac_f32_dpp v195, v15, v113 row_shl:15 row_mask:0xf bank_mask:0xf
	v_fmac_f32_dpp v188, v24, v154 row_shl:14 row_mask:0xf bank_mask:0xf
	v_fmac_f32_dpp v189, v25, v155 row_shl:14 row_mask:0xf bank_mask:0xf
	v_fmac_f32_dpp v190, v26, v156 row_shl:14 row_mask:0xf bank_mask:0xf
	v_fmac_f32_dpp v191, v27, v157 row_shl:14 row_mask:0xf bank_mask:0xf
	v_fmac_f32_dpp v192, v12, v118 row_shl:14 row_mask:0xf bank_mask:0xf
	v_fmac_f32_dpp v193, v13, v119 row_shl:14 row_mask:0xf bank_mask:0xf
	v_fmac_f32_dpp v194, v14, v120 row_shl:14 row_mask:0xf bank_mask:0xf
	v_fmac_f32_dpp v195, v15, v121 row_shl:14 row_mask:0xf bank_mask:0xf
	v_pk_mul_f32 v[196:197], v[188:189], v[216:217] op_sel_hi:[1,0]
	v_pk_mul_f32 v[198:199], v[190:191], v[216:217] op_sel_hi:[1,0]
	v_exp_f32_e32 v196, v196
	v_exp_f32_e32 v197, v197
	v_exp_f32_e32 v198, v198
	v_exp_f32_e32 v199, v199
	v_pk_add_f32 v[196:197], v[196:197], v[214:215] op_sel_hi:[1,0]
	v_pk_add_f32 v[198:199], v[198:199], v[214:215] op_sel_hi:[1,0]
	v_rcp_f32_e32 v196, v196
	v_rcp_f32_e32 v197, v197
	v_rcp_f32_e32 v198, v198
	v_rcp_f32_e32 v199, v199
	v_pk_mul_f32 v[188:189], v[188:189], v[196:197]
	v_pk_mul_f32 v[190:191], v[190:191], v[198:199]
	v_pk_mul_f32 v[188:189], v[188:189], v[192:193]
	v_pk_mul_f32 v[190:191], v[190:191], v[194:195]
	v_cvt_pk_bf16_f32 v124, v188, v189
	v_cvt_pk_bf16_f32 v125, v190, v191
	v_add_u32_e32 v213, 0x108000, v215
	global_store_dwordx4 v213, v[122:125], s[96:97]
	v_pk_fma_f32 v[188:189], v[4:5], v[134:135], v[130:131]
	v_pk_fma_f32 v[190:191], v[6:7], v[136:137], v[132:133]
	v_pk_fma_f32 v[192:193], v[0:1], v[204:205], v[208:209]
	v_pk_fma_f32 v[194:195], v[2:3], v[206:207], v[210:211]
	v_fmac_f32_dpp v188, v4, v142 row_shr:1 row_mask:0xf bank_mask:0xf
	v_fmac_f32_dpp v189, v5, v143 row_shr:1 row_mask:0xf bank_mask:0xf
	v_fmac_f32_dpp v190, v6, v144 row_shr:1 row_mask:0xf bank_mask:0xf
	v_fmac_f32_dpp v191, v7, v145 row_shr:1 row_mask:0xf bank_mask:0xf
	v_fmac_f32_dpp v192, v0, v110 row_shr:1 row_mask:0xf bank_mask:0xf
	v_fmac_f32_dpp v193, v1, v111 row_shr:1 row_mask:0xf bank_mask:0xf
	v_fmac_f32_dpp v194, v2, v112 row_shr:1 row_mask:0xf bank_mask:0xf
	v_fmac_f32_dpp v195, v3, v113 row_shr:1 row_mask:0xf bank_mask:0xf
	v_fmac_f32_dpp v188, v4, v154 row_shr:2 row_mask:0xf bank_mask:0xf
	v_fmac_f32_dpp v189, v5, v155 row_shr:2 row_mask:0xf bank_mask:0xf
	v_fmac_f32_dpp v190, v6, v156 row_shr:2 row_mask:0xf bank_mask:0xf
	v_fmac_f32_dpp v191, v7, v157 row_shr:2 row_mask:0xf bank_mask:0xf
	v_fmac_f32_dpp v192, v0, v118 row_shr:2 row_mask:0xf bank_mask:0xf
	v_fmac_f32_dpp v193, v1, v119 row_shr:2 row_mask:0xf bank_mask:0xf
	v_fmac_f32_dpp v194, v2, v120 row_shr:2 row_mask:0xf bank_mask:0xf
	v_fmac_f32_dpp v195, v3, v121 row_shr:2 row_mask:0xf bank_mask:0xf
	v_fmac_f32_dpp v188, v20, v142 row_shl:15 row_mask:0xf bank_mask:0xf
	v_fmac_f32_dpp v189, v21, v143 row_shl:15 row_mask:0xf bank_mask:0xf
	v_fmac_f32_dpp v190, v22, v144 row_shl:15 row_mask:0xf bank_mask:0xf
	v_fmac_f32_dpp v191, v23, v145 row_shl:15 row_mask:0xf bank_mask:0xf
	v_fmac_f32_dpp v192, v8, v110 row_shl:15 row_mask:0xf bank_mask:0xf
	v_fmac_f32_dpp v193, v9, v111 row_shl:15 row_mask:0xf bank_mask:0xf
	v_fmac_f32_dpp v194, v10, v112 row_shl:15 row_mask:0xf bank_mask:0xf
	v_fmac_f32_dpp v195, v11, v113 row_shl:15 row_mask:0xf bank_mask:0xf
	v_fmac_f32_dpp v188, v20, v154 row_shl:14 row_mask:0xf bank_mask:0xf
	v_fmac_f32_dpp v189, v21, v155 row_shl:14 row_mask:0xf bank_mask:0xf
	v_fmac_f32_dpp v190, v22, v156 row_shl:14 row_mask:0xf bank_mask:0xf
	v_fmac_f32_dpp v191, v23, v157 row_shl:14 row_mask:0xf bank_mask:0xf
	v_fmac_f32_dpp v192, v8, v118 row_shl:14 row_mask:0xf bank_mask:0xf
	v_fmac_f32_dpp v193, v9, v119 row_shl:14 row_mask:0xf bank_mask:0xf
	v_fmac_f32_dpp v194, v10, v120 row_shl:14 row_mask:0xf bank_mask:0xf
	v_fmac_f32_dpp v195, v11, v121 row_shl:14 row_mask:0xf bank_mask:0xf
	v_pk_mul_f32 v[196:197], v[188:189], v[216:217] op_sel_hi:[1,0]
	v_pk_mul_f32 v[198:199], v[190:191], v[216:217] op_sel_hi:[1,0]
	v_exp_f32_e32 v196, v196
	v_exp_f32_e32 v197, v197
	v_exp_f32_e32 v198, v198
	v_exp_f32_e32 v199, v199
	v_pk_add_f32 v[196:197], v[196:197], v[214:215] op_sel_hi:[1,0]
	v_pk_add_f32 v[198:199], v[198:199], v[214:215] op_sel_hi:[1,0]
	v_rcp_f32_e32 v196, v196
	v_rcp_f32_e32 v197, v197
	v_rcp_f32_e32 v198, v198
	v_rcp_f32_e32 v199, v199
	v_pk_mul_f32 v[188:189], v[188:189], v[196:197]
	v_pk_mul_f32 v[190:191], v[190:191], v[198:199]
	v_pk_mul_f32 v[188:189], v[188:189], v[192:193]
	v_pk_mul_f32 v[190:191], v[190:191], v[194:195]
	v_cvt_pk_bf16_f32 v116, v188, v189
	v_cvt_pk_bf16_f32 v117, v190, v191
	v_add_u32_e32 v213, 0x134000, v215
	global_store_dwordx4 v213, v[114:117], s[96:97]
	s_branch .LBB0_836

	.amdhsa_kernel _Z14fwd_megakernel6Params
		.amdhsa_group_segment_fixed_size 24576
		.amdhsa_private_segment_fixed_size 0
		.amdhsa_kernarg_size 408
		.amdhsa_user_sgpr_count 2
		.amdhsa_user_sgpr_dispatch_ptr 0
		.amdhsa_user_sgpr_queue_ptr 0
		.amdhsa_user_sgpr_kernarg_segment_ptr 1
		.amdhsa_user_sgpr_dispatch_id 0
		.amdhsa_user_sgpr_kernarg_preload_length 0
		.amdhsa_user_sgpr_kernarg_preload_offset 0
		.amdhsa_user_sgpr_private_segment_size 0
		.amdhsa_uses_dynamic_stack 0
		.amdhsa_enable_private_segment 0
		.amdhsa_system_sgpr_workgroup_id_x 1
		.amdhsa_system_sgpr_workgroup_id_y 0
		.amdhsa_system_sgpr_workgroup_id_z 0
		.amdhsa_system_sgpr_workgroup_info 0
		.amdhsa_system_vgpr_workitem_id 2
		.amdhsa_next_free_vgpr 256
		.amdhsa_next_free_sgpr 102
		.amdhsa_accum_offset 256
		.amdhsa_reserve_vcc 1
		.amdhsa_float_round_mode_32 0
		.amdhsa_float_round_mode_16_64 0
		.amdhsa_float_denorm_mode_32 3
		.amdhsa_float_denorm_mode_16_64 3
		.amdhsa_dx10_clamp 1
		.amdhsa_ieee_mode 1
		.amdhsa_fp16_overflow 0
		.amdhsa_tg_split 0
		.amdhsa_exception_fp_ieee_invalid_op 0
		.amdhsa_exception_fp_denorm_src 0
		.amdhsa_exception_fp_ieee_div_zero 0
		.amdhsa_exception_fp_ieee_overflow 0
		.amdhsa_exception_fp_ieee_underflow 0
		.amdhsa_exception_fp_ieee_inexact 0
		.amdhsa_exception_int_div_zero 0
	.end_amdhsa_kernel

amdhsa.kernels:
  - .agpr_count:     0
    .args:
      - .offset:         0
        .size:           152
        .value_kind:     by_value
      - .offset:         152
        .size:           4
        .value_kind:     hidden_block_count_x
      - .offset:         156
        .size:           4
        .value_kind:     hidden_block_count_y
      - .offset:         160
        .size:           4
        .value_kind:     hidden_block_count_z
      - .offset:         164
        .size:           2
        .value_kind:     hidden_group_size_x
      - .offset:         166
        .size:           2
        .value_kind:     hidden_group_size_y
      - .offset:         168
        .size:           2
        .value_kind:     hidden_group_size_z
      - .offset:         170
        .size:           2
        .value_kind:     hidden_remainder_x
      - .offset:         172
        .size:           2
        .value_kind:     hidden_remainder_y
      - .offset:         174
        .size:           2
        .value_kind:     hidden_remainder_z
      - .offset:         192
        .size:           8
        .value_kind:     hidden_global_offset_x
      - .offset:         200
        .size:           8
        .value_kind:     hidden_global_offset_y
      - .offset:         208
        .size:           8
        .value_kind:     hidden_global_offset_z
      - .offset:         216
        .size:           2
        .value_kind:     hidden_grid_dims
      - .offset:         240
        .size:           8
        .value_kind:     hidden_multigrid_sync_arg
      - .offset:         272
        .size:           4
        .value_kind:     hidden_dynamic_lds_size
    .group_segment_fixed_size: 24576
    .kernarg_segment_align: 8
    .kernarg_segment_size: 408
    .language:       OpenCL C
    .language_version:
      - 2
      - 0
    .max_flat_workgroup_size: 512
    .name:           _Z14fwd_megakernel6Params
    .private_segment_fixed_size: 0
    .sgpr_count:     108
    .sgpr_spill_count: 19
    .symbol:         _Z14fwd_megakernel6Params.kd
    .uniform_work_group_size: 1
    .uses_dynamic_stack: false
    .vgpr_count:     256
    .vgpr_spill_count: 0
    .wavefront_size: 64
